# v21: GEMM K-loops all LDS-DMA pieces in scalar-base form (no 64-bit VALU address adds), m0 wait-state slots filled with needed SALU
# baseline (speedup 1.0000x reference)
.LBB0_154:
	ds_read_b128 v[180:183], v163
	ds_read_b128 v[184:187], v164
	ds_read_b128 v[188:191], v165
	ds_read_b128 v[196:199], v167
	ds_read_b128 v[200:203], v168
	ds_read_b128 v[204:207], v169
	ds_read_b128 v[208:211], v170
	ds_read_b128 v[212:215], v171
	s_add_u32 s12, s10, 0xfffc0080
	s_addc_u32 s13, s11, -1
	s_cmp_eq_u32 s54, 12
	s_cselect_b32 s37, s5, s13
	s_cselect_b32 s36, s7, s12
	s_cselect_b32 s13, s27, s39
	s_cselect_b32 s12, s29, s38
	s_mov_b32 m0, s85
	ds_read_b128 v[216:219], v145
	ds_read_b128 v[220:223], v145 offset:1024
	ds_read_b128 v[224:227], v145 offset:2048
	ds_read_b128 v[228:231], v145 offset:3072
	ds_read_b128 v[232:235], v145 offset:4096
	ds_read_b128 v[236:239], v145 offset:5120
	ds_read_b128 v[240:243], v145 offset:6144
	ds_read_b128 v[244:247], v145 offset:7168
	global_load_lds_dwordx4 v138, s[10:11]
	s_mov_b32 m0, s86
	s_nop 0
	global_load_lds_dwordx4 v140, s[10:11]
	s_waitcnt vmcnt(8)
	s_waitcnt lgkmcnt(0)
	s_barrier
	s_setprio 1
	s_waitcnt lgkmcnt(0)
	v_mfma_f32_16x16x32_bf16 v[124:127], v[180:183], v[216:219], v[124:127]
	v_mfma_f32_16x16x32_bf16 v[120:123], v[188:191], v[216:219], v[120:123]
	v_mfma_f32_16x16x32_bf16 v[108:111], v[180:183], v[224:227], v[108:111]
	v_mfma_f32_16x16x32_bf16 v[104:107], v[188:191], v[224:227], v[104:107]
	v_mfma_f32_16x16x32_bf16 v[92:95], v[180:183], v[232:235], v[92:95]
	v_mfma_f32_16x16x32_bf16 v[88:91], v[188:191], v[232:235], v[88:91]
	v_mfma_f32_16x16x32_bf16 v[76:79], v[180:183], v[240:243], v[76:79]
	v_mfma_f32_16x16x32_bf16 v[72:75], v[188:191], v[240:243], v[72:75]
	v_mfma_f32_16x16x32_bf16 v[124:127], v[184:187], v[220:223], v[124:127]
	v_mfma_f32_16x16x32_bf16 v[120:123], v[196:199], v[220:223], v[120:123]
	v_mfma_f32_16x16x32_bf16 v[108:111], v[184:187], v[228:231], v[108:111]
	v_mfma_f32_16x16x32_bf16 v[104:107], v[196:199], v[228:231], v[104:107]
	v_mfma_f32_16x16x32_bf16 v[92:95], v[184:187], v[236:239], v[92:95]
	v_mfma_f32_16x16x32_bf16 v[88:91], v[196:199], v[236:239], v[88:91]
	v_mfma_f32_16x16x32_bf16 v[76:79], v[184:187], v[244:247], v[76:79]
	v_mfma_f32_16x16x32_bf16 v[72:75], v[196:199], v[244:247], v[72:75]
	s_setprio 0
	s_setprio 1
	v_mfma_f32_16x16x32_bf16 v[116:119], v[200:203], v[216:219], v[116:119]
	v_mfma_f32_16x16x32_bf16 v[112:115], v[208:211], v[216:219], v[112:115]
	v_mfma_f32_16x16x32_bf16 v[100:103], v[200:203], v[224:227], v[100:103]
	v_mfma_f32_16x16x32_bf16 v[96:99], v[208:211], v[224:227], v[96:99]
	v_mfma_f32_16x16x32_bf16 v[84:87], v[200:203], v[232:235], v[84:87]
	v_mfma_f32_16x16x32_bf16 v[80:83], v[208:211], v[232:235], v[80:83]
	v_mfma_f32_16x16x32_bf16 v[68:71], v[200:203], v[240:243], v[68:71]
	v_mfma_f32_16x16x32_bf16 v[64:67], v[208:211], v[240:243], v[64:67]
	v_mfma_f32_16x16x32_bf16 v[116:119], v[204:207], v[220:223], v[116:119]
	v_mfma_f32_16x16x32_bf16 v[112:115], v[212:215], v[220:223], v[112:115]
	v_mfma_f32_16x16x32_bf16 v[100:103], v[204:207], v[228:231], v[100:103]
	v_mfma_f32_16x16x32_bf16 v[96:99], v[212:215], v[228:231], v[96:99]
	v_mfma_f32_16x16x32_bf16 v[84:87], v[204:207], v[236:239], v[84:87]
	v_mfma_f32_16x16x32_bf16 v[80:83], v[212:215], v[236:239], v[80:83]
	v_mfma_f32_16x16x32_bf16 v[68:71], v[204:207], v[244:247], v[68:71]
	v_mfma_f32_16x16x32_bf16 v[64:67], v[212:215], v[244:247], v[64:67]
	s_setprio 0
	s_barrier
	s_mov_b32 m0, s25
	s_add_u32 s56, s12, 0x40000
	ds_read_b128 v[216:219], v145 offset:16384
	ds_read_b128 v[220:223], v145 offset:17408
	ds_read_b128 v[224:227], v145 offset:18432
	ds_read_b128 v[228:231], v145 offset:19456
	ds_read_b128 v[232:235], v145 offset:20480
	ds_read_b128 v[236:239], v145 offset:21504
	ds_read_b128 v[240:243], v145 offset:22528
	ds_read_b128 v[244:247], v145 offset:23552
	global_load_lds_dwordx4 v132, s[12:13]
	s_mov_b32 m0, s33
	s_addc_u32 s57, s13, 0
	global_load_lds_dwordx4 v134, s[12:13]
	s_mov_b32 m0, s62
	s_add_u32 s98, s12, s20
	global_load_lds_dwordx4 v132, s[56:57]
	s_mov_b32 m0, s63
	s_addc_u32 s99, s13, s21
	global_load_lds_dwordx4 v134, s[56:57]
	s_mov_b32 m0, s2
	s_add_u32 s100, s36, s20
	global_load_lds_dwordx4 v132, s[36:37]
	s_mov_b32 m0, s64
	s_addc_u32 s101, s37, s21
	global_load_lds_dwordx4 v134, s[36:37]
	s_waitcnt vmcnt(8)
	s_waitcnt lgkmcnt(0)
	s_barrier
	s_setprio 1
	s_waitcnt lgkmcnt(0)
	v_mfma_f32_16x16x32_bf16 v[60:63], v[180:183], v[216:219], v[60:63]
	v_mfma_f32_16x16x32_bf16 v[56:59], v[188:191], v[216:219], v[56:59]
	v_mfma_f32_16x16x32_bf16 v[44:47], v[180:183], v[224:227], v[44:47]
	v_mfma_f32_16x16x32_bf16 v[40:43], v[188:191], v[224:227], v[40:43]
	v_mfma_f32_16x16x32_bf16 v[28:31], v[180:183], v[232:235], v[28:31]
	v_mfma_f32_16x16x32_bf16 v[24:27], v[188:191], v[232:235], v[24:27]
	v_mfma_f32_16x16x32_bf16 v[12:15], v[180:183], v[240:243], v[12:15]
	v_mfma_f32_16x16x32_bf16 v[8:11], v[188:191], v[240:243], v[8:11]
	v_mfma_f32_16x16x32_bf16 v[60:63], v[184:187], v[220:223], v[60:63]
	v_mfma_f32_16x16x32_bf16 v[56:59], v[196:199], v[220:223], v[56:59]
	v_mfma_f32_16x16x32_bf16 v[44:47], v[184:187], v[228:231], v[44:47]
	v_mfma_f32_16x16x32_bf16 v[40:43], v[196:199], v[228:231], v[40:43]
	v_mfma_f32_16x16x32_bf16 v[28:31], v[184:187], v[236:239], v[28:31]
	v_mfma_f32_16x16x32_bf16 v[24:27], v[196:199], v[236:239], v[24:27]
	v_mfma_f32_16x16x32_bf16 v[12:15], v[184:187], v[244:247], v[12:15]
	v_mfma_f32_16x16x32_bf16 v[8:11], v[196:199], v[244:247], v[8:11]
	s_setprio 0
	s_setprio 1
	v_mfma_f32_16x16x32_bf16 v[52:55], v[200:203], v[216:219], v[52:55]
	v_mfma_f32_16x16x32_bf16 v[48:51], v[208:211], v[216:219], v[48:51]
	v_mfma_f32_16x16x32_bf16 v[36:39], v[200:203], v[224:227], v[36:39]
	v_mfma_f32_16x16x32_bf16 v[32:35], v[208:211], v[224:227], v[32:35]
	v_mfma_f32_16x16x32_bf16 v[20:23], v[200:203], v[232:235], v[20:23]
	v_mfma_f32_16x16x32_bf16 v[16:19], v[208:211], v[232:235], v[16:19]
	v_mfma_f32_16x16x32_bf16 v[4:7], v[200:203], v[240:243], v[4:7]
	v_mfma_f32_16x16x32_bf16 v[0:3], v[208:211], v[240:243], v[0:3]
	v_mfma_f32_16x16x32_bf16 v[52:55], v[204:207], v[220:223], v[52:55]
	v_mfma_f32_16x16x32_bf16 v[48:51], v[212:215], v[220:223], v[48:51]
	v_mfma_f32_16x16x32_bf16 v[36:39], v[204:207], v[228:231], v[36:39]
	v_mfma_f32_16x16x32_bf16 v[32:35], v[212:215], v[228:231], v[32:35]
	v_mfma_f32_16x16x32_bf16 v[20:23], v[204:207], v[236:239], v[20:23]
	v_mfma_f32_16x16x32_bf16 v[16:19], v[212:215], v[236:239], v[16:19]
	v_mfma_f32_16x16x32_bf16 v[4:7], v[204:207], v[244:247], v[4:7]
	v_mfma_f32_16x16x32_bf16 v[0:3], v[212:215], v[244:247], v[0:3]
	s_setprio 0
	s_barrier
	ds_read_b128 v[180:183], v172
	ds_read_b128 v[184:187], v173
	ds_read_b128 v[188:191], v174
	ds_read_b128 v[196:199], v175
	ds_read_b128 v[200:203], v176
	ds_read_b128 v[204:207], v177
	ds_read_b128 v[208:211], v178
	ds_read_b128 v[212:215], v179
	s_add_u32 s36, s36, 0x40000
	s_addc_u32 s37, s37, 0
	s_mov_b32 m0, s65
	ds_read_b128 v[216:219], v145 offset:32768
	ds_read_b128 v[220:223], v145 offset:33792
	ds_read_b128 v[224:227], v145 offset:34816
	ds_read_b128 v[228:231], v145 offset:35840
	ds_read_b128 v[232:235], v145 offset:36864
	ds_read_b128 v[236:239], v145 offset:37888
	ds_read_b128 v[240:243], v145 offset:38912
	ds_read_b128 v[244:247], v145 offset:39936
	global_load_lds_dwordx4 v132, s[36:37]
	s_mov_b32 m0, s66
	s_nop 0
	global_load_lds_dwordx4 v134, s[36:37]
	s_waitcnt vmcnt(8)
	s_waitcnt lgkmcnt(0)
	s_barrier
	s_setprio 1
	s_waitcnt lgkmcnt(0)
	v_mfma_f32_16x16x32_bf16 v[124:127], v[180:183], v[216:219], v[124:127]
	v_mfma_f32_16x16x32_bf16 v[120:123], v[188:191], v[216:219], v[120:123]
	v_mfma_f32_16x16x32_bf16 v[108:111], v[180:183], v[224:227], v[108:111]
	v_mfma_f32_16x16x32_bf16 v[104:107], v[188:191], v[224:227], v[104:107]
	v_mfma_f32_16x16x32_bf16 v[92:95], v[180:183], v[232:235], v[92:95]
	v_mfma_f32_16x16x32_bf16 v[88:91], v[188:191], v[232:235], v[88:91]
	v_mfma_f32_16x16x32_bf16 v[76:79], v[180:183], v[240:243], v[76:79]
	v_mfma_f32_16x16x32_bf16 v[72:75], v[188:191], v[240:243], v[72:75]
	v_mfma_f32_16x16x32_bf16 v[124:127], v[184:187], v[220:223], v[124:127]
	v_mfma_f32_16x16x32_bf16 v[120:123], v[196:199], v[220:223], v[120:123]
	v_mfma_f32_16x16x32_bf16 v[108:111], v[184:187], v[228:231], v[108:111]
	v_mfma_f32_16x16x32_bf16 v[104:107], v[196:199], v[228:231], v[104:107]
	v_mfma_f32_16x16x32_bf16 v[92:95], v[184:187], v[236:239], v[92:95]
	v_mfma_f32_16x16x32_bf16 v[88:91], v[196:199], v[236:239], v[88:91]
	v_mfma_f32_16x16x32_bf16 v[76:79], v[184:187], v[244:247], v[76:79]
	v_mfma_f32_16x16x32_bf16 v[72:75], v[196:199], v[244:247], v[72:75]
	s_setprio 0
	s_setprio 1
	v_mfma_f32_16x16x32_bf16 v[116:119], v[200:203], v[216:219], v[116:119]
	v_mfma_f32_16x16x32_bf16 v[112:115], v[208:211], v[216:219], v[112:115]
	v_mfma_f32_16x16x32_bf16 v[100:103], v[200:203], v[224:227], v[100:103]
	v_mfma_f32_16x16x32_bf16 v[96:99], v[208:211], v[224:227], v[96:99]
	v_mfma_f32_16x16x32_bf16 v[84:87], v[200:203], v[232:235], v[84:87]
	v_mfma_f32_16x16x32_bf16 v[80:83], v[208:211], v[232:235], v[80:83]
	v_mfma_f32_16x16x32_bf16 v[68:71], v[200:203], v[240:243], v[68:71]
	v_mfma_f32_16x16x32_bf16 v[64:67], v[208:211], v[240:243], v[64:67]
	v_mfma_f32_16x16x32_bf16 v[116:119], v[204:207], v[220:223], v[116:119]
	v_mfma_f32_16x16x32_bf16 v[112:115], v[212:215], v[220:223], v[112:115]
	v_mfma_f32_16x16x32_bf16 v[100:103], v[204:207], v[228:231], v[100:103]
	v_mfma_f32_16x16x32_bf16 v[96:99], v[212:215], v[228:231], v[96:99]
	v_mfma_f32_16x16x32_bf16 v[84:87], v[204:207], v[236:239], v[84:87]
	v_mfma_f32_16x16x32_bf16 v[80:83], v[212:215], v[236:239], v[80:83]
	v_mfma_f32_16x16x32_bf16 v[68:71], v[204:207], v[244:247], v[68:71]
	v_mfma_f32_16x16x32_bf16 v[64:67], v[212:215], v[244:247], v[64:67]
	s_setprio 0
	s_barrier
	s_mov_b32 m0, s67
	s_add_u32 s12, s12, 0x40080
	ds_read_b128 v[216:219], v145 offset:49152
	ds_read_b128 v[220:223], v145 offset:50176
	ds_read_b128 v[224:227], v145 offset:51200
	ds_read_b128 v[228:231], v145 offset:52224
	ds_read_b128 v[232:235], v145 offset:53248
	ds_read_b128 v[236:239], v145 offset:54272
	ds_read_b128 v[240:243], v145 offset:55296
	ds_read_b128 v[244:247], v145 offset:56320
	global_load_lds_dwordx4 v132, s[98:99]
	s_mov_b32 m0, s72
	s_addc_u32 s13, s13, 0
	global_load_lds_dwordx4 v134, s[98:99]
	s_mov_b32 m0, s75
	s_add_u32 s10, s10, 0x100
	global_load_lds_dwordx4 v132, s[12:13]
	s_mov_b32 m0, s78
	s_addc_u32 s11, s11, 0
	global_load_lds_dwordx4 v134, s[12:13]
	s_mov_b32 m0, s73
	s_add_u32 s38, s38, 0x100
	global_load_lds_dwordx4 v132, s[100:101]
	s_mov_b32 m0, s74
	s_addc_u32 s39, s39, 0
	global_load_lds_dwordx4 v134, s[100:101]
	s_waitcnt vmcnt(8)
	s_waitcnt lgkmcnt(0)
	s_barrier
	s_setprio 1
	s_waitcnt lgkmcnt(0)
	v_mfma_f32_16x16x32_bf16 v[60:63], v[180:183], v[216:219], v[60:63]
	v_mfma_f32_16x16x32_bf16 v[56:59], v[188:191], v[216:219], v[56:59]
	v_mfma_f32_16x16x32_bf16 v[44:47], v[180:183], v[224:227], v[44:47]
	v_mfma_f32_16x16x32_bf16 v[40:43], v[188:191], v[224:227], v[40:43]
	v_mfma_f32_16x16x32_bf16 v[28:31], v[180:183], v[232:235], v[28:31]
	v_mfma_f32_16x16x32_bf16 v[24:27], v[188:191], v[232:235], v[24:27]
	v_mfma_f32_16x16x32_bf16 v[12:15], v[180:183], v[240:243], v[12:15]
	v_mfma_f32_16x16x32_bf16 v[8:11], v[188:191], v[240:243], v[8:11]
	v_mfma_f32_16x16x32_bf16 v[60:63], v[184:187], v[220:223], v[60:63]
	v_mfma_f32_16x16x32_bf16 v[56:59], v[196:199], v[220:223], v[56:59]
	v_mfma_f32_16x16x32_bf16 v[44:47], v[184:187], v[228:231], v[44:47]
	v_mfma_f32_16x16x32_bf16 v[40:43], v[196:199], v[228:231], v[40:43]
	v_mfma_f32_16x16x32_bf16 v[28:31], v[184:187], v[236:239], v[28:31]
	v_mfma_f32_16x16x32_bf16 v[24:27], v[196:199], v[236:239], v[24:27]
	v_mfma_f32_16x16x32_bf16 v[12:15], v[184:187], v[244:247], v[12:15]
	v_mfma_f32_16x16x32_bf16 v[8:11], v[196:199], v[244:247], v[8:11]
	s_setprio 0
	s_setprio 1
	v_mfma_f32_16x16x32_bf16 v[52:55], v[200:203], v[216:219], v[52:55]
	v_mfma_f32_16x16x32_bf16 v[48:51], v[208:211], v[216:219], v[48:51]
	v_mfma_f32_16x16x32_bf16 v[36:39], v[200:203], v[224:227], v[36:39]
	v_mfma_f32_16x16x32_bf16 v[32:35], v[208:211], v[224:227], v[32:35]
	v_mfma_f32_16x16x32_bf16 v[20:23], v[200:203], v[232:235], v[20:23]
	v_mfma_f32_16x16x32_bf16 v[16:19], v[208:211], v[232:235], v[16:19]
	v_mfma_f32_16x16x32_bf16 v[4:7], v[200:203], v[240:243], v[4:7]
	v_mfma_f32_16x16x32_bf16 v[0:3], v[208:211], v[240:243], v[0:3]
	v_mfma_f32_16x16x32_bf16 v[52:55], v[204:207], v[220:223], v[52:55]
	v_mfma_f32_16x16x32_bf16 v[48:51], v[212:215], v[220:223], v[48:51]
	v_mfma_f32_16x16x32_bf16 v[36:39], v[204:207], v[228:231], v[36:39]
	v_mfma_f32_16x16x32_bf16 v[32:35], v[212:215], v[228:231], v[32:35]
	v_mfma_f32_16x16x32_bf16 v[20:23], v[204:207], v[236:239], v[20:23]
	v_mfma_f32_16x16x32_bf16 v[16:19], v[212:215], v[236:239], v[16:19]
	v_mfma_f32_16x16x32_bf16 v[4:7], v[204:207], v[244:247], v[4:7]
	v_mfma_f32_16x16x32_bf16 v[0:3], v[212:215], v[244:247], v[0:3]
	s_setprio 0
	s_barrier
	s_add_i32 s54, s54, 2
	s_cmp_gt_u32 s54, 13
	s_cbranch_scc0 .LBB0_154
	s_and_b64 vcc, exec, s[22:23]
	s_cbranch_vccz .LBB0_157
	s_barrier

.LBB0_251:
	ds_read_b128 v[160:163], v165
	ds_read_b128 v[182:185], v167
	ds_read_b128 v[186:189], v168
	ds_read_b128 v[190:193], v169
	ds_read_b128 v[196:199], v170
	ds_read_b128 v[200:203], v171
	ds_read_b128 v[204:207], v172
	ds_read_b128 v[208:211], v173
	s_add_u32 s14, s12, 0xfffc0080
	s_addc_u32 s15, s13, -1
	s_cmp_eq_u32 s54, 12
	s_cselect_b32 s29, s7, s15
	s_cselect_b32 s28, s11, s14
	s_cselect_b32 s15, s21, s39
	s_cselect_b32 s14, s23, s38
	s_mov_b32 m0, s82
	ds_read_b128 v[212:215], v145
	ds_read_b128 v[216:219], v145 offset:1024
	ds_read_b128 v[220:223], v145 offset:2048
	ds_read_b128 v[224:227], v145 offset:3072
	ds_read_b128 v[228:231], v145 offset:4096
	ds_read_b128 v[232:235], v145 offset:5120
	ds_read_b128 v[236:239], v145 offset:6144
	ds_read_b128 v[240:243], v145 offset:7168
	global_load_lds_dwordx4 v138, s[12:13]
	s_mov_b32 m0, s83
	s_nop 0
	global_load_lds_dwordx4 v140, s[12:13]
	s_waitcnt vmcnt(8)
	s_waitcnt lgkmcnt(0)
	s_barrier
	s_setprio 1
	s_waitcnt lgkmcnt(0)
	v_mfma_f32_16x16x32_bf16 v[124:127], v[160:163], v[212:215], v[124:127]
	v_mfma_f32_16x16x32_bf16 v[120:123], v[186:189], v[212:215], v[120:123]
	v_mfma_f32_16x16x32_bf16 v[108:111], v[160:163], v[220:223], v[108:111]
	v_mfma_f32_16x16x32_bf16 v[104:107], v[186:189], v[220:223], v[104:107]
	v_mfma_f32_16x16x32_bf16 v[92:95], v[160:163], v[228:231], v[92:95]
	v_mfma_f32_16x16x32_bf16 v[88:91], v[186:189], v[228:231], v[88:91]
	v_mfma_f32_16x16x32_bf16 v[76:79], v[160:163], v[236:239], v[76:79]
	v_mfma_f32_16x16x32_bf16 v[72:75], v[186:189], v[236:239], v[72:75]
	v_mfma_f32_16x16x32_bf16 v[124:127], v[182:185], v[216:219], v[124:127]
	v_mfma_f32_16x16x32_bf16 v[120:123], v[190:193], v[216:219], v[120:123]
	v_mfma_f32_16x16x32_bf16 v[108:111], v[182:185], v[224:227], v[108:111]
	v_mfma_f32_16x16x32_bf16 v[104:107], v[190:193], v[224:227], v[104:107]
	v_mfma_f32_16x16x32_bf16 v[92:95], v[182:185], v[232:235], v[92:95]
	v_mfma_f32_16x16x32_bf16 v[88:91], v[190:193], v[232:235], v[88:91]
	v_mfma_f32_16x16x32_bf16 v[76:79], v[182:185], v[240:243], v[76:79]
	v_mfma_f32_16x16x32_bf16 v[72:75], v[190:193], v[240:243], v[72:75]
	s_setprio 0
	s_setprio 1
	v_mfma_f32_16x16x32_bf16 v[116:119], v[196:199], v[212:215], v[116:119]
	v_mfma_f32_16x16x32_bf16 v[112:115], v[204:207], v[212:215], v[112:115]
	v_mfma_f32_16x16x32_bf16 v[100:103], v[196:199], v[220:223], v[100:103]
	v_mfma_f32_16x16x32_bf16 v[96:99], v[204:207], v[220:223], v[96:99]
	v_mfma_f32_16x16x32_bf16 v[84:87], v[196:199], v[228:231], v[84:87]
	v_mfma_f32_16x16x32_bf16 v[80:83], v[204:207], v[228:231], v[80:83]
	v_mfma_f32_16x16x32_bf16 v[68:71], v[196:199], v[236:239], v[68:71]
	v_mfma_f32_16x16x32_bf16 v[64:67], v[204:207], v[236:239], v[64:67]
	v_mfma_f32_16x16x32_bf16 v[116:119], v[200:203], v[216:219], v[116:119]
	v_mfma_f32_16x16x32_bf16 v[112:115], v[208:211], v[216:219], v[112:115]
	v_mfma_f32_16x16x32_bf16 v[100:103], v[200:203], v[224:227], v[100:103]
	v_mfma_f32_16x16x32_bf16 v[96:99], v[208:211], v[224:227], v[96:99]
	v_mfma_f32_16x16x32_bf16 v[84:87], v[200:203], v[232:235], v[84:87]
	v_mfma_f32_16x16x32_bf16 v[80:83], v[208:211], v[232:235], v[80:83]
	v_mfma_f32_16x16x32_bf16 v[68:71], v[200:203], v[240:243], v[68:71]
	v_mfma_f32_16x16x32_bf16 v[64:67], v[208:211], v[240:243], v[64:67]
	s_setprio 0
	s_barrier
	s_mov_b32 m0, s33
	s_add_u32 s56, s14, 0x40000
	ds_read_b128 v[212:215], v145 offset:16384
	ds_read_b128 v[216:219], v145 offset:17408
	ds_read_b128 v[220:223], v145 offset:18432
	ds_read_b128 v[224:227], v145 offset:19456
	ds_read_b128 v[228:231], v145 offset:20480
	ds_read_b128 v[232:235], v145 offset:21504
	ds_read_b128 v[236:239], v145 offset:22528
	ds_read_b128 v[240:243], v145 offset:23552
	global_load_lds_dwordx4 v132, s[14:15]
	s_mov_b32 m0, s34
	s_addc_u32 s57, s15, 0
	global_load_lds_dwordx4 v134, s[14:15]
	s_mov_b32 m0, s35
	s_add_u32 s98, s14, s16
	global_load_lds_dwordx4 v132, s[56:57]
	s_mov_b32 m0, s36
	s_addc_u32 s99, s15, s17
	global_load_lds_dwordx4 v134, s[56:57]
	s_mov_b32 m0, s31
	s_add_u32 s100, s28, s16
	global_load_lds_dwordx4 v132, s[28:29]
	s_mov_b32 m0, s37
	s_addc_u32 s101, s29, s17
	global_load_lds_dwordx4 v134, s[28:29]
	s_waitcnt vmcnt(8)
	s_waitcnt lgkmcnt(0)
	s_barrier
	s_setprio 1
	s_waitcnt lgkmcnt(0)
	v_mfma_f32_16x16x32_bf16 v[60:63], v[160:163], v[212:215], v[60:63]
	v_mfma_f32_16x16x32_bf16 v[56:59], v[186:189], v[212:215], v[56:59]
	v_mfma_f32_16x16x32_bf16 v[44:47], v[160:163], v[220:223], v[44:47]
	v_mfma_f32_16x16x32_bf16 v[40:43], v[186:189], v[220:223], v[40:43]
	v_mfma_f32_16x16x32_bf16 v[28:31], v[160:163], v[228:231], v[28:31]
	v_mfma_f32_16x16x32_bf16 v[24:27], v[186:189], v[228:231], v[24:27]
	v_mfma_f32_16x16x32_bf16 v[12:15], v[160:163], v[236:239], v[12:15]
	v_mfma_f32_16x16x32_bf16 v[8:11], v[186:189], v[236:239], v[8:11]
	v_mfma_f32_16x16x32_bf16 v[60:63], v[182:185], v[216:219], v[60:63]
	v_mfma_f32_16x16x32_bf16 v[56:59], v[190:193], v[216:219], v[56:59]
	v_mfma_f32_16x16x32_bf16 v[44:47], v[182:185], v[224:227], v[44:47]
	v_mfma_f32_16x16x32_bf16 v[40:43], v[190:193], v[224:227], v[40:43]
	v_mfma_f32_16x16x32_bf16 v[28:31], v[182:185], v[232:235], v[28:31]
	v_mfma_f32_16x16x32_bf16 v[24:27], v[190:193], v[232:235], v[24:27]
	v_mfma_f32_16x16x32_bf16 v[12:15], v[182:185], v[240:243], v[12:15]
	v_mfma_f32_16x16x32_bf16 v[8:11], v[190:193], v[240:243], v[8:11]
	s_setprio 0
	s_setprio 1
	v_mfma_f32_16x16x32_bf16 v[52:55], v[196:199], v[212:215], v[52:55]
	v_mfma_f32_16x16x32_bf16 v[48:51], v[204:207], v[212:215], v[48:51]
	v_mfma_f32_16x16x32_bf16 v[36:39], v[196:199], v[220:223], v[36:39]
	v_mfma_f32_16x16x32_bf16 v[32:35], v[204:207], v[220:223], v[32:35]
	v_mfma_f32_16x16x32_bf16 v[20:23], v[196:199], v[228:231], v[20:23]
	v_mfma_f32_16x16x32_bf16 v[16:19], v[204:207], v[228:231], v[16:19]
	v_mfma_f32_16x16x32_bf16 v[4:7], v[196:199], v[236:239], v[4:7]
	v_mfma_f32_16x16x32_bf16 v[0:3], v[204:207], v[236:239], v[0:3]
	v_mfma_f32_16x16x32_bf16 v[52:55], v[200:203], v[216:219], v[52:55]
	v_mfma_f32_16x16x32_bf16 v[48:51], v[208:211], v[216:219], v[48:51]
	v_mfma_f32_16x16x32_bf16 v[36:39], v[200:203], v[224:227], v[36:39]
	v_mfma_f32_16x16x32_bf16 v[32:35], v[208:211], v[224:227], v[32:35]
	v_mfma_f32_16x16x32_bf16 v[20:23], v[200:203], v[232:235], v[20:23]
	v_mfma_f32_16x16x32_bf16 v[16:19], v[208:211], v[232:235], v[16:19]
	v_mfma_f32_16x16x32_bf16 v[4:7], v[200:203], v[240:243], v[4:7]
	v_mfma_f32_16x16x32_bf16 v[0:3], v[208:211], v[240:243], v[0:3]
	s_setprio 0
	s_barrier
	ds_read_b128 v[160:163], v174
	ds_read_b128 v[182:185], v175
	ds_read_b128 v[186:189], v176
	ds_read_b128 v[190:193], v177
	ds_read_b128 v[196:199], v178
	ds_read_b128 v[200:203], v179
	ds_read_b128 v[204:207], v180
	ds_read_b128 v[208:211], v181
	s_add_u32 s28, s28, 0x40000
	s_addc_u32 s29, s29, 0
	s_mov_b32 m0, s62
	ds_read_b128 v[212:215], v145 offset:32768
	ds_read_b128 v[216:219], v145 offset:33792
	ds_read_b128 v[220:223], v145 offset:34816
	ds_read_b128 v[224:227], v145 offset:35840
	ds_read_b128 v[228:231], v145 offset:36864
	ds_read_b128 v[232:235], v145 offset:37888
	ds_read_b128 v[236:239], v145 offset:38912
	ds_read_b128 v[240:243], v145 offset:39936
	global_load_lds_dwordx4 v132, s[28:29]
	s_mov_b32 m0, s63
	s_nop 0
	global_load_lds_dwordx4 v134, s[28:29]
	s_waitcnt vmcnt(8)
	s_waitcnt lgkmcnt(0)
	s_barrier
	s_setprio 1
	s_waitcnt lgkmcnt(0)
	v_mfma_f32_16x16x32_bf16 v[124:127], v[160:163], v[212:215], v[124:127]
	v_mfma_f32_16x16x32_bf16 v[120:123], v[186:189], v[212:215], v[120:123]
	v_mfma_f32_16x16x32_bf16 v[108:111], v[160:163], v[220:223], v[108:111]
	v_mfma_f32_16x16x32_bf16 v[104:107], v[186:189], v[220:223], v[104:107]
	v_mfma_f32_16x16x32_bf16 v[92:95], v[160:163], v[228:231], v[92:95]
	v_mfma_f32_16x16x32_bf16 v[88:91], v[186:189], v[228:231], v[88:91]
	v_mfma_f32_16x16x32_bf16 v[76:79], v[160:163], v[236:239], v[76:79]
	v_mfma_f32_16x16x32_bf16 v[72:75], v[186:189], v[236:239], v[72:75]
	v_mfma_f32_16x16x32_bf16 v[124:127], v[182:185], v[216:219], v[124:127]
	v_mfma_f32_16x16x32_bf16 v[120:123], v[190:193], v[216:219], v[120:123]
	v_mfma_f32_16x16x32_bf16 v[108:111], v[182:185], v[224:227], v[108:111]
	v_mfma_f32_16x16x32_bf16 v[104:107], v[190:193], v[224:227], v[104:107]
	v_mfma_f32_16x16x32_bf16 v[92:95], v[182:185], v[232:235], v[92:95]
	v_mfma_f32_16x16x32_bf16 v[88:91], v[190:193], v[232:235], v[88:91]
	v_mfma_f32_16x16x32_bf16 v[76:79], v[182:185], v[240:243], v[76:79]
	v_mfma_f32_16x16x32_bf16 v[72:75], v[190:193], v[240:243], v[72:75]
	s_setprio 0
	s_setprio 1
	v_mfma_f32_16x16x32_bf16 v[116:119], v[196:199], v[212:215], v[116:119]
	v_mfma_f32_16x16x32_bf16 v[112:115], v[204:207], v[212:215], v[112:115]
	v_mfma_f32_16x16x32_bf16 v[100:103], v[196:199], v[220:223], v[100:103]
	v_mfma_f32_16x16x32_bf16 v[96:99], v[204:207], v[220:223], v[96:99]
	v_mfma_f32_16x16x32_bf16 v[84:87], v[196:199], v[228:231], v[84:87]
	v_mfma_f32_16x16x32_bf16 v[80:83], v[204:207], v[228:231], v[80:83]
	v_mfma_f32_16x16x32_bf16 v[68:71], v[196:199], v[236:239], v[68:71]
	v_mfma_f32_16x16x32_bf16 v[64:67], v[204:207], v[236:239], v[64:67]
	v_mfma_f32_16x16x32_bf16 v[116:119], v[200:203], v[216:219], v[116:119]
	v_mfma_f32_16x16x32_bf16 v[112:115], v[208:211], v[216:219], v[112:115]
	v_mfma_f32_16x16x32_bf16 v[100:103], v[200:203], v[224:227], v[100:103]
	v_mfma_f32_16x16x32_bf16 v[96:99], v[208:211], v[224:227], v[96:99]
	v_mfma_f32_16x16x32_bf16 v[84:87], v[200:203], v[232:235], v[84:87]
	v_mfma_f32_16x16x32_bf16 v[80:83], v[208:211], v[232:235], v[80:83]
	v_mfma_f32_16x16x32_bf16 v[68:71], v[200:203], v[240:243], v[68:71]
	v_mfma_f32_16x16x32_bf16 v[64:67], v[208:211], v[240:243], v[64:67]
	s_setprio 0
	s_barrier
	s_mov_b32 m0, s64
	s_add_u32 s14, s14, 0x40080
	ds_read_b128 v[212:215], v145 offset:49152
	ds_read_b128 v[216:219], v145 offset:50176
	ds_read_b128 v[220:223], v145 offset:51200
	ds_read_b128 v[224:227], v145 offset:52224
	ds_read_b128 v[228:231], v145 offset:53248
	ds_read_b128 v[232:235], v145 offset:54272
	ds_read_b128 v[236:239], v145 offset:55296
	ds_read_b128 v[240:243], v145 offset:56320
	global_load_lds_dwordx4 v132, s[98:99]
	s_mov_b32 m0, s65
	s_addc_u32 s15, s15, 0
	global_load_lds_dwordx4 v134, s[98:99]
	s_mov_b32 m0, s72
	s_add_u32 s12, s12, 0x100
	global_load_lds_dwordx4 v132, s[14:15]
	s_mov_b32 m0, s73
	s_addc_u32 s13, s13, 0
	global_load_lds_dwordx4 v134, s[14:15]
	s_mov_b32 m0, s66
	s_add_u32 s38, s38, 0x100
	global_load_lds_dwordx4 v132, s[100:101]
	s_mov_b32 m0, s67
	s_addc_u32 s39, s39, 0
	global_load_lds_dwordx4 v134, s[100:101]
	s_waitcnt vmcnt(8)
	s_waitcnt lgkmcnt(0)
	s_barrier
	s_setprio 1
	s_waitcnt lgkmcnt(0)
	v_mfma_f32_16x16x32_bf16 v[60:63], v[160:163], v[212:215], v[60:63]
	v_mfma_f32_16x16x32_bf16 v[56:59], v[186:189], v[212:215], v[56:59]
	v_mfma_f32_16x16x32_bf16 v[44:47], v[160:163], v[220:223], v[44:47]
	v_mfma_f32_16x16x32_bf16 v[40:43], v[186:189], v[220:223], v[40:43]
	v_mfma_f32_16x16x32_bf16 v[28:31], v[160:163], v[228:231], v[28:31]
	v_mfma_f32_16x16x32_bf16 v[24:27], v[186:189], v[228:231], v[24:27]
	v_mfma_f32_16x16x32_bf16 v[12:15], v[160:163], v[236:239], v[12:15]
	v_mfma_f32_16x16x32_bf16 v[8:11], v[186:189], v[236:239], v[8:11]
	v_mfma_f32_16x16x32_bf16 v[60:63], v[182:185], v[216:219], v[60:63]
	v_mfma_f32_16x16x32_bf16 v[56:59], v[190:193], v[216:219], v[56:59]
	v_mfma_f32_16x16x32_bf16 v[44:47], v[182:185], v[224:227], v[44:47]
	v_mfma_f32_16x16x32_bf16 v[40:43], v[190:193], v[224:227], v[40:43]
	v_mfma_f32_16x16x32_bf16 v[28:31], v[182:185], v[232:235], v[28:31]
	v_mfma_f32_16x16x32_bf16 v[24:27], v[190:193], v[232:235], v[24:27]
	v_mfma_f32_16x16x32_bf16 v[12:15], v[182:185], v[240:243], v[12:15]
	v_mfma_f32_16x16x32_bf16 v[8:11], v[190:193], v[240:243], v[8:11]
	s_setprio 0
	s_setprio 1
	v_mfma_f32_16x16x32_bf16 v[52:55], v[196:199], v[212:215], v[52:55]
	v_mfma_f32_16x16x32_bf16 v[48:51], v[204:207], v[212:215], v[48:51]
	v_mfma_f32_16x16x32_bf16 v[36:39], v[196:199], v[220:223], v[36:39]
	v_mfma_f32_16x16x32_bf16 v[32:35], v[204:207], v[220:223], v[32:35]
	v_mfma_f32_16x16x32_bf16 v[20:23], v[196:199], v[228:231], v[20:23]
	v_mfma_f32_16x16x32_bf16 v[16:19], v[204:207], v[228:231], v[16:19]
	v_mfma_f32_16x16x32_bf16 v[4:7], v[196:199], v[236:239], v[4:7]
	v_mfma_f32_16x16x32_bf16 v[0:3], v[204:207], v[236:239], v[0:3]
	v_mfma_f32_16x16x32_bf16 v[52:55], v[200:203], v[216:219], v[52:55]
	v_mfma_f32_16x16x32_bf16 v[48:51], v[208:211], v[216:219], v[48:51]
	v_mfma_f32_16x16x32_bf16 v[36:39], v[200:203], v[224:227], v[36:39]
	v_mfma_f32_16x16x32_bf16 v[32:35], v[208:211], v[224:227], v[32:35]
	v_mfma_f32_16x16x32_bf16 v[20:23], v[200:203], v[232:235], v[20:23]
	v_mfma_f32_16x16x32_bf16 v[16:19], v[208:211], v[232:235], v[16:19]
	v_mfma_f32_16x16x32_bf16 v[4:7], v[200:203], v[240:243], v[4:7]
	v_mfma_f32_16x16x32_bf16 v[0:3], v[208:211], v[240:243], v[0:3]
	s_setprio 0
	s_barrier
	s_add_i32 s54, s54, 2
	s_cmp_gt_u32 s54, 13
	s_cbranch_scc0 .LBB0_251
	s_and_b64 vcc, exec, s[18:19]
	s_cbranch_vccz .LBB0_254
	s_barrier

.LBB0_586:
	ds_read_b128 v[160:163], v165
	ds_read_b128 v[182:185], v167
	ds_read_b128 v[186:189], v168
	ds_read_b128 v[190:193], v169
	ds_read_b128 v[196:199], v170
	ds_read_b128 v[200:203], v171
	ds_read_b128 v[204:207], v172
	ds_read_b128 v[208:211], v173
	s_add_u32 s12, s10, 0xfffc0080
	s_addc_u32 s13, s11, -1
	s_cmp_eq_u32 s54, 12
	s_cselect_b32 s15, s7, s13
	s_cselect_b32 s14, s9, s12
	s_cselect_b32 s13, s21, s39
	s_cselect_b32 s12, s23, s38
	s_mov_b32 m0, s82
	ds_read_b128 v[212:215], v145
	ds_read_b128 v[216:219], v145 offset:1024
	ds_read_b128 v[220:223], v145 offset:2048
	ds_read_b128 v[224:227], v145 offset:3072
	ds_read_b128 v[228:231], v145 offset:4096
	ds_read_b128 v[232:235], v145 offset:5120
	ds_read_b128 v[236:239], v145 offset:6144
	ds_read_b128 v[240:243], v145 offset:7168
	global_load_lds_dwordx4 v138, s[10:11]
	s_mov_b32 m0, s83
	s_nop 0
	global_load_lds_dwordx4 v140, s[10:11]
	s_waitcnt vmcnt(8)
	s_waitcnt lgkmcnt(0)
	s_barrier
	s_setprio 1
	s_waitcnt lgkmcnt(0)
	v_mfma_f32_16x16x32_bf16 v[124:127], v[160:163], v[212:215], v[124:127]
	v_mfma_f32_16x16x32_bf16 v[120:123], v[186:189], v[212:215], v[120:123]
	v_mfma_f32_16x16x32_bf16 v[108:111], v[160:163], v[220:223], v[108:111]
	v_mfma_f32_16x16x32_bf16 v[104:107], v[186:189], v[220:223], v[104:107]
	v_mfma_f32_16x16x32_bf16 v[92:95], v[160:163], v[228:231], v[92:95]
	v_mfma_f32_16x16x32_bf16 v[88:91], v[186:189], v[228:231], v[88:91]
	v_mfma_f32_16x16x32_bf16 v[76:79], v[160:163], v[236:239], v[76:79]
	v_mfma_f32_16x16x32_bf16 v[72:75], v[186:189], v[236:239], v[72:75]
	v_mfma_f32_16x16x32_bf16 v[124:127], v[182:185], v[216:219], v[124:127]
	v_mfma_f32_16x16x32_bf16 v[120:123], v[190:193], v[216:219], v[120:123]
	v_mfma_f32_16x16x32_bf16 v[108:111], v[182:185], v[224:227], v[108:111]
	v_mfma_f32_16x16x32_bf16 v[104:107], v[190:193], v[224:227], v[104:107]
	v_mfma_f32_16x16x32_bf16 v[92:95], v[182:185], v[232:235], v[92:95]
	v_mfma_f32_16x16x32_bf16 v[88:91], v[190:193], v[232:235], v[88:91]
	v_mfma_f32_16x16x32_bf16 v[76:79], v[182:185], v[240:243], v[76:79]
	v_mfma_f32_16x16x32_bf16 v[72:75], v[190:193], v[240:243], v[72:75]
	s_setprio 0
	s_setprio 1
	v_mfma_f32_16x16x32_bf16 v[116:119], v[196:199], v[212:215], v[116:119]
	v_mfma_f32_16x16x32_bf16 v[112:115], v[204:207], v[212:215], v[112:115]
	v_mfma_f32_16x16x32_bf16 v[100:103], v[196:199], v[220:223], v[100:103]
	v_mfma_f32_16x16x32_bf16 v[96:99], v[204:207], v[220:223], v[96:99]
	v_mfma_f32_16x16x32_bf16 v[84:87], v[196:199], v[228:231], v[84:87]
	v_mfma_f32_16x16x32_bf16 v[80:83], v[204:207], v[228:231], v[80:83]
	v_mfma_f32_16x16x32_bf16 v[68:71], v[196:199], v[236:239], v[68:71]
	v_mfma_f32_16x16x32_bf16 v[64:67], v[204:207], v[236:239], v[64:67]
	v_mfma_f32_16x16x32_bf16 v[116:119], v[200:203], v[216:219], v[116:119]
	v_mfma_f32_16x16x32_bf16 v[112:115], v[208:211], v[216:219], v[112:115]
	v_mfma_f32_16x16x32_bf16 v[100:103], v[200:203], v[224:227], v[100:103]
	v_mfma_f32_16x16x32_bf16 v[96:99], v[208:211], v[224:227], v[96:99]
	v_mfma_f32_16x16x32_bf16 v[84:87], v[200:203], v[232:235], v[84:87]
	v_mfma_f32_16x16x32_bf16 v[80:83], v[208:211], v[232:235], v[80:83]
	v_mfma_f32_16x16x32_bf16 v[68:71], v[200:203], v[240:243], v[68:71]
	v_mfma_f32_16x16x32_bf16 v[64:67], v[208:211], v[240:243], v[64:67]
	s_setprio 0
	s_barrier
	s_mov_b32 m0, s30
	s_add_u32 s56, s12, 0x40000
	ds_read_b128 v[212:215], v145 offset:16384
	ds_read_b128 v[216:219], v145 offset:17408
	ds_read_b128 v[220:223], v145 offset:18432
	ds_read_b128 v[224:227], v145 offset:19456
	ds_read_b128 v[228:231], v145 offset:20480
	ds_read_b128 v[232:235], v145 offset:21504
	ds_read_b128 v[236:239], v145 offset:22528
	ds_read_b128 v[240:243], v145 offset:23552
	global_load_lds_dwordx4 v132, s[12:13]
	s_mov_b32 m0, s31
	s_addc_u32 s57, s13, 0
	global_load_lds_dwordx4 v134, s[12:13]
	s_mov_b32 m0, s33
	s_add_u32 s98, s12, s16
	global_load_lds_dwordx4 v132, s[56:57]
	s_mov_b32 m0, s34
	s_addc_u32 s99, s13, s17
	global_load_lds_dwordx4 v134, s[56:57]
	s_mov_b32 m0, s29
	s_add_u32 s100, s14, s16
	global_load_lds_dwordx4 v132, s[14:15]
	s_mov_b32 m0, s35
	s_addc_u32 s101, s15, s17
	global_load_lds_dwordx4 v134, s[14:15]
	s_waitcnt vmcnt(8)
	s_waitcnt lgkmcnt(0)
	s_barrier
	s_setprio 1
	s_waitcnt lgkmcnt(0)
	v_mfma_f32_16x16x32_bf16 v[60:63], v[160:163], v[212:215], v[60:63]
	v_mfma_f32_16x16x32_bf16 v[56:59], v[186:189], v[212:215], v[56:59]
	v_mfma_f32_16x16x32_bf16 v[44:47], v[160:163], v[220:223], v[44:47]
	v_mfma_f32_16x16x32_bf16 v[40:43], v[186:189], v[220:223], v[40:43]
	v_mfma_f32_16x16x32_bf16 v[28:31], v[160:163], v[228:231], v[28:31]
	v_mfma_f32_16x16x32_bf16 v[24:27], v[186:189], v[228:231], v[24:27]
	v_mfma_f32_16x16x32_bf16 v[12:15], v[160:163], v[236:239], v[12:15]
	v_mfma_f32_16x16x32_bf16 v[8:11], v[186:189], v[236:239], v[8:11]
	v_mfma_f32_16x16x32_bf16 v[60:63], v[182:185], v[216:219], v[60:63]
	v_mfma_f32_16x16x32_bf16 v[56:59], v[190:193], v[216:219], v[56:59]
	v_mfma_f32_16x16x32_bf16 v[44:47], v[182:185], v[224:227], v[44:47]
	v_mfma_f32_16x16x32_bf16 v[40:43], v[190:193], v[224:227], v[40:43]
	v_mfma_f32_16x16x32_bf16 v[28:31], v[182:185], v[232:235], v[28:31]
	v_mfma_f32_16x16x32_bf16 v[24:27], v[190:193], v[232:235], v[24:27]
	v_mfma_f32_16x16x32_bf16 v[12:15], v[182:185], v[240:243], v[12:15]
	v_mfma_f32_16x16x32_bf16 v[8:11], v[190:193], v[240:243], v[8:11]
	s_setprio 0
	s_setprio 1
	v_mfma_f32_16x16x32_bf16 v[52:55], v[196:199], v[212:215], v[52:55]
	v_mfma_f32_16x16x32_bf16 v[48:51], v[204:207], v[212:215], v[48:51]
	v_mfma_f32_16x16x32_bf16 v[36:39], v[196:199], v[220:223], v[36:39]
	v_mfma_f32_16x16x32_bf16 v[32:35], v[204:207], v[220:223], v[32:35]
	v_mfma_f32_16x16x32_bf16 v[20:23], v[196:199], v[228:231], v[20:23]
	v_mfma_f32_16x16x32_bf16 v[16:19], v[204:207], v[228:231], v[16:19]
	v_mfma_f32_16x16x32_bf16 v[4:7], v[196:199], v[236:239], v[4:7]
	v_mfma_f32_16x16x32_bf16 v[0:3], v[204:207], v[236:239], v[0:3]
	v_mfma_f32_16x16x32_bf16 v[52:55], v[200:203], v[216:219], v[52:55]
	v_mfma_f32_16x16x32_bf16 v[48:51], v[208:211], v[216:219], v[48:51]
	v_mfma_f32_16x16x32_bf16 v[36:39], v[200:203], v[224:227], v[36:39]
	v_mfma_f32_16x16x32_bf16 v[32:35], v[208:211], v[224:227], v[32:35]
	v_mfma_f32_16x16x32_bf16 v[20:23], v[200:203], v[232:235], v[20:23]
	v_mfma_f32_16x16x32_bf16 v[16:19], v[208:211], v[232:235], v[16:19]
	v_mfma_f32_16x16x32_bf16 v[4:7], v[200:203], v[240:243], v[4:7]
	v_mfma_f32_16x16x32_bf16 v[0:3], v[208:211], v[240:243], v[0:3]
	s_setprio 0
	s_barrier
	ds_read_b128 v[160:163], v174
	ds_read_b128 v[182:185], v175
	ds_read_b128 v[186:189], v176
	ds_read_b128 v[190:193], v177
	ds_read_b128 v[196:199], v178
	ds_read_b128 v[200:203], v179
	ds_read_b128 v[204:207], v180
	ds_read_b128 v[208:211], v181
	s_add_u32 s14, s14, 0x40000
	s_addc_u32 s15, s15, 0
	s_mov_b32 m0, s36
	ds_read_b128 v[212:215], v145 offset:32768
	ds_read_b128 v[216:219], v145 offset:33792
	ds_read_b128 v[220:223], v145 offset:34816
	ds_read_b128 v[224:227], v145 offset:35840
	ds_read_b128 v[228:231], v145 offset:36864
	ds_read_b128 v[232:235], v145 offset:37888
	ds_read_b128 v[236:239], v145 offset:38912
	ds_read_b128 v[240:243], v145 offset:39936
	global_load_lds_dwordx4 v132, s[14:15]
	s_mov_b32 m0, s37
	s_nop 0
	global_load_lds_dwordx4 v134, s[14:15]
	s_waitcnt vmcnt(8)
	s_waitcnt lgkmcnt(0)
	s_barrier
	s_setprio 1
	s_waitcnt lgkmcnt(0)
	v_mfma_f32_16x16x32_bf16 v[124:127], v[160:163], v[212:215], v[124:127]
	v_mfma_f32_16x16x32_bf16 v[120:123], v[186:189], v[212:215], v[120:123]
	v_mfma_f32_16x16x32_bf16 v[108:111], v[160:163], v[220:223], v[108:111]
	v_mfma_f32_16x16x32_bf16 v[104:107], v[186:189], v[220:223], v[104:107]
	v_mfma_f32_16x16x32_bf16 v[92:95], v[160:163], v[228:231], v[92:95]
	v_mfma_f32_16x16x32_bf16 v[88:91], v[186:189], v[228:231], v[88:91]
	v_mfma_f32_16x16x32_bf16 v[76:79], v[160:163], v[236:239], v[76:79]
	v_mfma_f32_16x16x32_bf16 v[72:75], v[186:189], v[236:239], v[72:75]
	v_mfma_f32_16x16x32_bf16 v[124:127], v[182:185], v[216:219], v[124:127]
	v_mfma_f32_16x16x32_bf16 v[120:123], v[190:193], v[216:219], v[120:123]
	v_mfma_f32_16x16x32_bf16 v[108:111], v[182:185], v[224:227], v[108:111]
	v_mfma_f32_16x16x32_bf16 v[104:107], v[190:193], v[224:227], v[104:107]
	v_mfma_f32_16x16x32_bf16 v[92:95], v[182:185], v[232:235], v[92:95]
	v_mfma_f32_16x16x32_bf16 v[88:91], v[190:193], v[232:235], v[88:91]
	v_mfma_f32_16x16x32_bf16 v[76:79], v[182:185], v[240:243], v[76:79]
	v_mfma_f32_16x16x32_bf16 v[72:75], v[190:193], v[240:243], v[72:75]
	s_setprio 0
	s_setprio 1
	v_mfma_f32_16x16x32_bf16 v[116:119], v[196:199], v[212:215], v[116:119]
	v_mfma_f32_16x16x32_bf16 v[112:115], v[204:207], v[212:215], v[112:115]
	v_mfma_f32_16x16x32_bf16 v[100:103], v[196:199], v[220:223], v[100:103]
	v_mfma_f32_16x16x32_bf16 v[96:99], v[204:207], v[220:223], v[96:99]
	v_mfma_f32_16x16x32_bf16 v[84:87], v[196:199], v[228:231], v[84:87]
	v_mfma_f32_16x16x32_bf16 v[80:83], v[204:207], v[228:231], v[80:83]
	v_mfma_f32_16x16x32_bf16 v[68:71], v[196:199], v[236:239], v[68:71]
	v_mfma_f32_16x16x32_bf16 v[64:67], v[204:207], v[236:239], v[64:67]
	v_mfma_f32_16x16x32_bf16 v[116:119], v[200:203], v[216:219], v[116:119]
	v_mfma_f32_16x16x32_bf16 v[112:115], v[208:211], v[216:219], v[112:115]
	v_mfma_f32_16x16x32_bf16 v[100:103], v[200:203], v[224:227], v[100:103]
	v_mfma_f32_16x16x32_bf16 v[96:99], v[208:211], v[224:227], v[96:99]
	v_mfma_f32_16x16x32_bf16 v[84:87], v[200:203], v[232:235], v[84:87]
	v_mfma_f32_16x16x32_bf16 v[80:83], v[208:211], v[232:235], v[80:83]
	v_mfma_f32_16x16x32_bf16 v[68:71], v[200:203], v[240:243], v[68:71]
	v_mfma_f32_16x16x32_bf16 v[64:67], v[208:211], v[240:243], v[64:67]
	s_setprio 0
	s_barrier
	s_mov_b32 m0, s64
	s_add_u32 s12, s12, 0x40080
	ds_read_b128 v[212:215], v145 offset:49152
	ds_read_b128 v[216:219], v145 offset:50176
	ds_read_b128 v[220:223], v145 offset:51200
	ds_read_b128 v[224:227], v145 offset:52224
	ds_read_b128 v[228:231], v145 offset:53248
	ds_read_b128 v[232:235], v145 offset:54272
	ds_read_b128 v[236:239], v145 offset:55296
	ds_read_b128 v[240:243], v145 offset:56320
	global_load_lds_dwordx4 v132, s[98:99]
	s_mov_b32 m0, s65
	s_addc_u32 s13, s13, 0
	global_load_lds_dwordx4 v134, s[98:99]
	s_mov_b32 m0, s72
	s_add_u32 s10, s10, 0x100
	global_load_lds_dwordx4 v132, s[12:13]
	s_mov_b32 m0, s73
	s_addc_u32 s11, s11, 0
	global_load_lds_dwordx4 v134, s[12:13]
	s_mov_b32 m0, s66
	s_add_u32 s38, s38, 0x100
	global_load_lds_dwordx4 v132, s[100:101]
	s_mov_b32 m0, s67
	s_addc_u32 s39, s39, 0
	global_load_lds_dwordx4 v134, s[100:101]
	s_waitcnt vmcnt(8)
	s_waitcnt lgkmcnt(0)
	s_barrier
	s_setprio 1
	s_waitcnt lgkmcnt(0)
	v_mfma_f32_16x16x32_bf16 v[60:63], v[160:163], v[212:215], v[60:63]
	v_mfma_f32_16x16x32_bf16 v[56:59], v[186:189], v[212:215], v[56:59]
	v_mfma_f32_16x16x32_bf16 v[44:47], v[160:163], v[220:223], v[44:47]
	v_mfma_f32_16x16x32_bf16 v[40:43], v[186:189], v[220:223], v[40:43]
	v_mfma_f32_16x16x32_bf16 v[28:31], v[160:163], v[228:231], v[28:31]
	v_mfma_f32_16x16x32_bf16 v[24:27], v[186:189], v[228:231], v[24:27]
	v_mfma_f32_16x16x32_bf16 v[12:15], v[160:163], v[236:239], v[12:15]
	v_mfma_f32_16x16x32_bf16 v[8:11], v[186:189], v[236:239], v[8:11]
	v_mfma_f32_16x16x32_bf16 v[60:63], v[182:185], v[216:219], v[60:63]
	v_mfma_f32_16x16x32_bf16 v[56:59], v[190:193], v[216:219], v[56:59]
	v_mfma_f32_16x16x32_bf16 v[44:47], v[182:185], v[224:227], v[44:47]
	v_mfma_f32_16x16x32_bf16 v[40:43], v[190:193], v[224:227], v[40:43]
	v_mfma_f32_16x16x32_bf16 v[28:31], v[182:185], v[232:235], v[28:31]
	v_mfma_f32_16x16x32_bf16 v[24:27], v[190:193], v[232:235], v[24:27]
	v_mfma_f32_16x16x32_bf16 v[12:15], v[182:185], v[240:243], v[12:15]
	v_mfma_f32_16x16x32_bf16 v[8:11], v[190:193], v[240:243], v[8:11]
	s_setprio 0
	s_setprio 1
	v_mfma_f32_16x16x32_bf16 v[52:55], v[196:199], v[212:215], v[52:55]
	v_mfma_f32_16x16x32_bf16 v[48:51], v[204:207], v[212:215], v[48:51]
	v_mfma_f32_16x16x32_bf16 v[36:39], v[196:199], v[220:223], v[36:39]
	v_mfma_f32_16x16x32_bf16 v[32:35], v[204:207], v[220:223], v[32:35]
	v_mfma_f32_16x16x32_bf16 v[20:23], v[196:199], v[228:231], v[20:23]
	v_mfma_f32_16x16x32_bf16 v[16:19], v[204:207], v[228:231], v[16:19]
	v_mfma_f32_16x16x32_bf16 v[4:7], v[196:199], v[236:239], v[4:7]
	v_mfma_f32_16x16x32_bf16 v[0:3], v[204:207], v[236:239], v[0:3]
	v_mfma_f32_16x16x32_bf16 v[52:55], v[200:203], v[216:219], v[52:55]
	v_mfma_f32_16x16x32_bf16 v[48:51], v[208:211], v[216:219], v[48:51]
	v_mfma_f32_16x16x32_bf16 v[36:39], v[200:203], v[224:227], v[36:39]
	v_mfma_f32_16x16x32_bf16 v[32:35], v[208:211], v[224:227], v[32:35]
	v_mfma_f32_16x16x32_bf16 v[20:23], v[200:203], v[232:235], v[20:23]
	v_mfma_f32_16x16x32_bf16 v[16:19], v[208:211], v[232:235], v[16:19]
	v_mfma_f32_16x16x32_bf16 v[4:7], v[200:203], v[240:243], v[4:7]
	v_mfma_f32_16x16x32_bf16 v[0:3], v[208:211], v[240:243], v[0:3]
	s_setprio 0
	s_barrier
	s_add_i32 s54, s54, 2
	s_cmp_gt_u32 s54, 13
	s_cbranch_scc0 .LBB0_586
	s_and_b64 vcc, exec, s[18:19]
	s_cbranch_vccz .LBB0_589
	s_barrier

.LBB0_856:
	ds_read_b128 v[178:181], v160
	ds_read_b128 v[182:185], v161
	ds_read_b128 v[186:189], v162
	ds_read_b128 v[190:193], v163
	ds_read_b128 v[198:201], v164
	ds_read_b128 v[202:205], v165
	ds_read_b128 v[206:209], v167
	ds_read_b128 v[210:213], v168
	s_add_u32 s28, s10, 0x100
	s_addc_u32 s29, s11, 0
	s_cmp_eq_u32 s56, 28
	s_cselect_b32 s35, s4, s29
	s_cselect_b32 s34, s5, s28
	s_cselect_b32 s31, s21, vcc_hi
	s_cselect_b32 s30, s23, vcc_lo
	s_mov_b32 m0, s55
	ds_read_b128 v[214:217], v152
	ds_read_b128 v[218:221], v152 offset:1024
	ds_read_b128 v[222:225], v152 offset:2048
	ds_read_b128 v[226:229], v152 offset:3072
	ds_read_b128 v[230:233], v152 offset:4096
	ds_read_b128 v[234:237], v152 offset:5120
	ds_read_b128 v[238:241], v152 offset:6144
	ds_read_b128 v[242:245], v152 offset:7168
	global_load_lds_dwordx4 v136, s[10:11]
	s_mov_b32 m0, s36
	s_nop 0
	global_load_lds_dwordx4 v138, s[10:11]
	s_waitcnt vmcnt(8)
	s_waitcnt lgkmcnt(0)
	s_barrier
	s_setprio 1
	s_waitcnt lgkmcnt(0)
	v_mfma_f32_16x16x32_bf16 v[124:127], v[178:181], v[214:217], v[124:127]
	v_mfma_f32_16x16x32_bf16 v[120:123], v[186:189], v[214:217], v[120:123]
	v_mfma_f32_16x16x32_bf16 v[108:111], v[178:181], v[222:225], v[108:111]
	v_mfma_f32_16x16x32_bf16 v[104:107], v[186:189], v[222:225], v[104:107]
	v_mfma_f32_16x16x32_bf16 v[92:95], v[178:181], v[230:233], v[92:95]
	v_mfma_f32_16x16x32_bf16 v[88:91], v[186:189], v[230:233], v[88:91]
	v_mfma_f32_16x16x32_bf16 v[76:79], v[178:181], v[238:241], v[76:79]
	v_mfma_f32_16x16x32_bf16 v[72:75], v[186:189], v[238:241], v[72:75]
	v_mfma_f32_16x16x32_bf16 v[124:127], v[182:185], v[218:221], v[124:127]
	v_mfma_f32_16x16x32_bf16 v[120:123], v[190:193], v[218:221], v[120:123]
	v_mfma_f32_16x16x32_bf16 v[108:111], v[182:185], v[226:229], v[108:111]
	v_mfma_f32_16x16x32_bf16 v[104:107], v[190:193], v[226:229], v[104:107]
	v_mfma_f32_16x16x32_bf16 v[92:95], v[182:185], v[234:237], v[92:95]
	v_mfma_f32_16x16x32_bf16 v[88:91], v[190:193], v[234:237], v[88:91]
	v_mfma_f32_16x16x32_bf16 v[76:79], v[182:185], v[242:245], v[76:79]
	v_mfma_f32_16x16x32_bf16 v[72:75], v[190:193], v[242:245], v[72:75]
	s_setprio 0
	s_setprio 1
	v_mfma_f32_16x16x32_bf16 v[116:119], v[198:201], v[214:217], v[116:119]
	v_mfma_f32_16x16x32_bf16 v[112:115], v[206:209], v[214:217], v[112:115]
	v_mfma_f32_16x16x32_bf16 v[100:103], v[198:201], v[222:225], v[100:103]
	v_mfma_f32_16x16x32_bf16 v[96:99], v[206:209], v[222:225], v[96:99]
	v_mfma_f32_16x16x32_bf16 v[84:87], v[198:201], v[230:233], v[84:87]
	v_mfma_f32_16x16x32_bf16 v[80:83], v[206:209], v[230:233], v[80:83]
	v_mfma_f32_16x16x32_bf16 v[68:71], v[198:201], v[238:241], v[68:71]
	v_mfma_f32_16x16x32_bf16 v[64:67], v[206:209], v[238:241], v[64:67]
	v_mfma_f32_16x16x32_bf16 v[116:119], v[202:205], v[218:221], v[116:119]
	v_mfma_f32_16x16x32_bf16 v[112:115], v[210:213], v[218:221], v[112:115]
	v_mfma_f32_16x16x32_bf16 v[100:103], v[202:205], v[226:229], v[100:103]
	v_mfma_f32_16x16x32_bf16 v[96:99], v[210:213], v[226:229], v[96:99]
	v_mfma_f32_16x16x32_bf16 v[84:87], v[202:205], v[234:237], v[84:87]
	v_mfma_f32_16x16x32_bf16 v[80:83], v[210:213], v[234:237], v[80:83]
	v_mfma_f32_16x16x32_bf16 v[68:71], v[202:205], v[242:245], v[68:71]
	v_mfma_f32_16x16x32_bf16 v[64:67], v[210:213], v[242:245], v[64:67]
	s_setprio 0
	s_barrier
	s_mov_b32 m0, s37
	s_add_u32 s10, s30, 0x80000
	ds_read_b128 v[214:217], v152 offset:16384
	ds_read_b128 v[218:221], v152 offset:17408
	ds_read_b128 v[222:225], v152 offset:18432
	ds_read_b128 v[226:229], v152 offset:19456
	ds_read_b128 v[230:233], v152 offset:20480
	ds_read_b128 v[234:237], v152 offset:21504
	ds_read_b128 v[238:241], v152 offset:22528
	ds_read_b128 v[242:245], v152 offset:23552
	global_load_lds_dwordx4 v132, s[30:31]
	s_mov_b32 m0, s41
	s_addc_u32 s11, s31, 0
	global_load_lds_dwordx4 v134, s[30:31]
	s_mov_b32 m0, s42
	s_add_u32 s98, s30, s14
	global_load_lds_dwordx4 v132, s[10:11]
	s_mov_b32 m0, s43
	s_addc_u32 s99, s31, s15
	global_load_lds_dwordx4 v134, s[10:11]
	s_mov_b32 m0, s40
	s_add_u32 s100, s34, s14
	global_load_lds_dwordx4 v132, s[34:35]
	s_mov_b32 m0, s72
	s_addc_u32 s101, s35, s15
	global_load_lds_dwordx4 v134, s[34:35]
	s_waitcnt vmcnt(8)
	s_waitcnt lgkmcnt(0)
	s_barrier
	s_setprio 1
	s_waitcnt lgkmcnt(0)
	v_mfma_f32_16x16x32_bf16 v[60:63], v[178:181], v[214:217], v[60:63]
	v_mfma_f32_16x16x32_bf16 v[56:59], v[186:189], v[214:217], v[56:59]
	v_mfma_f32_16x16x32_bf16 v[44:47], v[178:181], v[222:225], v[44:47]
	v_mfma_f32_16x16x32_bf16 v[40:43], v[186:189], v[222:225], v[40:43]
	v_mfma_f32_16x16x32_bf16 v[28:31], v[178:181], v[230:233], v[28:31]
	v_mfma_f32_16x16x32_bf16 v[24:27], v[186:189], v[230:233], v[24:27]
	v_mfma_f32_16x16x32_bf16 v[16:19], v[178:181], v[238:241], v[16:19]
	v_mfma_f32_16x16x32_bf16 v[8:11], v[186:189], v[238:241], v[8:11]
	v_mfma_f32_16x16x32_bf16 v[60:63], v[182:185], v[218:221], v[60:63]
	v_mfma_f32_16x16x32_bf16 v[56:59], v[190:193], v[218:221], v[56:59]
	v_mfma_f32_16x16x32_bf16 v[44:47], v[182:185], v[226:229], v[44:47]
	v_mfma_f32_16x16x32_bf16 v[40:43], v[190:193], v[226:229], v[40:43]
	v_mfma_f32_16x16x32_bf16 v[28:31], v[182:185], v[234:237], v[28:31]
	v_mfma_f32_16x16x32_bf16 v[24:27], v[190:193], v[234:237], v[24:27]
	v_mfma_f32_16x16x32_bf16 v[16:19], v[182:185], v[242:245], v[16:19]
	v_mfma_f32_16x16x32_bf16 v[8:11], v[190:193], v[242:245], v[8:11]
	s_setprio 0
	s_setprio 1
	v_mfma_f32_16x16x32_bf16 v[52:55], v[198:201], v[214:217], v[52:55]
	v_mfma_f32_16x16x32_bf16 v[48:51], v[206:209], v[214:217], v[48:51]
	v_mfma_f32_16x16x32_bf16 v[36:39], v[198:201], v[222:225], v[36:39]
	v_mfma_f32_16x16x32_bf16 v[32:35], v[206:209], v[222:225], v[32:35]
	v_mfma_f32_16x16x32_bf16 v[20:23], v[198:201], v[230:233], v[20:23]
	v_mfma_f32_16x16x32_bf16 v[12:15], v[206:209], v[230:233], v[12:15]
	v_mfma_f32_16x16x32_bf16 v[4:7], v[198:201], v[238:241], v[4:7]
	v_mfma_f32_16x16x32_bf16 v[0:3], v[206:209], v[238:241], v[0:3]
	v_mfma_f32_16x16x32_bf16 v[52:55], v[202:205], v[218:221], v[52:55]
	v_mfma_f32_16x16x32_bf16 v[48:51], v[210:213], v[218:221], v[48:51]
	v_mfma_f32_16x16x32_bf16 v[36:39], v[202:205], v[226:229], v[36:39]
	v_mfma_f32_16x16x32_bf16 v[32:35], v[210:213], v[226:229], v[32:35]
	v_mfma_f32_16x16x32_bf16 v[20:23], v[202:205], v[234:237], v[20:23]
	v_mfma_f32_16x16x32_bf16 v[12:15], v[210:213], v[234:237], v[12:15]
	v_mfma_f32_16x16x32_bf16 v[4:7], v[202:205], v[242:245], v[4:7]
	v_mfma_f32_16x16x32_bf16 v[0:3], v[210:213], v[242:245], v[0:3]
	s_setprio 0
	s_barrier
	ds_read_b128 v[178:181], v169
	ds_read_b128 v[182:185], v170
	ds_read_b128 v[186:189], v171
	ds_read_b128 v[190:193], v172
	ds_read_b128 v[198:201], v173
	ds_read_b128 v[202:205], v174
	ds_read_b128 v[206:209], v175
	ds_read_b128 v[210:213], v176
	s_add_u32 s10, s34, 0x80000
	s_addc_u32 s11, s35, 0
	s_mov_b32 m0, s73
	ds_read_b128 v[214:217], v152 offset:32768
	ds_read_b128 v[218:221], v152 offset:33792
	ds_read_b128 v[222:225], v152 offset:34816
	ds_read_b128 v[226:229], v152 offset:35840
	ds_read_b128 v[230:233], v152 offset:36864
	ds_read_b128 v[234:237], v152 offset:37888
	ds_read_b128 v[238:241], v152 offset:38912
	ds_read_b128 v[242:245], v152 offset:39936
	global_load_lds_dwordx4 v132, s[10:11]
	s_mov_b32 m0, s74
	s_nop 0
	global_load_lds_dwordx4 v134, s[10:11]
	s_waitcnt vmcnt(8)
	s_waitcnt lgkmcnt(0)
	s_barrier
	s_setprio 1
	s_waitcnt lgkmcnt(0)
	v_mfma_f32_16x16x32_bf16 v[124:127], v[178:181], v[214:217], v[124:127]
	v_mfma_f32_16x16x32_bf16 v[120:123], v[186:189], v[214:217], v[120:123]
	v_mfma_f32_16x16x32_bf16 v[108:111], v[178:181], v[222:225], v[108:111]
	v_mfma_f32_16x16x32_bf16 v[104:107], v[186:189], v[222:225], v[104:107]
	v_mfma_f32_16x16x32_bf16 v[92:95], v[178:181], v[230:233], v[92:95]
	v_mfma_f32_16x16x32_bf16 v[88:91], v[186:189], v[230:233], v[88:91]
	v_mfma_f32_16x16x32_bf16 v[76:79], v[178:181], v[238:241], v[76:79]
	v_mfma_f32_16x16x32_bf16 v[72:75], v[186:189], v[238:241], v[72:75]
	v_mfma_f32_16x16x32_bf16 v[124:127], v[182:185], v[218:221], v[124:127]
	v_mfma_f32_16x16x32_bf16 v[120:123], v[190:193], v[218:221], v[120:123]
	v_mfma_f32_16x16x32_bf16 v[108:111], v[182:185], v[226:229], v[108:111]
	v_mfma_f32_16x16x32_bf16 v[104:107], v[190:193], v[226:229], v[104:107]
	v_mfma_f32_16x16x32_bf16 v[92:95], v[182:185], v[234:237], v[92:95]
	v_mfma_f32_16x16x32_bf16 v[88:91], v[190:193], v[234:237], v[88:91]
	v_mfma_f32_16x16x32_bf16 v[76:79], v[182:185], v[242:245], v[76:79]
	v_mfma_f32_16x16x32_bf16 v[72:75], v[190:193], v[242:245], v[72:75]
	s_setprio 0
	s_setprio 1
	v_mfma_f32_16x16x32_bf16 v[116:119], v[198:201], v[214:217], v[116:119]
	v_mfma_f32_16x16x32_bf16 v[112:115], v[206:209], v[214:217], v[112:115]
	v_mfma_f32_16x16x32_bf16 v[100:103], v[198:201], v[222:225], v[100:103]
	v_mfma_f32_16x16x32_bf16 v[96:99], v[206:209], v[222:225], v[96:99]
	v_mfma_f32_16x16x32_bf16 v[84:87], v[198:201], v[230:233], v[84:87]
	v_mfma_f32_16x16x32_bf16 v[80:83], v[206:209], v[230:233], v[80:83]
	v_mfma_f32_16x16x32_bf16 v[68:71], v[198:201], v[238:241], v[68:71]
	v_mfma_f32_16x16x32_bf16 v[64:67], v[206:209], v[238:241], v[64:67]
	v_mfma_f32_16x16x32_bf16 v[116:119], v[202:205], v[218:221], v[116:119]
	v_mfma_f32_16x16x32_bf16 v[112:115], v[210:213], v[218:221], v[112:115]
	v_mfma_f32_16x16x32_bf16 v[100:103], v[202:205], v[226:229], v[100:103]
	v_mfma_f32_16x16x32_bf16 v[96:99], v[210:213], v[226:229], v[96:99]
	v_mfma_f32_16x16x32_bf16 v[84:87], v[202:205], v[234:237], v[84:87]
	v_mfma_f32_16x16x32_bf16 v[80:83], v[210:213], v[234:237], v[80:83]
	v_mfma_f32_16x16x32_bf16 v[68:71], v[202:205], v[242:245], v[68:71]
	v_mfma_f32_16x16x32_bf16 v[64:67], v[210:213], v[242:245], v[64:67]
	s_setprio 0
	s_barrier
	s_mov_b32 m0, s75
	s_add_u32 s10, s30, 0x80080
	ds_read_b128 v[214:217], v152 offset:49152
	ds_read_b128 v[218:221], v152 offset:50176
	ds_read_b128 v[222:225], v152 offset:51200
	ds_read_b128 v[226:229], v152 offset:52224
	ds_read_b128 v[230:233], v152 offset:53248
	ds_read_b128 v[234:237], v152 offset:54272
	ds_read_b128 v[238:241], v152 offset:55296
	ds_read_b128 v[242:245], v152 offset:56320
	global_load_lds_dwordx4 v132, s[98:99]
	s_mov_b32 m0, s78
	s_addc_u32 s11, s31, 0
	global_load_lds_dwordx4 v134, s[98:99]
	s_mov_b32 m0, s83
	s_add_u32 vcc_lo, vcc_lo, 0x100
	global_load_lds_dwordx4 v132, s[10:11]
	s_mov_b32 m0, s84
	s_addc_u32 vcc_hi, vcc_hi, 0
	global_load_lds_dwordx4 v134, s[10:11]
	s_mov_b32 m0, s79
	s_nop 0
	global_load_lds_dwordx4 v132, s[100:101]
	s_mov_b32 m0, s82
	s_nop 0
	global_load_lds_dwordx4 v134, s[100:101]
	s_waitcnt vmcnt(8)
	s_waitcnt lgkmcnt(0)
	s_barrier
	s_setprio 1
	s_waitcnt lgkmcnt(0)
	v_mfma_f32_16x16x32_bf16 v[60:63], v[178:181], v[214:217], v[60:63]
	v_mfma_f32_16x16x32_bf16 v[56:59], v[186:189], v[214:217], v[56:59]
	v_mfma_f32_16x16x32_bf16 v[44:47], v[178:181], v[222:225], v[44:47]
	v_mfma_f32_16x16x32_bf16 v[40:43], v[186:189], v[222:225], v[40:43]
	v_mfma_f32_16x16x32_bf16 v[28:31], v[178:181], v[230:233], v[28:31]
	v_mfma_f32_16x16x32_bf16 v[24:27], v[186:189], v[230:233], v[24:27]
	v_mfma_f32_16x16x32_bf16 v[16:19], v[178:181], v[238:241], v[16:19]
	v_mfma_f32_16x16x32_bf16 v[8:11], v[186:189], v[238:241], v[8:11]
	v_mfma_f32_16x16x32_bf16 v[60:63], v[182:185], v[218:221], v[60:63]
	v_mfma_f32_16x16x32_bf16 v[56:59], v[190:193], v[218:221], v[56:59]
	v_mfma_f32_16x16x32_bf16 v[44:47], v[182:185], v[226:229], v[44:47]
	v_mfma_f32_16x16x32_bf16 v[40:43], v[190:193], v[226:229], v[40:43]
	v_mfma_f32_16x16x32_bf16 v[28:31], v[182:185], v[234:237], v[28:31]
	v_mfma_f32_16x16x32_bf16 v[24:27], v[190:193], v[234:237], v[24:27]
	v_mfma_f32_16x16x32_bf16 v[16:19], v[182:185], v[242:245], v[16:19]
	v_mfma_f32_16x16x32_bf16 v[8:11], v[190:193], v[242:245], v[8:11]
	s_setprio 0
	s_setprio 1
	v_mfma_f32_16x16x32_bf16 v[52:55], v[198:201], v[214:217], v[52:55]
	v_mfma_f32_16x16x32_bf16 v[48:51], v[206:209], v[214:217], v[48:51]
	v_mfma_f32_16x16x32_bf16 v[36:39], v[198:201], v[222:225], v[36:39]
	v_mfma_f32_16x16x32_bf16 v[32:35], v[206:209], v[222:225], v[32:35]
	v_mfma_f32_16x16x32_bf16 v[20:23], v[198:201], v[230:233], v[20:23]
	v_mfma_f32_16x16x32_bf16 v[12:15], v[206:209], v[230:233], v[12:15]
	v_mfma_f32_16x16x32_bf16 v[4:7], v[198:201], v[238:241], v[4:7]
	v_mfma_f32_16x16x32_bf16 v[0:3], v[206:209], v[238:241], v[0:3]
	v_mfma_f32_16x16x32_bf16 v[52:55], v[202:205], v[218:221], v[52:55]
	v_mfma_f32_16x16x32_bf16 v[48:51], v[210:213], v[218:221], v[48:51]
	v_mfma_f32_16x16x32_bf16 v[36:39], v[202:205], v[226:229], v[36:39]
	v_mfma_f32_16x16x32_bf16 v[32:35], v[210:213], v[226:229], v[32:35]
	v_mfma_f32_16x16x32_bf16 v[20:23], v[202:205], v[234:237], v[20:23]
	v_mfma_f32_16x16x32_bf16 v[12:15], v[210:213], v[234:237], v[12:15]
	v_mfma_f32_16x16x32_bf16 v[4:7], v[202:205], v[242:245], v[4:7]
	v_mfma_f32_16x16x32_bf16 v[0:3], v[210:213], v[242:245], v[0:3]
	s_setprio 0
	s_barrier
	s_add_i32 s56, s56, 2
	s_cmp_gt_u32 s56, 29
	s_mov_b64 s[10:11], s[28:29]
	s_cbranch_scc0 .LBB0_856
	s_and_b64 vcc, exec, s[16:17]
	s_cbranch_vccz .LBB0_859
	s_barrier

.LBB0_1096:
	ds_read_b128 v[174:177], v143
	ds_read_b128 v[178:181], v153
	ds_read_b128 v[182:185], v159
	ds_read_b128 v[186:189], v160
	ds_read_b128 v[190:193], v161
	ds_read_b128 v[198:201], v162
	ds_read_b128 v[202:205], v163
	ds_read_b128 v[206:209], v164
	s_add_u32 s48, s24, 0xfffc0080
	s_addc_u32 s49, s25, -1
	s_cmp_eq_u32 s55, 12
	s_cselect_b32 s51, s4, s49
	s_cselect_b32 s50, s5, s48
	s_cselect_b32 s49, s15, s54
	s_cselect_b32 s48, s27, s39
	s_mov_b32 m0, s65
	ds_read_b128 v[210:213], v141
	ds_read_b128 v[214:217], v141 offset:1024
	ds_read_b128 v[218:221], v141 offset:2048
	ds_read_b128 v[222:225], v141 offset:3072
	ds_read_b128 v[226:229], v141 offset:4096
	ds_read_b128 v[230:233], v141 offset:5120
	ds_read_b128 v[234:237], v141 offset:6144
	ds_read_b128 v[238:241], v141 offset:7168
	global_load_lds_dwordx4 v132, s[24:25]
	s_mov_b32 m0, s67
	s_nop 0
	global_load_lds_dwordx4 v134, s[24:25]
	s_waitcnt vmcnt(8)
	s_waitcnt lgkmcnt(0)
	s_barrier
	s_setprio 1
	s_waitcnt lgkmcnt(0)
	v_mfma_f32_16x16x32_bf16 v[124:127], v[174:177], v[210:213], v[124:127]
	v_mfma_f32_16x16x32_bf16 v[120:123], v[182:185], v[210:213], v[120:123]
	v_mfma_f32_16x16x32_bf16 v[108:111], v[174:177], v[218:221], v[108:111]
	v_mfma_f32_16x16x32_bf16 v[104:107], v[182:185], v[218:221], v[104:107]
	v_mfma_f32_16x16x32_bf16 v[92:95], v[174:177], v[226:229], v[92:95]
	v_mfma_f32_16x16x32_bf16 v[88:91], v[182:185], v[226:229], v[88:91]
	v_mfma_f32_16x16x32_bf16 v[76:79], v[174:177], v[234:237], v[76:79]
	v_mfma_f32_16x16x32_bf16 v[72:75], v[182:185], v[234:237], v[72:75]
	v_mfma_f32_16x16x32_bf16 v[124:127], v[178:181], v[214:217], v[124:127]
	v_mfma_f32_16x16x32_bf16 v[120:123], v[186:189], v[214:217], v[120:123]
	v_mfma_f32_16x16x32_bf16 v[108:111], v[178:181], v[222:225], v[108:111]
	v_mfma_f32_16x16x32_bf16 v[104:107], v[186:189], v[222:225], v[104:107]
	v_mfma_f32_16x16x32_bf16 v[92:95], v[178:181], v[230:233], v[92:95]
	v_mfma_f32_16x16x32_bf16 v[88:91], v[186:189], v[230:233], v[88:91]
	v_mfma_f32_16x16x32_bf16 v[76:79], v[178:181], v[238:241], v[76:79]
	v_mfma_f32_16x16x32_bf16 v[72:75], v[186:189], v[238:241], v[72:75]
	s_setprio 0
	s_setprio 1
	v_mfma_f32_16x16x32_bf16 v[116:119], v[190:193], v[210:213], v[116:119]
	v_mfma_f32_16x16x32_bf16 v[112:115], v[202:205], v[210:213], v[112:115]
	v_mfma_f32_16x16x32_bf16 v[100:103], v[190:193], v[218:221], v[100:103]
	v_mfma_f32_16x16x32_bf16 v[96:99], v[202:205], v[218:221], v[96:99]
	v_mfma_f32_16x16x32_bf16 v[84:87], v[190:193], v[226:229], v[84:87]
	v_mfma_f32_16x16x32_bf16 v[80:83], v[202:205], v[226:229], v[80:83]
	v_mfma_f32_16x16x32_bf16 v[68:71], v[190:193], v[234:237], v[68:71]
	v_mfma_f32_16x16x32_bf16 v[64:67], v[202:205], v[234:237], v[64:67]
	v_mfma_f32_16x16x32_bf16 v[116:119], v[198:201], v[214:217], v[116:119]
	v_mfma_f32_16x16x32_bf16 v[112:115], v[206:209], v[214:217], v[112:115]
	v_mfma_f32_16x16x32_bf16 v[100:103], v[198:201], v[222:225], v[100:103]
	v_mfma_f32_16x16x32_bf16 v[96:99], v[206:209], v[222:225], v[96:99]
	v_mfma_f32_16x16x32_bf16 v[84:87], v[198:201], v[230:233], v[84:87]
	v_mfma_f32_16x16x32_bf16 v[80:83], v[206:209], v[230:233], v[80:83]
	v_mfma_f32_16x16x32_bf16 v[68:71], v[198:201], v[238:241], v[68:71]
	v_mfma_f32_16x16x32_bf16 v[64:67], v[206:209], v[238:241], v[64:67]
	s_setprio 0
	s_barrier
	s_mov_b32 m0, s28
	s_add_u32 s68, s48, 0x40000
	ds_read_b128 v[210:213], v141 offset:16384
	ds_read_b128 v[214:217], v141 offset:17408
	ds_read_b128 v[218:221], v141 offset:18432
	ds_read_b128 v[222:225], v141 offset:19456
	ds_read_b128 v[226:229], v141 offset:20480
	ds_read_b128 v[230:233], v141 offset:21504
	ds_read_b128 v[234:237], v141 offset:22528
	ds_read_b128 v[238:241], v141 offset:23552
	global_load_lds_dwordx4 v130, s[48:49]
	s_mov_b32 m0, s29
	s_addc_u32 s69, s49, 0
	global_load_lds_dwordx4 v128, s[48:49]
	s_mov_b32 m0, s30
	s_add_u32 s98, s48, s8
	global_load_lds_dwordx4 v130, s[68:69]
	s_mov_b32 m0, s31
	s_addc_u32 s99, s49, s9
	global_load_lds_dwordx4 v128, s[68:69]
	s_mov_b32 m0, s2
	s_add_u32 s100, s50, s8
	global_load_lds_dwordx4 v130, s[50:51]
	s_mov_b32 m0, s33
	s_addc_u32 s101, s51, s9
	global_load_lds_dwordx4 v128, s[50:51]
	s_waitcnt vmcnt(8)
	s_waitcnt lgkmcnt(0)
	s_barrier
	s_setprio 1
	s_waitcnt lgkmcnt(0)
	v_mfma_f32_16x16x32_bf16 v[60:63], v[174:177], v[210:213], v[60:63]
	v_mfma_f32_16x16x32_bf16 v[56:59], v[182:185], v[210:213], v[56:59]
	v_mfma_f32_16x16x32_bf16 v[44:47], v[174:177], v[218:221], v[44:47]
	v_mfma_f32_16x16x32_bf16 v[40:43], v[182:185], v[218:221], v[40:43]
	v_mfma_f32_16x16x32_bf16 v[28:31], v[174:177], v[226:229], v[28:31]
	v_mfma_f32_16x16x32_bf16 v[24:27], v[182:185], v[226:229], v[24:27]
	v_mfma_f32_16x16x32_bf16 v[12:15], v[174:177], v[234:237], v[12:15]
	v_mfma_f32_16x16x32_bf16 v[8:11], v[182:185], v[234:237], v[8:11]
	v_mfma_f32_16x16x32_bf16 v[60:63], v[178:181], v[214:217], v[60:63]
	v_mfma_f32_16x16x32_bf16 v[56:59], v[186:189], v[214:217], v[56:59]
	v_mfma_f32_16x16x32_bf16 v[44:47], v[178:181], v[222:225], v[44:47]
	v_mfma_f32_16x16x32_bf16 v[40:43], v[186:189], v[222:225], v[40:43]
	v_mfma_f32_16x16x32_bf16 v[28:31], v[178:181], v[230:233], v[28:31]
	v_mfma_f32_16x16x32_bf16 v[24:27], v[186:189], v[230:233], v[24:27]
	v_mfma_f32_16x16x32_bf16 v[12:15], v[178:181], v[238:241], v[12:15]
	v_mfma_f32_16x16x32_bf16 v[8:11], v[186:189], v[238:241], v[8:11]
	s_setprio 0
	s_setprio 1
	v_mfma_f32_16x16x32_bf16 v[52:55], v[190:193], v[210:213], v[52:55]
	v_mfma_f32_16x16x32_bf16 v[48:51], v[202:205], v[210:213], v[48:51]
	v_mfma_f32_16x16x32_bf16 v[36:39], v[190:193], v[218:221], v[36:39]
	v_mfma_f32_16x16x32_bf16 v[32:35], v[202:205], v[218:221], v[32:35]
	v_mfma_f32_16x16x32_bf16 v[20:23], v[190:193], v[226:229], v[20:23]
	v_mfma_f32_16x16x32_bf16 v[16:19], v[202:205], v[226:229], v[16:19]
	v_mfma_f32_16x16x32_bf16 v[4:7], v[190:193], v[234:237], v[4:7]
	v_mfma_f32_16x16x32_bf16 v[0:3], v[202:205], v[234:237], v[0:3]
	v_mfma_f32_16x16x32_bf16 v[52:55], v[198:201], v[214:217], v[52:55]
	v_mfma_f32_16x16x32_bf16 v[48:51], v[206:209], v[214:217], v[48:51]
	v_mfma_f32_16x16x32_bf16 v[36:39], v[198:201], v[222:225], v[36:39]
	v_mfma_f32_16x16x32_bf16 v[32:35], v[206:209], v[222:225], v[32:35]
	v_mfma_f32_16x16x32_bf16 v[20:23], v[198:201], v[230:233], v[20:23]
	v_mfma_f32_16x16x32_bf16 v[16:19], v[206:209], v[230:233], v[16:19]
	v_mfma_f32_16x16x32_bf16 v[4:7], v[198:201], v[238:241], v[4:7]
	v_mfma_f32_16x16x32_bf16 v[0:3], v[206:209], v[238:241], v[0:3]
	s_setprio 0
	s_barrier
	ds_read_b128 v[174:177], v165
	ds_read_b128 v[178:181], v166
	ds_read_b128 v[182:185], v167
	ds_read_b128 v[186:189], v168
	ds_read_b128 v[190:193], v169
	ds_read_b128 v[198:201], v170
	ds_read_b128 v[202:205], v171
	ds_read_b128 v[206:209], v172
	s_add_u32 s50, s50, 0x40000
	s_addc_u32 s51, s51, 0
	s_mov_b32 m0, s34
	ds_read_b128 v[210:213], v141 offset:32768
	ds_read_b128 v[214:217], v141 offset:33792
	ds_read_b128 v[218:221], v141 offset:34816
	ds_read_b128 v[222:225], v141 offset:35840
	ds_read_b128 v[226:229], v141 offset:36864
	ds_read_b128 v[230:233], v141 offset:37888
	ds_read_b128 v[234:237], v141 offset:38912
	ds_read_b128 v[238:241], v141 offset:39936
	global_load_lds_dwordx4 v130, s[50:51]
	s_mov_b32 m0, s35
	s_nop 0
	global_load_lds_dwordx4 v128, s[50:51]
	s_waitcnt vmcnt(8)
	s_waitcnt lgkmcnt(0)
	s_barrier
	s_setprio 1
	s_waitcnt lgkmcnt(0)
	v_mfma_f32_16x16x32_bf16 v[124:127], v[174:177], v[210:213], v[124:127]
	v_mfma_f32_16x16x32_bf16 v[120:123], v[182:185], v[210:213], v[120:123]
	v_mfma_f32_16x16x32_bf16 v[108:111], v[174:177], v[218:221], v[108:111]
	v_mfma_f32_16x16x32_bf16 v[104:107], v[182:185], v[218:221], v[104:107]
	v_mfma_f32_16x16x32_bf16 v[92:95], v[174:177], v[226:229], v[92:95]
	v_mfma_f32_16x16x32_bf16 v[88:91], v[182:185], v[226:229], v[88:91]
	v_mfma_f32_16x16x32_bf16 v[76:79], v[174:177], v[234:237], v[76:79]
	v_mfma_f32_16x16x32_bf16 v[72:75], v[182:185], v[234:237], v[72:75]
	v_mfma_f32_16x16x32_bf16 v[124:127], v[178:181], v[214:217], v[124:127]
	v_mfma_f32_16x16x32_bf16 v[120:123], v[186:189], v[214:217], v[120:123]
	v_mfma_f32_16x16x32_bf16 v[108:111], v[178:181], v[222:225], v[108:111]
	v_mfma_f32_16x16x32_bf16 v[104:107], v[186:189], v[222:225], v[104:107]
	v_mfma_f32_16x16x32_bf16 v[92:95], v[178:181], v[230:233], v[92:95]
	v_mfma_f32_16x16x32_bf16 v[88:91], v[186:189], v[230:233], v[88:91]
	v_mfma_f32_16x16x32_bf16 v[76:79], v[178:181], v[238:241], v[76:79]
	v_mfma_f32_16x16x32_bf16 v[72:75], v[186:189], v[238:241], v[72:75]
	s_setprio 0
	s_setprio 1
	v_mfma_f32_16x16x32_bf16 v[116:119], v[190:193], v[210:213], v[116:119]
	v_mfma_f32_16x16x32_bf16 v[112:115], v[202:205], v[210:213], v[112:115]
	v_mfma_f32_16x16x32_bf16 v[100:103], v[190:193], v[218:221], v[100:103]
	v_mfma_f32_16x16x32_bf16 v[96:99], v[202:205], v[218:221], v[96:99]
	v_mfma_f32_16x16x32_bf16 v[84:87], v[190:193], v[226:229], v[84:87]
	v_mfma_f32_16x16x32_bf16 v[80:83], v[202:205], v[226:229], v[80:83]
	v_mfma_f32_16x16x32_bf16 v[68:71], v[190:193], v[234:237], v[68:71]
	v_mfma_f32_16x16x32_bf16 v[64:67], v[202:205], v[234:237], v[64:67]
	v_mfma_f32_16x16x32_bf16 v[116:119], v[198:201], v[214:217], v[116:119]
	v_mfma_f32_16x16x32_bf16 v[112:115], v[206:209], v[214:217], v[112:115]
	v_mfma_f32_16x16x32_bf16 v[100:103], v[198:201], v[222:225], v[100:103]
	v_mfma_f32_16x16x32_bf16 v[96:99], v[206:209], v[222:225], v[96:99]
	v_mfma_f32_16x16x32_bf16 v[84:87], v[198:201], v[230:233], v[84:87]
	v_mfma_f32_16x16x32_bf16 v[80:83], v[206:209], v[230:233], v[80:83]
	v_mfma_f32_16x16x32_bf16 v[68:71], v[198:201], v[238:241], v[68:71]
	v_mfma_f32_16x16x32_bf16 v[64:67], v[206:209], v[238:241], v[64:67]
	s_setprio 0
	s_barrier
	s_mov_b32 m0, s40
	s_add_u32 s48, s48, 0x40080
	ds_read_b128 v[210:213], v141 offset:49152
	ds_read_b128 v[214:217], v141 offset:50176
	ds_read_b128 v[218:221], v141 offset:51200
	ds_read_b128 v[222:225], v141 offset:52224
	ds_read_b128 v[226:229], v141 offset:53248
	ds_read_b128 v[230:233], v141 offset:54272
	ds_read_b128 v[234:237], v141 offset:55296
	ds_read_b128 v[238:241], v141 offset:56320
	global_load_lds_dwordx4 v130, s[98:99]
	s_mov_b32 m0, s41
	s_addc_u32 s49, s49, 0
	global_load_lds_dwordx4 v128, s[98:99]
	s_mov_b32 m0, s53
	s_add_u32 s24, s24, 0x100
	global_load_lds_dwordx4 v130, s[48:49]
	s_mov_b32 m0, s60
	s_addc_u32 s25, s25, 0
	global_load_lds_dwordx4 v128, s[48:49]
	s_mov_b32 m0, s47
	s_add_u32 s39, s39, 0x100
	global_load_lds_dwordx4 v130, s[100:101]
	s_mov_b32 m0, s52
	s_addc_u32 s54, s54, 0
	global_load_lds_dwordx4 v128, s[100:101]
	s_waitcnt vmcnt(8)
	s_waitcnt lgkmcnt(0)
	s_barrier
	s_setprio 1
	s_waitcnt lgkmcnt(0)
	v_mfma_f32_16x16x32_bf16 v[60:63], v[174:177], v[210:213], v[60:63]
	v_mfma_f32_16x16x32_bf16 v[56:59], v[182:185], v[210:213], v[56:59]
	v_mfma_f32_16x16x32_bf16 v[44:47], v[174:177], v[218:221], v[44:47]
	v_mfma_f32_16x16x32_bf16 v[40:43], v[182:185], v[218:221], v[40:43]
	v_mfma_f32_16x16x32_bf16 v[28:31], v[174:177], v[226:229], v[28:31]
	v_mfma_f32_16x16x32_bf16 v[24:27], v[182:185], v[226:229], v[24:27]
	v_mfma_f32_16x16x32_bf16 v[12:15], v[174:177], v[234:237], v[12:15]
	v_mfma_f32_16x16x32_bf16 v[8:11], v[182:185], v[234:237], v[8:11]
	v_mfma_f32_16x16x32_bf16 v[60:63], v[178:181], v[214:217], v[60:63]
	v_mfma_f32_16x16x32_bf16 v[56:59], v[186:189], v[214:217], v[56:59]
	v_mfma_f32_16x16x32_bf16 v[44:47], v[178:181], v[222:225], v[44:47]
	v_mfma_f32_16x16x32_bf16 v[40:43], v[186:189], v[222:225], v[40:43]
	v_mfma_f32_16x16x32_bf16 v[28:31], v[178:181], v[230:233], v[28:31]
	v_mfma_f32_16x16x32_bf16 v[24:27], v[186:189], v[230:233], v[24:27]
	v_mfma_f32_16x16x32_bf16 v[12:15], v[178:181], v[238:241], v[12:15]
	v_mfma_f32_16x16x32_bf16 v[8:11], v[186:189], v[238:241], v[8:11]
	s_setprio 0
	s_setprio 1
	v_mfma_f32_16x16x32_bf16 v[52:55], v[190:193], v[210:213], v[52:55]
	v_mfma_f32_16x16x32_bf16 v[48:51], v[202:205], v[210:213], v[48:51]
	v_mfma_f32_16x16x32_bf16 v[36:39], v[190:193], v[218:221], v[36:39]
	v_mfma_f32_16x16x32_bf16 v[32:35], v[202:205], v[218:221], v[32:35]
	v_mfma_f32_16x16x32_bf16 v[20:23], v[190:193], v[226:229], v[20:23]
	v_mfma_f32_16x16x32_bf16 v[16:19], v[202:205], v[226:229], v[16:19]
	v_mfma_f32_16x16x32_bf16 v[4:7], v[190:193], v[234:237], v[4:7]
	v_mfma_f32_16x16x32_bf16 v[0:3], v[202:205], v[234:237], v[0:3]
	v_mfma_f32_16x16x32_bf16 v[52:55], v[198:201], v[214:217], v[52:55]
	v_mfma_f32_16x16x32_bf16 v[48:51], v[206:209], v[214:217], v[48:51]
	v_mfma_f32_16x16x32_bf16 v[36:39], v[198:201], v[222:225], v[36:39]
	v_mfma_f32_16x16x32_bf16 v[32:35], v[206:209], v[222:225], v[32:35]
	v_mfma_f32_16x16x32_bf16 v[20:23], v[198:201], v[230:233], v[20:23]
	v_mfma_f32_16x16x32_bf16 v[16:19], v[206:209], v[230:233], v[16:19]
	v_mfma_f32_16x16x32_bf16 v[4:7], v[198:201], v[238:241], v[4:7]
	v_mfma_f32_16x16x32_bf16 v[0:3], v[206:209], v[238:241], v[0:3]
	s_setprio 0
	s_barrier
	s_add_i32 s55, s55, 2
	s_cmp_gt_u32 s55, 13
	s_cbranch_scc0 .LBB0_1096
	s_and_b64 vcc, exec, s[12:13]
	s_cbranch_vccz .LBB0_1099
	s_barrier

.LBB0_1176:
	ds_read_b128 v[128:131], v183
	ds_read_b128 v[132:135], v184
	ds_read_b128 v[136:139], v185
	ds_read_b128 v[168:171], v186
	ds_read_b128 v[172:175], v187
	ds_read_b128 v[176:179], v188
	ds_read_b128 v[204:207], v189
	ds_read_b128 v[208:211], v190
	s_add_u32 s46, s24, 0x100
	s_addc_u32 s47, s25, 0
	s_cmp_eq_u32 s66, 40
	s_cselect_b32 s51, s13, s47
	s_cselect_b32 s50, s12, s46
	s_cselect_b32 s49, s45, s5
	s_cselect_b32 s48, s44, s4
	s_mov_b32 m0, s60
	ds_read_b128 v[212:215], v159
	ds_read_b128 v[216:219], v159 offset:1024
	ds_read_b128 v[220:223], v159 offset:2048
	ds_read_b128 v[224:227], v159 offset:3072
	ds_read_b128 v[228:231], v159 offset:4096
	ds_read_b128 v[232:235], v159 offset:5120
	ds_read_b128 v[236:239], v159 offset:6144
	ds_read_b128 v[240:243], v159 offset:7168
	global_load_lds_dwordx4 v160, s[24:25]
	s_mov_b32 m0, s61
	s_nop 0
	global_load_lds_dwordx4 v162, s[24:25]
	s_waitcnt vmcnt(8)
	s_waitcnt lgkmcnt(0)
	s_barrier
	s_setprio 1
	s_waitcnt lgkmcnt(0)
	v_mfma_f32_16x16x32_bf16 v[124:127], v[128:131], v[212:215], v[124:127]
	v_mfma_f32_16x16x32_bf16 v[120:123], v[136:139], v[212:215], v[120:123]
	v_mfma_f32_16x16x32_bf16 v[108:111], v[128:131], v[220:223], v[108:111]
	v_mfma_f32_16x16x32_bf16 v[104:107], v[136:139], v[220:223], v[104:107]
	v_mfma_f32_16x16x32_bf16 v[92:95], v[128:131], v[228:231], v[92:95]
	v_mfma_f32_16x16x32_bf16 v[88:91], v[136:139], v[228:231], v[88:91]
	v_mfma_f32_16x16x32_bf16 v[76:79], v[128:131], v[236:239], v[76:79]
	v_mfma_f32_16x16x32_bf16 v[72:75], v[136:139], v[236:239], v[72:75]
	v_mfma_f32_16x16x32_bf16 v[124:127], v[132:135], v[216:219], v[124:127]
	v_mfma_f32_16x16x32_bf16 v[120:123], v[168:171], v[216:219], v[120:123]
	v_mfma_f32_16x16x32_bf16 v[108:111], v[132:135], v[224:227], v[108:111]
	v_mfma_f32_16x16x32_bf16 v[104:107], v[168:171], v[224:227], v[104:107]
	v_mfma_f32_16x16x32_bf16 v[92:95], v[132:135], v[232:235], v[92:95]
	v_mfma_f32_16x16x32_bf16 v[88:91], v[168:171], v[232:235], v[88:91]
	v_mfma_f32_16x16x32_bf16 v[76:79], v[132:135], v[240:243], v[76:79]
	v_mfma_f32_16x16x32_bf16 v[72:75], v[168:171], v[240:243], v[72:75]
	s_setprio 0
	s_setprio 1
	v_mfma_f32_16x16x32_bf16 v[116:119], v[172:175], v[212:215], v[116:119]
	v_mfma_f32_16x16x32_bf16 v[112:115], v[204:207], v[212:215], v[112:115]
	v_mfma_f32_16x16x32_bf16 v[100:103], v[172:175], v[220:223], v[100:103]
	v_mfma_f32_16x16x32_bf16 v[96:99], v[204:207], v[220:223], v[96:99]
	v_mfma_f32_16x16x32_bf16 v[84:87], v[172:175], v[228:231], v[84:87]
	v_mfma_f32_16x16x32_bf16 v[80:83], v[204:207], v[228:231], v[80:83]
	v_mfma_f32_16x16x32_bf16 v[68:71], v[172:175], v[236:239], v[68:71]
	v_mfma_f32_16x16x32_bf16 v[64:67], v[204:207], v[236:239], v[64:67]
	v_mfma_f32_16x16x32_bf16 v[116:119], v[176:179], v[216:219], v[116:119]
	v_mfma_f32_16x16x32_bf16 v[112:115], v[208:211], v[216:219], v[112:115]
	v_mfma_f32_16x16x32_bf16 v[100:103], v[176:179], v[224:227], v[100:103]
	v_mfma_f32_16x16x32_bf16 v[96:99], v[208:211], v[224:227], v[96:99]
	v_mfma_f32_16x16x32_bf16 v[84:87], v[176:179], v[232:235], v[84:87]
	v_mfma_f32_16x16x32_bf16 v[80:83], v[208:211], v[232:235], v[80:83]
	v_mfma_f32_16x16x32_bf16 v[68:71], v[176:179], v[240:243], v[68:71]
	v_mfma_f32_16x16x32_bf16 v[64:67], v[208:211], v[240:243], v[64:67]
	s_setprio 0
	s_barrier
	s_mov_b32 m0, s7
	s_add_u32 s24, s48, 0xb0000
	ds_read_b128 v[212:215], v159 offset:16384
	ds_read_b128 v[216:219], v159 offset:17408
	ds_read_b128 v[220:223], v159 offset:18432
	ds_read_b128 v[224:227], v159 offset:19456
	ds_read_b128 v[228:231], v159 offset:20480
	ds_read_b128 v[232:235], v159 offset:21504
	ds_read_b128 v[236:239], v159 offset:22528
	ds_read_b128 v[240:243], v159 offset:23552
	global_load_lds_dwordx4 v140, s[48:49]
	s_mov_b32 m0, s28
	s_addc_u32 s25, s49, 0
	global_load_lds_dwordx4 v142, s[48:49]
	s_mov_b32 m0, s29
	s_add_u32 s98, s48, s14
	global_load_lds_dwordx4 v140, s[24:25]
	s_mov_b32 m0, s30
	s_addc_u32 s99, s49, s15
	global_load_lds_dwordx4 v142, s[24:25]
	s_mov_b32 m0, s6
	s_add_u32 s100, s50, s14
	global_load_lds_dwordx4 v140, s[50:51]
	s_mov_b32 m0, s31
	s_addc_u32 s101, s51, s15
	global_load_lds_dwordx4 v142, s[50:51]
	s_waitcnt vmcnt(8)
	s_waitcnt lgkmcnt(0)
	s_barrier
	s_setprio 1
	s_waitcnt lgkmcnt(0)
	v_mfma_f32_16x16x32_bf16 v[60:63], v[128:131], v[212:215], v[60:63]
	v_mfma_f32_16x16x32_bf16 v[56:59], v[136:139], v[212:215], v[56:59]
	v_mfma_f32_16x16x32_bf16 v[44:47], v[128:131], v[220:223], v[44:47]
	v_mfma_f32_16x16x32_bf16 v[40:43], v[136:139], v[220:223], v[40:43]
	v_mfma_f32_16x16x32_bf16 v[28:31], v[128:131], v[228:231], v[28:31]
	v_mfma_f32_16x16x32_bf16 v[24:27], v[136:139], v[228:231], v[24:27]
	v_mfma_f32_16x16x32_bf16 v[12:15], v[128:131], v[236:239], v[12:15]
	v_mfma_f32_16x16x32_bf16 v[8:11], v[136:139], v[236:239], v[8:11]
	v_mfma_f32_16x16x32_bf16 v[60:63], v[132:135], v[216:219], v[60:63]
	v_mfma_f32_16x16x32_bf16 v[56:59], v[168:171], v[216:219], v[56:59]
	v_mfma_f32_16x16x32_bf16 v[44:47], v[132:135], v[224:227], v[44:47]
	v_mfma_f32_16x16x32_bf16 v[40:43], v[168:171], v[224:227], v[40:43]
	v_mfma_f32_16x16x32_bf16 v[28:31], v[132:135], v[232:235], v[28:31]
	v_mfma_f32_16x16x32_bf16 v[24:27], v[168:171], v[232:235], v[24:27]
	v_mfma_f32_16x16x32_bf16 v[12:15], v[132:135], v[240:243], v[12:15]
	v_mfma_f32_16x16x32_bf16 v[8:11], v[168:171], v[240:243], v[8:11]
	s_setprio 0
	s_setprio 1
	v_mfma_f32_16x16x32_bf16 v[52:55], v[172:175], v[212:215], v[52:55]
	v_mfma_f32_16x16x32_bf16 v[48:51], v[204:207], v[212:215], v[48:51]
	v_mfma_f32_16x16x32_bf16 v[36:39], v[172:175], v[220:223], v[36:39]
	v_mfma_f32_16x16x32_bf16 v[32:35], v[204:207], v[220:223], v[32:35]
	v_mfma_f32_16x16x32_bf16 v[20:23], v[172:175], v[228:231], v[20:23]
	v_mfma_f32_16x16x32_bf16 v[16:19], v[204:207], v[228:231], v[16:19]
	v_mfma_f32_16x16x32_bf16 v[4:7], v[172:175], v[236:239], v[4:7]
	v_mfma_f32_16x16x32_bf16 v[0:3], v[204:207], v[236:239], v[0:3]
	v_mfma_f32_16x16x32_bf16 v[52:55], v[176:179], v[216:219], v[52:55]
	v_mfma_f32_16x16x32_bf16 v[48:51], v[208:211], v[216:219], v[48:51]
	v_mfma_f32_16x16x32_bf16 v[36:39], v[176:179], v[224:227], v[36:39]
	v_mfma_f32_16x16x32_bf16 v[32:35], v[208:211], v[224:227], v[32:35]
	v_mfma_f32_16x16x32_bf16 v[20:23], v[176:179], v[232:235], v[20:23]
	v_mfma_f32_16x16x32_bf16 v[16:19], v[208:211], v[232:235], v[16:19]
	v_mfma_f32_16x16x32_bf16 v[4:7], v[176:179], v[240:243], v[4:7]
	v_mfma_f32_16x16x32_bf16 v[0:3], v[208:211], v[240:243], v[0:3]
	s_setprio 0
	s_barrier
	ds_read_b128 v[128:131], v191
	ds_read_b128 v[132:135], v192
	ds_read_b128 v[136:139], v193
	ds_read_b128 v[168:171], v197
	ds_read_b128 v[172:175], v198
	ds_read_b128 v[176:179], v199
	ds_read_b128 v[204:207], v200
	ds_read_b128 v[208:211], v201
	s_add_u32 s24, s50, 0xb0000
	s_addc_u32 s25, s51, 0
	s_mov_b32 m0, s33
	ds_read_b128 v[212:215], v159 offset:32768
	ds_read_b128 v[216:219], v159 offset:33792
	ds_read_b128 v[220:223], v159 offset:34816
	ds_read_b128 v[224:227], v159 offset:35840
	ds_read_b128 v[228:231], v159 offset:36864
	ds_read_b128 v[232:235], v159 offset:37888
	ds_read_b128 v[236:239], v159 offset:38912
	ds_read_b128 v[240:243], v159 offset:39936
	global_load_lds_dwordx4 v140, s[24:25]
	s_mov_b32 m0, s34
	s_nop 0
	global_load_lds_dwordx4 v142, s[24:25]
	s_waitcnt vmcnt(8)
	s_waitcnt lgkmcnt(0)
	s_barrier
	s_setprio 1
	s_waitcnt lgkmcnt(0)
	v_mfma_f32_16x16x32_bf16 v[124:127], v[128:131], v[212:215], v[124:127]
	v_mfma_f32_16x16x32_bf16 v[120:123], v[136:139], v[212:215], v[120:123]
	v_mfma_f32_16x16x32_bf16 v[108:111], v[128:131], v[220:223], v[108:111]
	v_mfma_f32_16x16x32_bf16 v[104:107], v[136:139], v[220:223], v[104:107]
	v_mfma_f32_16x16x32_bf16 v[92:95], v[128:131], v[228:231], v[92:95]
	v_mfma_f32_16x16x32_bf16 v[88:91], v[136:139], v[228:231], v[88:91]
	v_mfma_f32_16x16x32_bf16 v[76:79], v[128:131], v[236:239], v[76:79]
	v_mfma_f32_16x16x32_bf16 v[72:75], v[136:139], v[236:239], v[72:75]
	v_mfma_f32_16x16x32_bf16 v[124:127], v[132:135], v[216:219], v[124:127]
	v_mfma_f32_16x16x32_bf16 v[120:123], v[168:171], v[216:219], v[120:123]
	v_mfma_f32_16x16x32_bf16 v[108:111], v[132:135], v[224:227], v[108:111]
	v_mfma_f32_16x16x32_bf16 v[104:107], v[168:171], v[224:227], v[104:107]
	v_mfma_f32_16x16x32_bf16 v[92:95], v[132:135], v[232:235], v[92:95]
	v_mfma_f32_16x16x32_bf16 v[88:91], v[168:171], v[232:235], v[88:91]
	v_mfma_f32_16x16x32_bf16 v[76:79], v[132:135], v[240:243], v[76:79]
	v_mfma_f32_16x16x32_bf16 v[72:75], v[168:171], v[240:243], v[72:75]
	s_setprio 0
	s_setprio 1
	v_mfma_f32_16x16x32_bf16 v[116:119], v[172:175], v[212:215], v[116:119]
	v_mfma_f32_16x16x32_bf16 v[112:115], v[204:207], v[212:215], v[112:115]
	v_mfma_f32_16x16x32_bf16 v[100:103], v[172:175], v[220:223], v[100:103]
	v_mfma_f32_16x16x32_bf16 v[96:99], v[204:207], v[220:223], v[96:99]
	v_mfma_f32_16x16x32_bf16 v[84:87], v[172:175], v[228:231], v[84:87]
	v_mfma_f32_16x16x32_bf16 v[80:83], v[204:207], v[228:231], v[80:83]
	v_mfma_f32_16x16x32_bf16 v[68:71], v[172:175], v[236:239], v[68:71]
	v_mfma_f32_16x16x32_bf16 v[64:67], v[204:207], v[236:239], v[64:67]
	v_mfma_f32_16x16x32_bf16 v[116:119], v[176:179], v[216:219], v[116:119]
	v_mfma_f32_16x16x32_bf16 v[112:115], v[208:211], v[216:219], v[112:115]
	v_mfma_f32_16x16x32_bf16 v[100:103], v[176:179], v[224:227], v[100:103]
	v_mfma_f32_16x16x32_bf16 v[96:99], v[208:211], v[224:227], v[96:99]
	v_mfma_f32_16x16x32_bf16 v[84:87], v[176:179], v[232:235], v[84:87]
	v_mfma_f32_16x16x32_bf16 v[80:83], v[208:211], v[232:235], v[80:83]
	v_mfma_f32_16x16x32_bf16 v[68:71], v[176:179], v[240:243], v[68:71]
	v_mfma_f32_16x16x32_bf16 v[64:67], v[208:211], v[240:243], v[64:67]
	s_setprio 0
	s_barrier
	s_mov_b32 m0, s35
	s_add_u32 s24, s48, 0xb0080
	ds_read_b128 v[212:215], v159 offset:49152
	ds_read_b128 v[216:219], v159 offset:50176
	ds_read_b128 v[220:223], v159 offset:51200
	ds_read_b128 v[224:227], v159 offset:52224
	ds_read_b128 v[228:231], v159 offset:53248
	ds_read_b128 v[232:235], v159 offset:54272
	ds_read_b128 v[236:239], v159 offset:55296
	ds_read_b128 v[240:243], v159 offset:56320
	global_load_lds_dwordx4 v140, s[98:99]
	s_mov_b32 m0, s36
	s_addc_u32 s25, s49, 0
	global_load_lds_dwordx4 v142, s[98:99]
	s_mov_b32 m0, s41
	s_add_u32 s4, s4, 0x100
	global_load_lds_dwordx4 v140, s[24:25]
	s_mov_b32 m0, s43
	s_addc_u32 s5, s5, 0
	global_load_lds_dwordx4 v142, s[24:25]
	s_mov_b32 m0, s37
	s_nop 0
	global_load_lds_dwordx4 v140, s[100:101]
	s_mov_b32 m0, s40
	s_nop 0
	global_load_lds_dwordx4 v142, s[100:101]
	s_waitcnt vmcnt(8)
	s_waitcnt lgkmcnt(0)
	s_barrier
	s_setprio 1
	s_waitcnt lgkmcnt(0)
	v_mfma_f32_16x16x32_bf16 v[60:63], v[128:131], v[212:215], v[60:63]
	v_mfma_f32_16x16x32_bf16 v[56:59], v[136:139], v[212:215], v[56:59]
	v_mfma_f32_16x16x32_bf16 v[44:47], v[128:131], v[220:223], v[44:47]
	v_mfma_f32_16x16x32_bf16 v[40:43], v[136:139], v[220:223], v[40:43]
	v_mfma_f32_16x16x32_bf16 v[28:31], v[128:131], v[228:231], v[28:31]
	v_mfma_f32_16x16x32_bf16 v[24:27], v[136:139], v[228:231], v[24:27]
	v_mfma_f32_16x16x32_bf16 v[12:15], v[128:131], v[236:239], v[12:15]
	v_mfma_f32_16x16x32_bf16 v[8:11], v[136:139], v[236:239], v[8:11]
	v_mfma_f32_16x16x32_bf16 v[60:63], v[132:135], v[216:219], v[60:63]
	v_mfma_f32_16x16x32_bf16 v[56:59], v[168:171], v[216:219], v[56:59]
	v_mfma_f32_16x16x32_bf16 v[44:47], v[132:135], v[224:227], v[44:47]
	v_mfma_f32_16x16x32_bf16 v[40:43], v[168:171], v[224:227], v[40:43]
	v_mfma_f32_16x16x32_bf16 v[28:31], v[132:135], v[232:235], v[28:31]
	v_mfma_f32_16x16x32_bf16 v[24:27], v[168:171], v[232:235], v[24:27]
	v_mfma_f32_16x16x32_bf16 v[12:15], v[132:135], v[240:243], v[12:15]
	v_mfma_f32_16x16x32_bf16 v[8:11], v[168:171], v[240:243], v[8:11]
	s_setprio 0
	s_setprio 1
	v_mfma_f32_16x16x32_bf16 v[52:55], v[172:175], v[212:215], v[52:55]
	v_mfma_f32_16x16x32_bf16 v[48:51], v[204:207], v[212:215], v[48:51]
	v_mfma_f32_16x16x32_bf16 v[36:39], v[172:175], v[220:223], v[36:39]
	v_mfma_f32_16x16x32_bf16 v[32:35], v[204:207], v[220:223], v[32:35]
	v_mfma_f32_16x16x32_bf16 v[20:23], v[172:175], v[228:231], v[20:23]
	v_mfma_f32_16x16x32_bf16 v[16:19], v[204:207], v[228:231], v[16:19]
	v_mfma_f32_16x16x32_bf16 v[4:7], v[172:175], v[236:239], v[4:7]
	v_mfma_f32_16x16x32_bf16 v[0:3], v[204:207], v[236:239], v[0:3]
	v_mfma_f32_16x16x32_bf16 v[52:55], v[176:179], v[216:219], v[52:55]
	v_mfma_f32_16x16x32_bf16 v[48:51], v[208:211], v[216:219], v[48:51]
	v_mfma_f32_16x16x32_bf16 v[36:39], v[176:179], v[224:227], v[36:39]
	v_mfma_f32_16x16x32_bf16 v[32:35], v[208:211], v[224:227], v[32:35]
	v_mfma_f32_16x16x32_bf16 v[20:23], v[176:179], v[232:235], v[20:23]
	v_mfma_f32_16x16x32_bf16 v[16:19], v[208:211], v[232:235], v[16:19]
	v_mfma_f32_16x16x32_bf16 v[4:7], v[176:179], v[240:243], v[4:7]
	v_mfma_f32_16x16x32_bf16 v[0:3], v[208:211], v[240:243], v[0:3]
	s_setprio 0
	s_barrier
	s_add_i32 s66, s66, 2
	s_cmp_gt_u32 s66, 41
	s_mov_b64 s[24:25], s[46:47]
	s_cbranch_scc0 .LBB0_1176
	s_mov_b64 s[88:89], s[78:79]
	s_and_b64 vcc, exec, s[26:27]
	s_cbranch_vccz .LBB0_1179
	s_barrier

.LBB0_1334:
	ds_read_b128 v[160:163], v167
	ds_read_b128 v[184:187], v168
	ds_read_b128 v[188:191], v169
	ds_read_b128 v[198:201], v170
	ds_read_b128 v[202:205], v171
	ds_read_b128 v[206:209], v172
	ds_read_b128 v[210:213], v173
	ds_read_b128 v[214:217], v174
	s_add_u32 s24, s14, 0xfffc0080
	s_addc_u32 s25, s15, -1
	s_cmp_eq_u32 s66, 12
	s_cselect_b32 s65, s4, s25
	s_cselect_b32 s64, s5, s24
	s_cselect_b32 s25, s11, s49
	s_cselect_b32 s24, s13, s47
	s_mov_b32 m0, s61
	ds_read_b128 v[218:221], v159
	ds_read_b128 v[222:225], v159 offset:1024
	ds_read_b128 v[226:229], v159 offset:2048
	ds_read_b128 v[230:233], v159 offset:3072
	ds_read_b128 v[234:237], v159 offset:4096
	ds_read_b128 v[238:241], v159 offset:5120
	ds_read_b128 v[242:245], v159 offset:6144
	ds_read_b128 v[246:249], v159 offset:7168
	global_load_lds_dwordx4 v134, s[14:15]
	s_mov_b32 m0, s67
	s_nop 0
	global_load_lds_dwordx4 v136, s[14:15]
	s_waitcnt vmcnt(8)
	s_waitcnt lgkmcnt(0)
	s_barrier
	s_setprio 1
	s_waitcnt lgkmcnt(0)
	v_mfma_f32_16x16x32_bf16 v[124:127], v[160:163], v[218:221], v[124:127]
	v_mfma_f32_16x16x32_bf16 v[120:123], v[188:191], v[218:221], v[120:123]
	v_mfma_f32_16x16x32_bf16 v[108:111], v[160:163], v[226:229], v[108:111]
	v_mfma_f32_16x16x32_bf16 v[104:107], v[188:191], v[226:229], v[104:107]
	v_mfma_f32_16x16x32_bf16 v[92:95], v[160:163], v[234:237], v[92:95]
	v_mfma_f32_16x16x32_bf16 v[88:91], v[188:191], v[234:237], v[88:91]
	v_mfma_f32_16x16x32_bf16 v[76:79], v[160:163], v[242:245], v[76:79]
	v_mfma_f32_16x16x32_bf16 v[72:75], v[188:191], v[242:245], v[72:75]
	v_mfma_f32_16x16x32_bf16 v[124:127], v[184:187], v[222:225], v[124:127]
	v_mfma_f32_16x16x32_bf16 v[120:123], v[198:201], v[222:225], v[120:123]
	v_mfma_f32_16x16x32_bf16 v[108:111], v[184:187], v[230:233], v[108:111]
	v_mfma_f32_16x16x32_bf16 v[104:107], v[198:201], v[230:233], v[104:107]
	v_mfma_f32_16x16x32_bf16 v[92:95], v[184:187], v[238:241], v[92:95]
	v_mfma_f32_16x16x32_bf16 v[88:91], v[198:201], v[238:241], v[88:91]
	v_mfma_f32_16x16x32_bf16 v[76:79], v[184:187], v[246:249], v[76:79]
	v_mfma_f32_16x16x32_bf16 v[72:75], v[198:201], v[246:249], v[72:75]
	s_setprio 0
	s_setprio 1
	v_mfma_f32_16x16x32_bf16 v[116:119], v[202:205], v[218:221], v[116:119]
	v_mfma_f32_16x16x32_bf16 v[112:115], v[210:213], v[218:221], v[112:115]
	v_mfma_f32_16x16x32_bf16 v[100:103], v[202:205], v[226:229], v[100:103]
	v_mfma_f32_16x16x32_bf16 v[96:99], v[210:213], v[226:229], v[96:99]
	v_mfma_f32_16x16x32_bf16 v[84:87], v[202:205], v[234:237], v[84:87]
	v_mfma_f32_16x16x32_bf16 v[80:83], v[210:213], v[234:237], v[80:83]
	v_mfma_f32_16x16x32_bf16 v[68:71], v[202:205], v[242:245], v[68:71]
	v_mfma_f32_16x16x32_bf16 v[64:67], v[210:213], v[242:245], v[64:67]
	v_mfma_f32_16x16x32_bf16 v[116:119], v[206:209], v[222:225], v[116:119]
	v_mfma_f32_16x16x32_bf16 v[112:115], v[214:217], v[222:225], v[112:115]
	v_mfma_f32_16x16x32_bf16 v[100:103], v[206:209], v[230:233], v[100:103]
	v_mfma_f32_16x16x32_bf16 v[96:99], v[214:217], v[230:233], v[96:99]
	v_mfma_f32_16x16x32_bf16 v[84:87], v[206:209], v[238:241], v[84:87]
	v_mfma_f32_16x16x32_bf16 v[80:83], v[214:217], v[238:241], v[80:83]
	v_mfma_f32_16x16x32_bf16 v[68:71], v[206:209], v[246:249], v[68:71]
	v_mfma_f32_16x16x32_bf16 v[64:67], v[214:217], v[246:249], v[64:67]
	s_setprio 0
	s_barrier
	s_mov_b32 m0, s6
	s_add_u32 s68, s24, 0x40000
	ds_read_b128 v[218:221], v159 offset:16384
	ds_read_b128 v[222:225], v159 offset:17408
	ds_read_b128 v[226:229], v159 offset:18432
	ds_read_b128 v[230:233], v159 offset:19456
	ds_read_b128 v[234:237], v159 offset:20480
	ds_read_b128 v[238:241], v159 offset:21504
	ds_read_b128 v[242:245], v159 offset:22528
	ds_read_b128 v[246:249], v159 offset:23552
	global_load_lds_dwordx4 v128, s[24:25]
	s_mov_b32 m0, s7
	s_addc_u32 s69, s25, 0
	global_load_lds_dwordx4 v130, s[24:25]
	s_mov_b32 m0, s28
	s_add_u32 s98, s24, s38
	global_load_lds_dwordx4 v128, s[68:69]
	s_mov_b32 m0, s29
	s_addc_u32 s99, s25, s39
	global_load_lds_dwordx4 v130, s[68:69]
	s_mov_b32 m0, s2
	s_add_u32 s100, s64, s38
	global_load_lds_dwordx4 v128, s[64:65]
	s_mov_b32 m0, s30
	s_addc_u32 s101, s65, s39
	global_load_lds_dwordx4 v130, s[64:65]
	s_waitcnt vmcnt(8)
	s_waitcnt lgkmcnt(0)
	s_barrier
	s_setprio 1
	s_waitcnt lgkmcnt(0)
	v_mfma_f32_16x16x32_bf16 v[60:63], v[160:163], v[218:221], v[60:63]
	v_mfma_f32_16x16x32_bf16 v[56:59], v[188:191], v[218:221], v[56:59]
	v_mfma_f32_16x16x32_bf16 v[44:47], v[160:163], v[226:229], v[44:47]
	v_mfma_f32_16x16x32_bf16 v[40:43], v[188:191], v[226:229], v[40:43]
	v_mfma_f32_16x16x32_bf16 v[28:31], v[160:163], v[234:237], v[28:31]
	v_mfma_f32_16x16x32_bf16 v[24:27], v[188:191], v[234:237], v[24:27]
	v_mfma_f32_16x16x32_bf16 v[12:15], v[160:163], v[242:245], v[12:15]
	v_mfma_f32_16x16x32_bf16 v[8:11], v[188:191], v[242:245], v[8:11]
	v_mfma_f32_16x16x32_bf16 v[60:63], v[184:187], v[222:225], v[60:63]
	v_mfma_f32_16x16x32_bf16 v[56:59], v[198:201], v[222:225], v[56:59]
	v_mfma_f32_16x16x32_bf16 v[44:47], v[184:187], v[230:233], v[44:47]
	v_mfma_f32_16x16x32_bf16 v[40:43], v[198:201], v[230:233], v[40:43]
	v_mfma_f32_16x16x32_bf16 v[28:31], v[184:187], v[238:241], v[28:31]
	v_mfma_f32_16x16x32_bf16 v[24:27], v[198:201], v[238:241], v[24:27]
	v_mfma_f32_16x16x32_bf16 v[12:15], v[184:187], v[246:249], v[12:15]
	v_mfma_f32_16x16x32_bf16 v[8:11], v[198:201], v[246:249], v[8:11]
	s_setprio 0
	s_setprio 1
	v_mfma_f32_16x16x32_bf16 v[52:55], v[202:205], v[218:221], v[52:55]
	v_mfma_f32_16x16x32_bf16 v[48:51], v[210:213], v[218:221], v[48:51]
	v_mfma_f32_16x16x32_bf16 v[36:39], v[202:205], v[226:229], v[36:39]
	v_mfma_f32_16x16x32_bf16 v[32:35], v[210:213], v[226:229], v[32:35]
	v_mfma_f32_16x16x32_bf16 v[20:23], v[202:205], v[234:237], v[20:23]
	v_mfma_f32_16x16x32_bf16 v[16:19], v[210:213], v[234:237], v[16:19]
	v_mfma_f32_16x16x32_bf16 v[4:7], v[202:205], v[242:245], v[4:7]
	v_mfma_f32_16x16x32_bf16 v[0:3], v[210:213], v[242:245], v[0:3]
	v_mfma_f32_16x16x32_bf16 v[52:55], v[206:209], v[222:225], v[52:55]
	v_mfma_f32_16x16x32_bf16 v[48:51], v[214:217], v[222:225], v[48:51]
	v_mfma_f32_16x16x32_bf16 v[36:39], v[206:209], v[230:233], v[36:39]
	v_mfma_f32_16x16x32_bf16 v[32:35], v[214:217], v[230:233], v[32:35]
	v_mfma_f32_16x16x32_bf16 v[20:23], v[206:209], v[238:241], v[20:23]
	v_mfma_f32_16x16x32_bf16 v[16:19], v[214:217], v[238:241], v[16:19]
	v_mfma_f32_16x16x32_bf16 v[4:7], v[206:209], v[246:249], v[4:7]
	v_mfma_f32_16x16x32_bf16 v[0:3], v[214:217], v[246:249], v[0:3]
	s_setprio 0
	s_barrier
	ds_read_b128 v[160:163], v175
	ds_read_b128 v[184:187], v176
	ds_read_b128 v[188:191], v177
	ds_read_b128 v[198:201], v178
	ds_read_b128 v[202:205], v179
	ds_read_b128 v[206:209], v180
	ds_read_b128 v[210:213], v181
	ds_read_b128 v[214:217], v182
	s_add_u32 s64, s64, 0x40000
	s_addc_u32 s65, s65, 0
	s_mov_b32 m0, s31
	ds_read_b128 v[218:221], v159 offset:32768
	ds_read_b128 v[222:225], v159 offset:33792
	ds_read_b128 v[226:229], v159 offset:34816
	ds_read_b128 v[230:233], v159 offset:35840
	ds_read_b128 v[234:237], v159 offset:36864
	ds_read_b128 v[238:241], v159 offset:37888
	ds_read_b128 v[242:245], v159 offset:38912
	ds_read_b128 v[246:249], v159 offset:39936
	global_load_lds_dwordx4 v128, s[64:65]
	s_mov_b32 m0, s33
	s_nop 0
	global_load_lds_dwordx4 v130, s[64:65]
	s_waitcnt vmcnt(8)
	s_waitcnt lgkmcnt(0)
	s_barrier
	s_setprio 1
	s_waitcnt lgkmcnt(0)
	v_mfma_f32_16x16x32_bf16 v[124:127], v[160:163], v[218:221], v[124:127]
	v_mfma_f32_16x16x32_bf16 v[120:123], v[188:191], v[218:221], v[120:123]
	v_mfma_f32_16x16x32_bf16 v[108:111], v[160:163], v[226:229], v[108:111]
	v_mfma_f32_16x16x32_bf16 v[104:107], v[188:191], v[226:229], v[104:107]
	v_mfma_f32_16x16x32_bf16 v[92:95], v[160:163], v[234:237], v[92:95]
	v_mfma_f32_16x16x32_bf16 v[88:91], v[188:191], v[234:237], v[88:91]
	v_mfma_f32_16x16x32_bf16 v[76:79], v[160:163], v[242:245], v[76:79]
	v_mfma_f32_16x16x32_bf16 v[72:75], v[188:191], v[242:245], v[72:75]
	v_mfma_f32_16x16x32_bf16 v[124:127], v[184:187], v[222:225], v[124:127]
	v_mfma_f32_16x16x32_bf16 v[120:123], v[198:201], v[222:225], v[120:123]
	v_mfma_f32_16x16x32_bf16 v[108:111], v[184:187], v[230:233], v[108:111]
	v_mfma_f32_16x16x32_bf16 v[104:107], v[198:201], v[230:233], v[104:107]
	v_mfma_f32_16x16x32_bf16 v[92:95], v[184:187], v[238:241], v[92:95]
	v_mfma_f32_16x16x32_bf16 v[88:91], v[198:201], v[238:241], v[88:91]
	v_mfma_f32_16x16x32_bf16 v[76:79], v[184:187], v[246:249], v[76:79]
	v_mfma_f32_16x16x32_bf16 v[72:75], v[198:201], v[246:249], v[72:75]
	s_setprio 0
	s_setprio 1
	v_mfma_f32_16x16x32_bf16 v[116:119], v[202:205], v[218:221], v[116:119]
	v_mfma_f32_16x16x32_bf16 v[112:115], v[210:213], v[218:221], v[112:115]
	v_mfma_f32_16x16x32_bf16 v[100:103], v[202:205], v[226:229], v[100:103]
	v_mfma_f32_16x16x32_bf16 v[96:99], v[210:213], v[226:229], v[96:99]
	v_mfma_f32_16x16x32_bf16 v[84:87], v[202:205], v[234:237], v[84:87]
	v_mfma_f32_16x16x32_bf16 v[80:83], v[210:213], v[234:237], v[80:83]
	v_mfma_f32_16x16x32_bf16 v[68:71], v[202:205], v[242:245], v[68:71]
	v_mfma_f32_16x16x32_bf16 v[64:67], v[210:213], v[242:245], v[64:67]
	v_mfma_f32_16x16x32_bf16 v[116:119], v[206:209], v[222:225], v[116:119]
	v_mfma_f32_16x16x32_bf16 v[112:115], v[214:217], v[222:225], v[112:115]
	v_mfma_f32_16x16x32_bf16 v[100:103], v[206:209], v[230:233], v[100:103]
	v_mfma_f32_16x16x32_bf16 v[96:99], v[214:217], v[230:233], v[96:99]
	v_mfma_f32_16x16x32_bf16 v[84:87], v[206:209], v[238:241], v[84:87]
	v_mfma_f32_16x16x32_bf16 v[80:83], v[214:217], v[238:241], v[80:83]
	v_mfma_f32_16x16x32_bf16 v[68:71], v[206:209], v[246:249], v[68:71]
	v_mfma_f32_16x16x32_bf16 v[64:67], v[214:217], v[246:249], v[64:67]
	s_setprio 0
	s_barrier
	s_mov_b32 m0, s34
	s_add_u32 s24, s24, 0x40080
	ds_read_b128 v[218:221], v159 offset:49152
	ds_read_b128 v[222:225], v159 offset:50176
	ds_read_b128 v[226:229], v159 offset:51200
	ds_read_b128 v[230:233], v159 offset:52224
	ds_read_b128 v[234:237], v159 offset:53248
	ds_read_b128 v[238:241], v159 offset:54272
	ds_read_b128 v[242:245], v159 offset:55296
	ds_read_b128 v[246:249], v159 offset:56320
	global_load_lds_dwordx4 v128, s[98:99]
	s_mov_b32 m0, s35
	s_addc_u32 s25, s25, 0
	global_load_lds_dwordx4 v130, s[98:99]
	s_mov_b32 m0, s40
	s_add_u32 s14, s14, 0x100
	global_load_lds_dwordx4 v128, s[24:25]
	s_mov_b32 m0, s41
	s_addc_u32 s15, s15, 0
	global_load_lds_dwordx4 v130, s[24:25]
	s_mov_b32 m0, s36
	s_add_u32 s47, s47, 0x100
	global_load_lds_dwordx4 v128, s[100:101]
	s_mov_b32 m0, s37
	s_addc_u32 s49, s49, 0
	global_load_lds_dwordx4 v130, s[100:101]
	s_waitcnt vmcnt(8)
	s_waitcnt lgkmcnt(0)
	s_barrier
	s_setprio 1
	s_waitcnt lgkmcnt(0)
	v_mfma_f32_16x16x32_bf16 v[60:63], v[160:163], v[218:221], v[60:63]
	v_mfma_f32_16x16x32_bf16 v[56:59], v[188:191], v[218:221], v[56:59]
	v_mfma_f32_16x16x32_bf16 v[44:47], v[160:163], v[226:229], v[44:47]
	v_mfma_f32_16x16x32_bf16 v[40:43], v[188:191], v[226:229], v[40:43]
	v_mfma_f32_16x16x32_bf16 v[28:31], v[160:163], v[234:237], v[28:31]
	v_mfma_f32_16x16x32_bf16 v[24:27], v[188:191], v[234:237], v[24:27]
	v_mfma_f32_16x16x32_bf16 v[12:15], v[160:163], v[242:245], v[12:15]
	v_mfma_f32_16x16x32_bf16 v[8:11], v[188:191], v[242:245], v[8:11]
	v_mfma_f32_16x16x32_bf16 v[60:63], v[184:187], v[222:225], v[60:63]
	v_mfma_f32_16x16x32_bf16 v[56:59], v[198:201], v[222:225], v[56:59]
	v_mfma_f32_16x16x32_bf16 v[44:47], v[184:187], v[230:233], v[44:47]
	v_mfma_f32_16x16x32_bf16 v[40:43], v[198:201], v[230:233], v[40:43]
	v_mfma_f32_16x16x32_bf16 v[28:31], v[184:187], v[238:241], v[28:31]
	v_mfma_f32_16x16x32_bf16 v[24:27], v[198:201], v[238:241], v[24:27]
	v_mfma_f32_16x16x32_bf16 v[12:15], v[184:187], v[246:249], v[12:15]
	v_mfma_f32_16x16x32_bf16 v[8:11], v[198:201], v[246:249], v[8:11]
	s_setprio 0
	s_setprio 1
	v_mfma_f32_16x16x32_bf16 v[52:55], v[202:205], v[218:221], v[52:55]
	v_mfma_f32_16x16x32_bf16 v[48:51], v[210:213], v[218:221], v[48:51]
	v_mfma_f32_16x16x32_bf16 v[36:39], v[202:205], v[226:229], v[36:39]
	v_mfma_f32_16x16x32_bf16 v[32:35], v[210:213], v[226:229], v[32:35]
	v_mfma_f32_16x16x32_bf16 v[20:23], v[202:205], v[234:237], v[20:23]
	v_mfma_f32_16x16x32_bf16 v[16:19], v[210:213], v[234:237], v[16:19]
	v_mfma_f32_16x16x32_bf16 v[4:7], v[202:205], v[242:245], v[4:7]
	v_mfma_f32_16x16x32_bf16 v[0:3], v[210:213], v[242:245], v[0:3]
	v_mfma_f32_16x16x32_bf16 v[52:55], v[206:209], v[222:225], v[52:55]
	v_mfma_f32_16x16x32_bf16 v[48:51], v[214:217], v[222:225], v[48:51]
	v_mfma_f32_16x16x32_bf16 v[36:39], v[206:209], v[230:233], v[36:39]
	v_mfma_f32_16x16x32_bf16 v[32:35], v[214:217], v[230:233], v[32:35]
	v_mfma_f32_16x16x32_bf16 v[20:23], v[206:209], v[238:241], v[20:23]
	v_mfma_f32_16x16x32_bf16 v[16:19], v[214:217], v[238:241], v[16:19]
	v_mfma_f32_16x16x32_bf16 v[4:7], v[206:209], v[246:249], v[4:7]
	v_mfma_f32_16x16x32_bf16 v[0:3], v[214:217], v[246:249], v[0:3]
	s_setprio 0
	s_barrier
	s_add_i32 s66, s66, 2
	s_cmp_gt_u32 s66, 13
	s_cbranch_scc0 .LBB0_1334
	s_and_b64 vcc, exec, s[42:43]
	s_cbranch_vccz .LBB0_1337
	s_barrier

.LBB0_1497:
	ds_read_b128 v[176:179], v159
	ds_read_b128 v[180:183], v160
	ds_read_b128 v[184:187], v161
	ds_read_b128 v[188:191], v162
	ds_read_b128 v[198:201], v163
	ds_read_b128 v[202:205], v164
	ds_read_b128 v[206:209], v165
	ds_read_b128 v[210:213], v166
	s_add_u32 s50, s24, 0x100
	s_addc_u32 s51, s25, 0
	s_cmp_eq_u32 s68, 12
	s_cselect_b32 s65, s4, s51
	s_cselect_b32 s64, s5, s50
	s_cselect_b32 s55, s39, s87
	s_cselect_b32 s54, s43, s86
	s_mov_b32 m0, s76
	ds_read_b128 v[214:217], v143
	ds_read_b128 v[218:221], v143 offset:1024
	ds_read_b128 v[222:225], v143 offset:2048
	ds_read_b128 v[226:229], v143 offset:3072
	ds_read_b128 v[230:233], v143 offset:4096
	ds_read_b128 v[234:237], v143 offset:5120
	ds_read_b128 v[238:241], v143 offset:6144
	ds_read_b128 v[242:245], v143 offset:7168
	global_load_lds_dwordx4 v132, s[24:25]
	s_mov_b32 m0, s77
	s_nop 0
	global_load_lds_dwordx4 v134, s[24:25]
	s_waitcnt vmcnt(8)
	s_waitcnt lgkmcnt(0)
	s_barrier
	s_setprio 1
	s_waitcnt lgkmcnt(0)
	v_mfma_f32_16x16x32_bf16 v[124:127], v[176:179], v[214:217], v[124:127]
	v_mfma_f32_16x16x32_bf16 v[120:123], v[184:187], v[214:217], v[120:123]
	v_mfma_f32_16x16x32_bf16 v[108:111], v[176:179], v[222:225], v[108:111]
	v_mfma_f32_16x16x32_bf16 v[104:107], v[184:187], v[222:225], v[104:107]
	v_mfma_f32_16x16x32_bf16 v[92:95], v[176:179], v[230:233], v[92:95]
	v_mfma_f32_16x16x32_bf16 v[88:91], v[184:187], v[230:233], v[88:91]
	v_mfma_f32_16x16x32_bf16 v[76:79], v[176:179], v[238:241], v[76:79]
	v_mfma_f32_16x16x32_bf16 v[72:75], v[184:187], v[238:241], v[72:75]
	v_mfma_f32_16x16x32_bf16 v[124:127], v[180:183], v[218:221], v[124:127]
	v_mfma_f32_16x16x32_bf16 v[120:123], v[188:191], v[218:221], v[120:123]
	v_mfma_f32_16x16x32_bf16 v[108:111], v[180:183], v[226:229], v[108:111]
	v_mfma_f32_16x16x32_bf16 v[104:107], v[188:191], v[226:229], v[104:107]
	v_mfma_f32_16x16x32_bf16 v[92:95], v[180:183], v[234:237], v[92:95]
	v_mfma_f32_16x16x32_bf16 v[88:91], v[188:191], v[234:237], v[88:91]
	v_mfma_f32_16x16x32_bf16 v[76:79], v[180:183], v[242:245], v[76:79]
	v_mfma_f32_16x16x32_bf16 v[72:75], v[188:191], v[242:245], v[72:75]
	s_setprio 0
	s_setprio 1
	v_mfma_f32_16x16x32_bf16 v[116:119], v[198:201], v[214:217], v[116:119]
	v_mfma_f32_16x16x32_bf16 v[112:115], v[206:209], v[214:217], v[112:115]
	v_mfma_f32_16x16x32_bf16 v[100:103], v[198:201], v[222:225], v[100:103]
	v_mfma_f32_16x16x32_bf16 v[96:99], v[206:209], v[222:225], v[96:99]
	v_mfma_f32_16x16x32_bf16 v[84:87], v[198:201], v[230:233], v[84:87]
	v_mfma_f32_16x16x32_bf16 v[80:83], v[206:209], v[230:233], v[80:83]
	v_mfma_f32_16x16x32_bf16 v[68:71], v[198:201], v[238:241], v[68:71]
	v_mfma_f32_16x16x32_bf16 v[64:67], v[206:209], v[238:241], v[64:67]
	v_mfma_f32_16x16x32_bf16 v[116:119], v[202:205], v[218:221], v[116:119]
	v_mfma_f32_16x16x32_bf16 v[112:115], v[210:213], v[218:221], v[112:115]
	v_mfma_f32_16x16x32_bf16 v[100:103], v[202:205], v[226:229], v[100:103]
	v_mfma_f32_16x16x32_bf16 v[96:99], v[210:213], v[226:229], v[96:99]
	v_mfma_f32_16x16x32_bf16 v[84:87], v[202:205], v[234:237], v[84:87]
	v_mfma_f32_16x16x32_bf16 v[80:83], v[210:213], v[234:237], v[80:83]
	v_mfma_f32_16x16x32_bf16 v[68:71], v[202:205], v[242:245], v[68:71]
	v_mfma_f32_16x16x32_bf16 v[64:67], v[210:213], v[242:245], v[64:67]
	s_setprio 0
	s_barrier
	s_mov_b32 m0, s29
	s_add_u32 s24, s54, 0x40000
	ds_read_b128 v[214:217], v143 offset:16384
	ds_read_b128 v[218:221], v143 offset:17408
	ds_read_b128 v[222:225], v143 offset:18432
	ds_read_b128 v[226:229], v143 offset:19456
	ds_read_b128 v[230:233], v143 offset:20480
	ds_read_b128 v[234:237], v143 offset:21504
	ds_read_b128 v[238:241], v143 offset:22528
	ds_read_b128 v[242:245], v143 offset:23552
	global_load_lds_dwordx4 v128, s[54:55]
	s_mov_b32 m0, s30
	s_addc_u32 s25, s55, 0
	global_load_lds_dwordx4 v130, s[54:55]
	s_mov_b32 m0, s31
	s_add_u32 s98, s54, s10
	global_load_lds_dwordx4 v128, s[24:25]
	s_mov_b32 m0, s33
	s_addc_u32 s99, s55, s11
	global_load_lds_dwordx4 v130, s[24:25]
	s_mov_b32 m0, s28
	s_add_u32 s100, s64, s10
	global_load_lds_dwordx4 v128, s[64:65]
	s_mov_b32 m0, s34
	s_addc_u32 s101, s65, s11
	global_load_lds_dwordx4 v130, s[64:65]
	s_waitcnt vmcnt(8)
	s_waitcnt lgkmcnt(0)
	s_barrier
	s_setprio 1
	s_waitcnt lgkmcnt(0)
	v_mfma_f32_16x16x32_bf16 v[60:63], v[176:179], v[214:217], v[60:63]
	v_mfma_f32_16x16x32_bf16 v[56:59], v[184:187], v[214:217], v[56:59]
	v_mfma_f32_16x16x32_bf16 v[44:47], v[176:179], v[222:225], v[44:47]
	v_mfma_f32_16x16x32_bf16 v[40:43], v[184:187], v[222:225], v[40:43]
	v_mfma_f32_16x16x32_bf16 v[28:31], v[176:179], v[230:233], v[28:31]
	v_mfma_f32_16x16x32_bf16 v[24:27], v[184:187], v[230:233], v[24:27]
	v_mfma_f32_16x16x32_bf16 v[12:15], v[176:179], v[238:241], v[12:15]
	v_mfma_f32_16x16x32_bf16 v[8:11], v[184:187], v[238:241], v[8:11]
	v_mfma_f32_16x16x32_bf16 v[60:63], v[180:183], v[218:221], v[60:63]
	v_mfma_f32_16x16x32_bf16 v[56:59], v[188:191], v[218:221], v[56:59]
	v_mfma_f32_16x16x32_bf16 v[44:47], v[180:183], v[226:229], v[44:47]
	v_mfma_f32_16x16x32_bf16 v[40:43], v[188:191], v[226:229], v[40:43]
	v_mfma_f32_16x16x32_bf16 v[28:31], v[180:183], v[234:237], v[28:31]
	v_mfma_f32_16x16x32_bf16 v[24:27], v[188:191], v[234:237], v[24:27]
	v_mfma_f32_16x16x32_bf16 v[12:15], v[180:183], v[242:245], v[12:15]
	v_mfma_f32_16x16x32_bf16 v[8:11], v[188:191], v[242:245], v[8:11]
	s_setprio 0
	s_setprio 1
	v_mfma_f32_16x16x32_bf16 v[52:55], v[198:201], v[214:217], v[52:55]
	v_mfma_f32_16x16x32_bf16 v[48:51], v[206:209], v[214:217], v[48:51]
	v_mfma_f32_16x16x32_bf16 v[36:39], v[198:201], v[222:225], v[36:39]
	v_mfma_f32_16x16x32_bf16 v[32:35], v[206:209], v[222:225], v[32:35]
	v_mfma_f32_16x16x32_bf16 v[20:23], v[198:201], v[230:233], v[20:23]
	v_mfma_f32_16x16x32_bf16 v[16:19], v[206:209], v[230:233], v[16:19]
	v_mfma_f32_16x16x32_bf16 v[4:7], v[198:201], v[238:241], v[4:7]
	v_mfma_f32_16x16x32_bf16 v[0:3], v[206:209], v[238:241], v[0:3]
	v_mfma_f32_16x16x32_bf16 v[52:55], v[202:205], v[218:221], v[52:55]
	v_mfma_f32_16x16x32_bf16 v[48:51], v[210:213], v[218:221], v[48:51]
	v_mfma_f32_16x16x32_bf16 v[36:39], v[202:205], v[226:229], v[36:39]
	v_mfma_f32_16x16x32_bf16 v[32:35], v[210:213], v[226:229], v[32:35]
	v_mfma_f32_16x16x32_bf16 v[20:23], v[202:205], v[234:237], v[20:23]
	v_mfma_f32_16x16x32_bf16 v[16:19], v[210:213], v[234:237], v[16:19]
	v_mfma_f32_16x16x32_bf16 v[4:7], v[202:205], v[242:245], v[4:7]
	v_mfma_f32_16x16x32_bf16 v[0:3], v[210:213], v[242:245], v[0:3]
	s_setprio 0
	s_barrier
	ds_read_b128 v[176:179], v167
	ds_read_b128 v[180:183], v168
	ds_read_b128 v[184:187], v169
	ds_read_b128 v[188:191], v170
	ds_read_b128 v[198:201], v171
	ds_read_b128 v[202:205], v172
	ds_read_b128 v[206:209], v173
	ds_read_b128 v[210:213], v174
	s_add_u32 s24, s64, 0x40000
	s_addc_u32 s25, s65, 0
	s_mov_b32 m0, s35
	ds_read_b128 v[214:217], v143 offset:32768
	ds_read_b128 v[218:221], v143 offset:33792
	ds_read_b128 v[222:225], v143 offset:34816
	ds_read_b128 v[226:229], v143 offset:35840
	ds_read_b128 v[230:233], v143 offset:36864
	ds_read_b128 v[234:237], v143 offset:37888
	ds_read_b128 v[238:241], v143 offset:38912
	ds_read_b128 v[242:245], v143 offset:39936
	global_load_lds_dwordx4 v128, s[24:25]
	s_mov_b32 m0, s36
	s_nop 0
	global_load_lds_dwordx4 v130, s[24:25]
	s_waitcnt vmcnt(8)
	s_waitcnt lgkmcnt(0)
	s_barrier
	s_setprio 1
	s_waitcnt lgkmcnt(0)
	v_mfma_f32_16x16x32_bf16 v[124:127], v[176:179], v[214:217], v[124:127]
	v_mfma_f32_16x16x32_bf16 v[120:123], v[184:187], v[214:217], v[120:123]
	v_mfma_f32_16x16x32_bf16 v[108:111], v[176:179], v[222:225], v[108:111]
	v_mfma_f32_16x16x32_bf16 v[104:107], v[184:187], v[222:225], v[104:107]
	v_mfma_f32_16x16x32_bf16 v[92:95], v[176:179], v[230:233], v[92:95]
	v_mfma_f32_16x16x32_bf16 v[88:91], v[184:187], v[230:233], v[88:91]
	v_mfma_f32_16x16x32_bf16 v[76:79], v[176:179], v[238:241], v[76:79]
	v_mfma_f32_16x16x32_bf16 v[72:75], v[184:187], v[238:241], v[72:75]
	v_mfma_f32_16x16x32_bf16 v[124:127], v[180:183], v[218:221], v[124:127]
	v_mfma_f32_16x16x32_bf16 v[120:123], v[188:191], v[218:221], v[120:123]
	v_mfma_f32_16x16x32_bf16 v[108:111], v[180:183], v[226:229], v[108:111]
	v_mfma_f32_16x16x32_bf16 v[104:107], v[188:191], v[226:229], v[104:107]
	v_mfma_f32_16x16x32_bf16 v[92:95], v[180:183], v[234:237], v[92:95]
	v_mfma_f32_16x16x32_bf16 v[88:91], v[188:191], v[234:237], v[88:91]
	v_mfma_f32_16x16x32_bf16 v[76:79], v[180:183], v[242:245], v[76:79]
	v_mfma_f32_16x16x32_bf16 v[72:75], v[188:191], v[242:245], v[72:75]
	s_setprio 0
	s_setprio 1
	v_mfma_f32_16x16x32_bf16 v[116:119], v[198:201], v[214:217], v[116:119]
	v_mfma_f32_16x16x32_bf16 v[112:115], v[206:209], v[214:217], v[112:115]
	v_mfma_f32_16x16x32_bf16 v[100:103], v[198:201], v[222:225], v[100:103]
	v_mfma_f32_16x16x32_bf16 v[96:99], v[206:209], v[222:225], v[96:99]
	v_mfma_f32_16x16x32_bf16 v[84:87], v[198:201], v[230:233], v[84:87]
	v_mfma_f32_16x16x32_bf16 v[80:83], v[206:209], v[230:233], v[80:83]
	v_mfma_f32_16x16x32_bf16 v[68:71], v[198:201], v[238:241], v[68:71]
	v_mfma_f32_16x16x32_bf16 v[64:67], v[206:209], v[238:241], v[64:67]
	v_mfma_f32_16x16x32_bf16 v[116:119], v[202:205], v[218:221], v[116:119]
	v_mfma_f32_16x16x32_bf16 v[112:115], v[210:213], v[218:221], v[112:115]
	v_mfma_f32_16x16x32_bf16 v[100:103], v[202:205], v[226:229], v[100:103]
	v_mfma_f32_16x16x32_bf16 v[96:99], v[210:213], v[226:229], v[96:99]
	v_mfma_f32_16x16x32_bf16 v[84:87], v[202:205], v[234:237], v[84:87]
	v_mfma_f32_16x16x32_bf16 v[80:83], v[210:213], v[234:237], v[80:83]
	v_mfma_f32_16x16x32_bf16 v[68:71], v[202:205], v[242:245], v[68:71]
	v_mfma_f32_16x16x32_bf16 v[64:67], v[210:213], v[242:245], v[64:67]
	s_setprio 0
	s_barrier
	s_mov_b32 m0, s40
	s_add_u32 s24, s54, 0x40080
	ds_read_b128 v[214:217], v143 offset:49152
	ds_read_b128 v[218:221], v143 offset:50176
	ds_read_b128 v[222:225], v143 offset:51200
	ds_read_b128 v[226:229], v143 offset:52224
	ds_read_b128 v[230:233], v143 offset:53248
	ds_read_b128 v[234:237], v143 offset:54272
	ds_read_b128 v[238:241], v143 offset:55296
	ds_read_b128 v[242:245], v143 offset:56320
	global_load_lds_dwordx4 v128, s[98:99]
	s_mov_b32 m0, s41
	s_addc_u32 s25, s55, 0
	global_load_lds_dwordx4 v130, s[98:99]
	s_mov_b32 m0, s53
	s_add_u32 s86, s86, 0x100
	global_load_lds_dwordx4 v128, s[24:25]
	s_mov_b32 m0, s60
	s_addc_u32 s87, s87, 0
	global_load_lds_dwordx4 v130, s[24:25]
	s_mov_b32 m0, s49
	s_nop 0
	global_load_lds_dwordx4 v128, s[100:101]
	s_mov_b32 m0, s52
	s_nop 0
	global_load_lds_dwordx4 v130, s[100:101]
	s_waitcnt vmcnt(8)
	s_waitcnt lgkmcnt(0)
	s_barrier
	s_setprio 1
	s_waitcnt lgkmcnt(0)
	v_mfma_f32_16x16x32_bf16 v[60:63], v[176:179], v[214:217], v[60:63]
	v_mfma_f32_16x16x32_bf16 v[56:59], v[184:187], v[214:217], v[56:59]
	v_mfma_f32_16x16x32_bf16 v[44:47], v[176:179], v[222:225], v[44:47]
	v_mfma_f32_16x16x32_bf16 v[40:43], v[184:187], v[222:225], v[40:43]
	v_mfma_f32_16x16x32_bf16 v[28:31], v[176:179], v[230:233], v[28:31]
	v_mfma_f32_16x16x32_bf16 v[24:27], v[184:187], v[230:233], v[24:27]
	v_mfma_f32_16x16x32_bf16 v[12:15], v[176:179], v[238:241], v[12:15]
	v_mfma_f32_16x16x32_bf16 v[8:11], v[184:187], v[238:241], v[8:11]
	v_mfma_f32_16x16x32_bf16 v[60:63], v[180:183], v[218:221], v[60:63]
	v_mfma_f32_16x16x32_bf16 v[56:59], v[188:191], v[218:221], v[56:59]
	v_mfma_f32_16x16x32_bf16 v[44:47], v[180:183], v[226:229], v[44:47]
	v_mfma_f32_16x16x32_bf16 v[40:43], v[188:191], v[226:229], v[40:43]
	v_mfma_f32_16x16x32_bf16 v[28:31], v[180:183], v[234:237], v[28:31]
	v_mfma_f32_16x16x32_bf16 v[24:27], v[188:191], v[234:237], v[24:27]
	v_mfma_f32_16x16x32_bf16 v[12:15], v[180:183], v[242:245], v[12:15]
	v_mfma_f32_16x16x32_bf16 v[8:11], v[188:191], v[242:245], v[8:11]
	s_setprio 0
	s_setprio 1
	v_mfma_f32_16x16x32_bf16 v[52:55], v[198:201], v[214:217], v[52:55]
	v_mfma_f32_16x16x32_bf16 v[48:51], v[206:209], v[214:217], v[48:51]
	v_mfma_f32_16x16x32_bf16 v[36:39], v[198:201], v[222:225], v[36:39]
	v_mfma_f32_16x16x32_bf16 v[32:35], v[206:209], v[222:225], v[32:35]
	v_mfma_f32_16x16x32_bf16 v[20:23], v[198:201], v[230:233], v[20:23]
	v_mfma_f32_16x16x32_bf16 v[16:19], v[206:209], v[230:233], v[16:19]
	v_mfma_f32_16x16x32_bf16 v[4:7], v[198:201], v[238:241], v[4:7]
	v_mfma_f32_16x16x32_bf16 v[0:3], v[206:209], v[238:241], v[0:3]
	v_mfma_f32_16x16x32_bf16 v[52:55], v[202:205], v[218:221], v[52:55]
	v_mfma_f32_16x16x32_bf16 v[48:51], v[210:213], v[218:221], v[48:51]
	v_mfma_f32_16x16x32_bf16 v[36:39], v[202:205], v[226:229], v[36:39]
	v_mfma_f32_16x16x32_bf16 v[32:35], v[210:213], v[226:229], v[32:35]
	v_mfma_f32_16x16x32_bf16 v[20:23], v[202:205], v[234:237], v[20:23]
	v_mfma_f32_16x16x32_bf16 v[16:19], v[210:213], v[234:237], v[16:19]
	v_mfma_f32_16x16x32_bf16 v[4:7], v[202:205], v[242:245], v[4:7]
	v_mfma_f32_16x16x32_bf16 v[0:3], v[210:213], v[242:245], v[0:3]
	s_setprio 0
	s_barrier
	s_add_i32 s68, s68, 2
	s_cmp_gt_u32 s68, 13
	s_mov_b64 s[24:25], s[50:51]
	s_cbranch_scc0 .LBB0_1497
	s_and_b64 vcc, exec, s[14:15]
	s_cbranch_vccz .LBB0_1500
	s_barrier

.LBB0_1766:
	ds_read_b128 v[128:131], v199
	ds_read_b128 v[132:135], v200
	ds_read_b128 v[136:139], v201
	ds_read_b128 v[140:143], v202
	ds_read_b128 v[172:175], v203
	ds_read_b128 v[176:179], v204
	ds_read_b128 v[180:183], v205
	ds_read_b128 v[184:187], v206
	s_add_u32 s74, s24, 0x100
	s_addc_u32 s75, s25, 0
	s_cmp_eq_u32 s68, 12
	s_cselect_b32 s85, s4, s75
	s_cselect_b32 s84, s5, s74
	s_cselect_b32 s81, s47, s87
	s_cselect_b32 s80, s49, s86
	s_mov_b32 m0, s65
	ds_read_b128 v[188:191], v159
	ds_read_b128 v[216:219], v159 offset:1024
	ds_read_b128 v[220:223], v159 offset:2048
	ds_read_b128 v[224:227], v159 offset:3072
	ds_read_b128 v[228:231], v159 offset:4096
	ds_read_b128 v[232:235], v159 offset:5120
	ds_read_b128 v[236:239], v159 offset:6144
	ds_read_b128 v[240:243], v159 offset:7168
	global_load_lds_dwordx4 v164, s[24:25]
	s_mov_b32 m0, s67
	s_nop 0
	global_load_lds_dwordx4 v166, s[24:25]
	s_waitcnt vmcnt(8)
	s_waitcnt lgkmcnt(0)
	s_barrier
	s_setprio 1
	s_waitcnt lgkmcnt(0)
	v_mfma_f32_16x16x32_bf16 v[124:127], v[128:131], v[188:191], v[124:127]
	v_mfma_f32_16x16x32_bf16 v[120:123], v[136:139], v[188:191], v[120:123]
	v_mfma_f32_16x16x32_bf16 v[108:111], v[128:131], v[220:223], v[108:111]
	v_mfma_f32_16x16x32_bf16 v[104:107], v[136:139], v[220:223], v[104:107]
	v_mfma_f32_16x16x32_bf16 v[92:95], v[128:131], v[228:231], v[92:95]
	v_mfma_f32_16x16x32_bf16 v[88:91], v[136:139], v[228:231], v[88:91]
	v_mfma_f32_16x16x32_bf16 v[76:79], v[128:131], v[236:239], v[76:79]
	v_mfma_f32_16x16x32_bf16 v[72:75], v[136:139], v[236:239], v[72:75]
	v_mfma_f32_16x16x32_bf16 v[124:127], v[132:135], v[216:219], v[124:127]
	v_mfma_f32_16x16x32_bf16 v[120:123], v[140:143], v[216:219], v[120:123]
	v_mfma_f32_16x16x32_bf16 v[108:111], v[132:135], v[224:227], v[108:111]
	v_mfma_f32_16x16x32_bf16 v[104:107], v[140:143], v[224:227], v[104:107]
	v_mfma_f32_16x16x32_bf16 v[92:95], v[132:135], v[232:235], v[92:95]
	v_mfma_f32_16x16x32_bf16 v[88:91], v[140:143], v[232:235], v[88:91]
	v_mfma_f32_16x16x32_bf16 v[76:79], v[132:135], v[240:243], v[76:79]
	v_mfma_f32_16x16x32_bf16 v[72:75], v[140:143], v[240:243], v[72:75]
	s_setprio 0
	s_setprio 1
	v_mfma_f32_16x16x32_bf16 v[116:119], v[172:175], v[188:191], v[116:119]
	v_mfma_f32_16x16x32_bf16 v[112:115], v[180:183], v[188:191], v[112:115]
	v_mfma_f32_16x16x32_bf16 v[100:103], v[172:175], v[220:223], v[100:103]
	v_mfma_f32_16x16x32_bf16 v[96:99], v[180:183], v[220:223], v[96:99]
	v_mfma_f32_16x16x32_bf16 v[84:87], v[172:175], v[228:231], v[84:87]
	v_mfma_f32_16x16x32_bf16 v[80:83], v[180:183], v[228:231], v[80:83]
	v_mfma_f32_16x16x32_bf16 v[68:71], v[172:175], v[236:239], v[68:71]
	v_mfma_f32_16x16x32_bf16 v[64:67], v[180:183], v[236:239], v[64:67]
	v_mfma_f32_16x16x32_bf16 v[116:119], v[176:179], v[216:219], v[116:119]
	v_mfma_f32_16x16x32_bf16 v[112:115], v[184:187], v[216:219], v[112:115]
	v_mfma_f32_16x16x32_bf16 v[100:103], v[176:179], v[224:227], v[100:103]
	v_mfma_f32_16x16x32_bf16 v[96:99], v[184:187], v[224:227], v[96:99]
	v_mfma_f32_16x16x32_bf16 v[84:87], v[176:179], v[232:235], v[84:87]
	v_mfma_f32_16x16x32_bf16 v[80:83], v[184:187], v[232:235], v[80:83]
	v_mfma_f32_16x16x32_bf16 v[68:71], v[176:179], v[240:243], v[68:71]
	v_mfma_f32_16x16x32_bf16 v[64:67], v[184:187], v[240:243], v[64:67]
	s_setprio 0
	s_barrier
	s_mov_b32 m0, s7
	s_add_u32 s24, s80, 0x40000
	ds_read_b128 v[188:191], v159 offset:16384
	ds_read_b128 v[216:219], v159 offset:17408
	ds_read_b128 v[220:223], v159 offset:18432
	ds_read_b128 v[224:227], v159 offset:19456
	ds_read_b128 v[228:231], v159 offset:20480
	ds_read_b128 v[232:235], v159 offset:21504
	ds_read_b128 v[236:239], v159 offset:22528
	ds_read_b128 v[240:243], v159 offset:23552
	global_load_lds_dwordx4 v160, s[80:81]
	s_mov_b32 m0, s28
	s_addc_u32 s25, s81, 0
	global_load_lds_dwordx4 v162, s[80:81]
	s_mov_b32 m0, s29
	s_add_u32 s98, s80, s38
	global_load_lds_dwordx4 v160, s[24:25]
	s_mov_b32 m0, s30
	s_addc_u32 s99, s81, s39
	global_load_lds_dwordx4 v162, s[24:25]
	s_mov_b32 m0, s6
	s_add_u32 s100, s84, s38
	global_load_lds_dwordx4 v160, s[84:85]
	s_mov_b32 m0, s31
	s_addc_u32 s101, s85, s39
	global_load_lds_dwordx4 v162, s[84:85]
	s_waitcnt vmcnt(8)
	s_waitcnt lgkmcnt(0)
	s_barrier
	s_setprio 1
	s_waitcnt lgkmcnt(0)
	v_mfma_f32_16x16x32_bf16 v[60:63], v[128:131], v[188:191], v[60:63]
	v_mfma_f32_16x16x32_bf16 v[56:59], v[136:139], v[188:191], v[56:59]
	v_mfma_f32_16x16x32_bf16 v[44:47], v[128:131], v[220:223], v[44:47]
	v_mfma_f32_16x16x32_bf16 v[40:43], v[136:139], v[220:223], v[40:43]
	v_mfma_f32_16x16x32_bf16 v[28:31], v[128:131], v[228:231], v[28:31]
	v_mfma_f32_16x16x32_bf16 v[24:27], v[136:139], v[228:231], v[24:27]
	v_mfma_f32_16x16x32_bf16 v[12:15], v[128:131], v[236:239], v[12:15]
	v_mfma_f32_16x16x32_bf16 v[8:11], v[136:139], v[236:239], v[8:11]
	v_mfma_f32_16x16x32_bf16 v[60:63], v[132:135], v[216:219], v[60:63]
	v_mfma_f32_16x16x32_bf16 v[56:59], v[140:143], v[216:219], v[56:59]
	v_mfma_f32_16x16x32_bf16 v[44:47], v[132:135], v[224:227], v[44:47]
	v_mfma_f32_16x16x32_bf16 v[40:43], v[140:143], v[224:227], v[40:43]
	v_mfma_f32_16x16x32_bf16 v[28:31], v[132:135], v[232:235], v[28:31]
	v_mfma_f32_16x16x32_bf16 v[24:27], v[140:143], v[232:235], v[24:27]
	v_mfma_f32_16x16x32_bf16 v[12:15], v[132:135], v[240:243], v[12:15]
	v_mfma_f32_16x16x32_bf16 v[8:11], v[140:143], v[240:243], v[8:11]
	s_setprio 0
	s_setprio 1
	v_mfma_f32_16x16x32_bf16 v[52:55], v[172:175], v[188:191], v[52:55]
	v_mfma_f32_16x16x32_bf16 v[48:51], v[180:183], v[188:191], v[48:51]
	v_mfma_f32_16x16x32_bf16 v[36:39], v[172:175], v[220:223], v[36:39]
	v_mfma_f32_16x16x32_bf16 v[32:35], v[180:183], v[220:223], v[32:35]
	v_mfma_f32_16x16x32_bf16 v[20:23], v[172:175], v[228:231], v[20:23]
	v_mfma_f32_16x16x32_bf16 v[16:19], v[180:183], v[228:231], v[16:19]
	v_mfma_f32_16x16x32_bf16 v[4:7], v[172:175], v[236:239], v[4:7]
	v_mfma_f32_16x16x32_bf16 v[0:3], v[180:183], v[236:239], v[0:3]
	v_mfma_f32_16x16x32_bf16 v[52:55], v[176:179], v[216:219], v[52:55]
	v_mfma_f32_16x16x32_bf16 v[48:51], v[184:187], v[216:219], v[48:51]
	v_mfma_f32_16x16x32_bf16 v[36:39], v[176:179], v[224:227], v[36:39]
	v_mfma_f32_16x16x32_bf16 v[32:35], v[184:187], v[224:227], v[32:35]
	v_mfma_f32_16x16x32_bf16 v[20:23], v[176:179], v[232:235], v[20:23]
	v_mfma_f32_16x16x32_bf16 v[16:19], v[184:187], v[232:235], v[16:19]
	v_mfma_f32_16x16x32_bf16 v[4:7], v[176:179], v[240:243], v[4:7]
	v_mfma_f32_16x16x32_bf16 v[0:3], v[184:187], v[240:243], v[0:3]
	s_setprio 0
	s_barrier
	ds_read_b128 v[128:131], v207
	ds_read_b128 v[132:135], v208
	ds_read_b128 v[136:139], v209
	ds_read_b128 v[140:143], v210
	ds_read_b128 v[172:175], v211
	ds_read_b128 v[176:179], v212
	ds_read_b128 v[180:183], v213
	ds_read_b128 v[184:187], v214
	s_add_u32 s24, s84, 0x40000
	s_addc_u32 s25, s85, 0
	s_mov_b32 m0, s33
	ds_read_b128 v[188:191], v159 offset:32768
	ds_read_b128 v[216:219], v159 offset:33792
	ds_read_b128 v[220:223], v159 offset:34816
	ds_read_b128 v[224:227], v159 offset:35840
	ds_read_b128 v[228:231], v159 offset:36864
	ds_read_b128 v[232:235], v159 offset:37888
	ds_read_b128 v[236:239], v159 offset:38912
	ds_read_b128 v[240:243], v159 offset:39936
	global_load_lds_dwordx4 v160, s[24:25]
	s_mov_b32 m0, s34
	s_nop 0
	global_load_lds_dwordx4 v162, s[24:25]
	s_waitcnt vmcnt(8)
	s_waitcnt lgkmcnt(0)
	s_barrier
	s_setprio 1
	s_waitcnt lgkmcnt(0)
	v_mfma_f32_16x16x32_bf16 v[124:127], v[128:131], v[188:191], v[124:127]
	v_mfma_f32_16x16x32_bf16 v[120:123], v[136:139], v[188:191], v[120:123]
	v_mfma_f32_16x16x32_bf16 v[108:111], v[128:131], v[220:223], v[108:111]
	v_mfma_f32_16x16x32_bf16 v[104:107], v[136:139], v[220:223], v[104:107]
	v_mfma_f32_16x16x32_bf16 v[92:95], v[128:131], v[228:231], v[92:95]
	v_mfma_f32_16x16x32_bf16 v[88:91], v[136:139], v[228:231], v[88:91]
	v_mfma_f32_16x16x32_bf16 v[76:79], v[128:131], v[236:239], v[76:79]
	v_mfma_f32_16x16x32_bf16 v[72:75], v[136:139], v[236:239], v[72:75]
	v_mfma_f32_16x16x32_bf16 v[124:127], v[132:135], v[216:219], v[124:127]
	v_mfma_f32_16x16x32_bf16 v[120:123], v[140:143], v[216:219], v[120:123]
	v_mfma_f32_16x16x32_bf16 v[108:111], v[132:135], v[224:227], v[108:111]
	v_mfma_f32_16x16x32_bf16 v[104:107], v[140:143], v[224:227], v[104:107]
	v_mfma_f32_16x16x32_bf16 v[92:95], v[132:135], v[232:235], v[92:95]
	v_mfma_f32_16x16x32_bf16 v[88:91], v[140:143], v[232:235], v[88:91]
	v_mfma_f32_16x16x32_bf16 v[76:79], v[132:135], v[240:243], v[76:79]
	v_mfma_f32_16x16x32_bf16 v[72:75], v[140:143], v[240:243], v[72:75]
	s_setprio 0
	s_setprio 1
	v_mfma_f32_16x16x32_bf16 v[116:119], v[172:175], v[188:191], v[116:119]
	v_mfma_f32_16x16x32_bf16 v[112:115], v[180:183], v[188:191], v[112:115]
	v_mfma_f32_16x16x32_bf16 v[100:103], v[172:175], v[220:223], v[100:103]
	v_mfma_f32_16x16x32_bf16 v[96:99], v[180:183], v[220:223], v[96:99]
	v_mfma_f32_16x16x32_bf16 v[84:87], v[172:175], v[228:231], v[84:87]
	v_mfma_f32_16x16x32_bf16 v[80:83], v[180:183], v[228:231], v[80:83]
	v_mfma_f32_16x16x32_bf16 v[68:71], v[172:175], v[236:239], v[68:71]
	v_mfma_f32_16x16x32_bf16 v[64:67], v[180:183], v[236:239], v[64:67]
	v_mfma_f32_16x16x32_bf16 v[116:119], v[176:179], v[216:219], v[116:119]
	v_mfma_f32_16x16x32_bf16 v[112:115], v[184:187], v[216:219], v[112:115]
	v_mfma_f32_16x16x32_bf16 v[100:103], v[176:179], v[224:227], v[100:103]
	v_mfma_f32_16x16x32_bf16 v[96:99], v[184:187], v[224:227], v[96:99]
	v_mfma_f32_16x16x32_bf16 v[84:87], v[176:179], v[232:235], v[84:87]
	v_mfma_f32_16x16x32_bf16 v[80:83], v[184:187], v[232:235], v[80:83]
	v_mfma_f32_16x16x32_bf16 v[68:71], v[176:179], v[240:243], v[68:71]
	v_mfma_f32_16x16x32_bf16 v[64:67], v[184:187], v[240:243], v[64:67]
	s_setprio 0
	s_barrier
	s_mov_b32 m0, s35
	s_add_u32 s24, s80, 0x40080
	ds_read_b128 v[188:191], v159 offset:49152
	ds_read_b128 v[216:219], v159 offset:50176
	ds_read_b128 v[220:223], v159 offset:51200
	ds_read_b128 v[224:227], v159 offset:52224
	ds_read_b128 v[228:231], v159 offset:53248
	ds_read_b128 v[232:235], v159 offset:54272
	ds_read_b128 v[236:239], v159 offset:55296
	ds_read_b128 v[240:243], v159 offset:56320
	global_load_lds_dwordx4 v160, s[98:99]
	s_mov_b32 m0, s36
	s_addc_u32 s25, s81, 0
	global_load_lds_dwordx4 v162, s[98:99]
	s_mov_b32 m0, s41
	s_add_u32 s86, s86, 0x100
	global_load_lds_dwordx4 v160, s[24:25]
	s_mov_b32 m0, s45
	s_addc_u32 s87, s87, 0
	global_load_lds_dwordx4 v162, s[24:25]
	s_mov_b32 m0, s37
	s_nop 0
	global_load_lds_dwordx4 v160, s[100:101]
	s_mov_b32 m0, s40
	s_nop 0
	global_load_lds_dwordx4 v162, s[100:101]
	s_waitcnt vmcnt(8)
	s_waitcnt lgkmcnt(0)
	s_barrier
	s_setprio 1
	s_waitcnt lgkmcnt(0)
	v_mfma_f32_16x16x32_bf16 v[60:63], v[128:131], v[188:191], v[60:63]
	v_mfma_f32_16x16x32_bf16 v[56:59], v[136:139], v[188:191], v[56:59]
	v_mfma_f32_16x16x32_bf16 v[44:47], v[128:131], v[220:223], v[44:47]
	v_mfma_f32_16x16x32_bf16 v[40:43], v[136:139], v[220:223], v[40:43]
	v_mfma_f32_16x16x32_bf16 v[28:31], v[128:131], v[228:231], v[28:31]
	v_mfma_f32_16x16x32_bf16 v[24:27], v[136:139], v[228:231], v[24:27]
	v_mfma_f32_16x16x32_bf16 v[12:15], v[128:131], v[236:239], v[12:15]
	v_mfma_f32_16x16x32_bf16 v[8:11], v[136:139], v[236:239], v[8:11]
	v_mfma_f32_16x16x32_bf16 v[60:63], v[132:135], v[216:219], v[60:63]
	v_mfma_f32_16x16x32_bf16 v[56:59], v[140:143], v[216:219], v[56:59]
	v_mfma_f32_16x16x32_bf16 v[44:47], v[132:135], v[224:227], v[44:47]
	v_mfma_f32_16x16x32_bf16 v[40:43], v[140:143], v[224:227], v[40:43]
	v_mfma_f32_16x16x32_bf16 v[28:31], v[132:135], v[232:235], v[28:31]
	v_mfma_f32_16x16x32_bf16 v[24:27], v[140:143], v[232:235], v[24:27]
	v_mfma_f32_16x16x32_bf16 v[12:15], v[132:135], v[240:243], v[12:15]
	v_mfma_f32_16x16x32_bf16 v[8:11], v[140:143], v[240:243], v[8:11]
	s_setprio 0
	s_setprio 1
	v_mfma_f32_16x16x32_bf16 v[52:55], v[172:175], v[188:191], v[52:55]
	v_mfma_f32_16x16x32_bf16 v[48:51], v[180:183], v[188:191], v[48:51]
	v_mfma_f32_16x16x32_bf16 v[36:39], v[172:175], v[220:223], v[36:39]
	v_mfma_f32_16x16x32_bf16 v[32:35], v[180:183], v[220:223], v[32:35]
	v_mfma_f32_16x16x32_bf16 v[20:23], v[172:175], v[228:231], v[20:23]
	v_mfma_f32_16x16x32_bf16 v[16:19], v[180:183], v[228:231], v[16:19]
	v_mfma_f32_16x16x32_bf16 v[4:7], v[172:175], v[236:239], v[4:7]
	v_mfma_f32_16x16x32_bf16 v[0:3], v[180:183], v[236:239], v[0:3]
	v_mfma_f32_16x16x32_bf16 v[52:55], v[176:179], v[216:219], v[52:55]
	v_mfma_f32_16x16x32_bf16 v[48:51], v[184:187], v[216:219], v[48:51]
	v_mfma_f32_16x16x32_bf16 v[36:39], v[176:179], v[224:227], v[36:39]
	v_mfma_f32_16x16x32_bf16 v[32:35], v[184:187], v[224:227], v[32:35]
	v_mfma_f32_16x16x32_bf16 v[20:23], v[176:179], v[232:235], v[20:23]
	v_mfma_f32_16x16x32_bf16 v[16:19], v[184:187], v[232:235], v[16:19]
	v_mfma_f32_16x16x32_bf16 v[4:7], v[176:179], v[240:243], v[4:7]
	v_mfma_f32_16x16x32_bf16 v[0:3], v[184:187], v[240:243], v[0:3]
	s_setprio 0
	s_barrier
	s_add_i32 s68, s68, 2
	s_cmp_gt_u32 s68, 13
	s_mov_b64 s[24:25], s[74:75]
	s_cbranch_scc0 .LBB0_1766
	s_and_b64 vcc, exec, s[42:43]
	s_cbranch_vccz .LBB0_1769
	s_barrier

.LBB0_1914:
	ds_read_b128 v[174:177], v143
	ds_read_b128 v[178:181], v153
	ds_read_b128 v[182:185], v159
	ds_read_b128 v[186:189], v160
	ds_read_b128 v[190:193], v161
	ds_read_b128 v[198:201], v162
	ds_read_b128 v[202:205], v163
	ds_read_b128 v[206:209], v164
	s_add_u32 s48, s24, 0xfffc0080
	s_addc_u32 s49, s25, -1
	s_cmp_eq_u32 s75, 12
	s_cselect_b32 s51, s4, s49
	s_cselect_b32 s50, s5, s48
	s_cselect_b32 s49, s39, s74
	s_cselect_b32 s48, s41, s67
	s_mov_b32 m0, s61
	ds_read_b128 v[210:213], v141
	ds_read_b128 v[214:217], v141 offset:1024
	ds_read_b128 v[218:221], v141 offset:2048
	ds_read_b128 v[222:225], v141 offset:3072
	ds_read_b128 v[226:229], v141 offset:4096
	ds_read_b128 v[230:233], v141 offset:5120
	ds_read_b128 v[234:237], v141 offset:6144
	ds_read_b128 v[238:241], v141 offset:7168
	global_load_lds_dwordx4 v132, s[24:25]
	s_mov_b32 m0, s64
	s_nop 0
	global_load_lds_dwordx4 v134, s[24:25]
	s_waitcnt vmcnt(8)
	s_waitcnt lgkmcnt(0)
	s_barrier
	s_setprio 1
	s_waitcnt lgkmcnt(0)
	v_mfma_f32_16x16x32_bf16 v[124:127], v[174:177], v[210:213], v[124:127]
	v_mfma_f32_16x16x32_bf16 v[120:123], v[182:185], v[210:213], v[120:123]
	v_mfma_f32_16x16x32_bf16 v[108:111], v[174:177], v[218:221], v[108:111]
	v_mfma_f32_16x16x32_bf16 v[104:107], v[182:185], v[218:221], v[104:107]
	v_mfma_f32_16x16x32_bf16 v[92:95], v[174:177], v[226:229], v[92:95]
	v_mfma_f32_16x16x32_bf16 v[88:91], v[182:185], v[226:229], v[88:91]
	v_mfma_f32_16x16x32_bf16 v[76:79], v[174:177], v[234:237], v[76:79]
	v_mfma_f32_16x16x32_bf16 v[72:75], v[182:185], v[234:237], v[72:75]
	v_mfma_f32_16x16x32_bf16 v[124:127], v[178:181], v[214:217], v[124:127]
	v_mfma_f32_16x16x32_bf16 v[120:123], v[186:189], v[214:217], v[120:123]
	v_mfma_f32_16x16x32_bf16 v[108:111], v[178:181], v[222:225], v[108:111]
	v_mfma_f32_16x16x32_bf16 v[104:107], v[186:189], v[222:225], v[104:107]
	v_mfma_f32_16x16x32_bf16 v[92:95], v[178:181], v[230:233], v[92:95]
	v_mfma_f32_16x16x32_bf16 v[88:91], v[186:189], v[230:233], v[88:91]
	v_mfma_f32_16x16x32_bf16 v[76:79], v[178:181], v[238:241], v[76:79]
	v_mfma_f32_16x16x32_bf16 v[72:75], v[186:189], v[238:241], v[72:75]
	s_setprio 0
	s_setprio 1
	v_mfma_f32_16x16x32_bf16 v[116:119], v[190:193], v[210:213], v[116:119]
	v_mfma_f32_16x16x32_bf16 v[112:115], v[202:205], v[210:213], v[112:115]
	v_mfma_f32_16x16x32_bf16 v[100:103], v[190:193], v[218:221], v[100:103]
	v_mfma_f32_16x16x32_bf16 v[96:99], v[202:205], v[218:221], v[96:99]
	v_mfma_f32_16x16x32_bf16 v[84:87], v[190:193], v[226:229], v[84:87]
	v_mfma_f32_16x16x32_bf16 v[80:83], v[202:205], v[226:229], v[80:83]
	v_mfma_f32_16x16x32_bf16 v[68:71], v[190:193], v[234:237], v[68:71]
	v_mfma_f32_16x16x32_bf16 v[64:67], v[202:205], v[234:237], v[64:67]
	v_mfma_f32_16x16x32_bf16 v[116:119], v[198:201], v[214:217], v[116:119]
	v_mfma_f32_16x16x32_bf16 v[112:115], v[206:209], v[214:217], v[112:115]
	v_mfma_f32_16x16x32_bf16 v[100:103], v[198:201], v[222:225], v[100:103]
	v_mfma_f32_16x16x32_bf16 v[96:99], v[206:209], v[222:225], v[96:99]
	v_mfma_f32_16x16x32_bf16 v[84:87], v[198:201], v[230:233], v[84:87]
	v_mfma_f32_16x16x32_bf16 v[80:83], v[206:209], v[230:233], v[80:83]
	v_mfma_f32_16x16x32_bf16 v[68:71], v[198:201], v[238:241], v[68:71]
	v_mfma_f32_16x16x32_bf16 v[64:67], v[206:209], v[238:241], v[64:67]
	s_setprio 0
	s_barrier
	s_mov_b32 m0, s8
	s_add_u32 s68, s48, 0x40000
	ds_read_b128 v[210:213], v141 offset:16384
	ds_read_b128 v[214:217], v141 offset:17408
	ds_read_b128 v[218:221], v141 offset:18432
	ds_read_b128 v[222:225], v141 offset:19456
	ds_read_b128 v[226:229], v141 offset:20480
	ds_read_b128 v[230:233], v141 offset:21504
	ds_read_b128 v[234:237], v141 offset:22528
	ds_read_b128 v[238:241], v141 offset:23552
	global_load_lds_dwordx4 v130, s[48:49]
	s_mov_b32 m0, s9
	s_addc_u32 s69, s49, 0
	global_load_lds_dwordx4 v128, s[48:49]
	s_mov_b32 m0, s28
	s_add_u32 s98, s48, s12
	global_load_lds_dwordx4 v130, s[68:69]
	s_mov_b32 m0, s29
	s_addc_u32 s99, s49, s13
	global_load_lds_dwordx4 v128, s[68:69]
	s_mov_b32 m0, s2
	s_add_u32 s100, s50, s12
	global_load_lds_dwordx4 v130, s[50:51]
	s_mov_b32 m0, s30
	s_addc_u32 s101, s51, s13
	global_load_lds_dwordx4 v128, s[50:51]
	s_waitcnt vmcnt(8)
	s_waitcnt lgkmcnt(0)
	s_barrier
	s_setprio 1
	s_waitcnt lgkmcnt(0)
	v_mfma_f32_16x16x32_bf16 v[60:63], v[174:177], v[210:213], v[60:63]
	v_mfma_f32_16x16x32_bf16 v[56:59], v[182:185], v[210:213], v[56:59]
	v_mfma_f32_16x16x32_bf16 v[44:47], v[174:177], v[218:221], v[44:47]
	v_mfma_f32_16x16x32_bf16 v[40:43], v[182:185], v[218:221], v[40:43]
	v_mfma_f32_16x16x32_bf16 v[28:31], v[174:177], v[226:229], v[28:31]
	v_mfma_f32_16x16x32_bf16 v[24:27], v[182:185], v[226:229], v[24:27]
	v_mfma_f32_16x16x32_bf16 v[12:15], v[174:177], v[234:237], v[12:15]
	v_mfma_f32_16x16x32_bf16 v[8:11], v[182:185], v[234:237], v[8:11]
	v_mfma_f32_16x16x32_bf16 v[60:63], v[178:181], v[214:217], v[60:63]
	v_mfma_f32_16x16x32_bf16 v[56:59], v[186:189], v[214:217], v[56:59]
	v_mfma_f32_16x16x32_bf16 v[44:47], v[178:181], v[222:225], v[44:47]
	v_mfma_f32_16x16x32_bf16 v[40:43], v[186:189], v[222:225], v[40:43]
	v_mfma_f32_16x16x32_bf16 v[28:31], v[178:181], v[230:233], v[28:31]
	v_mfma_f32_16x16x32_bf16 v[24:27], v[186:189], v[230:233], v[24:27]
	v_mfma_f32_16x16x32_bf16 v[12:15], v[178:181], v[238:241], v[12:15]
	v_mfma_f32_16x16x32_bf16 v[8:11], v[186:189], v[238:241], v[8:11]
	s_setprio 0
	s_setprio 1
	v_mfma_f32_16x16x32_bf16 v[52:55], v[190:193], v[210:213], v[52:55]
	v_mfma_f32_16x16x32_bf16 v[48:51], v[202:205], v[210:213], v[48:51]
	v_mfma_f32_16x16x32_bf16 v[36:39], v[190:193], v[218:221], v[36:39]
	v_mfma_f32_16x16x32_bf16 v[32:35], v[202:205], v[218:221], v[32:35]
	v_mfma_f32_16x16x32_bf16 v[20:23], v[190:193], v[226:229], v[20:23]
	v_mfma_f32_16x16x32_bf16 v[16:19], v[202:205], v[226:229], v[16:19]
	v_mfma_f32_16x16x32_bf16 v[4:7], v[190:193], v[234:237], v[4:7]
	v_mfma_f32_16x16x32_bf16 v[0:3], v[202:205], v[234:237], v[0:3]
	v_mfma_f32_16x16x32_bf16 v[52:55], v[198:201], v[214:217], v[52:55]
	v_mfma_f32_16x16x32_bf16 v[48:51], v[206:209], v[214:217], v[48:51]
	v_mfma_f32_16x16x32_bf16 v[36:39], v[198:201], v[222:225], v[36:39]
	v_mfma_f32_16x16x32_bf16 v[32:35], v[206:209], v[222:225], v[32:35]
	v_mfma_f32_16x16x32_bf16 v[20:23], v[198:201], v[230:233], v[20:23]
	v_mfma_f32_16x16x32_bf16 v[16:19], v[206:209], v[230:233], v[16:19]
	v_mfma_f32_16x16x32_bf16 v[4:7], v[198:201], v[238:241], v[4:7]
	v_mfma_f32_16x16x32_bf16 v[0:3], v[206:209], v[238:241], v[0:3]
	s_setprio 0
	s_barrier
	ds_read_b128 v[174:177], v165
	ds_read_b128 v[178:181], v166
	ds_read_b128 v[182:185], v167
	ds_read_b128 v[186:189], v168
	ds_read_b128 v[190:193], v169
	ds_read_b128 v[198:201], v170
	ds_read_b128 v[202:205], v171
	ds_read_b128 v[206:209], v172
	s_add_u32 s50, s50, 0x40000
	s_addc_u32 s51, s51, 0
	s_mov_b32 m0, s31
	ds_read_b128 v[210:213], v141 offset:32768
	ds_read_b128 v[214:217], v141 offset:33792
	ds_read_b128 v[218:221], v141 offset:34816
	ds_read_b128 v[222:225], v141 offset:35840
	ds_read_b128 v[226:229], v141 offset:36864
	ds_read_b128 v[230:233], v141 offset:37888
	ds_read_b128 v[234:237], v141 offset:38912
	ds_read_b128 v[238:241], v141 offset:39936
	global_load_lds_dwordx4 v130, s[50:51]
	s_mov_b32 m0, s33
	s_nop 0
	global_load_lds_dwordx4 v128, s[50:51]
	s_waitcnt vmcnt(8)
	s_waitcnt lgkmcnt(0)
	s_barrier
	s_setprio 1
	s_waitcnt lgkmcnt(0)
	v_mfma_f32_16x16x32_bf16 v[124:127], v[174:177], v[210:213], v[124:127]
	v_mfma_f32_16x16x32_bf16 v[120:123], v[182:185], v[210:213], v[120:123]
	v_mfma_f32_16x16x32_bf16 v[108:111], v[174:177], v[218:221], v[108:111]
	v_mfma_f32_16x16x32_bf16 v[104:107], v[182:185], v[218:221], v[104:107]
	v_mfma_f32_16x16x32_bf16 v[92:95], v[174:177], v[226:229], v[92:95]
	v_mfma_f32_16x16x32_bf16 v[88:91], v[182:185], v[226:229], v[88:91]
	v_mfma_f32_16x16x32_bf16 v[76:79], v[174:177], v[234:237], v[76:79]
	v_mfma_f32_16x16x32_bf16 v[72:75], v[182:185], v[234:237], v[72:75]
	v_mfma_f32_16x16x32_bf16 v[124:127], v[178:181], v[214:217], v[124:127]
	v_mfma_f32_16x16x32_bf16 v[120:123], v[186:189], v[214:217], v[120:123]
	v_mfma_f32_16x16x32_bf16 v[108:111], v[178:181], v[222:225], v[108:111]
	v_mfma_f32_16x16x32_bf16 v[104:107], v[186:189], v[222:225], v[104:107]
	v_mfma_f32_16x16x32_bf16 v[92:95], v[178:181], v[230:233], v[92:95]
	v_mfma_f32_16x16x32_bf16 v[88:91], v[186:189], v[230:233], v[88:91]
	v_mfma_f32_16x16x32_bf16 v[76:79], v[178:181], v[238:241], v[76:79]
	v_mfma_f32_16x16x32_bf16 v[72:75], v[186:189], v[238:241], v[72:75]
	s_setprio 0
	s_setprio 1
	v_mfma_f32_16x16x32_bf16 v[116:119], v[190:193], v[210:213], v[116:119]
	v_mfma_f32_16x16x32_bf16 v[112:115], v[202:205], v[210:213], v[112:115]
	v_mfma_f32_16x16x32_bf16 v[100:103], v[190:193], v[218:221], v[100:103]
	v_mfma_f32_16x16x32_bf16 v[96:99], v[202:205], v[218:221], v[96:99]
	v_mfma_f32_16x16x32_bf16 v[84:87], v[190:193], v[226:229], v[84:87]
	v_mfma_f32_16x16x32_bf16 v[80:83], v[202:205], v[226:229], v[80:83]
	v_mfma_f32_16x16x32_bf16 v[68:71], v[190:193], v[234:237], v[68:71]
	v_mfma_f32_16x16x32_bf16 v[64:67], v[202:205], v[234:237], v[64:67]
	v_mfma_f32_16x16x32_bf16 v[116:119], v[198:201], v[214:217], v[116:119]
	v_mfma_f32_16x16x32_bf16 v[112:115], v[206:209], v[214:217], v[112:115]
	v_mfma_f32_16x16x32_bf16 v[100:103], v[198:201], v[222:225], v[100:103]
	v_mfma_f32_16x16x32_bf16 v[96:99], v[206:209], v[222:225], v[96:99]
	v_mfma_f32_16x16x32_bf16 v[84:87], v[198:201], v[230:233], v[84:87]
	v_mfma_f32_16x16x32_bf16 v[80:83], v[206:209], v[230:233], v[80:83]
	v_mfma_f32_16x16x32_bf16 v[68:71], v[198:201], v[238:241], v[68:71]
	v_mfma_f32_16x16x32_bf16 v[64:67], v[206:209], v[238:241], v[64:67]
	s_setprio 0
	s_barrier
	s_mov_b32 m0, s36
	s_add_u32 s48, s48, 0x40080
	ds_read_b128 v[210:213], v141 offset:49152
	ds_read_b128 v[214:217], v141 offset:50176
	ds_read_b128 v[218:221], v141 offset:51200
	ds_read_b128 v[222:225], v141 offset:52224
	ds_read_b128 v[226:229], v141 offset:53248
	ds_read_b128 v[230:233], v141 offset:54272
	ds_read_b128 v[234:237], v141 offset:55296
	ds_read_b128 v[238:241], v141 offset:56320
	global_load_lds_dwordx4 v130, s[98:99]
	s_mov_b32 m0, s37
	s_addc_u32 s49, s49, 0
	global_load_lds_dwordx4 v128, s[98:99]
	s_mov_b32 m0, s53
	s_add_u32 s24, s24, 0x100
	global_load_lds_dwordx4 v130, s[48:49]
	s_mov_b32 m0, s54
	s_addc_u32 s25, s25, 0
	global_load_lds_dwordx4 v128, s[48:49]
	s_mov_b32 m0, s47
	s_add_u32 s67, s67, 0x100
	global_load_lds_dwordx4 v130, s[100:101]
	s_mov_b32 m0, s52
	s_addc_u32 s74, s74, 0
	global_load_lds_dwordx4 v128, s[100:101]
	s_waitcnt vmcnt(8)
	s_waitcnt lgkmcnt(0)
	s_barrier
	s_setprio 1
	s_waitcnt lgkmcnt(0)
	v_mfma_f32_16x16x32_bf16 v[60:63], v[174:177], v[210:213], v[60:63]
	v_mfma_f32_16x16x32_bf16 v[56:59], v[182:185], v[210:213], v[56:59]
	v_mfma_f32_16x16x32_bf16 v[44:47], v[174:177], v[218:221], v[44:47]
	v_mfma_f32_16x16x32_bf16 v[40:43], v[182:185], v[218:221], v[40:43]
	v_mfma_f32_16x16x32_bf16 v[28:31], v[174:177], v[226:229], v[28:31]
	v_mfma_f32_16x16x32_bf16 v[24:27], v[182:185], v[226:229], v[24:27]
	v_mfma_f32_16x16x32_bf16 v[12:15], v[174:177], v[234:237], v[12:15]
	v_mfma_f32_16x16x32_bf16 v[8:11], v[182:185], v[234:237], v[8:11]
	v_mfma_f32_16x16x32_bf16 v[60:63], v[178:181], v[214:217], v[60:63]
	v_mfma_f32_16x16x32_bf16 v[56:59], v[186:189], v[214:217], v[56:59]
	v_mfma_f32_16x16x32_bf16 v[44:47], v[178:181], v[222:225], v[44:47]
	v_mfma_f32_16x16x32_bf16 v[40:43], v[186:189], v[222:225], v[40:43]
	v_mfma_f32_16x16x32_bf16 v[28:31], v[178:181], v[230:233], v[28:31]
	v_mfma_f32_16x16x32_bf16 v[24:27], v[186:189], v[230:233], v[24:27]
	v_mfma_f32_16x16x32_bf16 v[12:15], v[178:181], v[238:241], v[12:15]
	v_mfma_f32_16x16x32_bf16 v[8:11], v[186:189], v[238:241], v[8:11]
	s_setprio 0
	s_setprio 1
	v_mfma_f32_16x16x32_bf16 v[52:55], v[190:193], v[210:213], v[52:55]
	v_mfma_f32_16x16x32_bf16 v[48:51], v[202:205], v[210:213], v[48:51]
	v_mfma_f32_16x16x32_bf16 v[36:39], v[190:193], v[218:221], v[36:39]
	v_mfma_f32_16x16x32_bf16 v[32:35], v[202:205], v[218:221], v[32:35]
	v_mfma_f32_16x16x32_bf16 v[20:23], v[190:193], v[226:229], v[20:23]
	v_mfma_f32_16x16x32_bf16 v[16:19], v[202:205], v[226:229], v[16:19]
	v_mfma_f32_16x16x32_bf16 v[4:7], v[190:193], v[234:237], v[4:7]
	v_mfma_f32_16x16x32_bf16 v[0:3], v[202:205], v[234:237], v[0:3]
	v_mfma_f32_16x16x32_bf16 v[52:55], v[198:201], v[214:217], v[52:55]
	v_mfma_f32_16x16x32_bf16 v[48:51], v[206:209], v[214:217], v[48:51]
	v_mfma_f32_16x16x32_bf16 v[36:39], v[198:201], v[222:225], v[36:39]
	v_mfma_f32_16x16x32_bf16 v[32:35], v[206:209], v[222:225], v[32:35]
	v_mfma_f32_16x16x32_bf16 v[20:23], v[198:201], v[230:233], v[20:23]
	v_mfma_f32_16x16x32_bf16 v[16:19], v[206:209], v[230:233], v[16:19]
	v_mfma_f32_16x16x32_bf16 v[4:7], v[198:201], v[238:241], v[4:7]
	v_mfma_f32_16x16x32_bf16 v[0:3], v[206:209], v[238:241], v[0:3]
	s_setprio 0
	s_barrier
	s_add_i32 s75, s75, 2
	s_cmp_gt_u32 s75, 13
	s_cbranch_scc0 .LBB0_1914
	s_and_b64 vcc, exec, s[14:15]
	s_cbranch_vccz .LBB0_1917
	s_barrier

.LBB0_1994:
	ds_read_b128 v[128:131], v199
	ds_read_b128 v[132:135], v200
	ds_read_b128 v[136:139], v201
	ds_read_b128 v[140:143], v202
	ds_read_b128 v[172:175], v203
	ds_read_b128 v[176:179], v204
	ds_read_b128 v[180:183], v205
	ds_read_b128 v[184:187], v206
	s_add_u32 s48, s24, 0x100
	s_addc_u32 s49, s25, 0
	s_cmp_eq_u32 s68, 40
	s_cselect_b32 s55, s13, s49
	s_cselect_b32 s54, s12, s48
	s_cselect_b32 s51, s47, s5
	s_cselect_b32 s50, s46, s4
	s_mov_b32 m0, s64
	ds_read_b128 v[188:191], v159
	ds_read_b128 v[216:219], v159 offset:1024
	ds_read_b128 v[220:223], v159 offset:2048
	ds_read_b128 v[224:227], v159 offset:3072
	ds_read_b128 v[228:231], v159 offset:4096
	ds_read_b128 v[232:235], v159 offset:5120
	ds_read_b128 v[236:239], v159 offset:6144
	ds_read_b128 v[240:243], v159 offset:7168
	global_load_lds_dwordx4 v164, s[24:25]
	s_mov_b32 m0, s65
	s_nop 0
	global_load_lds_dwordx4 v166, s[24:25]
	s_waitcnt vmcnt(8)
	s_waitcnt lgkmcnt(0)
	s_barrier
	s_setprio 1
	s_waitcnt lgkmcnt(0)
	v_mfma_f32_16x16x32_bf16 v[124:127], v[128:131], v[188:191], v[124:127]
	v_mfma_f32_16x16x32_bf16 v[120:123], v[136:139], v[188:191], v[120:123]
	v_mfma_f32_16x16x32_bf16 v[108:111], v[128:131], v[220:223], v[108:111]
	v_mfma_f32_16x16x32_bf16 v[104:107], v[136:139], v[220:223], v[104:107]
	v_mfma_f32_16x16x32_bf16 v[92:95], v[128:131], v[228:231], v[92:95]
	v_mfma_f32_16x16x32_bf16 v[88:91], v[136:139], v[228:231], v[88:91]
	v_mfma_f32_16x16x32_bf16 v[76:79], v[128:131], v[236:239], v[76:79]
	v_mfma_f32_16x16x32_bf16 v[72:75], v[136:139], v[236:239], v[72:75]
	v_mfma_f32_16x16x32_bf16 v[124:127], v[132:135], v[216:219], v[124:127]
	v_mfma_f32_16x16x32_bf16 v[120:123], v[140:143], v[216:219], v[120:123]
	v_mfma_f32_16x16x32_bf16 v[108:111], v[132:135], v[224:227], v[108:111]
	v_mfma_f32_16x16x32_bf16 v[104:107], v[140:143], v[224:227], v[104:107]
	v_mfma_f32_16x16x32_bf16 v[92:95], v[132:135], v[232:235], v[92:95]
	v_mfma_f32_16x16x32_bf16 v[88:91], v[140:143], v[232:235], v[88:91]
	v_mfma_f32_16x16x32_bf16 v[76:79], v[132:135], v[240:243], v[76:79]
	v_mfma_f32_16x16x32_bf16 v[72:75], v[140:143], v[240:243], v[72:75]
	s_setprio 0
	s_setprio 1
	v_mfma_f32_16x16x32_bf16 v[116:119], v[172:175], v[188:191], v[116:119]
	v_mfma_f32_16x16x32_bf16 v[112:115], v[180:183], v[188:191], v[112:115]
	v_mfma_f32_16x16x32_bf16 v[100:103], v[172:175], v[220:223], v[100:103]
	v_mfma_f32_16x16x32_bf16 v[96:99], v[180:183], v[220:223], v[96:99]
	v_mfma_f32_16x16x32_bf16 v[84:87], v[172:175], v[228:231], v[84:87]
	v_mfma_f32_16x16x32_bf16 v[80:83], v[180:183], v[228:231], v[80:83]
	v_mfma_f32_16x16x32_bf16 v[68:71], v[172:175], v[236:239], v[68:71]
	v_mfma_f32_16x16x32_bf16 v[64:67], v[180:183], v[236:239], v[64:67]
	v_mfma_f32_16x16x32_bf16 v[116:119], v[176:179], v[216:219], v[116:119]
	v_mfma_f32_16x16x32_bf16 v[112:115], v[184:187], v[216:219], v[112:115]
	v_mfma_f32_16x16x32_bf16 v[100:103], v[176:179], v[224:227], v[100:103]
	v_mfma_f32_16x16x32_bf16 v[96:99], v[184:187], v[224:227], v[96:99]
	v_mfma_f32_16x16x32_bf16 v[84:87], v[176:179], v[232:235], v[84:87]
	v_mfma_f32_16x16x32_bf16 v[80:83], v[184:187], v[232:235], v[80:83]
	v_mfma_f32_16x16x32_bf16 v[68:71], v[176:179], v[240:243], v[68:71]
	v_mfma_f32_16x16x32_bf16 v[64:67], v[184:187], v[240:243], v[64:67]
	s_setprio 0
	s_barrier
	s_mov_b32 m0, s7
	s_add_u32 s24, s50, 0xb0000
	ds_read_b128 v[188:191], v159 offset:16384
	ds_read_b128 v[216:219], v159 offset:17408
	ds_read_b128 v[220:223], v159 offset:18432
	ds_read_b128 v[224:227], v159 offset:19456
	ds_read_b128 v[228:231], v159 offset:20480
	ds_read_b128 v[232:235], v159 offset:21504
	ds_read_b128 v[236:239], v159 offset:22528
	ds_read_b128 v[240:243], v159 offset:23552
	global_load_lds_dwordx4 v160, s[50:51]
	s_mov_b32 m0, s8
	s_addc_u32 s25, s51, 0
	global_load_lds_dwordx4 v162, s[50:51]
	s_mov_b32 m0, s9
	s_add_u32 s98, s50, s40
	global_load_lds_dwordx4 v160, s[24:25]
	s_mov_b32 m0, s28
	s_addc_u32 s99, s51, s41
	global_load_lds_dwordx4 v162, s[24:25]
	s_mov_b32 m0, s6
	s_add_u32 s100, s54, s40
	global_load_lds_dwordx4 v160, s[54:55]
	s_mov_b32 m0, s29
	s_addc_u32 s101, s55, s41
	global_load_lds_dwordx4 v162, s[54:55]
	s_waitcnt vmcnt(8)
	s_waitcnt lgkmcnt(0)
	s_barrier
	s_setprio 1
	s_waitcnt lgkmcnt(0)
	v_mfma_f32_16x16x32_bf16 v[60:63], v[128:131], v[188:191], v[60:63]
	v_mfma_f32_16x16x32_bf16 v[56:59], v[136:139], v[188:191], v[56:59]
	v_mfma_f32_16x16x32_bf16 v[44:47], v[128:131], v[220:223], v[44:47]
	v_mfma_f32_16x16x32_bf16 v[40:43], v[136:139], v[220:223], v[40:43]
	v_mfma_f32_16x16x32_bf16 v[28:31], v[128:131], v[228:231], v[28:31]
	v_mfma_f32_16x16x32_bf16 v[24:27], v[136:139], v[228:231], v[24:27]
	v_mfma_f32_16x16x32_bf16 v[12:15], v[128:131], v[236:239], v[12:15]
	v_mfma_f32_16x16x32_bf16 v[8:11], v[136:139], v[236:239], v[8:11]
	v_mfma_f32_16x16x32_bf16 v[60:63], v[132:135], v[216:219], v[60:63]
	v_mfma_f32_16x16x32_bf16 v[56:59], v[140:143], v[216:219], v[56:59]
	v_mfma_f32_16x16x32_bf16 v[44:47], v[132:135], v[224:227], v[44:47]
	v_mfma_f32_16x16x32_bf16 v[40:43], v[140:143], v[224:227], v[40:43]
	v_mfma_f32_16x16x32_bf16 v[28:31], v[132:135], v[232:235], v[28:31]
	v_mfma_f32_16x16x32_bf16 v[24:27], v[140:143], v[232:235], v[24:27]
	v_mfma_f32_16x16x32_bf16 v[12:15], v[132:135], v[240:243], v[12:15]
	v_mfma_f32_16x16x32_bf16 v[8:11], v[140:143], v[240:243], v[8:11]
	s_setprio 0
	s_setprio 1
	v_mfma_f32_16x16x32_bf16 v[52:55], v[172:175], v[188:191], v[52:55]
	v_mfma_f32_16x16x32_bf16 v[48:51], v[180:183], v[188:191], v[48:51]
	v_mfma_f32_16x16x32_bf16 v[36:39], v[172:175], v[220:223], v[36:39]
	v_mfma_f32_16x16x32_bf16 v[32:35], v[180:183], v[220:223], v[32:35]
	v_mfma_f32_16x16x32_bf16 v[20:23], v[172:175], v[228:231], v[20:23]
	v_mfma_f32_16x16x32_bf16 v[16:19], v[180:183], v[228:231], v[16:19]
	v_mfma_f32_16x16x32_bf16 v[4:7], v[172:175], v[236:239], v[4:7]
	v_mfma_f32_16x16x32_bf16 v[0:3], v[180:183], v[236:239], v[0:3]
	v_mfma_f32_16x16x32_bf16 v[52:55], v[176:179], v[216:219], v[52:55]
	v_mfma_f32_16x16x32_bf16 v[48:51], v[184:187], v[216:219], v[48:51]
	v_mfma_f32_16x16x32_bf16 v[36:39], v[176:179], v[224:227], v[36:39]
	v_mfma_f32_16x16x32_bf16 v[32:35], v[184:187], v[224:227], v[32:35]
	v_mfma_f32_16x16x32_bf16 v[20:23], v[176:179], v[232:235], v[20:23]
	v_mfma_f32_16x16x32_bf16 v[16:19], v[184:187], v[232:235], v[16:19]
	v_mfma_f32_16x16x32_bf16 v[4:7], v[176:179], v[240:243], v[4:7]
	v_mfma_f32_16x16x32_bf16 v[0:3], v[184:187], v[240:243], v[0:3]
	s_setprio 0
	s_barrier
	ds_read_b128 v[128:131], v207
	ds_read_b128 v[132:135], v208
	ds_read_b128 v[136:139], v209
	ds_read_b128 v[140:143], v210
	ds_read_b128 v[172:175], v211
	ds_read_b128 v[176:179], v212
	ds_read_b128 v[180:183], v213
	ds_read_b128 v[184:187], v214
	s_add_u32 s24, s54, 0xb0000
	s_addc_u32 s25, s55, 0
	s_mov_b32 m0, s30
	ds_read_b128 v[188:191], v159 offset:32768
	ds_read_b128 v[216:219], v159 offset:33792
	ds_read_b128 v[220:223], v159 offset:34816
	ds_read_b128 v[224:227], v159 offset:35840
	ds_read_b128 v[228:231], v159 offset:36864
	ds_read_b128 v[232:235], v159 offset:37888
	ds_read_b128 v[236:239], v159 offset:38912
	ds_read_b128 v[240:243], v159 offset:39936
	global_load_lds_dwordx4 v160, s[24:25]
	s_mov_b32 m0, s31
	s_nop 0
	global_load_lds_dwordx4 v162, s[24:25]
	s_waitcnt vmcnt(8)
	s_waitcnt lgkmcnt(0)
	s_barrier
	s_setprio 1
	s_waitcnt lgkmcnt(0)
	v_mfma_f32_16x16x32_bf16 v[124:127], v[128:131], v[188:191], v[124:127]
	v_mfma_f32_16x16x32_bf16 v[120:123], v[136:139], v[188:191], v[120:123]
	v_mfma_f32_16x16x32_bf16 v[108:111], v[128:131], v[220:223], v[108:111]
	v_mfma_f32_16x16x32_bf16 v[104:107], v[136:139], v[220:223], v[104:107]
	v_mfma_f32_16x16x32_bf16 v[92:95], v[128:131], v[228:231], v[92:95]
	v_mfma_f32_16x16x32_bf16 v[88:91], v[136:139], v[228:231], v[88:91]
	v_mfma_f32_16x16x32_bf16 v[76:79], v[128:131], v[236:239], v[76:79]
	v_mfma_f32_16x16x32_bf16 v[72:75], v[136:139], v[236:239], v[72:75]
	v_mfma_f32_16x16x32_bf16 v[124:127], v[132:135], v[216:219], v[124:127]
	v_mfma_f32_16x16x32_bf16 v[120:123], v[140:143], v[216:219], v[120:123]
	v_mfma_f32_16x16x32_bf16 v[108:111], v[132:135], v[224:227], v[108:111]
	v_mfma_f32_16x16x32_bf16 v[104:107], v[140:143], v[224:227], v[104:107]
	v_mfma_f32_16x16x32_bf16 v[92:95], v[132:135], v[232:235], v[92:95]
	v_mfma_f32_16x16x32_bf16 v[88:91], v[140:143], v[232:235], v[88:91]
	v_mfma_f32_16x16x32_bf16 v[76:79], v[132:135], v[240:243], v[76:79]
	v_mfma_f32_16x16x32_bf16 v[72:75], v[140:143], v[240:243], v[72:75]
	s_setprio 0
	s_setprio 1
	v_mfma_f32_16x16x32_bf16 v[116:119], v[172:175], v[188:191], v[116:119]
	v_mfma_f32_16x16x32_bf16 v[112:115], v[180:183], v[188:191], v[112:115]
	v_mfma_f32_16x16x32_bf16 v[100:103], v[172:175], v[220:223], v[100:103]
	v_mfma_f32_16x16x32_bf16 v[96:99], v[180:183], v[220:223], v[96:99]
	v_mfma_f32_16x16x32_bf16 v[84:87], v[172:175], v[228:231], v[84:87]
	v_mfma_f32_16x16x32_bf16 v[80:83], v[180:183], v[228:231], v[80:83]
	v_mfma_f32_16x16x32_bf16 v[68:71], v[172:175], v[236:239], v[68:71]
	v_mfma_f32_16x16x32_bf16 v[64:67], v[180:183], v[236:239], v[64:67]
	v_mfma_f32_16x16x32_bf16 v[116:119], v[176:179], v[216:219], v[116:119]
	v_mfma_f32_16x16x32_bf16 v[112:115], v[184:187], v[216:219], v[112:115]
	v_mfma_f32_16x16x32_bf16 v[100:103], v[176:179], v[224:227], v[100:103]
	v_mfma_f32_16x16x32_bf16 v[96:99], v[184:187], v[224:227], v[96:99]
	v_mfma_f32_16x16x32_bf16 v[84:87], v[176:179], v[232:235], v[84:87]
	v_mfma_f32_16x16x32_bf16 v[80:83], v[184:187], v[232:235], v[80:83]
	v_mfma_f32_16x16x32_bf16 v[68:71], v[176:179], v[240:243], v[68:71]
	v_mfma_f32_16x16x32_bf16 v[64:67], v[184:187], v[240:243], v[64:67]
	s_setprio 0
	s_barrier
	s_mov_b32 m0, s33
	s_add_u32 s24, s50, 0xb0080
	ds_read_b128 v[188:191], v159 offset:49152
	ds_read_b128 v[216:219], v159 offset:50176
	ds_read_b128 v[220:223], v159 offset:51200
	ds_read_b128 v[224:227], v159 offset:52224
	ds_read_b128 v[228:231], v159 offset:53248
	ds_read_b128 v[232:235], v159 offset:54272
	ds_read_b128 v[236:239], v159 offset:55296
	ds_read_b128 v[240:243], v159 offset:56320
	global_load_lds_dwordx4 v160, s[98:99]
	s_mov_b32 m0, s34
	s_addc_u32 s25, s51, 0
	global_load_lds_dwordx4 v162, s[98:99]
	s_mov_b32 m0, s37
	s_add_u32 s4, s4, 0x100
	global_load_lds_dwordx4 v160, s[24:25]
	s_mov_b32 m0, s45
	s_addc_u32 s5, s5, 0
	global_load_lds_dwordx4 v162, s[24:25]
	s_mov_b32 m0, s35
	s_nop 0
	global_load_lds_dwordx4 v160, s[100:101]
	s_mov_b32 m0, s36
	s_nop 0
	global_load_lds_dwordx4 v162, s[100:101]
	s_waitcnt vmcnt(8)
	s_waitcnt lgkmcnt(0)
	s_barrier
	s_setprio 1
	s_waitcnt lgkmcnt(0)
	v_mfma_f32_16x16x32_bf16 v[60:63], v[128:131], v[188:191], v[60:63]
	v_mfma_f32_16x16x32_bf16 v[56:59], v[136:139], v[188:191], v[56:59]
	v_mfma_f32_16x16x32_bf16 v[44:47], v[128:131], v[220:223], v[44:47]
	v_mfma_f32_16x16x32_bf16 v[40:43], v[136:139], v[220:223], v[40:43]
	v_mfma_f32_16x16x32_bf16 v[28:31], v[128:131], v[228:231], v[28:31]
	v_mfma_f32_16x16x32_bf16 v[24:27], v[136:139], v[228:231], v[24:27]
	v_mfma_f32_16x16x32_bf16 v[12:15], v[128:131], v[236:239], v[12:15]
	v_mfma_f32_16x16x32_bf16 v[8:11], v[136:139], v[236:239], v[8:11]
	v_mfma_f32_16x16x32_bf16 v[60:63], v[132:135], v[216:219], v[60:63]
	v_mfma_f32_16x16x32_bf16 v[56:59], v[140:143], v[216:219], v[56:59]
	v_mfma_f32_16x16x32_bf16 v[44:47], v[132:135], v[224:227], v[44:47]
	v_mfma_f32_16x16x32_bf16 v[40:43], v[140:143], v[224:227], v[40:43]
	v_mfma_f32_16x16x32_bf16 v[28:31], v[132:135], v[232:235], v[28:31]
	v_mfma_f32_16x16x32_bf16 v[24:27], v[140:143], v[232:235], v[24:27]
	v_mfma_f32_16x16x32_bf16 v[12:15], v[132:135], v[240:243], v[12:15]
	v_mfma_f32_16x16x32_bf16 v[8:11], v[140:143], v[240:243], v[8:11]
	s_setprio 0
	s_setprio 1
	v_mfma_f32_16x16x32_bf16 v[52:55], v[172:175], v[188:191], v[52:55]
	v_mfma_f32_16x16x32_bf16 v[48:51], v[180:183], v[188:191], v[48:51]
	v_mfma_f32_16x16x32_bf16 v[36:39], v[172:175], v[220:223], v[36:39]
	v_mfma_f32_16x16x32_bf16 v[32:35], v[180:183], v[220:223], v[32:35]
	v_mfma_f32_16x16x32_bf16 v[20:23], v[172:175], v[228:231], v[20:23]
	v_mfma_f32_16x16x32_bf16 v[16:19], v[180:183], v[228:231], v[16:19]
	v_mfma_f32_16x16x32_bf16 v[4:7], v[172:175], v[236:239], v[4:7]
	v_mfma_f32_16x16x32_bf16 v[0:3], v[180:183], v[236:239], v[0:3]
	v_mfma_f32_16x16x32_bf16 v[52:55], v[176:179], v[216:219], v[52:55]
	v_mfma_f32_16x16x32_bf16 v[48:51], v[184:187], v[216:219], v[48:51]
	v_mfma_f32_16x16x32_bf16 v[36:39], v[176:179], v[224:227], v[36:39]
	v_mfma_f32_16x16x32_bf16 v[32:35], v[184:187], v[224:227], v[32:35]
	v_mfma_f32_16x16x32_bf16 v[20:23], v[176:179], v[232:235], v[20:23]
	v_mfma_f32_16x16x32_bf16 v[16:19], v[184:187], v[232:235], v[16:19]
	v_mfma_f32_16x16x32_bf16 v[4:7], v[176:179], v[240:243], v[4:7]
	v_mfma_f32_16x16x32_bf16 v[0:3], v[184:187], v[240:243], v[0:3]
	s_setprio 0
	s_barrier
	s_add_i32 s68, s68, 2
	s_cmp_gt_u32 s68, 41
	s_mov_b64 s[24:25], s[48:49]
	s_cbranch_scc0 .LBB0_1994
	s_and_b64 vcc, exec, s[42:43]
	s_cbranch_vccz .LBB0_1997
	s_barrier

.LBB0_2152:
	ds_read_b128 v[160:163], v169
	ds_read_b128 v[164:167], v170
	ds_read_b128 v[186:189], v171
	ds_read_b128 v[190:193], v172
	ds_read_b128 v[198:201], v173
	ds_read_b128 v[202:205], v174
	ds_read_b128 v[206:209], v175
	ds_read_b128 v[210:213], v176
	s_add_u32 s18, s16, 0xfffc0080
	s_addc_u32 s19, s17, -1
	s_cmp_eq_u32 s66, 12
	s_cselect_b32 s25, s4, s19
	s_cselect_b32 s24, s5, s18
	s_cselect_b32 s19, s13, s49
	s_cselect_b32 s18, s15, s47
	s_mov_b32 m0, s64
	ds_read_b128 v[214:217], v159
	ds_read_b128 v[218:221], v159 offset:1024
	ds_read_b128 v[222:225], v159 offset:2048
	ds_read_b128 v[226:229], v159 offset:3072
	ds_read_b128 v[230:233], v159 offset:4096
	ds_read_b128 v[234:237], v159 offset:5120
	ds_read_b128 v[238:241], v159 offset:6144
	ds_read_b128 v[242:245], v159 offset:7168
	global_load_lds_dwordx4 v134, s[16:17]
	s_mov_b32 m0, s65
	s_nop 0
	global_load_lds_dwordx4 v136, s[16:17]
	s_waitcnt vmcnt(8)
	s_waitcnt lgkmcnt(0)
	s_barrier
	s_setprio 1
	s_waitcnt lgkmcnt(0)
	v_mfma_f32_16x16x32_bf16 v[124:127], v[160:163], v[214:217], v[124:127]
	v_mfma_f32_16x16x32_bf16 v[120:123], v[186:189], v[214:217], v[120:123]
	v_mfma_f32_16x16x32_bf16 v[108:111], v[160:163], v[222:225], v[108:111]
	v_mfma_f32_16x16x32_bf16 v[104:107], v[186:189], v[222:225], v[104:107]
	v_mfma_f32_16x16x32_bf16 v[92:95], v[160:163], v[230:233], v[92:95]
	v_mfma_f32_16x16x32_bf16 v[88:91], v[186:189], v[230:233], v[88:91]
	v_mfma_f32_16x16x32_bf16 v[76:79], v[160:163], v[238:241], v[76:79]
	v_mfma_f32_16x16x32_bf16 v[72:75], v[186:189], v[238:241], v[72:75]
	v_mfma_f32_16x16x32_bf16 v[124:127], v[164:167], v[218:221], v[124:127]
	v_mfma_f32_16x16x32_bf16 v[120:123], v[190:193], v[218:221], v[120:123]
	v_mfma_f32_16x16x32_bf16 v[108:111], v[164:167], v[226:229], v[108:111]
	v_mfma_f32_16x16x32_bf16 v[104:107], v[190:193], v[226:229], v[104:107]
	v_mfma_f32_16x16x32_bf16 v[92:95], v[164:167], v[234:237], v[92:95]
	v_mfma_f32_16x16x32_bf16 v[88:91], v[190:193], v[234:237], v[88:91]
	v_mfma_f32_16x16x32_bf16 v[76:79], v[164:167], v[242:245], v[76:79]
	v_mfma_f32_16x16x32_bf16 v[72:75], v[190:193], v[242:245], v[72:75]
	s_setprio 0
	s_setprio 1
	v_mfma_f32_16x16x32_bf16 v[116:119], v[198:201], v[214:217], v[116:119]
	v_mfma_f32_16x16x32_bf16 v[112:115], v[206:209], v[214:217], v[112:115]
	v_mfma_f32_16x16x32_bf16 v[100:103], v[198:201], v[222:225], v[100:103]
	v_mfma_f32_16x16x32_bf16 v[96:99], v[206:209], v[222:225], v[96:99]
	v_mfma_f32_16x16x32_bf16 v[84:87], v[198:201], v[230:233], v[84:87]
	v_mfma_f32_16x16x32_bf16 v[80:83], v[206:209], v[230:233], v[80:83]
	v_mfma_f32_16x16x32_bf16 v[68:71], v[198:201], v[238:241], v[68:71]
	v_mfma_f32_16x16x32_bf16 v[64:67], v[206:209], v[238:241], v[64:67]
	v_mfma_f32_16x16x32_bf16 v[116:119], v[202:205], v[218:221], v[116:119]
	v_mfma_f32_16x16x32_bf16 v[112:115], v[210:213], v[218:221], v[112:115]
	v_mfma_f32_16x16x32_bf16 v[100:103], v[202:205], v[226:229], v[100:103]
	v_mfma_f32_16x16x32_bf16 v[96:99], v[210:213], v[226:229], v[96:99]
	v_mfma_f32_16x16x32_bf16 v[84:87], v[202:205], v[234:237], v[84:87]
	v_mfma_f32_16x16x32_bf16 v[80:83], v[210:213], v[234:237], v[80:83]
	v_mfma_f32_16x16x32_bf16 v[68:71], v[202:205], v[242:245], v[68:71]
	v_mfma_f32_16x16x32_bf16 v[64:67], v[210:213], v[242:245], v[64:67]
	s_setprio 0
	s_barrier
	s_mov_b32 m0, s6
	s_add_u32 s68, s18, 0x40000
	ds_read_b128 v[214:217], v159 offset:16384
	ds_read_b128 v[218:221], v159 offset:17408
	ds_read_b128 v[222:225], v159 offset:18432
	ds_read_b128 v[226:229], v159 offset:19456
	ds_read_b128 v[230:233], v159 offset:20480
	ds_read_b128 v[234:237], v159 offset:21504
	ds_read_b128 v[238:241], v159 offset:22528
	ds_read_b128 v[242:245], v159 offset:23552
	global_load_lds_dwordx4 v128, s[18:19]
	s_mov_b32 m0, s7
	s_addc_u32 s69, s19, 0
	global_load_lds_dwordx4 v130, s[18:19]
	s_mov_b32 m0, s8
	s_add_u32 s98, s18, s42
	global_load_lds_dwordx4 v128, s[68:69]
	s_mov_b32 m0, s9
	s_addc_u32 s99, s19, s43
	global_load_lds_dwordx4 v130, s[68:69]
	s_mov_b32 m0, s2
	s_add_u32 s100, s24, s42
	global_load_lds_dwordx4 v128, s[24:25]
	s_mov_b32 m0, s28
	s_addc_u32 s101, s25, s43
	global_load_lds_dwordx4 v130, s[24:25]
	s_waitcnt vmcnt(8)
	s_waitcnt lgkmcnt(0)
	s_barrier
	s_setprio 1
	s_waitcnt lgkmcnt(0)
	v_mfma_f32_16x16x32_bf16 v[60:63], v[160:163], v[214:217], v[60:63]
	v_mfma_f32_16x16x32_bf16 v[56:59], v[186:189], v[214:217], v[56:59]
	v_mfma_f32_16x16x32_bf16 v[44:47], v[160:163], v[222:225], v[44:47]
	v_mfma_f32_16x16x32_bf16 v[40:43], v[186:189], v[222:225], v[40:43]
	v_mfma_f32_16x16x32_bf16 v[28:31], v[160:163], v[230:233], v[28:31]
	v_mfma_f32_16x16x32_bf16 v[24:27], v[186:189], v[230:233], v[24:27]
	v_mfma_f32_16x16x32_bf16 v[12:15], v[160:163], v[238:241], v[12:15]
	v_mfma_f32_16x16x32_bf16 v[8:11], v[186:189], v[238:241], v[8:11]
	v_mfma_f32_16x16x32_bf16 v[60:63], v[164:167], v[218:221], v[60:63]
	v_mfma_f32_16x16x32_bf16 v[56:59], v[190:193], v[218:221], v[56:59]
	v_mfma_f32_16x16x32_bf16 v[44:47], v[164:167], v[226:229], v[44:47]
	v_mfma_f32_16x16x32_bf16 v[40:43], v[190:193], v[226:229], v[40:43]
	v_mfma_f32_16x16x32_bf16 v[28:31], v[164:167], v[234:237], v[28:31]
	v_mfma_f32_16x16x32_bf16 v[24:27], v[190:193], v[234:237], v[24:27]
	v_mfma_f32_16x16x32_bf16 v[12:15], v[164:167], v[242:245], v[12:15]
	v_mfma_f32_16x16x32_bf16 v[8:11], v[190:193], v[242:245], v[8:11]
	s_setprio 0
	s_setprio 1
	v_mfma_f32_16x16x32_bf16 v[52:55], v[198:201], v[214:217], v[52:55]
	v_mfma_f32_16x16x32_bf16 v[48:51], v[206:209], v[214:217], v[48:51]
	v_mfma_f32_16x16x32_bf16 v[36:39], v[198:201], v[222:225], v[36:39]
	v_mfma_f32_16x16x32_bf16 v[32:35], v[206:209], v[222:225], v[32:35]
	v_mfma_f32_16x16x32_bf16 v[20:23], v[198:201], v[230:233], v[20:23]
	v_mfma_f32_16x16x32_bf16 v[16:19], v[206:209], v[230:233], v[16:19]
	v_mfma_f32_16x16x32_bf16 v[4:7], v[198:201], v[238:241], v[4:7]
	v_mfma_f32_16x16x32_bf16 v[0:3], v[206:209], v[238:241], v[0:3]
	v_mfma_f32_16x16x32_bf16 v[52:55], v[202:205], v[218:221], v[52:55]
	v_mfma_f32_16x16x32_bf16 v[48:51], v[210:213], v[218:221], v[48:51]
	v_mfma_f32_16x16x32_bf16 v[36:39], v[202:205], v[226:229], v[36:39]
	v_mfma_f32_16x16x32_bf16 v[32:35], v[210:213], v[226:229], v[32:35]
	v_mfma_f32_16x16x32_bf16 v[20:23], v[202:205], v[234:237], v[20:23]
	v_mfma_f32_16x16x32_bf16 v[16:19], v[210:213], v[234:237], v[16:19]
	v_mfma_f32_16x16x32_bf16 v[4:7], v[202:205], v[242:245], v[4:7]
	v_mfma_f32_16x16x32_bf16 v[0:3], v[210:213], v[242:245], v[0:3]
	s_setprio 0
	s_barrier
	ds_read_b128 v[160:163], v177
	ds_read_b128 v[164:167], v178
	ds_read_b128 v[186:189], v179
	ds_read_b128 v[190:193], v180
	ds_read_b128 v[198:201], v181
	ds_read_b128 v[202:205], v182
	ds_read_b128 v[206:209], v183
	ds_read_b128 v[210:213], v184
	s_add_u32 s24, s24, 0x40000
	s_addc_u32 s25, s25, 0
	s_mov_b32 m0, s29
	ds_read_b128 v[214:217], v159 offset:32768
	ds_read_b128 v[218:221], v159 offset:33792
	ds_read_b128 v[222:225], v159 offset:34816
	ds_read_b128 v[226:229], v159 offset:35840
	ds_read_b128 v[230:233], v159 offset:36864
	ds_read_b128 v[234:237], v159 offset:37888
	ds_read_b128 v[238:241], v159 offset:38912
	ds_read_b128 v[242:245], v159 offset:39936
	global_load_lds_dwordx4 v128, s[24:25]
	s_mov_b32 m0, s30
	s_nop 0
	global_load_lds_dwordx4 v130, s[24:25]
	s_waitcnt vmcnt(8)
	s_waitcnt lgkmcnt(0)
	s_barrier
	s_setprio 1
	s_waitcnt lgkmcnt(0)
	v_mfma_f32_16x16x32_bf16 v[124:127], v[160:163], v[214:217], v[124:127]
	v_mfma_f32_16x16x32_bf16 v[120:123], v[186:189], v[214:217], v[120:123]
	v_mfma_f32_16x16x32_bf16 v[108:111], v[160:163], v[222:225], v[108:111]
	v_mfma_f32_16x16x32_bf16 v[104:107], v[186:189], v[222:225], v[104:107]
	v_mfma_f32_16x16x32_bf16 v[92:95], v[160:163], v[230:233], v[92:95]
	v_mfma_f32_16x16x32_bf16 v[88:91], v[186:189], v[230:233], v[88:91]
	v_mfma_f32_16x16x32_bf16 v[76:79], v[160:163], v[238:241], v[76:79]
	v_mfma_f32_16x16x32_bf16 v[72:75], v[186:189], v[238:241], v[72:75]
	v_mfma_f32_16x16x32_bf16 v[124:127], v[164:167], v[218:221], v[124:127]
	v_mfma_f32_16x16x32_bf16 v[120:123], v[190:193], v[218:221], v[120:123]
	v_mfma_f32_16x16x32_bf16 v[108:111], v[164:167], v[226:229], v[108:111]
	v_mfma_f32_16x16x32_bf16 v[104:107], v[190:193], v[226:229], v[104:107]
	v_mfma_f32_16x16x32_bf16 v[92:95], v[164:167], v[234:237], v[92:95]
	v_mfma_f32_16x16x32_bf16 v[88:91], v[190:193], v[234:237], v[88:91]
	v_mfma_f32_16x16x32_bf16 v[76:79], v[164:167], v[242:245], v[76:79]
	v_mfma_f32_16x16x32_bf16 v[72:75], v[190:193], v[242:245], v[72:75]
	s_setprio 0
	s_setprio 1
	v_mfma_f32_16x16x32_bf16 v[116:119], v[198:201], v[214:217], v[116:119]
	v_mfma_f32_16x16x32_bf16 v[112:115], v[206:209], v[214:217], v[112:115]
	v_mfma_f32_16x16x32_bf16 v[100:103], v[198:201], v[222:225], v[100:103]
	v_mfma_f32_16x16x32_bf16 v[96:99], v[206:209], v[222:225], v[96:99]
	v_mfma_f32_16x16x32_bf16 v[84:87], v[198:201], v[230:233], v[84:87]
	v_mfma_f32_16x16x32_bf16 v[80:83], v[206:209], v[230:233], v[80:83]
	v_mfma_f32_16x16x32_bf16 v[68:71], v[198:201], v[238:241], v[68:71]
	v_mfma_f32_16x16x32_bf16 v[64:67], v[206:209], v[238:241], v[64:67]
	v_mfma_f32_16x16x32_bf16 v[116:119], v[202:205], v[218:221], v[116:119]
	v_mfma_f32_16x16x32_bf16 v[112:115], v[210:213], v[218:221], v[112:115]
	v_mfma_f32_16x16x32_bf16 v[100:103], v[202:205], v[226:229], v[100:103]
	v_mfma_f32_16x16x32_bf16 v[96:99], v[210:213], v[226:229], v[96:99]
	v_mfma_f32_16x16x32_bf16 v[84:87], v[202:205], v[234:237], v[84:87]
	v_mfma_f32_16x16x32_bf16 v[80:83], v[210:213], v[234:237], v[80:83]
	v_mfma_f32_16x16x32_bf16 v[68:71], v[202:205], v[242:245], v[68:71]
	v_mfma_f32_16x16x32_bf16 v[64:67], v[210:213], v[242:245], v[64:67]
	s_setprio 0
	s_barrier
	s_mov_b32 m0, s31
	s_add_u32 s18, s18, 0x40080
	ds_read_b128 v[214:217], v159 offset:49152
	ds_read_b128 v[218:221], v159 offset:50176
	ds_read_b128 v[222:225], v159 offset:51200
	ds_read_b128 v[226:229], v159 offset:52224
	ds_read_b128 v[230:233], v159 offset:53248
	ds_read_b128 v[234:237], v159 offset:54272
	ds_read_b128 v[238:241], v159 offset:55296
	ds_read_b128 v[242:245], v159 offset:56320
	global_load_lds_dwordx4 v128, s[98:99]
	s_mov_b32 m0, s33
	s_addc_u32 s19, s19, 0
	global_load_lds_dwordx4 v130, s[98:99]
	s_mov_b32 m0, s36
	s_add_u32 s16, s16, 0x100
	global_load_lds_dwordx4 v128, s[18:19]
	s_mov_b32 m0, s37
	s_addc_u32 s17, s17, 0
	global_load_lds_dwordx4 v130, s[18:19]
	s_mov_b32 m0, s34
	s_add_u32 s47, s47, 0x100
	global_load_lds_dwordx4 v128, s[100:101]
	s_mov_b32 m0, s35
	s_addc_u32 s49, s49, 0
	global_load_lds_dwordx4 v130, s[100:101]
	s_waitcnt vmcnt(8)
	s_waitcnt lgkmcnt(0)
	s_barrier
	s_setprio 1
	s_waitcnt lgkmcnt(0)
	v_mfma_f32_16x16x32_bf16 v[60:63], v[160:163], v[214:217], v[60:63]
	v_mfma_f32_16x16x32_bf16 v[56:59], v[186:189], v[214:217], v[56:59]
	v_mfma_f32_16x16x32_bf16 v[44:47], v[160:163], v[222:225], v[44:47]
	v_mfma_f32_16x16x32_bf16 v[40:43], v[186:189], v[222:225], v[40:43]
	v_mfma_f32_16x16x32_bf16 v[28:31], v[160:163], v[230:233], v[28:31]
	v_mfma_f32_16x16x32_bf16 v[24:27], v[186:189], v[230:233], v[24:27]
	v_mfma_f32_16x16x32_bf16 v[12:15], v[160:163], v[238:241], v[12:15]
	v_mfma_f32_16x16x32_bf16 v[8:11], v[186:189], v[238:241], v[8:11]
	v_mfma_f32_16x16x32_bf16 v[60:63], v[164:167], v[218:221], v[60:63]
	v_mfma_f32_16x16x32_bf16 v[56:59], v[190:193], v[218:221], v[56:59]
	v_mfma_f32_16x16x32_bf16 v[44:47], v[164:167], v[226:229], v[44:47]
	v_mfma_f32_16x16x32_bf16 v[40:43], v[190:193], v[226:229], v[40:43]
	v_mfma_f32_16x16x32_bf16 v[28:31], v[164:167], v[234:237], v[28:31]
	v_mfma_f32_16x16x32_bf16 v[24:27], v[190:193], v[234:237], v[24:27]
	v_mfma_f32_16x16x32_bf16 v[12:15], v[164:167], v[242:245], v[12:15]
	v_mfma_f32_16x16x32_bf16 v[8:11], v[190:193], v[242:245], v[8:11]
	s_setprio 0
	s_setprio 1
	v_mfma_f32_16x16x32_bf16 v[52:55], v[198:201], v[214:217], v[52:55]
	v_mfma_f32_16x16x32_bf16 v[48:51], v[206:209], v[214:217], v[48:51]
	v_mfma_f32_16x16x32_bf16 v[36:39], v[198:201], v[222:225], v[36:39]
	v_mfma_f32_16x16x32_bf16 v[32:35], v[206:209], v[222:225], v[32:35]
	v_mfma_f32_16x16x32_bf16 v[20:23], v[198:201], v[230:233], v[20:23]
	v_mfma_f32_16x16x32_bf16 v[16:19], v[206:209], v[230:233], v[16:19]
	v_mfma_f32_16x16x32_bf16 v[4:7], v[198:201], v[238:241], v[4:7]
	v_mfma_f32_16x16x32_bf16 v[0:3], v[206:209], v[238:241], v[0:3]
	v_mfma_f32_16x16x32_bf16 v[52:55], v[202:205], v[218:221], v[52:55]
	v_mfma_f32_16x16x32_bf16 v[48:51], v[210:213], v[218:221], v[48:51]
	v_mfma_f32_16x16x32_bf16 v[36:39], v[202:205], v[226:229], v[36:39]
	v_mfma_f32_16x16x32_bf16 v[32:35], v[210:213], v[226:229], v[32:35]
	v_mfma_f32_16x16x32_bf16 v[20:23], v[202:205], v[234:237], v[20:23]
	v_mfma_f32_16x16x32_bf16 v[16:19], v[210:213], v[234:237], v[16:19]
	v_mfma_f32_16x16x32_bf16 v[4:7], v[202:205], v[242:245], v[4:7]
	v_mfma_f32_16x16x32_bf16 v[0:3], v[210:213], v[242:245], v[0:3]
	s_setprio 0
	s_barrier
	s_add_i32 s66, s66, 2
	s_cmp_gt_u32 s66, 13
	s_cbranch_scc0 .LBB0_2152
	s_and_b64 vcc, exec, s[44:45]
	s_cbranch_vccz .LBB0_2155
	s_barrier

.LBB0_2530:
	ds_read_b128 v[140:143], v162
	ds_read_b128 v[178:181], v163
	ds_read_b128 v[182:185], v164
	ds_read_b128 v[186:189], v165
	ds_read_b128 v[190:193], v166
	ds_read_b128 v[198:201], v167
	ds_read_b128 v[202:205], v168
	ds_read_b128 v[206:209], v169
	s_add_u32 s16, s0, 0xfffe0080
	s_addc_u32 s17, s1, -1
	s_cmp_eq_u32 s64, 4
	s_cselect_b32 s19, s4, s17
	s_cselect_b32 s18, s5, s16
	s_cselect_b32 s17, s13, s51
	s_cselect_b32 s16, s15, s49
	s_mov_b32 m0, s77
	ds_read_b128 v[210:213], v160
	ds_read_b128 v[214:217], v160 offset:1024
	ds_read_b128 v[218:221], v160 offset:2048
	ds_read_b128 v[222:225], v160 offset:3072
	ds_read_b128 v[226:229], v160 offset:4096
	ds_read_b128 v[230:233], v160 offset:5120
	ds_read_b128 v[234:237], v160 offset:6144
	ds_read_b128 v[238:241], v160 offset:7168
	global_load_lds_dwordx4 v132, s[0:1]
	s_mov_b32 m0, s78
	s_nop 0
	global_load_lds_dwordx4 v134, s[0:1]
	s_waitcnt vmcnt(8)
	s_waitcnt lgkmcnt(0)
	s_barrier
	s_setprio 1
	s_waitcnt lgkmcnt(0)
	v_mfma_f32_16x16x32_bf16 v[124:127], v[140:143], v[210:213], v[124:127]
	v_mfma_f32_16x16x32_bf16 v[120:123], v[182:185], v[210:213], v[120:123]
	v_mfma_f32_16x16x32_bf16 v[108:111], v[140:143], v[218:221], v[108:111]
	v_mfma_f32_16x16x32_bf16 v[104:107], v[182:185], v[218:221], v[104:107]
	v_mfma_f32_16x16x32_bf16 v[92:95], v[140:143], v[226:229], v[92:95]
	v_mfma_f32_16x16x32_bf16 v[88:91], v[182:185], v[226:229], v[88:91]
	v_mfma_f32_16x16x32_bf16 v[76:79], v[140:143], v[234:237], v[76:79]
	v_mfma_f32_16x16x32_bf16 v[72:75], v[182:185], v[234:237], v[72:75]
	v_mfma_f32_16x16x32_bf16 v[124:127], v[178:181], v[214:217], v[124:127]
	v_mfma_f32_16x16x32_bf16 v[120:123], v[186:189], v[214:217], v[120:123]
	v_mfma_f32_16x16x32_bf16 v[108:111], v[178:181], v[222:225], v[108:111]
	v_mfma_f32_16x16x32_bf16 v[104:107], v[186:189], v[222:225], v[104:107]
	v_mfma_f32_16x16x32_bf16 v[92:95], v[178:181], v[230:233], v[92:95]
	v_mfma_f32_16x16x32_bf16 v[88:91], v[186:189], v[230:233], v[88:91]
	v_mfma_f32_16x16x32_bf16 v[76:79], v[178:181], v[238:241], v[76:79]
	v_mfma_f32_16x16x32_bf16 v[72:75], v[186:189], v[238:241], v[72:75]
	s_setprio 0
	s_setprio 1
	v_mfma_f32_16x16x32_bf16 v[116:119], v[190:193], v[210:213], v[116:119]
	v_mfma_f32_16x16x32_bf16 v[112:115], v[202:205], v[210:213], v[112:115]
	v_mfma_f32_16x16x32_bf16 v[100:103], v[190:193], v[218:221], v[100:103]
	v_mfma_f32_16x16x32_bf16 v[96:99], v[202:205], v[218:221], v[96:99]
	v_mfma_f32_16x16x32_bf16 v[84:87], v[190:193], v[226:229], v[84:87]
	v_mfma_f32_16x16x32_bf16 v[80:83], v[202:205], v[226:229], v[80:83]
	v_mfma_f32_16x16x32_bf16 v[68:71], v[190:193], v[234:237], v[68:71]
	v_mfma_f32_16x16x32_bf16 v[64:67], v[202:205], v[234:237], v[64:67]
	v_mfma_f32_16x16x32_bf16 v[116:119], v[198:201], v[214:217], v[116:119]
	v_mfma_f32_16x16x32_bf16 v[112:115], v[206:209], v[214:217], v[112:115]
	v_mfma_f32_16x16x32_bf16 v[100:103], v[198:201], v[222:225], v[100:103]
	v_mfma_f32_16x16x32_bf16 v[96:99], v[206:209], v[222:225], v[96:99]
	v_mfma_f32_16x16x32_bf16 v[84:87], v[198:201], v[230:233], v[84:87]
	v_mfma_f32_16x16x32_bf16 v[80:83], v[206:209], v[230:233], v[80:83]
	v_mfma_f32_16x16x32_bf16 v[68:71], v[198:201], v[238:241], v[68:71]
	v_mfma_f32_16x16x32_bf16 v[64:67], v[206:209], v[238:241], v[64:67]
	s_setprio 0
	s_barrier
	s_mov_b32 m0, s6
	s_add_u32 s68, s16, 0x20000
	ds_read_b128 v[210:213], v160 offset:16384
	ds_read_b128 v[214:217], v160 offset:17408
	ds_read_b128 v[218:221], v160 offset:18432
	ds_read_b128 v[222:225], v160 offset:19456
	ds_read_b128 v[226:229], v160 offset:20480
	ds_read_b128 v[230:233], v160 offset:21504
	ds_read_b128 v[234:237], v160 offset:22528
	ds_read_b128 v[238:241], v160 offset:23552
	global_load_lds_dwordx4 v128, s[16:17]
	s_mov_b32 m0, s7
	s_addc_u32 s69, s17, 0
	global_load_lds_dwordx4 v130, s[16:17]
	s_mov_b32 m0, s8
	s_add_u32 s98, s16, s44
	global_load_lds_dwordx4 v128, s[68:69]
	s_mov_b32 m0, s9
	s_addc_u32 s99, s17, s45
	global_load_lds_dwordx4 v130, s[68:69]
	s_mov_b32 m0, s2
	s_add_u32 s100, s18, s44
	global_load_lds_dwordx4 v128, s[18:19]
	s_mov_b32 m0, s28
	s_addc_u32 s101, s19, s45
	global_load_lds_dwordx4 v130, s[18:19]
	s_waitcnt vmcnt(8)
	s_waitcnt lgkmcnt(0)
	s_barrier
	s_setprio 1
	s_waitcnt lgkmcnt(0)
	v_mfma_f32_16x16x32_bf16 v[60:63], v[140:143], v[210:213], v[60:63]
	v_mfma_f32_16x16x32_bf16 v[56:59], v[182:185], v[210:213], v[56:59]
	v_mfma_f32_16x16x32_bf16 v[44:47], v[140:143], v[218:221], v[44:47]
	v_mfma_f32_16x16x32_bf16 v[40:43], v[182:185], v[218:221], v[40:43]
	v_mfma_f32_16x16x32_bf16 v[28:31], v[140:143], v[226:229], v[28:31]
	v_mfma_f32_16x16x32_bf16 v[24:27], v[182:185], v[226:229], v[24:27]
	v_mfma_f32_16x16x32_bf16 v[12:15], v[140:143], v[234:237], v[12:15]
	v_mfma_f32_16x16x32_bf16 v[8:11], v[182:185], v[234:237], v[8:11]
	v_mfma_f32_16x16x32_bf16 v[60:63], v[178:181], v[214:217], v[60:63]
	v_mfma_f32_16x16x32_bf16 v[56:59], v[186:189], v[214:217], v[56:59]
	v_mfma_f32_16x16x32_bf16 v[44:47], v[178:181], v[222:225], v[44:47]
	v_mfma_f32_16x16x32_bf16 v[40:43], v[186:189], v[222:225], v[40:43]
	v_mfma_f32_16x16x32_bf16 v[28:31], v[178:181], v[230:233], v[28:31]
	v_mfma_f32_16x16x32_bf16 v[24:27], v[186:189], v[230:233], v[24:27]
	v_mfma_f32_16x16x32_bf16 v[12:15], v[178:181], v[238:241], v[12:15]
	v_mfma_f32_16x16x32_bf16 v[8:11], v[186:189], v[238:241], v[8:11]
	s_setprio 0
	s_setprio 1
	v_mfma_f32_16x16x32_bf16 v[52:55], v[190:193], v[210:213], v[52:55]
	v_mfma_f32_16x16x32_bf16 v[48:51], v[202:205], v[210:213], v[48:51]
	v_mfma_f32_16x16x32_bf16 v[36:39], v[190:193], v[218:221], v[36:39]
	v_mfma_f32_16x16x32_bf16 v[32:35], v[202:205], v[218:221], v[32:35]
	v_mfma_f32_16x16x32_bf16 v[20:23], v[190:193], v[226:229], v[20:23]
	v_mfma_f32_16x16x32_bf16 v[16:19], v[202:205], v[226:229], v[16:19]
	v_mfma_f32_16x16x32_bf16 v[4:7], v[190:193], v[234:237], v[4:7]
	v_mfma_f32_16x16x32_bf16 v[0:3], v[202:205], v[234:237], v[0:3]
	v_mfma_f32_16x16x32_bf16 v[52:55], v[198:201], v[214:217], v[52:55]
	v_mfma_f32_16x16x32_bf16 v[48:51], v[206:209], v[214:217], v[48:51]
	v_mfma_f32_16x16x32_bf16 v[36:39], v[198:201], v[222:225], v[36:39]
	v_mfma_f32_16x16x32_bf16 v[32:35], v[206:209], v[222:225], v[32:35]
	v_mfma_f32_16x16x32_bf16 v[20:23], v[198:201], v[230:233], v[20:23]
	v_mfma_f32_16x16x32_bf16 v[16:19], v[206:209], v[230:233], v[16:19]
	v_mfma_f32_16x16x32_bf16 v[4:7], v[198:201], v[238:241], v[4:7]
	v_mfma_f32_16x16x32_bf16 v[0:3], v[206:209], v[238:241], v[0:3]
	s_setprio 0
	s_barrier
	ds_read_b128 v[140:143], v170
	ds_read_b128 v[178:181], v171
	ds_read_b128 v[182:185], v172
	ds_read_b128 v[186:189], v173
	ds_read_b128 v[190:193], v174
	ds_read_b128 v[198:201], v175
	ds_read_b128 v[202:205], v176
	ds_read_b128 v[206:209], v177
	s_add_u32 s18, s18, 0x20000
	s_addc_u32 s19, s19, 0
	s_mov_b32 m0, s29
	ds_read_b128 v[210:213], v160 offset:32768
	ds_read_b128 v[214:217], v160 offset:33792
	ds_read_b128 v[218:221], v160 offset:34816
	ds_read_b128 v[222:225], v160 offset:35840
	ds_read_b128 v[226:229], v160 offset:36864
	ds_read_b128 v[230:233], v160 offset:37888
	ds_read_b128 v[234:237], v160 offset:38912
	ds_read_b128 v[238:241], v160 offset:39936
	global_load_lds_dwordx4 v128, s[18:19]
	s_mov_b32 m0, s30
	s_nop 0
	global_load_lds_dwordx4 v130, s[18:19]
	s_waitcnt vmcnt(8)
	s_waitcnt lgkmcnt(0)
	s_barrier
	s_setprio 1
	s_waitcnt lgkmcnt(0)
	v_mfma_f32_16x16x32_bf16 v[124:127], v[140:143], v[210:213], v[124:127]
	v_mfma_f32_16x16x32_bf16 v[120:123], v[182:185], v[210:213], v[120:123]
	v_mfma_f32_16x16x32_bf16 v[108:111], v[140:143], v[218:221], v[108:111]
	v_mfma_f32_16x16x32_bf16 v[104:107], v[182:185], v[218:221], v[104:107]
	v_mfma_f32_16x16x32_bf16 v[92:95], v[140:143], v[226:229], v[92:95]
	v_mfma_f32_16x16x32_bf16 v[88:91], v[182:185], v[226:229], v[88:91]
	v_mfma_f32_16x16x32_bf16 v[76:79], v[140:143], v[234:237], v[76:79]
	v_mfma_f32_16x16x32_bf16 v[72:75], v[182:185], v[234:237], v[72:75]
	v_mfma_f32_16x16x32_bf16 v[124:127], v[178:181], v[214:217], v[124:127]
	v_mfma_f32_16x16x32_bf16 v[120:123], v[186:189], v[214:217], v[120:123]
	v_mfma_f32_16x16x32_bf16 v[108:111], v[178:181], v[222:225], v[108:111]
	v_mfma_f32_16x16x32_bf16 v[104:107], v[186:189], v[222:225], v[104:107]
	v_mfma_f32_16x16x32_bf16 v[92:95], v[178:181], v[230:233], v[92:95]
	v_mfma_f32_16x16x32_bf16 v[88:91], v[186:189], v[230:233], v[88:91]
	v_mfma_f32_16x16x32_bf16 v[76:79], v[178:181], v[238:241], v[76:79]
	v_mfma_f32_16x16x32_bf16 v[72:75], v[186:189], v[238:241], v[72:75]
	s_setprio 0
	s_setprio 1
	v_mfma_f32_16x16x32_bf16 v[116:119], v[190:193], v[210:213], v[116:119]
	v_mfma_f32_16x16x32_bf16 v[112:115], v[202:205], v[210:213], v[112:115]
	v_mfma_f32_16x16x32_bf16 v[100:103], v[190:193], v[218:221], v[100:103]
	v_mfma_f32_16x16x32_bf16 v[96:99], v[202:205], v[218:221], v[96:99]
	v_mfma_f32_16x16x32_bf16 v[84:87], v[190:193], v[226:229], v[84:87]
	v_mfma_f32_16x16x32_bf16 v[80:83], v[202:205], v[226:229], v[80:83]
	v_mfma_f32_16x16x32_bf16 v[68:71], v[190:193], v[234:237], v[68:71]
	v_mfma_f32_16x16x32_bf16 v[64:67], v[202:205], v[234:237], v[64:67]
	v_mfma_f32_16x16x32_bf16 v[116:119], v[198:201], v[214:217], v[116:119]
	v_mfma_f32_16x16x32_bf16 v[112:115], v[206:209], v[214:217], v[112:115]
	v_mfma_f32_16x16x32_bf16 v[100:103], v[198:201], v[222:225], v[100:103]
	v_mfma_f32_16x16x32_bf16 v[96:99], v[206:209], v[222:225], v[96:99]
	v_mfma_f32_16x16x32_bf16 v[84:87], v[198:201], v[230:233], v[84:87]
	v_mfma_f32_16x16x32_bf16 v[80:83], v[206:209], v[230:233], v[80:83]
	v_mfma_f32_16x16x32_bf16 v[68:71], v[198:201], v[238:241], v[68:71]
	v_mfma_f32_16x16x32_bf16 v[64:67], v[206:209], v[238:241], v[64:67]
	s_setprio 0
	s_barrier
	s_mov_b32 m0, s31
	s_add_u32 s16, s16, 0x20080
	ds_read_b128 v[210:213], v160 offset:49152
	ds_read_b128 v[214:217], v160 offset:50176
	ds_read_b128 v[218:221], v160 offset:51200
	ds_read_b128 v[222:225], v160 offset:52224
	ds_read_b128 v[226:229], v160 offset:53248
	ds_read_b128 v[230:233], v160 offset:54272
	ds_read_b128 v[234:237], v160 offset:55296
	ds_read_b128 v[238:241], v160 offset:56320
	global_load_lds_dwordx4 v128, s[98:99]
	s_mov_b32 m0, s33
	s_addc_u32 s17, s17, 0
	global_load_lds_dwordx4 v130, s[98:99]
	s_mov_b32 m0, s36
	s_add_u32 s0, s0, 0x100
	global_load_lds_dwordx4 v128, s[16:17]
	s_mov_b32 m0, s37
	s_addc_u32 s1, s1, 0
	global_load_lds_dwordx4 v130, s[16:17]
	s_mov_b32 m0, s34
	s_add_u32 s49, s49, 0x100
	global_load_lds_dwordx4 v128, s[100:101]
	s_mov_b32 m0, s35
	s_addc_u32 s51, s51, 0
	global_load_lds_dwordx4 v130, s[100:101]
	s_waitcnt vmcnt(8)
	s_waitcnt lgkmcnt(0)
	s_barrier
	s_setprio 1
	s_waitcnt lgkmcnt(0)
	v_mfma_f32_16x16x32_bf16 v[60:63], v[140:143], v[210:213], v[60:63]
	v_mfma_f32_16x16x32_bf16 v[56:59], v[182:185], v[210:213], v[56:59]
	v_mfma_f32_16x16x32_bf16 v[44:47], v[140:143], v[218:221], v[44:47]
	v_mfma_f32_16x16x32_bf16 v[40:43], v[182:185], v[218:221], v[40:43]
	v_mfma_f32_16x16x32_bf16 v[28:31], v[140:143], v[226:229], v[28:31]
	v_mfma_f32_16x16x32_bf16 v[24:27], v[182:185], v[226:229], v[24:27]
	v_mfma_f32_16x16x32_bf16 v[12:15], v[140:143], v[234:237], v[12:15]
	v_mfma_f32_16x16x32_bf16 v[8:11], v[182:185], v[234:237], v[8:11]
	v_mfma_f32_16x16x32_bf16 v[60:63], v[178:181], v[214:217], v[60:63]
	v_mfma_f32_16x16x32_bf16 v[56:59], v[186:189], v[214:217], v[56:59]
	v_mfma_f32_16x16x32_bf16 v[44:47], v[178:181], v[222:225], v[44:47]
	v_mfma_f32_16x16x32_bf16 v[40:43], v[186:189], v[222:225], v[40:43]
	v_mfma_f32_16x16x32_bf16 v[28:31], v[178:181], v[230:233], v[28:31]
	v_mfma_f32_16x16x32_bf16 v[24:27], v[186:189], v[230:233], v[24:27]
	v_mfma_f32_16x16x32_bf16 v[12:15], v[178:181], v[238:241], v[12:15]
	v_mfma_f32_16x16x32_bf16 v[8:11], v[186:189], v[238:241], v[8:11]
	s_setprio 0
	s_setprio 1
	v_mfma_f32_16x16x32_bf16 v[52:55], v[190:193], v[210:213], v[52:55]
	v_mfma_f32_16x16x32_bf16 v[48:51], v[202:205], v[210:213], v[48:51]
	v_mfma_f32_16x16x32_bf16 v[36:39], v[190:193], v[218:221], v[36:39]
	v_mfma_f32_16x16x32_bf16 v[32:35], v[202:205], v[218:221], v[32:35]
	v_mfma_f32_16x16x32_bf16 v[20:23], v[190:193], v[226:229], v[20:23]
	v_mfma_f32_16x16x32_bf16 v[16:19], v[202:205], v[226:229], v[16:19]
	v_mfma_f32_16x16x32_bf16 v[4:7], v[190:193], v[234:237], v[4:7]
	v_mfma_f32_16x16x32_bf16 v[0:3], v[202:205], v[234:237], v[0:3]
	v_mfma_f32_16x16x32_bf16 v[52:55], v[198:201], v[214:217], v[52:55]
	v_mfma_f32_16x16x32_bf16 v[48:51], v[206:209], v[214:217], v[48:51]
	v_mfma_f32_16x16x32_bf16 v[36:39], v[198:201], v[222:225], v[36:39]
	v_mfma_f32_16x16x32_bf16 v[32:35], v[206:209], v[222:225], v[32:35]
	v_mfma_f32_16x16x32_bf16 v[20:23], v[198:201], v[230:233], v[20:23]
	v_mfma_f32_16x16x32_bf16 v[16:19], v[206:209], v[230:233], v[16:19]
	v_mfma_f32_16x16x32_bf16 v[4:7], v[198:201], v[238:241], v[4:7]
	v_mfma_f32_16x16x32_bf16 v[0:3], v[206:209], v[238:241], v[0:3]
	s_setprio 0
	s_barrier
	s_add_i32 s64, s64, 2
	s_cmp_gt_u32 s64, 5
	s_cbranch_scc0 .LBB0_2530
	s_and_b64 vcc, exec, s[46:47]
	s_cbranch_vccz .LBB0_2533
	s_barrier

.LBB0_2628:
	s_add_u32 s65, s48, s64
	s_addc_u32 s70, s49, 0
	s_add_u32 s71, s65, 0x100
	s_addc_u32 s74, s70, 0
	s_and_b64 s[68:69], s[54:55], exec
	s_cselect_b32 s75, s4, s74
	s_cselect_b32 s74, s5, s71
	s_add_u32 s64, s46, s64
	s_addc_u32 s68, s47, 0
	s_add_u32 s64, s64, 0x100
	ds_read_b128 v[170:173], v141
	ds_read_b128 v[174:177], v142
	ds_read_b128 v[178:181], v143
	ds_read_b128 v[182:185], v153
	ds_read_b128 v[186:189], v158
	ds_read_b128 v[190:193], v159
	ds_read_b128 v[196:199], v160
	ds_read_b128 v[200:203], v161
	s_addc_u32 s68, s68, 0
	s_and_b64 s[54:55], s[54:55], exec
	s_cselect_b32 s79, s21, s68
	s_cselect_b32 s78, s23, s64
	s_add_u32 s82, s65, 0x10080
	s_addc_u32 s83, s70, 0
	s_add_u32 s80, s78, 0x10000
	s_addc_u32 s81, s79, 0
	s_add_u32 s64, s74, 0x10000
	s_addc_u32 s65, s75, 0
	s_add_u32 s54, s78, 0x10080
	s_addc_u32 s55, s79, 0
	s_mov_b32 m0, s35
	ds_read_b128 v[204:207], v139
	ds_read_b128 v[208:211], v139 offset:1024
	ds_read_b128 v[212:215], v139 offset:2048
	ds_read_b128 v[216:219], v139 offset:3072
	ds_read_b128 v[220:223], v139 offset:4096
	ds_read_b128 v[224:227], v139 offset:5120
	ds_read_b128 v[228:231], v139 offset:6144
	ds_read_b128 v[232:235], v139 offset:7168
	global_load_lds_dwordx4 v128, s[82:83]
	s_mov_b32 m0, s60
	s_nop 0
	global_load_lds_dwordx4 v130, s[82:83]
	s_waitcnt vmcnt(8)
	s_waitcnt lgkmcnt(0)
	s_barrier
	s_setprio 1
	s_waitcnt lgkmcnt(0)
	v_mfma_f32_16x16x32_bf16 v[124:127], v[170:173], v[204:207], v[124:127]
	v_mfma_f32_16x16x32_bf16 v[120:123], v[178:181], v[204:207], v[120:123]
	v_mfma_f32_16x16x32_bf16 v[108:111], v[170:173], v[212:215], v[108:111]
	v_mfma_f32_16x16x32_bf16 v[104:107], v[178:181], v[212:215], v[104:107]
	v_mfma_f32_16x16x32_bf16 v[92:95], v[170:173], v[220:223], v[92:95]
	v_mfma_f32_16x16x32_bf16 v[88:91], v[178:181], v[220:223], v[88:91]
	v_mfma_f32_16x16x32_bf16 v[76:79], v[170:173], v[228:231], v[76:79]
	v_mfma_f32_16x16x32_bf16 v[72:75], v[178:181], v[228:231], v[72:75]
	v_mfma_f32_16x16x32_bf16 v[124:127], v[174:177], v[208:211], v[124:127]
	v_mfma_f32_16x16x32_bf16 v[120:123], v[182:185], v[208:211], v[120:123]
	v_mfma_f32_16x16x32_bf16 v[108:111], v[174:177], v[216:219], v[108:111]
	v_mfma_f32_16x16x32_bf16 v[104:107], v[182:185], v[216:219], v[104:107]
	v_mfma_f32_16x16x32_bf16 v[92:95], v[174:177], v[224:227], v[92:95]
	v_mfma_f32_16x16x32_bf16 v[88:91], v[182:185], v[224:227], v[88:91]
	v_mfma_f32_16x16x32_bf16 v[76:79], v[174:177], v[232:235], v[76:79]
	v_mfma_f32_16x16x32_bf16 v[72:75], v[182:185], v[232:235], v[72:75]
	s_setprio 0
	s_setprio 1
	v_mfma_f32_16x16x32_bf16 v[116:119], v[186:189], v[204:207], v[116:119]
	v_mfma_f32_16x16x32_bf16 v[112:115], v[196:199], v[204:207], v[112:115]
	v_mfma_f32_16x16x32_bf16 v[100:103], v[186:189], v[212:215], v[100:103]
	v_mfma_f32_16x16x32_bf16 v[96:99], v[196:199], v[212:215], v[96:99]
	v_mfma_f32_16x16x32_bf16 v[84:87], v[186:189], v[220:223], v[84:87]
	v_mfma_f32_16x16x32_bf16 v[80:83], v[196:199], v[220:223], v[80:83]
	v_mfma_f32_16x16x32_bf16 v[68:71], v[186:189], v[228:231], v[68:71]
	v_mfma_f32_16x16x32_bf16 v[64:67], v[196:199], v[228:231], v[64:67]
	v_mfma_f32_16x16x32_bf16 v[116:119], v[190:193], v[208:211], v[116:119]
	v_mfma_f32_16x16x32_bf16 v[112:115], v[200:203], v[208:211], v[112:115]
	v_mfma_f32_16x16x32_bf16 v[100:103], v[190:193], v[216:219], v[100:103]
	v_mfma_f32_16x16x32_bf16 v[96:99], v[200:203], v[216:219], v[96:99]
	v_mfma_f32_16x16x32_bf16 v[84:87], v[190:193], v[224:227], v[84:87]
	v_mfma_f32_16x16x32_bf16 v[80:83], v[200:203], v[224:227], v[80:83]
	v_mfma_f32_16x16x32_bf16 v[68:71], v[190:193], v[232:235], v[68:71]
	v_mfma_f32_16x16x32_bf16 v[64:67], v[200:203], v[232:235], v[64:67]
	s_setprio 0
	s_barrier
	s_mov_b32 m0, s45
	ds_read_b128 v[204:207], v139 offset:16384
	ds_read_b128 v[208:211], v139 offset:17408
	ds_read_b128 v[212:215], v139 offset:18432
	ds_read_b128 v[216:219], v139 offset:19456
	ds_read_b128 v[220:223], v139 offset:20480
	ds_read_b128 v[224:227], v139 offset:21504
	ds_read_b128 v[228:231], v139 offset:22528
	ds_read_b128 v[232:235], v139 offset:23552
	global_load_lds_dwordx4 v128, s[78:79]
	s_mov_b32 m0, s67
	s_nop 0
	global_load_lds_dwordx4 v130, s[78:79]
	s_mov_b32 m0, s84
	s_add_u32 s98, s78, s16
	global_load_lds_dwordx4 v128, s[80:81]
	s_mov_b32 m0, s85
	s_addc_u32 s99, s79, s17
	global_load_lds_dwordx4 v130, s[80:81]
	s_mov_b32 m0, s30
	s_add_u32 s100, s74, s16
	global_load_lds_dwordx4 v128, s[74:75]
	s_mov_b32 m0, s86
	s_addc_u32 s101, s75, s17
	global_load_lds_dwordx4 v130, s[74:75]
	s_waitcnt vmcnt(8)
	s_waitcnt lgkmcnt(0)
	s_barrier
	s_setprio 1
	s_waitcnt lgkmcnt(0)
	v_mfma_f32_16x16x32_bf16 v[60:63], v[170:173], v[204:207], v[60:63]
	v_mfma_f32_16x16x32_bf16 v[56:59], v[178:181], v[204:207], v[56:59]
	v_mfma_f32_16x16x32_bf16 v[44:47], v[170:173], v[212:215], v[44:47]
	v_mfma_f32_16x16x32_bf16 v[40:43], v[178:181], v[212:215], v[40:43]
	v_mfma_f32_16x16x32_bf16 v[28:31], v[170:173], v[220:223], v[28:31]
	v_mfma_f32_16x16x32_bf16 v[24:27], v[178:181], v[220:223], v[24:27]
	v_mfma_f32_16x16x32_bf16 v[12:15], v[170:173], v[228:231], v[12:15]
	v_mfma_f32_16x16x32_bf16 v[8:11], v[178:181], v[228:231], v[8:11]
	v_mfma_f32_16x16x32_bf16 v[60:63], v[174:177], v[208:211], v[60:63]
	v_mfma_f32_16x16x32_bf16 v[56:59], v[182:185], v[208:211], v[56:59]
	v_mfma_f32_16x16x32_bf16 v[44:47], v[174:177], v[216:219], v[44:47]
	v_mfma_f32_16x16x32_bf16 v[40:43], v[182:185], v[216:219], v[40:43]
	v_mfma_f32_16x16x32_bf16 v[28:31], v[174:177], v[224:227], v[28:31]
	v_mfma_f32_16x16x32_bf16 v[24:27], v[182:185], v[224:227], v[24:27]
	v_mfma_f32_16x16x32_bf16 v[12:15], v[174:177], v[232:235], v[12:15]
	v_mfma_f32_16x16x32_bf16 v[8:11], v[182:185], v[232:235], v[8:11]
	s_setprio 0
	s_setprio 1
	v_mfma_f32_16x16x32_bf16 v[52:55], v[186:189], v[204:207], v[52:55]
	v_mfma_f32_16x16x32_bf16 v[48:51], v[196:199], v[204:207], v[48:51]
	v_mfma_f32_16x16x32_bf16 v[36:39], v[186:189], v[212:215], v[36:39]
	v_mfma_f32_16x16x32_bf16 v[32:35], v[196:199], v[212:215], v[32:35]
	v_mfma_f32_16x16x32_bf16 v[20:23], v[186:189], v[220:223], v[20:23]
	v_mfma_f32_16x16x32_bf16 v[16:19], v[196:199], v[220:223], v[16:19]
	v_mfma_f32_16x16x32_bf16 v[4:7], v[186:189], v[228:231], v[4:7]
	v_mfma_f32_16x16x32_bf16 v[0:3], v[196:199], v[228:231], v[0:3]
	v_mfma_f32_16x16x32_bf16 v[52:55], v[190:193], v[208:211], v[52:55]
	v_mfma_f32_16x16x32_bf16 v[48:51], v[200:203], v[208:211], v[48:51]
	v_mfma_f32_16x16x32_bf16 v[36:39], v[190:193], v[216:219], v[36:39]
	v_mfma_f32_16x16x32_bf16 v[32:35], v[200:203], v[216:219], v[32:35]
	v_mfma_f32_16x16x32_bf16 v[20:23], v[190:193], v[224:227], v[20:23]
	v_mfma_f32_16x16x32_bf16 v[16:19], v[200:203], v[224:227], v[16:19]
	v_mfma_f32_16x16x32_bf16 v[4:7], v[190:193], v[232:235], v[4:7]
	v_mfma_f32_16x16x32_bf16 v[0:3], v[200:203], v[232:235], v[0:3]
	s_setprio 0
	s_barrier
	ds_read_b128 v[170:173], v162
	ds_read_b128 v[174:177], v163
	ds_read_b128 v[178:181], v164
	ds_read_b128 v[182:185], v165
	ds_read_b128 v[186:189], v166
	ds_read_b128 v[190:193], v167
	ds_read_b128 v[196:199], v168
	ds_read_b128 v[200:203], v169
	s_mov_b32 m0, s87
	ds_read_b128 v[204:207], v139 offset:32768
	ds_read_b128 v[208:211], v139 offset:33792
	ds_read_b128 v[212:215], v139 offset:34816
	ds_read_b128 v[216:219], v139 offset:35840
	ds_read_b128 v[220:223], v139 offset:36864
	ds_read_b128 v[224:227], v139 offset:37888
	ds_read_b128 v[228:231], v139 offset:38912
	ds_read_b128 v[232:235], v139 offset:39936
	global_load_lds_dwordx4 v128, s[64:65]
	s_mov_b32 m0, s90
	s_nop 0
	global_load_lds_dwordx4 v130, s[64:65]
	s_waitcnt vmcnt(8)
	s_waitcnt lgkmcnt(0)
	s_barrier
	s_setprio 1
	s_waitcnt lgkmcnt(0)
	v_mfma_f32_16x16x32_bf16 v[124:127], v[170:173], v[204:207], v[124:127]
	v_mfma_f32_16x16x32_bf16 v[120:123], v[178:181], v[204:207], v[120:123]
	v_mfma_f32_16x16x32_bf16 v[108:111], v[170:173], v[212:215], v[108:111]
	v_mfma_f32_16x16x32_bf16 v[104:107], v[178:181], v[212:215], v[104:107]
	v_mfma_f32_16x16x32_bf16 v[92:95], v[170:173], v[220:223], v[92:95]
	v_mfma_f32_16x16x32_bf16 v[88:91], v[178:181], v[220:223], v[88:91]
	v_mfma_f32_16x16x32_bf16 v[76:79], v[170:173], v[228:231], v[76:79]
	v_mfma_f32_16x16x32_bf16 v[72:75], v[178:181], v[228:231], v[72:75]
	v_mfma_f32_16x16x32_bf16 v[124:127], v[174:177], v[208:211], v[124:127]
	v_mfma_f32_16x16x32_bf16 v[120:123], v[182:185], v[208:211], v[120:123]
	v_mfma_f32_16x16x32_bf16 v[108:111], v[174:177], v[216:219], v[108:111]
	v_mfma_f32_16x16x32_bf16 v[104:107], v[182:185], v[216:219], v[104:107]
	v_mfma_f32_16x16x32_bf16 v[92:95], v[174:177], v[224:227], v[92:95]
	v_mfma_f32_16x16x32_bf16 v[88:91], v[182:185], v[224:227], v[88:91]
	v_mfma_f32_16x16x32_bf16 v[76:79], v[174:177], v[232:235], v[76:79]
	v_mfma_f32_16x16x32_bf16 v[72:75], v[182:185], v[232:235], v[72:75]
	s_setprio 0
	s_setprio 1
	v_mfma_f32_16x16x32_bf16 v[116:119], v[186:189], v[204:207], v[116:119]
	v_mfma_f32_16x16x32_bf16 v[112:115], v[196:199], v[204:207], v[112:115]
	v_mfma_f32_16x16x32_bf16 v[100:103], v[186:189], v[212:215], v[100:103]
	v_mfma_f32_16x16x32_bf16 v[96:99], v[196:199], v[212:215], v[96:99]
	v_mfma_f32_16x16x32_bf16 v[84:87], v[186:189], v[220:223], v[84:87]
	v_mfma_f32_16x16x32_bf16 v[80:83], v[196:199], v[220:223], v[80:83]
	v_mfma_f32_16x16x32_bf16 v[68:71], v[186:189], v[228:231], v[68:71]
	v_mfma_f32_16x16x32_bf16 v[64:67], v[196:199], v[228:231], v[64:67]
	v_mfma_f32_16x16x32_bf16 v[116:119], v[190:193], v[208:211], v[116:119]
	v_mfma_f32_16x16x32_bf16 v[112:115], v[200:203], v[208:211], v[112:115]
	v_mfma_f32_16x16x32_bf16 v[100:103], v[190:193], v[216:219], v[100:103]
	v_mfma_f32_16x16x32_bf16 v[96:99], v[200:203], v[216:219], v[96:99]
	v_mfma_f32_16x16x32_bf16 v[84:87], v[190:193], v[224:227], v[84:87]
	v_mfma_f32_16x16x32_bf16 v[80:83], v[200:203], v[224:227], v[80:83]
	v_mfma_f32_16x16x32_bf16 v[68:71], v[190:193], v[232:235], v[68:71]
	v_mfma_f32_16x16x32_bf16 v[64:67], v[200:203], v[232:235], v[64:67]
	s_setprio 0
	s_barrier
	s_mov_b32 m0, s33
	ds_read_b128 v[204:207], v139 offset:49152
	ds_read_b128 v[208:211], v139 offset:50176
	ds_read_b128 v[212:215], v139 offset:51200
	ds_read_b128 v[216:219], v139 offset:52224
	ds_read_b128 v[220:223], v139 offset:53248
	ds_read_b128 v[224:227], v139 offset:54272
	ds_read_b128 v[228:231], v139 offset:55296
	ds_read_b128 v[232:235], v139 offset:56320
	global_load_lds_dwordx4 v128, s[98:99]
	s_mov_b32 m0, s9
	s_nop 0
	global_load_lds_dwordx4 v130, s[98:99]
	s_mov_b32 m0, s52
	s_nop 0
	global_load_lds_dwordx4 v128, s[54:55]
	s_mov_b32 m0, s61
	s_nop 0
	global_load_lds_dwordx4 v130, s[54:55]
	s_mov_b32 m0, s8
	s_nop 0
	global_load_lds_dwordx4 v128, s[100:101]
	s_mov_b32 m0, s53
	s_nop 0
	global_load_lds_dwordx4 v130, s[100:101]
	s_waitcnt vmcnt(8)
	s_waitcnt lgkmcnt(0)
	s_barrier
	s_setprio 1
	s_waitcnt lgkmcnt(0)
	v_mfma_f32_16x16x32_bf16 v[60:63], v[170:173], v[204:207], v[60:63]
	v_mfma_f32_16x16x32_bf16 v[56:59], v[178:181], v[204:207], v[56:59]
	v_mfma_f32_16x16x32_bf16 v[44:47], v[170:173], v[212:215], v[44:47]
	v_mfma_f32_16x16x32_bf16 v[40:43], v[178:181], v[212:215], v[40:43]
	v_mfma_f32_16x16x32_bf16 v[28:31], v[170:173], v[220:223], v[28:31]
	v_mfma_f32_16x16x32_bf16 v[24:27], v[178:181], v[220:223], v[24:27]
	v_mfma_f32_16x16x32_bf16 v[12:15], v[170:173], v[228:231], v[12:15]
	v_mfma_f32_16x16x32_bf16 v[8:11], v[178:181], v[228:231], v[8:11]
	v_mfma_f32_16x16x32_bf16 v[60:63], v[174:177], v[208:211], v[60:63]
	v_mfma_f32_16x16x32_bf16 v[56:59], v[182:185], v[208:211], v[56:59]
	v_mfma_f32_16x16x32_bf16 v[44:47], v[174:177], v[216:219], v[44:47]
	v_mfma_f32_16x16x32_bf16 v[40:43], v[182:185], v[216:219], v[40:43]
	v_mfma_f32_16x16x32_bf16 v[28:31], v[174:177], v[224:227], v[28:31]
	v_mfma_f32_16x16x32_bf16 v[24:27], v[182:185], v[224:227], v[24:27]
	v_mfma_f32_16x16x32_bf16 v[12:15], v[174:177], v[232:235], v[12:15]
	v_mfma_f32_16x16x32_bf16 v[8:11], v[182:185], v[232:235], v[8:11]
	s_setprio 0
	s_setprio 1
	v_mfma_f32_16x16x32_bf16 v[52:55], v[186:189], v[204:207], v[52:55]
	v_mfma_f32_16x16x32_bf16 v[48:51], v[196:199], v[204:207], v[48:51]
	v_mfma_f32_16x16x32_bf16 v[36:39], v[186:189], v[212:215], v[36:39]
	v_mfma_f32_16x16x32_bf16 v[32:35], v[196:199], v[212:215], v[32:35]
	v_mfma_f32_16x16x32_bf16 v[20:23], v[186:189], v[220:223], v[20:23]
	v_mfma_f32_16x16x32_bf16 v[16:19], v[196:199], v[220:223], v[16:19]
	v_mfma_f32_16x16x32_bf16 v[4:7], v[186:189], v[228:231], v[4:7]
	v_mfma_f32_16x16x32_bf16 v[0:3], v[196:199], v[228:231], v[0:3]
	v_mfma_f32_16x16x32_bf16 v[52:55], v[190:193], v[208:211], v[52:55]
	v_mfma_f32_16x16x32_bf16 v[48:51], v[200:203], v[208:211], v[48:51]
	v_mfma_f32_16x16x32_bf16 v[36:39], v[190:193], v[216:219], v[36:39]
	v_mfma_f32_16x16x32_bf16 v[32:35], v[200:203], v[216:219], v[32:35]
	v_mfma_f32_16x16x32_bf16 v[20:23], v[190:193], v[224:227], v[20:23]
	v_mfma_f32_16x16x32_bf16 v[16:19], v[200:203], v[224:227], v[16:19]
	v_mfma_f32_16x16x32_bf16 v[4:7], v[190:193], v[232:235], v[4:7]
	v_mfma_f32_16x16x32_bf16 v[0:3], v[200:203], v[232:235], v[0:3]
	s_setprio 0
	s_barrier
	s_movk_i32 s64, 0x100
	s_andn2_b64 vcc, exec, s[50:51]
	s_mov_b64 s[54:55], -1
	s_mov_b64 s[50:51], 0
	s_cbranch_vccz .LBB0_2628
	s_and_b64 vcc, exec, s[18:19]
	s_cbranch_vccz .LBB0_2631
	s_barrier

.LBB0_2801:
	ds_read_b128 v[128:131], v195
	ds_read_b128 v[132:135], v196
	ds_read_b128 v[136:139], v197
	ds_read_b128 v[140:143], v198
	ds_read_b128 v[170:173], v199
	ds_read_b128 v[174:177], v200
	ds_read_b128 v[178:181], v201
	ds_read_b128 v[182:185], v202
	s_add_u32 s46, s44, 0x100
	s_addc_u32 s47, s45, 0
	s_cmp_eq_u32 s68, 12
	s_cselect_b32 s51, s4, s47
	s_cselect_b32 s50, s5, s46
	s_cselect_b32 s49, s25, s67
	s_cselect_b32 s48, s27, s66
	s_mov_b32 m0, s55
	ds_read_b128 v[186:189], v192
	ds_read_b128 v[212:215], v192 offset:1024
	ds_read_b128 v[216:219], v192 offset:2048
	ds_read_b128 v[220:223], v192 offset:3072
	ds_read_b128 v[224:227], v192 offset:4096
	ds_read_b128 v[228:231], v192 offset:5120
	ds_read_b128 v[232:235], v192 offset:6144
	ds_read_b128 v[236:239], v192 offset:7168
	global_load_lds_dwordx4 v162, s[44:45]
	s_mov_b32 m0, s60
	s_nop 0
	global_load_lds_dwordx4 v164, s[44:45]
	s_waitcnt vmcnt(8)
	s_waitcnt lgkmcnt(0)
	s_barrier
	s_setprio 1
	s_waitcnt lgkmcnt(0)
	v_mfma_f32_16x16x32_bf16 v[124:127], v[128:131], v[186:189], v[124:127]
	v_mfma_f32_16x16x32_bf16 v[120:123], v[136:139], v[186:189], v[120:123]
	v_mfma_f32_16x16x32_bf16 v[108:111], v[128:131], v[216:219], v[108:111]
	v_mfma_f32_16x16x32_bf16 v[104:107], v[136:139], v[216:219], v[104:107]
	v_mfma_f32_16x16x32_bf16 v[92:95], v[128:131], v[224:227], v[92:95]
	v_mfma_f32_16x16x32_bf16 v[88:91], v[136:139], v[224:227], v[88:91]
	v_mfma_f32_16x16x32_bf16 v[76:79], v[128:131], v[232:235], v[76:79]
	v_mfma_f32_16x16x32_bf16 v[72:75], v[136:139], v[232:235], v[72:75]
	v_mfma_f32_16x16x32_bf16 v[124:127], v[132:135], v[212:215], v[124:127]
	v_mfma_f32_16x16x32_bf16 v[120:123], v[140:143], v[212:215], v[120:123]
	v_mfma_f32_16x16x32_bf16 v[108:111], v[132:135], v[220:223], v[108:111]
	v_mfma_f32_16x16x32_bf16 v[104:107], v[140:143], v[220:223], v[104:107]
	v_mfma_f32_16x16x32_bf16 v[92:95], v[132:135], v[228:231], v[92:95]
	v_mfma_f32_16x16x32_bf16 v[88:91], v[140:143], v[228:231], v[88:91]
	v_mfma_f32_16x16x32_bf16 v[76:79], v[132:135], v[236:239], v[76:79]
	v_mfma_f32_16x16x32_bf16 v[72:75], v[140:143], v[236:239], v[72:75]
	s_setprio 0
	s_setprio 1
	v_mfma_f32_16x16x32_bf16 v[116:119], v[170:173], v[186:189], v[116:119]
	v_mfma_f32_16x16x32_bf16 v[112:115], v[178:181], v[186:189], v[112:115]
	v_mfma_f32_16x16x32_bf16 v[100:103], v[170:173], v[216:219], v[100:103]
	v_mfma_f32_16x16x32_bf16 v[96:99], v[178:181], v[216:219], v[96:99]
	v_mfma_f32_16x16x32_bf16 v[84:87], v[170:173], v[224:227], v[84:87]
	v_mfma_f32_16x16x32_bf16 v[80:83], v[178:181], v[224:227], v[80:83]
	v_mfma_f32_16x16x32_bf16 v[68:71], v[170:173], v[232:235], v[68:71]
	v_mfma_f32_16x16x32_bf16 v[64:67], v[178:181], v[232:235], v[64:67]
	v_mfma_f32_16x16x32_bf16 v[116:119], v[174:177], v[212:215], v[116:119]
	v_mfma_f32_16x16x32_bf16 v[112:115], v[182:185], v[212:215], v[112:115]
	v_mfma_f32_16x16x32_bf16 v[100:103], v[174:177], v[220:223], v[100:103]
	v_mfma_f32_16x16x32_bf16 v[96:99], v[182:185], v[220:223], v[96:99]
	v_mfma_f32_16x16x32_bf16 v[84:87], v[174:177], v[228:231], v[84:87]
	v_mfma_f32_16x16x32_bf16 v[80:83], v[182:185], v[228:231], v[80:83]
	v_mfma_f32_16x16x32_bf16 v[68:71], v[174:177], v[236:239], v[68:71]
	v_mfma_f32_16x16x32_bf16 v[64:67], v[182:185], v[236:239], v[64:67]
	s_setprio 0
	s_barrier
	s_mov_b32 m0, s7
	s_add_u32 s44, s48, 0x40000
	ds_read_b128 v[186:189], v192 offset:16384
	ds_read_b128 v[212:215], v192 offset:17408
	ds_read_b128 v[216:219], v192 offset:18432
	ds_read_b128 v[220:223], v192 offset:19456
	ds_read_b128 v[224:227], v192 offset:20480
	ds_read_b128 v[228:231], v192 offset:21504
	ds_read_b128 v[232:235], v192 offset:22528
	ds_read_b128 v[236:239], v192 offset:23552
	global_load_lds_dwordx4 v158, s[48:49]
	s_mov_b32 m0, s8
	s_addc_u32 s45, s49, 0
	global_load_lds_dwordx4 v160, s[48:49]
	s_mov_b32 m0, s9
	s_add_u32 s98, s48, s18
	global_load_lds_dwordx4 v158, s[44:45]
	s_mov_b32 m0, s23
	s_addc_u32 s99, s49, s19
	global_load_lds_dwordx4 v160, s[44:45]
	s_mov_b32 m0, s6
	s_add_u32 s100, s50, s18
	global_load_lds_dwordx4 v158, s[50:51]
	s_mov_b32 m0, s28
	s_addc_u32 s101, s51, s19
	global_load_lds_dwordx4 v160, s[50:51]
	s_waitcnt vmcnt(8)
	s_waitcnt lgkmcnt(0)
	s_barrier
	s_setprio 1
	s_waitcnt lgkmcnt(0)
	v_mfma_f32_16x16x32_bf16 v[60:63], v[128:131], v[186:189], v[60:63]
	v_mfma_f32_16x16x32_bf16 v[56:59], v[136:139], v[186:189], v[56:59]
	v_mfma_f32_16x16x32_bf16 v[44:47], v[128:131], v[216:219], v[44:47]
	v_mfma_f32_16x16x32_bf16 v[40:43], v[136:139], v[216:219], v[40:43]
	v_mfma_f32_16x16x32_bf16 v[28:31], v[128:131], v[224:227], v[28:31]
	v_mfma_f32_16x16x32_bf16 v[24:27], v[136:139], v[224:227], v[24:27]
	v_mfma_f32_16x16x32_bf16 v[12:15], v[128:131], v[232:235], v[12:15]
	v_mfma_f32_16x16x32_bf16 v[8:11], v[136:139], v[232:235], v[8:11]
	v_mfma_f32_16x16x32_bf16 v[60:63], v[132:135], v[212:215], v[60:63]
	v_mfma_f32_16x16x32_bf16 v[56:59], v[140:143], v[212:215], v[56:59]
	v_mfma_f32_16x16x32_bf16 v[44:47], v[132:135], v[220:223], v[44:47]
	v_mfma_f32_16x16x32_bf16 v[40:43], v[140:143], v[220:223], v[40:43]
	v_mfma_f32_16x16x32_bf16 v[28:31], v[132:135], v[228:231], v[28:31]
	v_mfma_f32_16x16x32_bf16 v[24:27], v[140:143], v[228:231], v[24:27]
	v_mfma_f32_16x16x32_bf16 v[12:15], v[132:135], v[236:239], v[12:15]
	v_mfma_f32_16x16x32_bf16 v[8:11], v[140:143], v[236:239], v[8:11]
	s_setprio 0
	s_setprio 1
	v_mfma_f32_16x16x32_bf16 v[52:55], v[170:173], v[186:189], v[52:55]
	v_mfma_f32_16x16x32_bf16 v[48:51], v[178:181], v[186:189], v[48:51]
	v_mfma_f32_16x16x32_bf16 v[36:39], v[170:173], v[216:219], v[36:39]
	v_mfma_f32_16x16x32_bf16 v[32:35], v[178:181], v[216:219], v[32:35]
	v_mfma_f32_16x16x32_bf16 v[20:23], v[170:173], v[224:227], v[20:23]
	v_mfma_f32_16x16x32_bf16 v[16:19], v[178:181], v[224:227], v[16:19]
	v_mfma_f32_16x16x32_bf16 v[4:7], v[170:173], v[232:235], v[4:7]
	v_mfma_f32_16x16x32_bf16 v[0:3], v[178:181], v[232:235], v[0:3]
	v_mfma_f32_16x16x32_bf16 v[52:55], v[174:177], v[212:215], v[52:55]
	v_mfma_f32_16x16x32_bf16 v[48:51], v[182:185], v[212:215], v[48:51]
	v_mfma_f32_16x16x32_bf16 v[36:39], v[174:177], v[220:223], v[36:39]
	v_mfma_f32_16x16x32_bf16 v[32:35], v[182:185], v[220:223], v[32:35]
	v_mfma_f32_16x16x32_bf16 v[20:23], v[174:177], v[228:231], v[20:23]
	v_mfma_f32_16x16x32_bf16 v[16:19], v[182:185], v[228:231], v[16:19]
	v_mfma_f32_16x16x32_bf16 v[4:7], v[174:177], v[236:239], v[4:7]
	v_mfma_f32_16x16x32_bf16 v[0:3], v[182:185], v[236:239], v[0:3]
	s_setprio 0
	s_barrier
	ds_read_b128 v[128:131], v203
	ds_read_b128 v[132:135], v204
	ds_read_b128 v[136:139], v205
	ds_read_b128 v[140:143], v206
	ds_read_b128 v[170:173], v207
	ds_read_b128 v[174:177], v208
	ds_read_b128 v[178:181], v209
	ds_read_b128 v[182:185], v210
	s_add_u32 s44, s50, 0x40000
	s_addc_u32 s45, s51, 0
	s_mov_b32 m0, s29
	ds_read_b128 v[186:189], v192 offset:32768
	ds_read_b128 v[212:215], v192 offset:33792
	ds_read_b128 v[216:219], v192 offset:34816
	ds_read_b128 v[220:223], v192 offset:35840
	ds_read_b128 v[224:227], v192 offset:36864
	ds_read_b128 v[228:231], v192 offset:37888
	ds_read_b128 v[232:235], v192 offset:38912
	ds_read_b128 v[236:239], v192 offset:39936
	global_load_lds_dwordx4 v158, s[44:45]
	s_mov_b32 m0, s30
	s_nop 0
	global_load_lds_dwordx4 v160, s[44:45]
	s_waitcnt vmcnt(8)
	s_waitcnt lgkmcnt(0)
	s_barrier
	s_setprio 1
	s_waitcnt lgkmcnt(0)
	v_mfma_f32_16x16x32_bf16 v[124:127], v[128:131], v[186:189], v[124:127]
	v_mfma_f32_16x16x32_bf16 v[120:123], v[136:139], v[186:189], v[120:123]
	v_mfma_f32_16x16x32_bf16 v[108:111], v[128:131], v[216:219], v[108:111]
	v_mfma_f32_16x16x32_bf16 v[104:107], v[136:139], v[216:219], v[104:107]
	v_mfma_f32_16x16x32_bf16 v[92:95], v[128:131], v[224:227], v[92:95]
	v_mfma_f32_16x16x32_bf16 v[88:91], v[136:139], v[224:227], v[88:91]
	v_mfma_f32_16x16x32_bf16 v[76:79], v[128:131], v[232:235], v[76:79]
	v_mfma_f32_16x16x32_bf16 v[72:75], v[136:139], v[232:235], v[72:75]
	v_mfma_f32_16x16x32_bf16 v[124:127], v[132:135], v[212:215], v[124:127]
	v_mfma_f32_16x16x32_bf16 v[120:123], v[140:143], v[212:215], v[120:123]
	v_mfma_f32_16x16x32_bf16 v[108:111], v[132:135], v[220:223], v[108:111]
	v_mfma_f32_16x16x32_bf16 v[104:107], v[140:143], v[220:223], v[104:107]
	v_mfma_f32_16x16x32_bf16 v[92:95], v[132:135], v[228:231], v[92:95]
	v_mfma_f32_16x16x32_bf16 v[88:91], v[140:143], v[228:231], v[88:91]
	v_mfma_f32_16x16x32_bf16 v[76:79], v[132:135], v[236:239], v[76:79]
	v_mfma_f32_16x16x32_bf16 v[72:75], v[140:143], v[236:239], v[72:75]
	s_setprio 0
	s_setprio 1
	v_mfma_f32_16x16x32_bf16 v[116:119], v[170:173], v[186:189], v[116:119]
	v_mfma_f32_16x16x32_bf16 v[112:115], v[178:181], v[186:189], v[112:115]
	v_mfma_f32_16x16x32_bf16 v[100:103], v[170:173], v[216:219], v[100:103]
	v_mfma_f32_16x16x32_bf16 v[96:99], v[178:181], v[216:219], v[96:99]
	v_mfma_f32_16x16x32_bf16 v[84:87], v[170:173], v[224:227], v[84:87]
	v_mfma_f32_16x16x32_bf16 v[80:83], v[178:181], v[224:227], v[80:83]
	v_mfma_f32_16x16x32_bf16 v[68:71], v[170:173], v[232:235], v[68:71]
	v_mfma_f32_16x16x32_bf16 v[64:67], v[178:181], v[232:235], v[64:67]
	v_mfma_f32_16x16x32_bf16 v[116:119], v[174:177], v[212:215], v[116:119]
	v_mfma_f32_16x16x32_bf16 v[112:115], v[182:185], v[212:215], v[112:115]
	v_mfma_f32_16x16x32_bf16 v[100:103], v[174:177], v[220:223], v[100:103]
	v_mfma_f32_16x16x32_bf16 v[96:99], v[182:185], v[220:223], v[96:99]
	v_mfma_f32_16x16x32_bf16 v[84:87], v[174:177], v[228:231], v[84:87]
	v_mfma_f32_16x16x32_bf16 v[80:83], v[182:185], v[228:231], v[80:83]
	v_mfma_f32_16x16x32_bf16 v[68:71], v[174:177], v[236:239], v[68:71]
	v_mfma_f32_16x16x32_bf16 v[64:67], v[182:185], v[236:239], v[64:67]
	s_setprio 0
	s_barrier
	s_mov_b32 m0, s31
	s_add_u32 s44, s48, 0x40080
	ds_read_b128 v[186:189], v192 offset:49152
	ds_read_b128 v[212:215], v192 offset:50176
	ds_read_b128 v[216:219], v192 offset:51200
	ds_read_b128 v[220:223], v192 offset:52224
	ds_read_b128 v[224:227], v192 offset:53248
	ds_read_b128 v[228:231], v192 offset:54272
	ds_read_b128 v[232:235], v192 offset:55296
	ds_read_b128 v[236:239], v192 offset:56320
	global_load_lds_dwordx4 v158, s[98:99]
	s_mov_b32 m0, s33
	s_addc_u32 s45, s49, 0
	global_load_lds_dwordx4 v160, s[98:99]
	s_mov_b32 m0, s36
	s_add_u32 s66, s66, 0x100
	global_load_lds_dwordx4 v158, s[44:45]
	s_mov_b32 m0, s37
	s_addc_u32 s67, s67, 0
	global_load_lds_dwordx4 v160, s[44:45]
	s_mov_b32 m0, s34
	s_nop 0
	global_load_lds_dwordx4 v158, s[100:101]
	s_mov_b32 m0, s35
	s_nop 0
	global_load_lds_dwordx4 v160, s[100:101]
	s_waitcnt vmcnt(8)
	s_waitcnt lgkmcnt(0)
	s_barrier
	s_setprio 1
	s_waitcnt lgkmcnt(0)
	v_mfma_f32_16x16x32_bf16 v[60:63], v[128:131], v[186:189], v[60:63]
	v_mfma_f32_16x16x32_bf16 v[56:59], v[136:139], v[186:189], v[56:59]
	v_mfma_f32_16x16x32_bf16 v[44:47], v[128:131], v[216:219], v[44:47]
	v_mfma_f32_16x16x32_bf16 v[40:43], v[136:139], v[216:219], v[40:43]
	v_mfma_f32_16x16x32_bf16 v[28:31], v[128:131], v[224:227], v[28:31]
	v_mfma_f32_16x16x32_bf16 v[24:27], v[136:139], v[224:227], v[24:27]
	v_mfma_f32_16x16x32_bf16 v[12:15], v[128:131], v[232:235], v[12:15]
	v_mfma_f32_16x16x32_bf16 v[8:11], v[136:139], v[232:235], v[8:11]
	v_mfma_f32_16x16x32_bf16 v[60:63], v[132:135], v[212:215], v[60:63]
	v_mfma_f32_16x16x32_bf16 v[56:59], v[140:143], v[212:215], v[56:59]
	v_mfma_f32_16x16x32_bf16 v[44:47], v[132:135], v[220:223], v[44:47]
	v_mfma_f32_16x16x32_bf16 v[40:43], v[140:143], v[220:223], v[40:43]
	v_mfma_f32_16x16x32_bf16 v[28:31], v[132:135], v[228:231], v[28:31]
	v_mfma_f32_16x16x32_bf16 v[24:27], v[140:143], v[228:231], v[24:27]
	v_mfma_f32_16x16x32_bf16 v[12:15], v[132:135], v[236:239], v[12:15]
	v_mfma_f32_16x16x32_bf16 v[8:11], v[140:143], v[236:239], v[8:11]
	s_setprio 0
	s_setprio 1
	v_mfma_f32_16x16x32_bf16 v[52:55], v[170:173], v[186:189], v[52:55]
	v_mfma_f32_16x16x32_bf16 v[48:51], v[178:181], v[186:189], v[48:51]
	v_mfma_f32_16x16x32_bf16 v[36:39], v[170:173], v[216:219], v[36:39]
	v_mfma_f32_16x16x32_bf16 v[32:35], v[178:181], v[216:219], v[32:35]
	v_mfma_f32_16x16x32_bf16 v[20:23], v[170:173], v[224:227], v[20:23]
	v_mfma_f32_16x16x32_bf16 v[16:19], v[178:181], v[224:227], v[16:19]
	v_mfma_f32_16x16x32_bf16 v[4:7], v[170:173], v[232:235], v[4:7]
	v_mfma_f32_16x16x32_bf16 v[0:3], v[178:181], v[232:235], v[0:3]
	v_mfma_f32_16x16x32_bf16 v[52:55], v[174:177], v[212:215], v[52:55]
	v_mfma_f32_16x16x32_bf16 v[48:51], v[182:185], v[212:215], v[48:51]
	v_mfma_f32_16x16x32_bf16 v[36:39], v[174:177], v[220:223], v[36:39]
	v_mfma_f32_16x16x32_bf16 v[32:35], v[182:185], v[220:223], v[32:35]
	v_mfma_f32_16x16x32_bf16 v[20:23], v[174:177], v[228:231], v[20:23]
	v_mfma_f32_16x16x32_bf16 v[16:19], v[182:185], v[228:231], v[16:19]
	v_mfma_f32_16x16x32_bf16 v[4:7], v[174:177], v[236:239], v[4:7]
	v_mfma_f32_16x16x32_bf16 v[0:3], v[182:185], v[236:239], v[0:3]
	s_setprio 0
	s_barrier
	s_add_i32 s68, s68, 2
	s_cmp_gt_u32 s68, 13
	s_mov_b64 s[44:45], s[46:47]
	s_cbranch_scc0 .LBB0_2801
	s_and_b64 vcc, exec, s[20:21]
	s_cbranch_vccz .LBB0_2804
	s_barrier

.LBB0_2949:
	ds_read_b128 v[172:175], v143
	ds_read_b128 v[176:179], v153
	ds_read_b128 v[180:183], v158
	ds_read_b128 v[184:187], v159
	ds_read_b128 v[188:191], v160
	ds_read_b128 v[196:199], v161
	ds_read_b128 v[200:203], v162
	ds_read_b128 v[204:207], v163
	s_add_u32 s26, s24, 0xfffc0080
	s_addc_u32 s27, s25, -1
	s_cmp_eq_u32 s53, 12
	s_cselect_b32 s37, s4, s27
	s_cselect_b32 s36, s5, s26
	s_cselect_b32 s27, s15, s52
	s_cselect_b32 s26, s17, s51
	s_mov_b32 m0, s47
	ds_read_b128 v[208:211], v141
	ds_read_b128 v[212:215], v141 offset:1024
	ds_read_b128 v[216:219], v141 offset:2048
	ds_read_b128 v[220:223], v141 offset:3072
	ds_read_b128 v[224:227], v141 offset:4096
	ds_read_b128 v[228:231], v141 offset:5120
	ds_read_b128 v[232:235], v141 offset:6144
	ds_read_b128 v[236:239], v141 offset:7168
	global_load_lds_dwordx4 v132, s[24:25]
	s_mov_b32 m0, s48
	s_nop 0
	global_load_lds_dwordx4 v134, s[24:25]
	s_waitcnt vmcnt(8)
	s_waitcnt lgkmcnt(0)
	s_barrier
	s_setprio 1
	s_waitcnt lgkmcnt(0)
	v_mfma_f32_16x16x32_bf16 v[124:127], v[172:175], v[208:211], v[124:127]
	v_mfma_f32_16x16x32_bf16 v[120:123], v[180:183], v[208:211], v[120:123]
	v_mfma_f32_16x16x32_bf16 v[108:111], v[172:175], v[216:219], v[108:111]
	v_mfma_f32_16x16x32_bf16 v[104:107], v[180:183], v[216:219], v[104:107]
	v_mfma_f32_16x16x32_bf16 v[92:95], v[172:175], v[224:227], v[92:95]
	v_mfma_f32_16x16x32_bf16 v[88:91], v[180:183], v[224:227], v[88:91]
	v_mfma_f32_16x16x32_bf16 v[76:79], v[172:175], v[232:235], v[76:79]
	v_mfma_f32_16x16x32_bf16 v[72:75], v[180:183], v[232:235], v[72:75]
	v_mfma_f32_16x16x32_bf16 v[124:127], v[176:179], v[212:215], v[124:127]
	v_mfma_f32_16x16x32_bf16 v[120:123], v[184:187], v[212:215], v[120:123]
	v_mfma_f32_16x16x32_bf16 v[108:111], v[176:179], v[220:223], v[108:111]
	v_mfma_f32_16x16x32_bf16 v[104:107], v[184:187], v[220:223], v[104:107]
	v_mfma_f32_16x16x32_bf16 v[92:95], v[176:179], v[228:231], v[92:95]
	v_mfma_f32_16x16x32_bf16 v[88:91], v[184:187], v[228:231], v[88:91]
	v_mfma_f32_16x16x32_bf16 v[76:79], v[176:179], v[236:239], v[76:79]
	v_mfma_f32_16x16x32_bf16 v[72:75], v[184:187], v[236:239], v[72:75]
	s_setprio 0
	s_setprio 1
	v_mfma_f32_16x16x32_bf16 v[116:119], v[188:191], v[208:211], v[116:119]
	v_mfma_f32_16x16x32_bf16 v[112:115], v[200:203], v[208:211], v[112:115]
	v_mfma_f32_16x16x32_bf16 v[100:103], v[188:191], v[216:219], v[100:103]
	v_mfma_f32_16x16x32_bf16 v[96:99], v[200:203], v[216:219], v[96:99]
	v_mfma_f32_16x16x32_bf16 v[84:87], v[188:191], v[224:227], v[84:87]
	v_mfma_f32_16x16x32_bf16 v[80:83], v[200:203], v[224:227], v[80:83]
	v_mfma_f32_16x16x32_bf16 v[68:71], v[188:191], v[232:235], v[68:71]
	v_mfma_f32_16x16x32_bf16 v[64:67], v[200:203], v[232:235], v[64:67]
	v_mfma_f32_16x16x32_bf16 v[116:119], v[196:199], v[212:215], v[116:119]
	v_mfma_f32_16x16x32_bf16 v[112:115], v[204:207], v[212:215], v[112:115]
	v_mfma_f32_16x16x32_bf16 v[100:103], v[196:199], v[220:223], v[100:103]
	v_mfma_f32_16x16x32_bf16 v[96:99], v[204:207], v[220:223], v[96:99]
	v_mfma_f32_16x16x32_bf16 v[84:87], v[196:199], v[228:231], v[84:87]
	v_mfma_f32_16x16x32_bf16 v[80:83], v[204:207], v[228:231], v[80:83]
	v_mfma_f32_16x16x32_bf16 v[68:71], v[196:199], v[236:239], v[68:71]
	v_mfma_f32_16x16x32_bf16 v[64:67], v[204:207], v[236:239], v[64:67]
	s_setprio 0
	s_barrier
	s_mov_b32 m0, s23
	s_add_u32 s54, s26, 0x40000
	ds_read_b128 v[208:211], v141 offset:16384
	ds_read_b128 v[212:215], v141 offset:17408
	ds_read_b128 v[216:219], v141 offset:18432
	ds_read_b128 v[220:223], v141 offset:19456
	ds_read_b128 v[224:227], v141 offset:20480
	ds_read_b128 v[228:231], v141 offset:21504
	ds_read_b128 v[232:235], v141 offset:22528
	ds_read_b128 v[236:239], v141 offset:23552
	global_load_lds_dwordx4 v130, s[26:27]
	s_mov_b32 m0, s28
	s_addc_u32 s55, s27, 0
	global_load_lds_dwordx4 v128, s[26:27]
	s_mov_b32 m0, s29
	s_add_u32 s98, s26, s10
	global_load_lds_dwordx4 v130, s[54:55]
	s_mov_b32 m0, s30
	s_addc_u32 s99, s27, s11
	global_load_lds_dwordx4 v128, s[54:55]
	s_mov_b32 m0, s2
	s_add_u32 s100, s36, s10
	global_load_lds_dwordx4 v130, s[36:37]
	s_mov_b32 m0, s31
	s_addc_u32 s101, s37, s11
	global_load_lds_dwordx4 v128, s[36:37]
	s_waitcnt vmcnt(8)
	s_waitcnt lgkmcnt(0)
	s_barrier
	s_setprio 1
	s_waitcnt lgkmcnt(0)
	v_mfma_f32_16x16x32_bf16 v[60:63], v[172:175], v[208:211], v[60:63]
	v_mfma_f32_16x16x32_bf16 v[56:59], v[180:183], v[208:211], v[56:59]
	v_mfma_f32_16x16x32_bf16 v[44:47], v[172:175], v[216:219], v[44:47]
	v_mfma_f32_16x16x32_bf16 v[40:43], v[180:183], v[216:219], v[40:43]
	v_mfma_f32_16x16x32_bf16 v[28:31], v[172:175], v[224:227], v[28:31]
	v_mfma_f32_16x16x32_bf16 v[24:27], v[180:183], v[224:227], v[24:27]
	v_mfma_f32_16x16x32_bf16 v[12:15], v[172:175], v[232:235], v[12:15]
	v_mfma_f32_16x16x32_bf16 v[8:11], v[180:183], v[232:235], v[8:11]
	v_mfma_f32_16x16x32_bf16 v[60:63], v[176:179], v[212:215], v[60:63]
	v_mfma_f32_16x16x32_bf16 v[56:59], v[184:187], v[212:215], v[56:59]
	v_mfma_f32_16x16x32_bf16 v[44:47], v[176:179], v[220:223], v[44:47]
	v_mfma_f32_16x16x32_bf16 v[40:43], v[184:187], v[220:223], v[40:43]
	v_mfma_f32_16x16x32_bf16 v[28:31], v[176:179], v[228:231], v[28:31]
	v_mfma_f32_16x16x32_bf16 v[24:27], v[184:187], v[228:231], v[24:27]
	v_mfma_f32_16x16x32_bf16 v[12:15], v[176:179], v[236:239], v[12:15]
	v_mfma_f32_16x16x32_bf16 v[8:11], v[184:187], v[236:239], v[8:11]
	s_setprio 0
	s_setprio 1
	v_mfma_f32_16x16x32_bf16 v[52:55], v[188:191], v[208:211], v[52:55]
	v_mfma_f32_16x16x32_bf16 v[48:51], v[200:203], v[208:211], v[48:51]
	v_mfma_f32_16x16x32_bf16 v[36:39], v[188:191], v[216:219], v[36:39]
	v_mfma_f32_16x16x32_bf16 v[32:35], v[200:203], v[216:219], v[32:35]
	v_mfma_f32_16x16x32_bf16 v[20:23], v[188:191], v[224:227], v[20:23]
	v_mfma_f32_16x16x32_bf16 v[16:19], v[200:203], v[224:227], v[16:19]
	v_mfma_f32_16x16x32_bf16 v[4:7], v[188:191], v[232:235], v[4:7]
	v_mfma_f32_16x16x32_bf16 v[0:3], v[200:203], v[232:235], v[0:3]
	v_mfma_f32_16x16x32_bf16 v[52:55], v[196:199], v[212:215], v[52:55]
	v_mfma_f32_16x16x32_bf16 v[48:51], v[204:207], v[212:215], v[48:51]
	v_mfma_f32_16x16x32_bf16 v[36:39], v[196:199], v[220:223], v[36:39]
	v_mfma_f32_16x16x32_bf16 v[32:35], v[204:207], v[220:223], v[32:35]
	v_mfma_f32_16x16x32_bf16 v[20:23], v[196:199], v[228:231], v[20:23]
	v_mfma_f32_16x16x32_bf16 v[16:19], v[204:207], v[228:231], v[16:19]
	v_mfma_f32_16x16x32_bf16 v[4:7], v[196:199], v[236:239], v[4:7]
	v_mfma_f32_16x16x32_bf16 v[0:3], v[204:207], v[236:239], v[0:3]
	s_setprio 0
	s_barrier
	ds_read_b128 v[172:175], v164
	ds_read_b128 v[176:179], v165
	ds_read_b128 v[180:183], v166
	ds_read_b128 v[184:187], v167
	ds_read_b128 v[188:191], v168
	ds_read_b128 v[196:199], v169
	ds_read_b128 v[200:203], v170
	ds_read_b128 v[204:207], v171
	s_add_u32 s36, s36, 0x40000
	s_addc_u32 s37, s37, 0
	s_mov_b32 m0, s33
	ds_read_b128 v[208:211], v141 offset:32768
	ds_read_b128 v[212:215], v141 offset:33792
	ds_read_b128 v[216:219], v141 offset:34816
	ds_read_b128 v[220:223], v141 offset:35840
	ds_read_b128 v[224:227], v141 offset:36864
	ds_read_b128 v[228:231], v141 offset:37888
	ds_read_b128 v[232:235], v141 offset:38912
	ds_read_b128 v[236:239], v141 offset:39936
	global_load_lds_dwordx4 v130, s[36:37]
	s_mov_b32 m0, s34
	s_nop 0
	global_load_lds_dwordx4 v128, s[36:37]
	s_waitcnt vmcnt(8)
	s_waitcnt lgkmcnt(0)
	s_barrier
	s_setprio 1
	s_waitcnt lgkmcnt(0)
	v_mfma_f32_16x16x32_bf16 v[124:127], v[172:175], v[208:211], v[124:127]
	v_mfma_f32_16x16x32_bf16 v[120:123], v[180:183], v[208:211], v[120:123]
	v_mfma_f32_16x16x32_bf16 v[108:111], v[172:175], v[216:219], v[108:111]
	v_mfma_f32_16x16x32_bf16 v[104:107], v[180:183], v[216:219], v[104:107]
	v_mfma_f32_16x16x32_bf16 v[92:95], v[172:175], v[224:227], v[92:95]
	v_mfma_f32_16x16x32_bf16 v[88:91], v[180:183], v[224:227], v[88:91]
	v_mfma_f32_16x16x32_bf16 v[76:79], v[172:175], v[232:235], v[76:79]
	v_mfma_f32_16x16x32_bf16 v[72:75], v[180:183], v[232:235], v[72:75]
	v_mfma_f32_16x16x32_bf16 v[124:127], v[176:179], v[212:215], v[124:127]
	v_mfma_f32_16x16x32_bf16 v[120:123], v[184:187], v[212:215], v[120:123]
	v_mfma_f32_16x16x32_bf16 v[108:111], v[176:179], v[220:223], v[108:111]
	v_mfma_f32_16x16x32_bf16 v[104:107], v[184:187], v[220:223], v[104:107]
	v_mfma_f32_16x16x32_bf16 v[92:95], v[176:179], v[228:231], v[92:95]
	v_mfma_f32_16x16x32_bf16 v[88:91], v[184:187], v[228:231], v[88:91]
	v_mfma_f32_16x16x32_bf16 v[76:79], v[176:179], v[236:239], v[76:79]
	v_mfma_f32_16x16x32_bf16 v[72:75], v[184:187], v[236:239], v[72:75]
	s_setprio 0
	s_setprio 1
	v_mfma_f32_16x16x32_bf16 v[116:119], v[188:191], v[208:211], v[116:119]
	v_mfma_f32_16x16x32_bf16 v[112:115], v[200:203], v[208:211], v[112:115]
	v_mfma_f32_16x16x32_bf16 v[100:103], v[188:191], v[216:219], v[100:103]
	v_mfma_f32_16x16x32_bf16 v[96:99], v[200:203], v[216:219], v[96:99]
	v_mfma_f32_16x16x32_bf16 v[84:87], v[188:191], v[224:227], v[84:87]
	v_mfma_f32_16x16x32_bf16 v[80:83], v[200:203], v[224:227], v[80:83]
	v_mfma_f32_16x16x32_bf16 v[68:71], v[188:191], v[232:235], v[68:71]
	v_mfma_f32_16x16x32_bf16 v[64:67], v[200:203], v[232:235], v[64:67]
	v_mfma_f32_16x16x32_bf16 v[116:119], v[196:199], v[212:215], v[116:119]
	v_mfma_f32_16x16x32_bf16 v[112:115], v[204:207], v[212:215], v[112:115]
	v_mfma_f32_16x16x32_bf16 v[100:103], v[196:199], v[220:223], v[100:103]
	v_mfma_f32_16x16x32_bf16 v[96:99], v[204:207], v[220:223], v[96:99]
	v_mfma_f32_16x16x32_bf16 v[84:87], v[196:199], v[228:231], v[84:87]
	v_mfma_f32_16x16x32_bf16 v[80:83], v[204:207], v[228:231], v[80:83]
	v_mfma_f32_16x16x32_bf16 v[68:71], v[196:199], v[236:239], v[68:71]
	v_mfma_f32_16x16x32_bf16 v[64:67], v[204:207], v[236:239], v[64:67]
	s_setprio 0
	s_barrier
	s_mov_b32 m0, s39
	s_add_u32 s26, s26, 0x40080
	ds_read_b128 v[208:211], v141 offset:49152
	ds_read_b128 v[212:215], v141 offset:50176
	ds_read_b128 v[216:219], v141 offset:51200
	ds_read_b128 v[220:223], v141 offset:52224
	ds_read_b128 v[224:227], v141 offset:53248
	ds_read_b128 v[228:231], v141 offset:54272
	ds_read_b128 v[232:235], v141 offset:55296
	ds_read_b128 v[236:239], v141 offset:56320
	global_load_lds_dwordx4 v130, s[98:99]
	s_mov_b32 m0, s40
	s_addc_u32 s27, s27, 0
	global_load_lds_dwordx4 v128, s[98:99]
	s_mov_b32 m0, s43
	s_add_u32 s24, s24, 0x100
	global_load_lds_dwordx4 v130, s[26:27]
	s_mov_b32 m0, s44
	s_addc_u32 s25, s25, 0
	global_load_lds_dwordx4 v128, s[26:27]
	s_mov_b32 m0, s41
	s_add_u32 s51, s51, 0x100
	global_load_lds_dwordx4 v130, s[100:101]
	s_mov_b32 m0, s42
	s_addc_u32 s52, s52, 0
	global_load_lds_dwordx4 v128, s[100:101]
	s_waitcnt vmcnt(8)
	s_waitcnt lgkmcnt(0)
	s_barrier
	s_setprio 1
	s_waitcnt lgkmcnt(0)
	v_mfma_f32_16x16x32_bf16 v[60:63], v[172:175], v[208:211], v[60:63]
	v_mfma_f32_16x16x32_bf16 v[56:59], v[180:183], v[208:211], v[56:59]
	v_mfma_f32_16x16x32_bf16 v[44:47], v[172:175], v[216:219], v[44:47]
	v_mfma_f32_16x16x32_bf16 v[40:43], v[180:183], v[216:219], v[40:43]
	v_mfma_f32_16x16x32_bf16 v[28:31], v[172:175], v[224:227], v[28:31]
	v_mfma_f32_16x16x32_bf16 v[24:27], v[180:183], v[224:227], v[24:27]
	v_mfma_f32_16x16x32_bf16 v[12:15], v[172:175], v[232:235], v[12:15]
	v_mfma_f32_16x16x32_bf16 v[8:11], v[180:183], v[232:235], v[8:11]
	v_mfma_f32_16x16x32_bf16 v[60:63], v[176:179], v[212:215], v[60:63]
	v_mfma_f32_16x16x32_bf16 v[56:59], v[184:187], v[212:215], v[56:59]
	v_mfma_f32_16x16x32_bf16 v[44:47], v[176:179], v[220:223], v[44:47]
	v_mfma_f32_16x16x32_bf16 v[40:43], v[184:187], v[220:223], v[40:43]
	v_mfma_f32_16x16x32_bf16 v[28:31], v[176:179], v[228:231], v[28:31]
	v_mfma_f32_16x16x32_bf16 v[24:27], v[184:187], v[228:231], v[24:27]
	v_mfma_f32_16x16x32_bf16 v[12:15], v[176:179], v[236:239], v[12:15]
	v_mfma_f32_16x16x32_bf16 v[8:11], v[184:187], v[236:239], v[8:11]
	s_setprio 0
	s_setprio 1
	v_mfma_f32_16x16x32_bf16 v[52:55], v[188:191], v[208:211], v[52:55]
	v_mfma_f32_16x16x32_bf16 v[48:51], v[200:203], v[208:211], v[48:51]
	v_mfma_f32_16x16x32_bf16 v[36:39], v[188:191], v[216:219], v[36:39]
	v_mfma_f32_16x16x32_bf16 v[32:35], v[200:203], v[216:219], v[32:35]
	v_mfma_f32_16x16x32_bf16 v[20:23], v[188:191], v[224:227], v[20:23]
	v_mfma_f32_16x16x32_bf16 v[16:19], v[200:203], v[224:227], v[16:19]
	v_mfma_f32_16x16x32_bf16 v[4:7], v[188:191], v[232:235], v[4:7]
	v_mfma_f32_16x16x32_bf16 v[0:3], v[200:203], v[232:235], v[0:3]
	v_mfma_f32_16x16x32_bf16 v[52:55], v[196:199], v[212:215], v[52:55]
	v_mfma_f32_16x16x32_bf16 v[48:51], v[204:207], v[212:215], v[48:51]
	v_mfma_f32_16x16x32_bf16 v[36:39], v[196:199], v[220:223], v[36:39]
	v_mfma_f32_16x16x32_bf16 v[32:35], v[204:207], v[220:223], v[32:35]
	v_mfma_f32_16x16x32_bf16 v[20:23], v[196:199], v[228:231], v[20:23]
	v_mfma_f32_16x16x32_bf16 v[16:19], v[204:207], v[228:231], v[16:19]
	v_mfma_f32_16x16x32_bf16 v[4:7], v[196:199], v[236:239], v[4:7]
	v_mfma_f32_16x16x32_bf16 v[0:3], v[204:207], v[236:239], v[0:3]
	s_setprio 0
	s_barrier
	s_add_i32 s53, s53, 2
	s_cmp_gt_u32 s53, 13
	s_cbranch_scc0 .LBB0_2949
	s_and_b64 vcc, exec, s[12:13]
	s_cbranch_vccz .LBB0_2952
	s_barrier

.LBB0_3029:
	ds_read_b128 v[128:131], v195
	ds_read_b128 v[132:135], v196
	ds_read_b128 v[136:139], v197
	ds_read_b128 v[140:143], v198
	ds_read_b128 v[170:173], v199
	ds_read_b128 v[174:177], v200
	ds_read_b128 v[178:181], v201
	ds_read_b128 v[182:185], v202
	s_add_u32 s34, s26, 0x100
	s_addc_u32 s35, s27, 0
	s_cmp_eq_u32 s64, 40
	s_cselect_b32 s39, s11, s35
	s_cselect_b32 s38, s10, s34
	s_cselect_b32 s37, s25, s5
	s_cselect_b32 s36, s24, s4
	s_mov_b32 m0, s50
	ds_read_b128 v[186:189], v192
	ds_read_b128 v[212:215], v192 offset:1024
	ds_read_b128 v[216:219], v192 offset:2048
	ds_read_b128 v[220:223], v192 offset:3072
	ds_read_b128 v[224:227], v192 offset:4096
	ds_read_b128 v[228:231], v192 offset:5120
	ds_read_b128 v[232:235], v192 offset:6144
	ds_read_b128 v[236:239], v192 offset:7168
	global_load_lds_dwordx4 v162, s[26:27]
	s_mov_b32 m0, s51
	s_nop 0
	global_load_lds_dwordx4 v164, s[26:27]
	s_waitcnt vmcnt(8)
	s_waitcnt lgkmcnt(0)
	s_barrier
	s_setprio 1
	s_waitcnt lgkmcnt(0)
	v_mfma_f32_16x16x32_bf16 v[124:127], v[128:131], v[186:189], v[124:127]
	v_mfma_f32_16x16x32_bf16 v[120:123], v[136:139], v[186:189], v[120:123]
	v_mfma_f32_16x16x32_bf16 v[108:111], v[128:131], v[216:219], v[108:111]
	v_mfma_f32_16x16x32_bf16 v[104:107], v[136:139], v[216:219], v[104:107]
	v_mfma_f32_16x16x32_bf16 v[92:95], v[128:131], v[224:227], v[92:95]
	v_mfma_f32_16x16x32_bf16 v[88:91], v[136:139], v[224:227], v[88:91]
	v_mfma_f32_16x16x32_bf16 v[76:79], v[128:131], v[232:235], v[76:79]
	v_mfma_f32_16x16x32_bf16 v[72:75], v[136:139], v[232:235], v[72:75]
	v_mfma_f32_16x16x32_bf16 v[124:127], v[132:135], v[212:215], v[124:127]
	v_mfma_f32_16x16x32_bf16 v[120:123], v[140:143], v[212:215], v[120:123]
	v_mfma_f32_16x16x32_bf16 v[108:111], v[132:135], v[220:223], v[108:111]
	v_mfma_f32_16x16x32_bf16 v[104:107], v[140:143], v[220:223], v[104:107]
	v_mfma_f32_16x16x32_bf16 v[92:95], v[132:135], v[228:231], v[92:95]
	v_mfma_f32_16x16x32_bf16 v[88:91], v[140:143], v[228:231], v[88:91]
	v_mfma_f32_16x16x32_bf16 v[76:79], v[132:135], v[236:239], v[76:79]
	v_mfma_f32_16x16x32_bf16 v[72:75], v[140:143], v[236:239], v[72:75]
	s_setprio 0
	s_setprio 1
	v_mfma_f32_16x16x32_bf16 v[116:119], v[170:173], v[186:189], v[116:119]
	v_mfma_f32_16x16x32_bf16 v[112:115], v[178:181], v[186:189], v[112:115]
	v_mfma_f32_16x16x32_bf16 v[100:103], v[170:173], v[216:219], v[100:103]
	v_mfma_f32_16x16x32_bf16 v[96:99], v[178:181], v[216:219], v[96:99]
	v_mfma_f32_16x16x32_bf16 v[84:87], v[170:173], v[224:227], v[84:87]
	v_mfma_f32_16x16x32_bf16 v[80:83], v[178:181], v[224:227], v[80:83]
	v_mfma_f32_16x16x32_bf16 v[68:71], v[170:173], v[232:235], v[68:71]
	v_mfma_f32_16x16x32_bf16 v[64:67], v[178:181], v[232:235], v[64:67]
	v_mfma_f32_16x16x32_bf16 v[116:119], v[174:177], v[212:215], v[116:119]
	v_mfma_f32_16x16x32_bf16 v[112:115], v[182:185], v[212:215], v[112:115]
	v_mfma_f32_16x16x32_bf16 v[100:103], v[174:177], v[220:223], v[100:103]
	v_mfma_f32_16x16x32_bf16 v[96:99], v[182:185], v[220:223], v[96:99]
	v_mfma_f32_16x16x32_bf16 v[84:87], v[174:177], v[228:231], v[84:87]
	v_mfma_f32_16x16x32_bf16 v[80:83], v[182:185], v[228:231], v[80:83]
	v_mfma_f32_16x16x32_bf16 v[68:71], v[174:177], v[236:239], v[68:71]
	v_mfma_f32_16x16x32_bf16 v[64:67], v[182:185], v[236:239], v[64:67]
	s_setprio 0
	s_barrier
	s_mov_b32 m0, s7
	s_add_u32 s26, s36, 0xb0000
	ds_read_b128 v[186:189], v192 offset:16384
	ds_read_b128 v[212:215], v192 offset:17408
	ds_read_b128 v[216:219], v192 offset:18432
	ds_read_b128 v[220:223], v192 offset:19456
	ds_read_b128 v[224:227], v192 offset:20480
	ds_read_b128 v[228:231], v192 offset:21504
	ds_read_b128 v[232:235], v192 offset:22528
	ds_read_b128 v[236:239], v192 offset:23552
	global_load_lds_dwordx4 v158, s[36:37]
	s_mov_b32 m0, s23
	s_addc_u32 s27, s37, 0
	global_load_lds_dwordx4 v160, s[36:37]
	s_mov_b32 m0, s28
	s_add_u32 s98, s36, s18
	global_load_lds_dwordx4 v158, s[26:27]
	s_mov_b32 m0, s29
	s_addc_u32 s99, s37, s19
	global_load_lds_dwordx4 v160, s[26:27]
	s_mov_b32 m0, s6
	s_add_u32 s100, s38, s18
	global_load_lds_dwordx4 v158, s[38:39]
	s_mov_b32 m0, s30
	s_addc_u32 s101, s39, s19
	global_load_lds_dwordx4 v160, s[38:39]
	s_waitcnt vmcnt(8)
	s_waitcnt lgkmcnt(0)
	s_barrier
	s_setprio 1
	s_waitcnt lgkmcnt(0)
	v_mfma_f32_16x16x32_bf16 v[60:63], v[128:131], v[186:189], v[60:63]
	v_mfma_f32_16x16x32_bf16 v[56:59], v[136:139], v[186:189], v[56:59]
	v_mfma_f32_16x16x32_bf16 v[44:47], v[128:131], v[216:219], v[44:47]
	v_mfma_f32_16x16x32_bf16 v[40:43], v[136:139], v[216:219], v[40:43]
	v_mfma_f32_16x16x32_bf16 v[28:31], v[128:131], v[224:227], v[28:31]
	v_mfma_f32_16x16x32_bf16 v[24:27], v[136:139], v[224:227], v[24:27]
	v_mfma_f32_16x16x32_bf16 v[12:15], v[128:131], v[232:235], v[12:15]
	v_mfma_f32_16x16x32_bf16 v[8:11], v[136:139], v[232:235], v[8:11]
	v_mfma_f32_16x16x32_bf16 v[60:63], v[132:135], v[212:215], v[60:63]
	v_mfma_f32_16x16x32_bf16 v[56:59], v[140:143], v[212:215], v[56:59]
	v_mfma_f32_16x16x32_bf16 v[44:47], v[132:135], v[220:223], v[44:47]
	v_mfma_f32_16x16x32_bf16 v[40:43], v[140:143], v[220:223], v[40:43]
	v_mfma_f32_16x16x32_bf16 v[28:31], v[132:135], v[228:231], v[28:31]
	v_mfma_f32_16x16x32_bf16 v[24:27], v[140:143], v[228:231], v[24:27]
	v_mfma_f32_16x16x32_bf16 v[12:15], v[132:135], v[236:239], v[12:15]
	v_mfma_f32_16x16x32_bf16 v[8:11], v[140:143], v[236:239], v[8:11]
	s_setprio 0
	s_setprio 1
	v_mfma_f32_16x16x32_bf16 v[52:55], v[170:173], v[186:189], v[52:55]
	v_mfma_f32_16x16x32_bf16 v[48:51], v[178:181], v[186:189], v[48:51]
	v_mfma_f32_16x16x32_bf16 v[36:39], v[170:173], v[216:219], v[36:39]
	v_mfma_f32_16x16x32_bf16 v[32:35], v[178:181], v[216:219], v[32:35]
	v_mfma_f32_16x16x32_bf16 v[20:23], v[170:173], v[224:227], v[20:23]
	v_mfma_f32_16x16x32_bf16 v[16:19], v[178:181], v[224:227], v[16:19]
	v_mfma_f32_16x16x32_bf16 v[4:7], v[170:173], v[232:235], v[4:7]
	v_mfma_f32_16x16x32_bf16 v[0:3], v[178:181], v[232:235], v[0:3]
	v_mfma_f32_16x16x32_bf16 v[52:55], v[174:177], v[212:215], v[52:55]
	v_mfma_f32_16x16x32_bf16 v[48:51], v[182:185], v[212:215], v[48:51]
	v_mfma_f32_16x16x32_bf16 v[36:39], v[174:177], v[220:223], v[36:39]
	v_mfma_f32_16x16x32_bf16 v[32:35], v[182:185], v[220:223], v[32:35]
	v_mfma_f32_16x16x32_bf16 v[20:23], v[174:177], v[228:231], v[20:23]
	v_mfma_f32_16x16x32_bf16 v[16:19], v[182:185], v[228:231], v[16:19]
	v_mfma_f32_16x16x32_bf16 v[4:7], v[174:177], v[236:239], v[4:7]
	v_mfma_f32_16x16x32_bf16 v[0:3], v[182:185], v[236:239], v[0:3]
	s_setprio 0
	s_barrier
	ds_read_b128 v[128:131], v203
	ds_read_b128 v[132:135], v204
	ds_read_b128 v[136:139], v205
	ds_read_b128 v[140:143], v206
	ds_read_b128 v[170:173], v207
	ds_read_b128 v[174:177], v208
	ds_read_b128 v[178:181], v209
	ds_read_b128 v[182:185], v210
	s_add_u32 s26, s38, 0xb0000
	s_addc_u32 s27, s39, 0
	s_mov_b32 m0, s31
	ds_read_b128 v[186:189], v192 offset:32768
	ds_read_b128 v[212:215], v192 offset:33792
	ds_read_b128 v[216:219], v192 offset:34816
	ds_read_b128 v[220:223], v192 offset:35840
	ds_read_b128 v[224:227], v192 offset:36864
	ds_read_b128 v[228:231], v192 offset:37888
	ds_read_b128 v[232:235], v192 offset:38912
	ds_read_b128 v[236:239], v192 offset:39936
	global_load_lds_dwordx4 v158, s[26:27]
	s_mov_b32 m0, s33
	s_nop 0
	global_load_lds_dwordx4 v160, s[26:27]
	s_waitcnt vmcnt(8)
	s_waitcnt lgkmcnt(0)
	s_barrier
	s_setprio 1
	s_waitcnt lgkmcnt(0)
	v_mfma_f32_16x16x32_bf16 v[124:127], v[128:131], v[186:189], v[124:127]
	v_mfma_f32_16x16x32_bf16 v[120:123], v[136:139], v[186:189], v[120:123]
	v_mfma_f32_16x16x32_bf16 v[108:111], v[128:131], v[216:219], v[108:111]
	v_mfma_f32_16x16x32_bf16 v[104:107], v[136:139], v[216:219], v[104:107]
	v_mfma_f32_16x16x32_bf16 v[92:95], v[128:131], v[224:227], v[92:95]
	v_mfma_f32_16x16x32_bf16 v[88:91], v[136:139], v[224:227], v[88:91]
	v_mfma_f32_16x16x32_bf16 v[76:79], v[128:131], v[232:235], v[76:79]
	v_mfma_f32_16x16x32_bf16 v[72:75], v[136:139], v[232:235], v[72:75]
	v_mfma_f32_16x16x32_bf16 v[124:127], v[132:135], v[212:215], v[124:127]
	v_mfma_f32_16x16x32_bf16 v[120:123], v[140:143], v[212:215], v[120:123]
	v_mfma_f32_16x16x32_bf16 v[108:111], v[132:135], v[220:223], v[108:111]
	v_mfma_f32_16x16x32_bf16 v[104:107], v[140:143], v[220:223], v[104:107]
	v_mfma_f32_16x16x32_bf16 v[92:95], v[132:135], v[228:231], v[92:95]
	v_mfma_f32_16x16x32_bf16 v[88:91], v[140:143], v[228:231], v[88:91]
	v_mfma_f32_16x16x32_bf16 v[76:79], v[132:135], v[236:239], v[76:79]
	v_mfma_f32_16x16x32_bf16 v[72:75], v[140:143], v[236:239], v[72:75]
	s_setprio 0
	s_setprio 1
	v_mfma_f32_16x16x32_bf16 v[116:119], v[170:173], v[186:189], v[116:119]
	v_mfma_f32_16x16x32_bf16 v[112:115], v[178:181], v[186:189], v[112:115]
	v_mfma_f32_16x16x32_bf16 v[100:103], v[170:173], v[216:219], v[100:103]
	v_mfma_f32_16x16x32_bf16 v[96:99], v[178:181], v[216:219], v[96:99]
	v_mfma_f32_16x16x32_bf16 v[84:87], v[170:173], v[224:227], v[84:87]
	v_mfma_f32_16x16x32_bf16 v[80:83], v[178:181], v[224:227], v[80:83]
	v_mfma_f32_16x16x32_bf16 v[68:71], v[170:173], v[232:235], v[68:71]
	v_mfma_f32_16x16x32_bf16 v[64:67], v[178:181], v[232:235], v[64:67]
	v_mfma_f32_16x16x32_bf16 v[116:119], v[174:177], v[212:215], v[116:119]
	v_mfma_f32_16x16x32_bf16 v[112:115], v[182:185], v[212:215], v[112:115]
	v_mfma_f32_16x16x32_bf16 v[100:103], v[174:177], v[220:223], v[100:103]
	v_mfma_f32_16x16x32_bf16 v[96:99], v[182:185], v[220:223], v[96:99]
	v_mfma_f32_16x16x32_bf16 v[84:87], v[174:177], v[228:231], v[84:87]
	v_mfma_f32_16x16x32_bf16 v[80:83], v[182:185], v[228:231], v[80:83]
	v_mfma_f32_16x16x32_bf16 v[68:71], v[174:177], v[236:239], v[68:71]
	v_mfma_f32_16x16x32_bf16 v[64:67], v[182:185], v[236:239], v[64:67]
	s_setprio 0
	s_barrier
	s_mov_b32 m0, s40
	s_add_u32 s26, s36, 0xb0080
	ds_read_b128 v[186:189], v192 offset:49152
	ds_read_b128 v[212:215], v192 offset:50176
	ds_read_b128 v[216:219], v192 offset:51200
	ds_read_b128 v[220:223], v192 offset:52224
	ds_read_b128 v[224:227], v192 offset:53248
	ds_read_b128 v[228:231], v192 offset:54272
	ds_read_b128 v[232:235], v192 offset:55296
	ds_read_b128 v[236:239], v192 offset:56320
	global_load_lds_dwordx4 v158, s[98:99]
	s_mov_b32 m0, s41
	s_addc_u32 s27, s37, 0
	global_load_lds_dwordx4 v160, s[98:99]
	s_mov_b32 m0, s44
	s_add_u32 s4, s4, 0x100
	global_load_lds_dwordx4 v158, s[26:27]
	s_mov_b32 m0, s45
	s_addc_u32 s5, s5, 0
	global_load_lds_dwordx4 v160, s[26:27]
	s_mov_b32 m0, s42
	s_nop 0
	global_load_lds_dwordx4 v158, s[100:101]
	s_mov_b32 m0, s43
	s_nop 0
	global_load_lds_dwordx4 v160, s[100:101]
	s_waitcnt vmcnt(8)
	s_waitcnt lgkmcnt(0)
	s_barrier
	s_setprio 1
	s_waitcnt lgkmcnt(0)
	v_mfma_f32_16x16x32_bf16 v[60:63], v[128:131], v[186:189], v[60:63]
	v_mfma_f32_16x16x32_bf16 v[56:59], v[136:139], v[186:189], v[56:59]
	v_mfma_f32_16x16x32_bf16 v[44:47], v[128:131], v[216:219], v[44:47]
	v_mfma_f32_16x16x32_bf16 v[40:43], v[136:139], v[216:219], v[40:43]
	v_mfma_f32_16x16x32_bf16 v[28:31], v[128:131], v[224:227], v[28:31]
	v_mfma_f32_16x16x32_bf16 v[24:27], v[136:139], v[224:227], v[24:27]
	v_mfma_f32_16x16x32_bf16 v[12:15], v[128:131], v[232:235], v[12:15]
	v_mfma_f32_16x16x32_bf16 v[8:11], v[136:139], v[232:235], v[8:11]
	v_mfma_f32_16x16x32_bf16 v[60:63], v[132:135], v[212:215], v[60:63]
	v_mfma_f32_16x16x32_bf16 v[56:59], v[140:143], v[212:215], v[56:59]
	v_mfma_f32_16x16x32_bf16 v[44:47], v[132:135], v[220:223], v[44:47]
	v_mfma_f32_16x16x32_bf16 v[40:43], v[140:143], v[220:223], v[40:43]
	v_mfma_f32_16x16x32_bf16 v[28:31], v[132:135], v[228:231], v[28:31]
	v_mfma_f32_16x16x32_bf16 v[24:27], v[140:143], v[228:231], v[24:27]
	v_mfma_f32_16x16x32_bf16 v[12:15], v[132:135], v[236:239], v[12:15]
	v_mfma_f32_16x16x32_bf16 v[8:11], v[140:143], v[236:239], v[8:11]
	s_setprio 0
	s_setprio 1
	v_mfma_f32_16x16x32_bf16 v[52:55], v[170:173], v[186:189], v[52:55]
	v_mfma_f32_16x16x32_bf16 v[48:51], v[178:181], v[186:189], v[48:51]
	v_mfma_f32_16x16x32_bf16 v[36:39], v[170:173], v[216:219], v[36:39]
	v_mfma_f32_16x16x32_bf16 v[32:35], v[178:181], v[216:219], v[32:35]
	v_mfma_f32_16x16x32_bf16 v[20:23], v[170:173], v[224:227], v[20:23]
	v_mfma_f32_16x16x32_bf16 v[16:19], v[178:181], v[224:227], v[16:19]
	v_mfma_f32_16x16x32_bf16 v[4:7], v[170:173], v[232:235], v[4:7]
	v_mfma_f32_16x16x32_bf16 v[0:3], v[178:181], v[232:235], v[0:3]
	v_mfma_f32_16x16x32_bf16 v[52:55], v[174:177], v[212:215], v[52:55]
	v_mfma_f32_16x16x32_bf16 v[48:51], v[182:185], v[212:215], v[48:51]
	v_mfma_f32_16x16x32_bf16 v[36:39], v[174:177], v[220:223], v[36:39]
	v_mfma_f32_16x16x32_bf16 v[32:35], v[182:185], v[220:223], v[32:35]
	v_mfma_f32_16x16x32_bf16 v[20:23], v[174:177], v[228:231], v[20:23]
	v_mfma_f32_16x16x32_bf16 v[16:19], v[182:185], v[228:231], v[16:19]
	v_mfma_f32_16x16x32_bf16 v[4:7], v[174:177], v[236:239], v[4:7]
	v_mfma_f32_16x16x32_bf16 v[0:3], v[182:185], v[236:239], v[0:3]
	s_setprio 0
	s_barrier
	s_add_i32 s64, s64, 2
	s_cmp_gt_u32 s64, 41
	s_mov_b64 s[26:27], s[34:35]
	s_cbranch_scc0 .LBB0_3029
	s_and_b64 vcc, exec, s[20:21]
	s_cbranch_vccz .LBB0_3032
	s_barrier

.LBB0_3179:
	ds_read_b128 v[140:143], v154
	ds_read_b128 v[170:173], v155
	ds_read_b128 v[174:177], v156
	ds_read_b128 v[178:181], v157
	ds_read_b128 v[182:185], v158
	ds_read_b128 v[186:189], v159
	ds_read_b128 v[190:193], v160
	ds_read_b128 v[194:197], v161
	s_add_u32 s34, s14, 0xfffc0080
	s_addc_u32 s35, s15, -1
	s_cmp_eq_u32 s54, 12
	s_cselect_b32 s37, s4, s35
	s_cselect_b32 s36, s5, s34
	s_cselect_b32 s35, s11, s25
	s_cselect_b32 s34, s13, s23
	s_mov_b32 m0, s51
	ds_read_b128 v[198:201], v149
	ds_read_b128 v[202:205], v149 offset:1024
	ds_read_b128 v[206:209], v149 offset:2048
	ds_read_b128 v[210:213], v149 offset:3072
	ds_read_b128 v[214:217], v149 offset:4096
	ds_read_b128 v[218:221], v149 offset:5120
	ds_read_b128 v[222:225], v149 offset:6144
	ds_read_b128 v[226:229], v149 offset:7168
	global_load_lds_dwordx4 v132, s[14:15]
	s_mov_b32 m0, s52
	s_nop 0
	global_load_lds_dwordx4 v134, s[14:15]
	s_waitcnt vmcnt(8)
	s_waitcnt lgkmcnt(0)
	s_barrier
	s_setprio 1
	s_waitcnt lgkmcnt(0)
	v_mfma_f32_16x16x32_bf16 v[124:127], v[140:143], v[198:201], v[124:127]
	v_mfma_f32_16x16x32_bf16 v[120:123], v[174:177], v[198:201], v[120:123]
	v_mfma_f32_16x16x32_bf16 v[108:111], v[140:143], v[206:209], v[108:111]
	v_mfma_f32_16x16x32_bf16 v[104:107], v[174:177], v[206:209], v[104:107]
	v_mfma_f32_16x16x32_bf16 v[92:95], v[140:143], v[214:217], v[92:95]
	v_mfma_f32_16x16x32_bf16 v[88:91], v[174:177], v[214:217], v[88:91]
	v_mfma_f32_16x16x32_bf16 v[76:79], v[140:143], v[222:225], v[76:79]
	v_mfma_f32_16x16x32_bf16 v[72:75], v[174:177], v[222:225], v[72:75]
	v_mfma_f32_16x16x32_bf16 v[124:127], v[170:173], v[202:205], v[124:127]
	v_mfma_f32_16x16x32_bf16 v[120:123], v[178:181], v[202:205], v[120:123]
	v_mfma_f32_16x16x32_bf16 v[108:111], v[170:173], v[210:213], v[108:111]
	v_mfma_f32_16x16x32_bf16 v[104:107], v[178:181], v[210:213], v[104:107]
	v_mfma_f32_16x16x32_bf16 v[92:95], v[170:173], v[218:221], v[92:95]
	v_mfma_f32_16x16x32_bf16 v[88:91], v[178:181], v[218:221], v[88:91]
	v_mfma_f32_16x16x32_bf16 v[76:79], v[170:173], v[226:229], v[76:79]
	v_mfma_f32_16x16x32_bf16 v[72:75], v[178:181], v[226:229], v[72:75]
	s_setprio 0
	s_setprio 1
	v_mfma_f32_16x16x32_bf16 v[116:119], v[182:185], v[198:201], v[116:119]
	v_mfma_f32_16x16x32_bf16 v[112:115], v[190:193], v[198:201], v[112:115]
	v_mfma_f32_16x16x32_bf16 v[100:103], v[182:185], v[206:209], v[100:103]
	v_mfma_f32_16x16x32_bf16 v[96:99], v[190:193], v[206:209], v[96:99]
	v_mfma_f32_16x16x32_bf16 v[84:87], v[182:185], v[214:217], v[84:87]
	v_mfma_f32_16x16x32_bf16 v[80:83], v[190:193], v[214:217], v[80:83]
	v_mfma_f32_16x16x32_bf16 v[68:71], v[182:185], v[222:225], v[68:71]
	v_mfma_f32_16x16x32_bf16 v[64:67], v[190:193], v[222:225], v[64:67]
	v_mfma_f32_16x16x32_bf16 v[116:119], v[186:189], v[202:205], v[116:119]
	v_mfma_f32_16x16x32_bf16 v[112:115], v[194:197], v[202:205], v[112:115]
	v_mfma_f32_16x16x32_bf16 v[100:103], v[186:189], v[210:213], v[100:103]
	v_mfma_f32_16x16x32_bf16 v[96:99], v[194:197], v[210:213], v[96:99]
	v_mfma_f32_16x16x32_bf16 v[84:87], v[186:189], v[218:221], v[84:87]
	v_mfma_f32_16x16x32_bf16 v[80:83], v[194:197], v[218:221], v[80:83]
	v_mfma_f32_16x16x32_bf16 v[68:71], v[186:189], v[226:229], v[68:71]
	v_mfma_f32_16x16x32_bf16 v[64:67], v[194:197], v[226:229], v[64:67]
	s_setprio 0
	s_barrier
	s_mov_b32 m0, s6
	s_add_u32 s60, s34, 0x40000
	ds_read_b128 v[198:201], v149 offset:16384
	ds_read_b128 v[202:205], v149 offset:17408
	ds_read_b128 v[206:209], v149 offset:18432
	ds_read_b128 v[210:213], v149 offset:19456
	ds_read_b128 v[214:217], v149 offset:20480
	ds_read_b128 v[218:221], v149 offset:21504
	ds_read_b128 v[222:225], v149 offset:22528
	ds_read_b128 v[226:229], v149 offset:23552
	global_load_lds_dwordx4 v128, s[34:35]
	s_mov_b32 m0, s7
	s_addc_u32 s61, s35, 0
	global_load_lds_dwordx4 v130, s[34:35]
	s_mov_b32 m0, s21
	s_add_u32 s98, s34, s16
	global_load_lds_dwordx4 v128, s[60:61]
	s_mov_b32 m0, s28
	s_addc_u32 s99, s35, s17
	global_load_lds_dwordx4 v130, s[60:61]
	s_mov_b32 m0, s2
	s_add_u32 s100, s36, s16
	global_load_lds_dwordx4 v128, s[36:37]
	s_mov_b32 m0, s29
	s_addc_u32 s101, s37, s17
	global_load_lds_dwordx4 v130, s[36:37]
	s_waitcnt vmcnt(8)
	s_waitcnt lgkmcnt(0)
	s_barrier
	s_setprio 1
	s_waitcnt lgkmcnt(0)
	v_mfma_f32_16x16x32_bf16 v[60:63], v[140:143], v[198:201], v[60:63]
	v_mfma_f32_16x16x32_bf16 v[56:59], v[174:177], v[198:201], v[56:59]
	v_mfma_f32_16x16x32_bf16 v[44:47], v[140:143], v[206:209], v[44:47]
	v_mfma_f32_16x16x32_bf16 v[40:43], v[174:177], v[206:209], v[40:43]
	v_mfma_f32_16x16x32_bf16 v[28:31], v[140:143], v[214:217], v[28:31]
	v_mfma_f32_16x16x32_bf16 v[24:27], v[174:177], v[214:217], v[24:27]
	v_mfma_f32_16x16x32_bf16 v[12:15], v[140:143], v[222:225], v[12:15]
	v_mfma_f32_16x16x32_bf16 v[8:11], v[174:177], v[222:225], v[8:11]
	v_mfma_f32_16x16x32_bf16 v[60:63], v[170:173], v[202:205], v[60:63]
	v_mfma_f32_16x16x32_bf16 v[56:59], v[178:181], v[202:205], v[56:59]
	v_mfma_f32_16x16x32_bf16 v[44:47], v[170:173], v[210:213], v[44:47]
	v_mfma_f32_16x16x32_bf16 v[40:43], v[178:181], v[210:213], v[40:43]
	v_mfma_f32_16x16x32_bf16 v[28:31], v[170:173], v[218:221], v[28:31]
	v_mfma_f32_16x16x32_bf16 v[24:27], v[178:181], v[218:221], v[24:27]
	v_mfma_f32_16x16x32_bf16 v[12:15], v[170:173], v[226:229], v[12:15]
	v_mfma_f32_16x16x32_bf16 v[8:11], v[178:181], v[226:229], v[8:11]
	s_setprio 0
	s_setprio 1
	v_mfma_f32_16x16x32_bf16 v[52:55], v[182:185], v[198:201], v[52:55]
	v_mfma_f32_16x16x32_bf16 v[48:51], v[190:193], v[198:201], v[48:51]
	v_mfma_f32_16x16x32_bf16 v[36:39], v[182:185], v[206:209], v[36:39]
	v_mfma_f32_16x16x32_bf16 v[32:35], v[190:193], v[206:209], v[32:35]
	v_mfma_f32_16x16x32_bf16 v[20:23], v[182:185], v[214:217], v[20:23]
	v_mfma_f32_16x16x32_bf16 v[16:19], v[190:193], v[214:217], v[16:19]
	v_mfma_f32_16x16x32_bf16 v[4:7], v[182:185], v[222:225], v[4:7]
	v_mfma_f32_16x16x32_bf16 v[0:3], v[190:193], v[222:225], v[0:3]
	v_mfma_f32_16x16x32_bf16 v[52:55], v[186:189], v[202:205], v[52:55]
	v_mfma_f32_16x16x32_bf16 v[48:51], v[194:197], v[202:205], v[48:51]
	v_mfma_f32_16x16x32_bf16 v[36:39], v[186:189], v[210:213], v[36:39]
	v_mfma_f32_16x16x32_bf16 v[32:35], v[194:197], v[210:213], v[32:35]
	v_mfma_f32_16x16x32_bf16 v[20:23], v[186:189], v[218:221], v[20:23]
	v_mfma_f32_16x16x32_bf16 v[16:19], v[194:197], v[218:221], v[16:19]
	v_mfma_f32_16x16x32_bf16 v[4:7], v[186:189], v[226:229], v[4:7]
	v_mfma_f32_16x16x32_bf16 v[0:3], v[194:197], v[226:229], v[0:3]
	s_setprio 0
	s_barrier
	ds_read_b128 v[140:143], v162
	ds_read_b128 v[170:173], v163
	ds_read_b128 v[174:177], v164
	ds_read_b128 v[178:181], v165
	ds_read_b128 v[182:185], v166
	ds_read_b128 v[186:189], v167
	ds_read_b128 v[190:193], v168
	ds_read_b128 v[194:197], v169
	s_add_u32 s36, s36, 0x40000
	s_addc_u32 s37, s37, 0
	s_mov_b32 m0, s33
	ds_read_b128 v[198:201], v149 offset:32768
	ds_read_b128 v[202:205], v149 offset:33792
	ds_read_b128 v[206:209], v149 offset:34816
	ds_read_b128 v[210:213], v149 offset:35840
	ds_read_b128 v[214:217], v149 offset:36864
	ds_read_b128 v[218:221], v149 offset:37888
	ds_read_b128 v[222:225], v149 offset:38912
	ds_read_b128 v[226:229], v149 offset:39936
	global_load_lds_dwordx4 v128, s[36:37]
	s_mov_b32 m0, s38
	s_nop 0
	global_load_lds_dwordx4 v130, s[36:37]
	s_waitcnt vmcnt(8)
	s_waitcnt lgkmcnt(0)
	s_barrier
	s_setprio 1
	s_waitcnt lgkmcnt(0)
	v_mfma_f32_16x16x32_bf16 v[124:127], v[140:143], v[198:201], v[124:127]
	v_mfma_f32_16x16x32_bf16 v[120:123], v[174:177], v[198:201], v[120:123]
	v_mfma_f32_16x16x32_bf16 v[108:111], v[140:143], v[206:209], v[108:111]
	v_mfma_f32_16x16x32_bf16 v[104:107], v[174:177], v[206:209], v[104:107]
	v_mfma_f32_16x16x32_bf16 v[92:95], v[140:143], v[214:217], v[92:95]
	v_mfma_f32_16x16x32_bf16 v[88:91], v[174:177], v[214:217], v[88:91]
	v_mfma_f32_16x16x32_bf16 v[76:79], v[140:143], v[222:225], v[76:79]
	v_mfma_f32_16x16x32_bf16 v[72:75], v[174:177], v[222:225], v[72:75]
	v_mfma_f32_16x16x32_bf16 v[124:127], v[170:173], v[202:205], v[124:127]
	v_mfma_f32_16x16x32_bf16 v[120:123], v[178:181], v[202:205], v[120:123]
	v_mfma_f32_16x16x32_bf16 v[108:111], v[170:173], v[210:213], v[108:111]
	v_mfma_f32_16x16x32_bf16 v[104:107], v[178:181], v[210:213], v[104:107]
	v_mfma_f32_16x16x32_bf16 v[92:95], v[170:173], v[218:221], v[92:95]
	v_mfma_f32_16x16x32_bf16 v[88:91], v[178:181], v[218:221], v[88:91]
	v_mfma_f32_16x16x32_bf16 v[76:79], v[170:173], v[226:229], v[76:79]
	v_mfma_f32_16x16x32_bf16 v[72:75], v[178:181], v[226:229], v[72:75]
	s_setprio 0
	s_setprio 1
	v_mfma_f32_16x16x32_bf16 v[116:119], v[182:185], v[198:201], v[116:119]
	v_mfma_f32_16x16x32_bf16 v[112:115], v[190:193], v[198:201], v[112:115]
	v_mfma_f32_16x16x32_bf16 v[100:103], v[182:185], v[206:209], v[100:103]
	v_mfma_f32_16x16x32_bf16 v[96:99], v[190:193], v[206:209], v[96:99]
	v_mfma_f32_16x16x32_bf16 v[84:87], v[182:185], v[214:217], v[84:87]
	v_mfma_f32_16x16x32_bf16 v[80:83], v[190:193], v[214:217], v[80:83]
	v_mfma_f32_16x16x32_bf16 v[68:71], v[182:185], v[222:225], v[68:71]
	v_mfma_f32_16x16x32_bf16 v[64:67], v[190:193], v[222:225], v[64:67]
	v_mfma_f32_16x16x32_bf16 v[116:119], v[186:189], v[202:205], v[116:119]
	v_mfma_f32_16x16x32_bf16 v[112:115], v[194:197], v[202:205], v[112:115]
	v_mfma_f32_16x16x32_bf16 v[100:103], v[186:189], v[210:213], v[100:103]
	v_mfma_f32_16x16x32_bf16 v[96:99], v[194:197], v[210:213], v[96:99]
	v_mfma_f32_16x16x32_bf16 v[84:87], v[186:189], v[218:221], v[84:87]
	v_mfma_f32_16x16x32_bf16 v[80:83], v[194:197], v[218:221], v[80:83]
	v_mfma_f32_16x16x32_bf16 v[68:71], v[186:189], v[226:229], v[68:71]
	v_mfma_f32_16x16x32_bf16 v[64:67], v[194:197], v[226:229], v[64:67]
	s_setprio 0
	s_barrier
	s_mov_b32 m0, s40
	s_add_u32 s34, s34, 0x40080
	ds_read_b128 v[198:201], v149 offset:49152
	ds_read_b128 v[202:205], v149 offset:50176
	ds_read_b128 v[206:209], v149 offset:51200
	ds_read_b128 v[210:213], v149 offset:52224
	ds_read_b128 v[214:217], v149 offset:53248
	ds_read_b128 v[218:221], v149 offset:54272
	ds_read_b128 v[222:225], v149 offset:55296
	ds_read_b128 v[226:229], v149 offset:56320
	global_load_lds_dwordx4 v128, s[98:99]
	s_mov_b32 m0, s41
	s_addc_u32 s35, s35, 0
	global_load_lds_dwordx4 v130, s[98:99]
	s_mov_b32 m0, s44
	s_add_u32 s14, s14, 0x100
	global_load_lds_dwordx4 v128, s[34:35]
	s_mov_b32 m0, s45
	s_addc_u32 s15, s15, 0
	global_load_lds_dwordx4 v130, s[34:35]
	s_mov_b32 m0, s42
	s_add_u32 s23, s23, 0x100
	global_load_lds_dwordx4 v128, s[100:101]
	s_mov_b32 m0, s43
	s_addc_u32 s25, s25, 0
	global_load_lds_dwordx4 v130, s[100:101]
	s_waitcnt vmcnt(8)
	s_waitcnt lgkmcnt(0)
	s_barrier
	s_setprio 1
	s_waitcnt lgkmcnt(0)
	v_mfma_f32_16x16x32_bf16 v[60:63], v[140:143], v[198:201], v[60:63]
	v_mfma_f32_16x16x32_bf16 v[56:59], v[174:177], v[198:201], v[56:59]
	v_mfma_f32_16x16x32_bf16 v[44:47], v[140:143], v[206:209], v[44:47]
	v_mfma_f32_16x16x32_bf16 v[40:43], v[174:177], v[206:209], v[40:43]
	v_mfma_f32_16x16x32_bf16 v[28:31], v[140:143], v[214:217], v[28:31]
	v_mfma_f32_16x16x32_bf16 v[24:27], v[174:177], v[214:217], v[24:27]
	v_mfma_f32_16x16x32_bf16 v[12:15], v[140:143], v[222:225], v[12:15]
	v_mfma_f32_16x16x32_bf16 v[8:11], v[174:177], v[222:225], v[8:11]
	v_mfma_f32_16x16x32_bf16 v[60:63], v[170:173], v[202:205], v[60:63]
	v_mfma_f32_16x16x32_bf16 v[56:59], v[178:181], v[202:205], v[56:59]
	v_mfma_f32_16x16x32_bf16 v[44:47], v[170:173], v[210:213], v[44:47]
	v_mfma_f32_16x16x32_bf16 v[40:43], v[178:181], v[210:213], v[40:43]
	v_mfma_f32_16x16x32_bf16 v[28:31], v[170:173], v[218:221], v[28:31]
	v_mfma_f32_16x16x32_bf16 v[24:27], v[178:181], v[218:221], v[24:27]
	v_mfma_f32_16x16x32_bf16 v[12:15], v[170:173], v[226:229], v[12:15]
	v_mfma_f32_16x16x32_bf16 v[8:11], v[178:181], v[226:229], v[8:11]
	s_setprio 0
	s_setprio 1
	v_mfma_f32_16x16x32_bf16 v[52:55], v[182:185], v[198:201], v[52:55]
	v_mfma_f32_16x16x32_bf16 v[48:51], v[190:193], v[198:201], v[48:51]
	v_mfma_f32_16x16x32_bf16 v[36:39], v[182:185], v[206:209], v[36:39]
	v_mfma_f32_16x16x32_bf16 v[32:35], v[190:193], v[206:209], v[32:35]
	v_mfma_f32_16x16x32_bf16 v[20:23], v[182:185], v[214:217], v[20:23]
	v_mfma_f32_16x16x32_bf16 v[16:19], v[190:193], v[214:217], v[16:19]
	v_mfma_f32_16x16x32_bf16 v[4:7], v[182:185], v[222:225], v[4:7]
	v_mfma_f32_16x16x32_bf16 v[0:3], v[190:193], v[222:225], v[0:3]
	v_mfma_f32_16x16x32_bf16 v[52:55], v[186:189], v[202:205], v[52:55]
	v_mfma_f32_16x16x32_bf16 v[48:51], v[194:197], v[202:205], v[48:51]
	v_mfma_f32_16x16x32_bf16 v[36:39], v[186:189], v[210:213], v[36:39]
	v_mfma_f32_16x16x32_bf16 v[32:35], v[194:197], v[210:213], v[32:35]
	v_mfma_f32_16x16x32_bf16 v[20:23], v[186:189], v[218:221], v[20:23]
	v_mfma_f32_16x16x32_bf16 v[16:19], v[194:197], v[218:221], v[16:19]
	v_mfma_f32_16x16x32_bf16 v[4:7], v[186:189], v[226:229], v[4:7]
	v_mfma_f32_16x16x32_bf16 v[0:3], v[194:197], v[226:229], v[0:3]
	s_setprio 0
	s_barrier
	s_add_i32 s54, s54, 2
	s_cmp_gt_u32 s54, 13
	s_cbranch_scc0 .LBB0_3179
	s_and_b64 vcc, exec, s[18:19]
	s_cbranch_vccz .LBB0_3182
	s_barrier

.LBB0_3534:
	ds_read_b128 v[128:131], v188
	ds_read_b128 v[132:135], v189
	ds_read_b128 v[136:139], v190
	ds_read_b128 v[140:143], v191
	ds_read_b128 v[166:169], v192
	ds_read_b128 v[170:173], v193
	ds_read_b128 v[174:177], v194
	ds_read_b128 v[178:181], v195
	s_add_u32 s34, s30, 0x100
	s_addc_u32 s35, s31, 0
	s_cmp_eq_u32 s68, 12
	s_cselect_b32 s39, s4, s35
	s_cselect_b32 s38, s5, s34
	s_cselect_b32 s37, s21, s67
	s_cselect_b32 s36, s23, s66
	s_mov_b32 m0, s55
	ds_read_b128 v[182:185], v149
	ds_read_b128 v[206:209], v149 offset:1024
	ds_read_b128 v[210:213], v149 offset:2048
	ds_read_b128 v[214:217], v149 offset:3072
	ds_read_b128 v[218:221], v149 offset:4096
	ds_read_b128 v[222:225], v149 offset:5120
	ds_read_b128 v[226:229], v149 offset:6144
	ds_read_b128 v[230:233], v149 offset:7168
	global_load_lds_dwordx4 v158, s[30:31]
	s_mov_b32 m0, s60
	s_nop 0
	global_load_lds_dwordx4 v160, s[30:31]
	s_waitcnt vmcnt(8)
	s_waitcnt lgkmcnt(0)
	s_barrier
	s_setprio 1
	s_waitcnt lgkmcnt(0)
	v_mfma_f32_16x16x32_bf16 v[124:127], v[128:131], v[182:185], v[124:127]
	v_mfma_f32_16x16x32_bf16 v[120:123], v[136:139], v[182:185], v[120:123]
	v_mfma_f32_16x16x32_bf16 v[108:111], v[128:131], v[210:213], v[108:111]
	v_mfma_f32_16x16x32_bf16 v[104:107], v[136:139], v[210:213], v[104:107]
	v_mfma_f32_16x16x32_bf16 v[92:95], v[128:131], v[218:221], v[92:95]
	v_mfma_f32_16x16x32_bf16 v[88:91], v[136:139], v[218:221], v[88:91]
	v_mfma_f32_16x16x32_bf16 v[76:79], v[128:131], v[226:229], v[76:79]
	v_mfma_f32_16x16x32_bf16 v[72:75], v[136:139], v[226:229], v[72:75]
	v_mfma_f32_16x16x32_bf16 v[124:127], v[132:135], v[206:209], v[124:127]
	v_mfma_f32_16x16x32_bf16 v[120:123], v[140:143], v[206:209], v[120:123]
	v_mfma_f32_16x16x32_bf16 v[108:111], v[132:135], v[214:217], v[108:111]
	v_mfma_f32_16x16x32_bf16 v[104:107], v[140:143], v[214:217], v[104:107]
	v_mfma_f32_16x16x32_bf16 v[92:95], v[132:135], v[222:225], v[92:95]
	v_mfma_f32_16x16x32_bf16 v[88:91], v[140:143], v[222:225], v[88:91]
	v_mfma_f32_16x16x32_bf16 v[76:79], v[132:135], v[230:233], v[76:79]
	v_mfma_f32_16x16x32_bf16 v[72:75], v[140:143], v[230:233], v[72:75]
	s_setprio 0
	s_setprio 1
	v_mfma_f32_16x16x32_bf16 v[116:119], v[166:169], v[182:185], v[116:119]
	v_mfma_f32_16x16x32_bf16 v[112:115], v[174:177], v[182:185], v[112:115]
	v_mfma_f32_16x16x32_bf16 v[100:103], v[166:169], v[210:213], v[100:103]
	v_mfma_f32_16x16x32_bf16 v[96:99], v[174:177], v[210:213], v[96:99]
	v_mfma_f32_16x16x32_bf16 v[84:87], v[166:169], v[218:221], v[84:87]
	v_mfma_f32_16x16x32_bf16 v[80:83], v[174:177], v[218:221], v[80:83]
	v_mfma_f32_16x16x32_bf16 v[68:71], v[166:169], v[226:229], v[68:71]
	v_mfma_f32_16x16x32_bf16 v[64:67], v[174:177], v[226:229], v[64:67]
	v_mfma_f32_16x16x32_bf16 v[116:119], v[170:173], v[206:209], v[116:119]
	v_mfma_f32_16x16x32_bf16 v[112:115], v[178:181], v[206:209], v[112:115]
	v_mfma_f32_16x16x32_bf16 v[100:103], v[170:173], v[214:217], v[100:103]
	v_mfma_f32_16x16x32_bf16 v[96:99], v[178:181], v[214:217], v[96:99]
	v_mfma_f32_16x16x32_bf16 v[84:87], v[170:173], v[222:225], v[84:87]
	v_mfma_f32_16x16x32_bf16 v[80:83], v[178:181], v[222:225], v[80:83]
	v_mfma_f32_16x16x32_bf16 v[68:71], v[170:173], v[230:233], v[68:71]
	v_mfma_f32_16x16x32_bf16 v[64:67], v[178:181], v[230:233], v[64:67]
	s_setprio 0
	s_barrier
	s_mov_b32 m0, s29
	s_add_u32 s30, s36, 0x40000
	ds_read_b128 v[182:185], v149 offset:16384
	ds_read_b128 v[206:209], v149 offset:17408
	ds_read_b128 v[210:213], v149 offset:18432
	ds_read_b128 v[214:217], v149 offset:19456
	ds_read_b128 v[218:221], v149 offset:20480
	ds_read_b128 v[222:225], v149 offset:21504
	ds_read_b128 v[226:229], v149 offset:22528
	ds_read_b128 v[230:233], v149 offset:23552
	global_load_lds_dwordx4 v154, s[36:37]
	s_mov_b32 m0, s33
	s_addc_u32 s31, s37, 0
	global_load_lds_dwordx4 v156, s[36:37]
	s_mov_b32 m0, s40
	s_add_u32 s98, s36, s14
	global_load_lds_dwordx4 v154, s[30:31]
	s_mov_b32 m0, s41
	s_addc_u32 s99, s37, s15
	global_load_lds_dwordx4 v156, s[30:31]
	s_mov_b32 m0, s19
	s_add_u32 s100, s38, s14
	global_load_lds_dwordx4 v154, s[38:39]
	s_mov_b32 m0, s42
	s_addc_u32 s101, s39, s15
	global_load_lds_dwordx4 v156, s[38:39]
	s_waitcnt vmcnt(8)
	s_waitcnt lgkmcnt(0)
	s_barrier
	s_setprio 1
	s_waitcnt lgkmcnt(0)
	v_mfma_f32_16x16x32_bf16 v[60:63], v[128:131], v[182:185], v[60:63]
	v_mfma_f32_16x16x32_bf16 v[56:59], v[136:139], v[182:185], v[56:59]
	v_mfma_f32_16x16x32_bf16 v[44:47], v[128:131], v[210:213], v[44:47]
	v_mfma_f32_16x16x32_bf16 v[40:43], v[136:139], v[210:213], v[40:43]
	v_mfma_f32_16x16x32_bf16 v[28:31], v[128:131], v[218:221], v[28:31]
	v_mfma_f32_16x16x32_bf16 v[24:27], v[136:139], v[218:221], v[24:27]
	v_mfma_f32_16x16x32_bf16 v[12:15], v[128:131], v[226:229], v[12:15]
	v_mfma_f32_16x16x32_bf16 v[8:11], v[136:139], v[226:229], v[8:11]
	v_mfma_f32_16x16x32_bf16 v[60:63], v[132:135], v[206:209], v[60:63]
	v_mfma_f32_16x16x32_bf16 v[56:59], v[140:143], v[206:209], v[56:59]
	v_mfma_f32_16x16x32_bf16 v[44:47], v[132:135], v[214:217], v[44:47]
	v_mfma_f32_16x16x32_bf16 v[40:43], v[140:143], v[214:217], v[40:43]
	v_mfma_f32_16x16x32_bf16 v[28:31], v[132:135], v[222:225], v[28:31]
	v_mfma_f32_16x16x32_bf16 v[24:27], v[140:143], v[222:225], v[24:27]
	v_mfma_f32_16x16x32_bf16 v[12:15], v[132:135], v[230:233], v[12:15]
	v_mfma_f32_16x16x32_bf16 v[8:11], v[140:143], v[230:233], v[8:11]
	s_setprio 0
	s_setprio 1
	v_mfma_f32_16x16x32_bf16 v[52:55], v[166:169], v[182:185], v[52:55]
	v_mfma_f32_16x16x32_bf16 v[48:51], v[174:177], v[182:185], v[48:51]
	v_mfma_f32_16x16x32_bf16 v[36:39], v[166:169], v[210:213], v[36:39]
	v_mfma_f32_16x16x32_bf16 v[32:35], v[174:177], v[210:213], v[32:35]
	v_mfma_f32_16x16x32_bf16 v[20:23], v[166:169], v[218:221], v[20:23]
	v_mfma_f32_16x16x32_bf16 v[16:19], v[174:177], v[218:221], v[16:19]
	v_mfma_f32_16x16x32_bf16 v[4:7], v[166:169], v[226:229], v[4:7]
	v_mfma_f32_16x16x32_bf16 v[0:3], v[174:177], v[226:229], v[0:3]
	v_mfma_f32_16x16x32_bf16 v[52:55], v[170:173], v[206:209], v[52:55]
	v_mfma_f32_16x16x32_bf16 v[48:51], v[178:181], v[206:209], v[48:51]
	v_mfma_f32_16x16x32_bf16 v[36:39], v[170:173], v[214:217], v[36:39]
	v_mfma_f32_16x16x32_bf16 v[32:35], v[178:181], v[214:217], v[32:35]
	v_mfma_f32_16x16x32_bf16 v[20:23], v[170:173], v[222:225], v[20:23]
	v_mfma_f32_16x16x32_bf16 v[16:19], v[178:181], v[222:225], v[16:19]
	v_mfma_f32_16x16x32_bf16 v[4:7], v[170:173], v[230:233], v[4:7]
	v_mfma_f32_16x16x32_bf16 v[0:3], v[178:181], v[230:233], v[0:3]
	s_setprio 0
	s_barrier
	ds_read_b128 v[128:131], v196
	ds_read_b128 v[132:135], v197
	ds_read_b128 v[136:139], v198
	ds_read_b128 v[140:143], v199
	ds_read_b128 v[166:169], v200
	ds_read_b128 v[170:173], v201
	ds_read_b128 v[174:177], v202
	ds_read_b128 v[178:181], v203
	s_add_u32 s30, s38, 0x40000
	s_addc_u32 s31, s39, 0
	s_mov_b32 m0, s43
	ds_read_b128 v[182:185], v149 offset:32768
	ds_read_b128 v[206:209], v149 offset:33792
	ds_read_b128 v[210:213], v149 offset:34816
	ds_read_b128 v[214:217], v149 offset:35840
	ds_read_b128 v[218:221], v149 offset:36864
	ds_read_b128 v[222:225], v149 offset:37888
	ds_read_b128 v[226:229], v149 offset:38912
	ds_read_b128 v[230:233], v149 offset:39936
	global_load_lds_dwordx4 v154, s[30:31]
	s_mov_b32 m0, s44
	s_nop 0
	global_load_lds_dwordx4 v156, s[30:31]
	s_waitcnt vmcnt(8)
	s_waitcnt lgkmcnt(0)
	s_barrier
	s_setprio 1
	s_waitcnt lgkmcnt(0)
	v_mfma_f32_16x16x32_bf16 v[124:127], v[128:131], v[182:185], v[124:127]
	v_mfma_f32_16x16x32_bf16 v[120:123], v[136:139], v[182:185], v[120:123]
	v_mfma_f32_16x16x32_bf16 v[108:111], v[128:131], v[210:213], v[108:111]
	v_mfma_f32_16x16x32_bf16 v[104:107], v[136:139], v[210:213], v[104:107]
	v_mfma_f32_16x16x32_bf16 v[92:95], v[128:131], v[218:221], v[92:95]
	v_mfma_f32_16x16x32_bf16 v[88:91], v[136:139], v[218:221], v[88:91]
	v_mfma_f32_16x16x32_bf16 v[76:79], v[128:131], v[226:229], v[76:79]
	v_mfma_f32_16x16x32_bf16 v[72:75], v[136:139], v[226:229], v[72:75]
	v_mfma_f32_16x16x32_bf16 v[124:127], v[132:135], v[206:209], v[124:127]
	v_mfma_f32_16x16x32_bf16 v[120:123], v[140:143], v[206:209], v[120:123]
	v_mfma_f32_16x16x32_bf16 v[108:111], v[132:135], v[214:217], v[108:111]
	v_mfma_f32_16x16x32_bf16 v[104:107], v[140:143], v[214:217], v[104:107]
	v_mfma_f32_16x16x32_bf16 v[92:95], v[132:135], v[222:225], v[92:95]
	v_mfma_f32_16x16x32_bf16 v[88:91], v[140:143], v[222:225], v[88:91]
	v_mfma_f32_16x16x32_bf16 v[76:79], v[132:135], v[230:233], v[76:79]
	v_mfma_f32_16x16x32_bf16 v[72:75], v[140:143], v[230:233], v[72:75]
	s_setprio 0
	s_setprio 1
	v_mfma_f32_16x16x32_bf16 v[116:119], v[166:169], v[182:185], v[116:119]
	v_mfma_f32_16x16x32_bf16 v[112:115], v[174:177], v[182:185], v[112:115]
	v_mfma_f32_16x16x32_bf16 v[100:103], v[166:169], v[210:213], v[100:103]
	v_mfma_f32_16x16x32_bf16 v[96:99], v[174:177], v[210:213], v[96:99]
	v_mfma_f32_16x16x32_bf16 v[84:87], v[166:169], v[218:221], v[84:87]
	v_mfma_f32_16x16x32_bf16 v[80:83], v[174:177], v[218:221], v[80:83]
	v_mfma_f32_16x16x32_bf16 v[68:71], v[166:169], v[226:229], v[68:71]
	v_mfma_f32_16x16x32_bf16 v[64:67], v[174:177], v[226:229], v[64:67]
	v_mfma_f32_16x16x32_bf16 v[116:119], v[170:173], v[206:209], v[116:119]
	v_mfma_f32_16x16x32_bf16 v[112:115], v[178:181], v[206:209], v[112:115]
	v_mfma_f32_16x16x32_bf16 v[100:103], v[170:173], v[214:217], v[100:103]
	v_mfma_f32_16x16x32_bf16 v[96:99], v[178:181], v[214:217], v[96:99]
	v_mfma_f32_16x16x32_bf16 v[84:87], v[170:173], v[222:225], v[84:87]
	v_mfma_f32_16x16x32_bf16 v[80:83], v[178:181], v[222:225], v[80:83]
	v_mfma_f32_16x16x32_bf16 v[68:71], v[170:173], v[230:233], v[68:71]
	v_mfma_f32_16x16x32_bf16 v[64:67], v[178:181], v[230:233], v[64:67]
	s_setprio 0
	s_barrier
	s_mov_b32 m0, s45
	s_add_u32 s30, s36, 0x40080
	ds_read_b128 v[182:185], v149 offset:49152
	ds_read_b128 v[206:209], v149 offset:50176
	ds_read_b128 v[210:213], v149 offset:51200
	ds_read_b128 v[214:217], v149 offset:52224
	ds_read_b128 v[218:221], v149 offset:53248
	ds_read_b128 v[222:225], v149 offset:54272
	ds_read_b128 v[226:229], v149 offset:55296
	ds_read_b128 v[230:233], v149 offset:56320
	global_load_lds_dwordx4 v154, s[98:99]
	s_mov_b32 m0, s46
	s_addc_u32 s31, s37, 0
	global_load_lds_dwordx4 v156, s[98:99]
	s_mov_b32 m0, s49
	s_add_u32 s66, s66, 0x100
	global_load_lds_dwordx4 v154, s[30:31]
	s_mov_b32 m0, s50
	s_addc_u32 s67, s67, 0
	global_load_lds_dwordx4 v156, s[30:31]
	s_mov_b32 m0, s47
	s_nop 0
	global_load_lds_dwordx4 v154, s[100:101]
	s_mov_b32 m0, s48
	s_nop 0
	global_load_lds_dwordx4 v156, s[100:101]
	s_waitcnt vmcnt(8)
	s_waitcnt lgkmcnt(0)
	s_barrier
	s_setprio 1
	s_waitcnt lgkmcnt(0)
	v_mfma_f32_16x16x32_bf16 v[60:63], v[128:131], v[182:185], v[60:63]
	v_mfma_f32_16x16x32_bf16 v[56:59], v[136:139], v[182:185], v[56:59]
	v_mfma_f32_16x16x32_bf16 v[44:47], v[128:131], v[210:213], v[44:47]
	v_mfma_f32_16x16x32_bf16 v[40:43], v[136:139], v[210:213], v[40:43]
	v_mfma_f32_16x16x32_bf16 v[28:31], v[128:131], v[218:221], v[28:31]
	v_mfma_f32_16x16x32_bf16 v[24:27], v[136:139], v[218:221], v[24:27]
	v_mfma_f32_16x16x32_bf16 v[12:15], v[128:131], v[226:229], v[12:15]
	v_mfma_f32_16x16x32_bf16 v[8:11], v[136:139], v[226:229], v[8:11]
	v_mfma_f32_16x16x32_bf16 v[60:63], v[132:135], v[206:209], v[60:63]
	v_mfma_f32_16x16x32_bf16 v[56:59], v[140:143], v[206:209], v[56:59]
	v_mfma_f32_16x16x32_bf16 v[44:47], v[132:135], v[214:217], v[44:47]
	v_mfma_f32_16x16x32_bf16 v[40:43], v[140:143], v[214:217], v[40:43]
	v_mfma_f32_16x16x32_bf16 v[28:31], v[132:135], v[222:225], v[28:31]
	v_mfma_f32_16x16x32_bf16 v[24:27], v[140:143], v[222:225], v[24:27]
	v_mfma_f32_16x16x32_bf16 v[12:15], v[132:135], v[230:233], v[12:15]
	v_mfma_f32_16x16x32_bf16 v[8:11], v[140:143], v[230:233], v[8:11]
	s_setprio 0
	s_setprio 1
	v_mfma_f32_16x16x32_bf16 v[52:55], v[166:169], v[182:185], v[52:55]
	v_mfma_f32_16x16x32_bf16 v[48:51], v[174:177], v[182:185], v[48:51]
	v_mfma_f32_16x16x32_bf16 v[36:39], v[166:169], v[210:213], v[36:39]
	v_mfma_f32_16x16x32_bf16 v[32:35], v[174:177], v[210:213], v[32:35]
	v_mfma_f32_16x16x32_bf16 v[20:23], v[166:169], v[218:221], v[20:23]
	v_mfma_f32_16x16x32_bf16 v[16:19], v[174:177], v[218:221], v[16:19]
	v_mfma_f32_16x16x32_bf16 v[4:7], v[166:169], v[226:229], v[4:7]
	v_mfma_f32_16x16x32_bf16 v[0:3], v[174:177], v[226:229], v[0:3]
	v_mfma_f32_16x16x32_bf16 v[52:55], v[170:173], v[206:209], v[52:55]
	v_mfma_f32_16x16x32_bf16 v[48:51], v[178:181], v[206:209], v[48:51]
	v_mfma_f32_16x16x32_bf16 v[36:39], v[170:173], v[214:217], v[36:39]
	v_mfma_f32_16x16x32_bf16 v[32:35], v[178:181], v[214:217], v[32:35]
	v_mfma_f32_16x16x32_bf16 v[20:23], v[170:173], v[222:225], v[20:23]
	v_mfma_f32_16x16x32_bf16 v[16:19], v[178:181], v[222:225], v[16:19]
	v_mfma_f32_16x16x32_bf16 v[4:7], v[170:173], v[230:233], v[4:7]
	v_mfma_f32_16x16x32_bf16 v[0:3], v[178:181], v[230:233], v[0:3]
	s_setprio 0
	s_barrier
	s_add_i32 s68, s68, 2
	s_cmp_gt_u32 s68, 13
	s_mov_b64 s[30:31], s[34:35]
	s_cbranch_scc0 .LBB0_3534
	s_and_b64 vcc, exec, s[16:17]
	s_cbranch_vccz .LBB0_3537
	s_barrier

.LBB0_3663:
	ds_read_b128 v[164:167], v143
	ds_read_b128 v[168:171], v147
	ds_read_b128 v[172:175], v148
	ds_read_b128 v[176:179], v149
	ds_read_b128 v[180:183], v151
	ds_read_b128 v[184:187], v153
	ds_read_b128 v[188:191], v154
	ds_read_b128 v[192:195], v155
	s_add_u32 s24, s22, 0xfffc0080
	s_addc_u32 s25, s23, -1
	s_cmp_eq_u32 s53, 12
	s_cselect_b32 s27, s4, s25
	s_cselect_b32 s26, s5, s24
	s_cselect_b32 s25, s13, s52
	s_cselect_b32 s24, s15, s51
	s_mov_b32 m0, s47
	ds_read_b128 v[196:199], v141
	ds_read_b128 v[200:203], v141 offset:1024
	ds_read_b128 v[204:207], v141 offset:2048
	ds_read_b128 v[208:211], v141 offset:3072
	ds_read_b128 v[212:215], v141 offset:4096
	ds_read_b128 v[216:219], v141 offset:5120
	ds_read_b128 v[220:223], v141 offset:6144
	ds_read_b128 v[224:227], v141 offset:7168
	global_load_lds_dwordx4 v132, s[22:23]
	s_mov_b32 m0, s48
	s_nop 0
	global_load_lds_dwordx4 v134, s[22:23]
	s_waitcnt vmcnt(8)
	s_waitcnt lgkmcnt(0)
	s_barrier
	s_setprio 1
	s_waitcnt lgkmcnt(0)
	v_mfma_f32_16x16x32_bf16 v[124:127], v[164:167], v[196:199], v[124:127]
	v_mfma_f32_16x16x32_bf16 v[120:123], v[172:175], v[196:199], v[120:123]
	v_mfma_f32_16x16x32_bf16 v[108:111], v[164:167], v[204:207], v[108:111]
	v_mfma_f32_16x16x32_bf16 v[104:107], v[172:175], v[204:207], v[104:107]
	v_mfma_f32_16x16x32_bf16 v[92:95], v[164:167], v[212:215], v[92:95]
	v_mfma_f32_16x16x32_bf16 v[88:91], v[172:175], v[212:215], v[88:91]
	v_mfma_f32_16x16x32_bf16 v[76:79], v[164:167], v[220:223], v[76:79]
	v_mfma_f32_16x16x32_bf16 v[72:75], v[172:175], v[220:223], v[72:75]
	v_mfma_f32_16x16x32_bf16 v[124:127], v[168:171], v[200:203], v[124:127]
	v_mfma_f32_16x16x32_bf16 v[120:123], v[176:179], v[200:203], v[120:123]
	v_mfma_f32_16x16x32_bf16 v[108:111], v[168:171], v[208:211], v[108:111]
	v_mfma_f32_16x16x32_bf16 v[104:107], v[176:179], v[208:211], v[104:107]
	v_mfma_f32_16x16x32_bf16 v[92:95], v[168:171], v[216:219], v[92:95]
	v_mfma_f32_16x16x32_bf16 v[88:91], v[176:179], v[216:219], v[88:91]
	v_mfma_f32_16x16x32_bf16 v[76:79], v[168:171], v[224:227], v[76:79]
	v_mfma_f32_16x16x32_bf16 v[72:75], v[176:179], v[224:227], v[72:75]
	s_setprio 0
	s_setprio 1
	v_mfma_f32_16x16x32_bf16 v[116:119], v[180:183], v[196:199], v[116:119]
	v_mfma_f32_16x16x32_bf16 v[112:115], v[188:191], v[196:199], v[112:115]
	v_mfma_f32_16x16x32_bf16 v[100:103], v[180:183], v[204:207], v[100:103]
	v_mfma_f32_16x16x32_bf16 v[96:99], v[188:191], v[204:207], v[96:99]
	v_mfma_f32_16x16x32_bf16 v[84:87], v[180:183], v[212:215], v[84:87]
	v_mfma_f32_16x16x32_bf16 v[80:83], v[188:191], v[212:215], v[80:83]
	v_mfma_f32_16x16x32_bf16 v[68:71], v[180:183], v[220:223], v[68:71]
	v_mfma_f32_16x16x32_bf16 v[64:67], v[188:191], v[220:223], v[64:67]
	v_mfma_f32_16x16x32_bf16 v[116:119], v[184:187], v[200:203], v[116:119]
	v_mfma_f32_16x16x32_bf16 v[112:115], v[192:195], v[200:203], v[112:115]
	v_mfma_f32_16x16x32_bf16 v[100:103], v[184:187], v[208:211], v[100:103]
	v_mfma_f32_16x16x32_bf16 v[96:99], v[192:195], v[208:211], v[96:99]
	v_mfma_f32_16x16x32_bf16 v[84:87], v[184:187], v[216:219], v[84:87]
	v_mfma_f32_16x16x32_bf16 v[80:83], v[192:195], v[216:219], v[80:83]
	v_mfma_f32_16x16x32_bf16 v[68:71], v[184:187], v[224:227], v[68:71]
	v_mfma_f32_16x16x32_bf16 v[64:67], v[192:195], v[224:227], v[64:67]
	s_setprio 0
	s_barrier
	s_mov_b32 m0, s21
	s_add_u32 s54, s24, 0x40000
	ds_read_b128 v[196:199], v141 offset:16384
	ds_read_b128 v[200:203], v141 offset:17408
	ds_read_b128 v[204:207], v141 offset:18432
	ds_read_b128 v[208:211], v141 offset:19456
	ds_read_b128 v[212:215], v141 offset:20480
	ds_read_b128 v[216:219], v141 offset:21504
	ds_read_b128 v[220:223], v141 offset:22528
	ds_read_b128 v[224:227], v141 offset:23552
	global_load_lds_dwordx4 v130, s[24:25]
	s_mov_b32 m0, s30
	s_addc_u32 s55, s25, 0
	global_load_lds_dwordx4 v128, s[24:25]
	s_mov_b32 m0, s31
	s_add_u32 s98, s24, s8
	global_load_lds_dwordx4 v130, s[54:55]
	s_mov_b32 m0, s33
	s_addc_u32 s99, s25, s9
	global_load_lds_dwordx4 v128, s[54:55]
	s_mov_b32 m0, s2
	s_add_u32 s100, s26, s8
	global_load_lds_dwordx4 v130, s[26:27]
	s_mov_b32 m0, s34
	s_addc_u32 s101, s27, s9
	global_load_lds_dwordx4 v128, s[26:27]
	s_waitcnt vmcnt(8)
	s_waitcnt lgkmcnt(0)
	s_barrier
	s_setprio 1
	s_waitcnt lgkmcnt(0)
	v_mfma_f32_16x16x32_bf16 v[60:63], v[164:167], v[196:199], v[60:63]
	v_mfma_f32_16x16x32_bf16 v[56:59], v[172:175], v[196:199], v[56:59]
	v_mfma_f32_16x16x32_bf16 v[44:47], v[164:167], v[204:207], v[44:47]
	v_mfma_f32_16x16x32_bf16 v[40:43], v[172:175], v[204:207], v[40:43]
	v_mfma_f32_16x16x32_bf16 v[28:31], v[164:167], v[212:215], v[28:31]
	v_mfma_f32_16x16x32_bf16 v[24:27], v[172:175], v[212:215], v[24:27]
	v_mfma_f32_16x16x32_bf16 v[12:15], v[164:167], v[220:223], v[12:15]
	v_mfma_f32_16x16x32_bf16 v[8:11], v[172:175], v[220:223], v[8:11]
	v_mfma_f32_16x16x32_bf16 v[60:63], v[168:171], v[200:203], v[60:63]
	v_mfma_f32_16x16x32_bf16 v[56:59], v[176:179], v[200:203], v[56:59]
	v_mfma_f32_16x16x32_bf16 v[44:47], v[168:171], v[208:211], v[44:47]
	v_mfma_f32_16x16x32_bf16 v[40:43], v[176:179], v[208:211], v[40:43]
	v_mfma_f32_16x16x32_bf16 v[28:31], v[168:171], v[216:219], v[28:31]
	v_mfma_f32_16x16x32_bf16 v[24:27], v[176:179], v[216:219], v[24:27]
	v_mfma_f32_16x16x32_bf16 v[12:15], v[168:171], v[224:227], v[12:15]
	v_mfma_f32_16x16x32_bf16 v[8:11], v[176:179], v[224:227], v[8:11]
	s_setprio 0
	s_setprio 1
	v_mfma_f32_16x16x32_bf16 v[52:55], v[180:183], v[196:199], v[52:55]
	v_mfma_f32_16x16x32_bf16 v[48:51], v[188:191], v[196:199], v[48:51]
	v_mfma_f32_16x16x32_bf16 v[36:39], v[180:183], v[204:207], v[36:39]
	v_mfma_f32_16x16x32_bf16 v[32:35], v[188:191], v[204:207], v[32:35]
	v_mfma_f32_16x16x32_bf16 v[20:23], v[180:183], v[212:215], v[20:23]
	v_mfma_f32_16x16x32_bf16 v[16:19], v[188:191], v[212:215], v[16:19]
	v_mfma_f32_16x16x32_bf16 v[4:7], v[180:183], v[220:223], v[4:7]
	v_mfma_f32_16x16x32_bf16 v[0:3], v[188:191], v[220:223], v[0:3]
	v_mfma_f32_16x16x32_bf16 v[52:55], v[184:187], v[200:203], v[52:55]
	v_mfma_f32_16x16x32_bf16 v[48:51], v[192:195], v[200:203], v[48:51]
	v_mfma_f32_16x16x32_bf16 v[36:39], v[184:187], v[208:211], v[36:39]
	v_mfma_f32_16x16x32_bf16 v[32:35], v[192:195], v[208:211], v[32:35]
	v_mfma_f32_16x16x32_bf16 v[20:23], v[184:187], v[216:219], v[20:23]
	v_mfma_f32_16x16x32_bf16 v[16:19], v[192:195], v[216:219], v[16:19]
	v_mfma_f32_16x16x32_bf16 v[4:7], v[184:187], v[224:227], v[4:7]
	v_mfma_f32_16x16x32_bf16 v[0:3], v[192:195], v[224:227], v[0:3]
	s_setprio 0
	s_barrier
	ds_read_b128 v[164:167], v156
	ds_read_b128 v[168:171], v157
	ds_read_b128 v[172:175], v158
	ds_read_b128 v[176:179], v159
	ds_read_b128 v[180:183], v160
	ds_read_b128 v[184:187], v161
	ds_read_b128 v[188:191], v162
	ds_read_b128 v[192:195], v163
	s_add_u32 s26, s26, 0x40000
	s_addc_u32 s27, s27, 0
	s_mov_b32 m0, s35
	ds_read_b128 v[196:199], v141 offset:32768
	ds_read_b128 v[200:203], v141 offset:33792
	ds_read_b128 v[204:207], v141 offset:34816
	ds_read_b128 v[208:211], v141 offset:35840
	ds_read_b128 v[212:215], v141 offset:36864
	ds_read_b128 v[216:219], v141 offset:37888
	ds_read_b128 v[220:223], v141 offset:38912
	ds_read_b128 v[224:227], v141 offset:39936
	global_load_lds_dwordx4 v130, s[26:27]
	s_mov_b32 m0, s36
	s_nop 0
	global_load_lds_dwordx4 v128, s[26:27]
	s_waitcnt vmcnt(8)
	s_waitcnt lgkmcnt(0)
	s_barrier
	s_setprio 1
	s_waitcnt lgkmcnt(0)
	v_mfma_f32_16x16x32_bf16 v[124:127], v[164:167], v[196:199], v[124:127]
	v_mfma_f32_16x16x32_bf16 v[120:123], v[172:175], v[196:199], v[120:123]
	v_mfma_f32_16x16x32_bf16 v[108:111], v[164:167], v[204:207], v[108:111]
	v_mfma_f32_16x16x32_bf16 v[104:107], v[172:175], v[204:207], v[104:107]
	v_mfma_f32_16x16x32_bf16 v[92:95], v[164:167], v[212:215], v[92:95]
	v_mfma_f32_16x16x32_bf16 v[88:91], v[172:175], v[212:215], v[88:91]
	v_mfma_f32_16x16x32_bf16 v[76:79], v[164:167], v[220:223], v[76:79]
	v_mfma_f32_16x16x32_bf16 v[72:75], v[172:175], v[220:223], v[72:75]
	v_mfma_f32_16x16x32_bf16 v[124:127], v[168:171], v[200:203], v[124:127]
	v_mfma_f32_16x16x32_bf16 v[120:123], v[176:179], v[200:203], v[120:123]
	v_mfma_f32_16x16x32_bf16 v[108:111], v[168:171], v[208:211], v[108:111]
	v_mfma_f32_16x16x32_bf16 v[104:107], v[176:179], v[208:211], v[104:107]
	v_mfma_f32_16x16x32_bf16 v[92:95], v[168:171], v[216:219], v[92:95]
	v_mfma_f32_16x16x32_bf16 v[88:91], v[176:179], v[216:219], v[88:91]
	v_mfma_f32_16x16x32_bf16 v[76:79], v[168:171], v[224:227], v[76:79]
	v_mfma_f32_16x16x32_bf16 v[72:75], v[176:179], v[224:227], v[72:75]
	s_setprio 0
	s_setprio 1
	v_mfma_f32_16x16x32_bf16 v[116:119], v[180:183], v[196:199], v[116:119]
	v_mfma_f32_16x16x32_bf16 v[112:115], v[188:191], v[196:199], v[112:115]
	v_mfma_f32_16x16x32_bf16 v[100:103], v[180:183], v[204:207], v[100:103]
	v_mfma_f32_16x16x32_bf16 v[96:99], v[188:191], v[204:207], v[96:99]
	v_mfma_f32_16x16x32_bf16 v[84:87], v[180:183], v[212:215], v[84:87]
	v_mfma_f32_16x16x32_bf16 v[80:83], v[188:191], v[212:215], v[80:83]
	v_mfma_f32_16x16x32_bf16 v[68:71], v[180:183], v[220:223], v[68:71]
	v_mfma_f32_16x16x32_bf16 v[64:67], v[188:191], v[220:223], v[64:67]
	v_mfma_f32_16x16x32_bf16 v[116:119], v[184:187], v[200:203], v[116:119]
	v_mfma_f32_16x16x32_bf16 v[112:115], v[192:195], v[200:203], v[112:115]
	v_mfma_f32_16x16x32_bf16 v[100:103], v[184:187], v[208:211], v[100:103]
	v_mfma_f32_16x16x32_bf16 v[96:99], v[192:195], v[208:211], v[96:99]
	v_mfma_f32_16x16x32_bf16 v[84:87], v[184:187], v[216:219], v[84:87]
	v_mfma_f32_16x16x32_bf16 v[80:83], v[192:195], v[216:219], v[80:83]
	v_mfma_f32_16x16x32_bf16 v[68:71], v[184:187], v[224:227], v[68:71]
	v_mfma_f32_16x16x32_bf16 v[64:67], v[192:195], v[224:227], v[64:67]
	s_setprio 0
	s_barrier
	s_mov_b32 m0, s39
	s_add_u32 s24, s24, 0x40080
	ds_read_b128 v[196:199], v141 offset:49152
	ds_read_b128 v[200:203], v141 offset:50176
	ds_read_b128 v[204:207], v141 offset:51200
	ds_read_b128 v[208:211], v141 offset:52224
	ds_read_b128 v[212:215], v141 offset:53248
	ds_read_b128 v[216:219], v141 offset:54272
	ds_read_b128 v[220:223], v141 offset:55296
	ds_read_b128 v[224:227], v141 offset:56320
	global_load_lds_dwordx4 v130, s[98:99]
	s_mov_b32 m0, s40
	s_addc_u32 s25, s25, 0
	global_load_lds_dwordx4 v128, s[98:99]
	s_mov_b32 m0, s43
	s_add_u32 s22, s22, 0x100
	global_load_lds_dwordx4 v130, s[24:25]
	s_mov_b32 m0, s44
	s_addc_u32 s23, s23, 0
	global_load_lds_dwordx4 v128, s[24:25]
	s_mov_b32 m0, s41
	s_add_u32 s51, s51, 0x100
	global_load_lds_dwordx4 v130, s[100:101]
	s_mov_b32 m0, s42
	s_addc_u32 s52, s52, 0
	global_load_lds_dwordx4 v128, s[100:101]
	s_waitcnt vmcnt(8)
	s_waitcnt lgkmcnt(0)
	s_barrier
	s_setprio 1
	s_waitcnt lgkmcnt(0)
	v_mfma_f32_16x16x32_bf16 v[60:63], v[164:167], v[196:199], v[60:63]
	v_mfma_f32_16x16x32_bf16 v[56:59], v[172:175], v[196:199], v[56:59]
	v_mfma_f32_16x16x32_bf16 v[44:47], v[164:167], v[204:207], v[44:47]
	v_mfma_f32_16x16x32_bf16 v[40:43], v[172:175], v[204:207], v[40:43]
	v_mfma_f32_16x16x32_bf16 v[28:31], v[164:167], v[212:215], v[28:31]
	v_mfma_f32_16x16x32_bf16 v[24:27], v[172:175], v[212:215], v[24:27]
	v_mfma_f32_16x16x32_bf16 v[12:15], v[164:167], v[220:223], v[12:15]
	v_mfma_f32_16x16x32_bf16 v[8:11], v[172:175], v[220:223], v[8:11]
	v_mfma_f32_16x16x32_bf16 v[60:63], v[168:171], v[200:203], v[60:63]
	v_mfma_f32_16x16x32_bf16 v[56:59], v[176:179], v[200:203], v[56:59]
	v_mfma_f32_16x16x32_bf16 v[44:47], v[168:171], v[208:211], v[44:47]
	v_mfma_f32_16x16x32_bf16 v[40:43], v[176:179], v[208:211], v[40:43]
	v_mfma_f32_16x16x32_bf16 v[28:31], v[168:171], v[216:219], v[28:31]
	v_mfma_f32_16x16x32_bf16 v[24:27], v[176:179], v[216:219], v[24:27]
	v_mfma_f32_16x16x32_bf16 v[12:15], v[168:171], v[224:227], v[12:15]
	v_mfma_f32_16x16x32_bf16 v[8:11], v[176:179], v[224:227], v[8:11]
	s_setprio 0
	s_setprio 1
	v_mfma_f32_16x16x32_bf16 v[52:55], v[180:183], v[196:199], v[52:55]
	v_mfma_f32_16x16x32_bf16 v[48:51], v[188:191], v[196:199], v[48:51]
	v_mfma_f32_16x16x32_bf16 v[36:39], v[180:183], v[204:207], v[36:39]
	v_mfma_f32_16x16x32_bf16 v[32:35], v[188:191], v[204:207], v[32:35]
	v_mfma_f32_16x16x32_bf16 v[20:23], v[180:183], v[212:215], v[20:23]
	v_mfma_f32_16x16x32_bf16 v[16:19], v[188:191], v[212:215], v[16:19]
	v_mfma_f32_16x16x32_bf16 v[4:7], v[180:183], v[220:223], v[4:7]
	v_mfma_f32_16x16x32_bf16 v[0:3], v[188:191], v[220:223], v[0:3]
	v_mfma_f32_16x16x32_bf16 v[52:55], v[184:187], v[200:203], v[52:55]
	v_mfma_f32_16x16x32_bf16 v[48:51], v[192:195], v[200:203], v[48:51]
	v_mfma_f32_16x16x32_bf16 v[36:39], v[184:187], v[208:211], v[36:39]
	v_mfma_f32_16x16x32_bf16 v[32:35], v[192:195], v[208:211], v[32:35]
	v_mfma_f32_16x16x32_bf16 v[20:23], v[184:187], v[216:219], v[20:23]
	v_mfma_f32_16x16x32_bf16 v[16:19], v[192:195], v[216:219], v[16:19]
	v_mfma_f32_16x16x32_bf16 v[4:7], v[184:187], v[224:227], v[4:7]
	v_mfma_f32_16x16x32_bf16 v[0:3], v[192:195], v[224:227], v[0:3]
	s_setprio 0
	s_barrier
	s_add_i32 s53, s53, 2
	s_cmp_gt_u32 s53, 13
	s_cbranch_scc0 .LBB0_3663
	s_and_b64 vcc, exec, s[10:11]
	s_cbranch_vccz .LBB0_3666
	s_barrier

.LBB0_3743:
	ds_read_b128 v[128:131], v185
	ds_read_b128 v[132:135], v186
	ds_read_b128 v[136:139], v187
	ds_read_b128 v[140:143], v188
	ds_read_b128 v[162:165], v189
	ds_read_b128 v[166:169], v190
	ds_read_b128 v[170:173], v191
	ds_read_b128 v[174:177], v192
	s_add_u32 s26, s24, 0x100
	s_addc_u32 s27, s25, 0
	s_cmp_eq_u32 s60, 40
	s_cselect_b32 s31, s7, s27
	s_cselect_b32 s30, s6, s26
	s_cselect_b32 s29, s23, s59
	s_cselect_b32 s28, s22, s58
	s_mov_b32 m0, s48
	ds_read_b128 v[178:181], v153
	ds_read_b128 v[202:205], v153 offset:1024
	ds_read_b128 v[206:209], v153 offset:2048
	ds_read_b128 v[210:213], v153 offset:3072
	ds_read_b128 v[214:217], v153 offset:4096
	ds_read_b128 v[218:221], v153 offset:5120
	ds_read_b128 v[222:225], v153 offset:6144
	ds_read_b128 v[226:229], v153 offset:7168
	global_load_lds_dwordx4 v146, s[24:25]
	s_mov_b32 m0, s49
	s_nop 0
	global_load_lds_dwordx4 v156, s[24:25]
	s_waitcnt vmcnt(8)
	s_waitcnt lgkmcnt(0)
	s_barrier
	s_setprio 1
	s_waitcnt lgkmcnt(0)
	v_mfma_f32_16x16x32_bf16 v[124:127], v[128:131], v[178:181], v[124:127]
	v_mfma_f32_16x16x32_bf16 v[120:123], v[136:139], v[178:181], v[120:123]
	v_mfma_f32_16x16x32_bf16 v[108:111], v[128:131], v[206:209], v[108:111]
	v_mfma_f32_16x16x32_bf16 v[104:107], v[136:139], v[206:209], v[104:107]
	v_mfma_f32_16x16x32_bf16 v[92:95], v[128:131], v[214:217], v[92:95]
	v_mfma_f32_16x16x32_bf16 v[88:91], v[136:139], v[214:217], v[88:91]
	v_mfma_f32_16x16x32_bf16 v[76:79], v[128:131], v[222:225], v[76:79]
	v_mfma_f32_16x16x32_bf16 v[72:75], v[136:139], v[222:225], v[72:75]
	v_mfma_f32_16x16x32_bf16 v[124:127], v[132:135], v[202:205], v[124:127]
	v_mfma_f32_16x16x32_bf16 v[120:123], v[140:143], v[202:205], v[120:123]
	v_mfma_f32_16x16x32_bf16 v[108:111], v[132:135], v[210:213], v[108:111]
	v_mfma_f32_16x16x32_bf16 v[104:107], v[140:143], v[210:213], v[104:107]
	v_mfma_f32_16x16x32_bf16 v[92:95], v[132:135], v[218:221], v[92:95]
	v_mfma_f32_16x16x32_bf16 v[88:91], v[140:143], v[218:221], v[88:91]
	v_mfma_f32_16x16x32_bf16 v[76:79], v[132:135], v[226:229], v[76:79]
	v_mfma_f32_16x16x32_bf16 v[72:75], v[140:143], v[226:229], v[72:75]
	s_setprio 0
	s_setprio 1
	v_mfma_f32_16x16x32_bf16 v[116:119], v[162:165], v[178:181], v[116:119]
	v_mfma_f32_16x16x32_bf16 v[112:115], v[170:173], v[178:181], v[112:115]
	v_mfma_f32_16x16x32_bf16 v[100:103], v[162:165], v[206:209], v[100:103]
	v_mfma_f32_16x16x32_bf16 v[96:99], v[170:173], v[206:209], v[96:99]
	v_mfma_f32_16x16x32_bf16 v[84:87], v[162:165], v[214:217], v[84:87]
	v_mfma_f32_16x16x32_bf16 v[80:83], v[170:173], v[214:217], v[80:83]
	v_mfma_f32_16x16x32_bf16 v[68:71], v[162:165], v[222:225], v[68:71]
	v_mfma_f32_16x16x32_bf16 v[64:67], v[170:173], v[222:225], v[64:67]
	v_mfma_f32_16x16x32_bf16 v[116:119], v[166:169], v[202:205], v[116:119]
	v_mfma_f32_16x16x32_bf16 v[112:115], v[174:177], v[202:205], v[112:115]
	v_mfma_f32_16x16x32_bf16 v[100:103], v[166:169], v[210:213], v[100:103]
	v_mfma_f32_16x16x32_bf16 v[96:99], v[174:177], v[210:213], v[96:99]
	v_mfma_f32_16x16x32_bf16 v[84:87], v[166:169], v[218:221], v[84:87]
	v_mfma_f32_16x16x32_bf16 v[80:83], v[174:177], v[218:221], v[80:83]
	v_mfma_f32_16x16x32_bf16 v[68:71], v[166:169], v[226:229], v[68:71]
	v_mfma_f32_16x16x32_bf16 v[64:67], v[174:177], v[226:229], v[64:67]
	s_setprio 0
	s_barrier
	s_mov_b32 m0, s5
	s_add_u32 s24, s28, 0xb0000
	ds_read_b128 v[178:181], v153 offset:16384
	ds_read_b128 v[202:205], v153 offset:17408
	ds_read_b128 v[206:209], v153 offset:18432
	ds_read_b128 v[210:213], v153 offset:19456
	ds_read_b128 v[214:217], v153 offset:20480
	ds_read_b128 v[218:221], v153 offset:21504
	ds_read_b128 v[222:225], v153 offset:22528
	ds_read_b128 v[226:229], v153 offset:23552
	global_load_lds_dwordx4 v148, s[28:29]
	s_mov_b32 m0, s21
	s_addc_u32 s25, s29, 0
	global_load_lds_dwordx4 v154, s[28:29]
	s_mov_b32 m0, s33
	s_add_u32 s98, s28, s16
	global_load_lds_dwordx4 v148, s[24:25]
	s_mov_b32 m0, s34
	s_addc_u32 s99, s29, s17
	global_load_lds_dwordx4 v154, s[24:25]
	s_mov_b32 m0, s4
	s_add_u32 s100, s30, s16
	global_load_lds_dwordx4 v148, s[30:31]
	s_mov_b32 m0, s35
	s_addc_u32 s101, s31, s17
	global_load_lds_dwordx4 v154, s[30:31]
	s_waitcnt vmcnt(8)
	s_waitcnt lgkmcnt(0)
	s_barrier
	s_setprio 1
	s_waitcnt lgkmcnt(0)
	v_mfma_f32_16x16x32_bf16 v[60:63], v[128:131], v[178:181], v[60:63]
	v_mfma_f32_16x16x32_bf16 v[56:59], v[136:139], v[178:181], v[56:59]
	v_mfma_f32_16x16x32_bf16 v[44:47], v[128:131], v[206:209], v[44:47]
	v_mfma_f32_16x16x32_bf16 v[40:43], v[136:139], v[206:209], v[40:43]
	v_mfma_f32_16x16x32_bf16 v[28:31], v[128:131], v[214:217], v[28:31]
	v_mfma_f32_16x16x32_bf16 v[24:27], v[136:139], v[214:217], v[24:27]
	v_mfma_f32_16x16x32_bf16 v[12:15], v[128:131], v[222:225], v[12:15]
	v_mfma_f32_16x16x32_bf16 v[8:11], v[136:139], v[222:225], v[8:11]
	v_mfma_f32_16x16x32_bf16 v[60:63], v[132:135], v[202:205], v[60:63]
	v_mfma_f32_16x16x32_bf16 v[56:59], v[140:143], v[202:205], v[56:59]
	v_mfma_f32_16x16x32_bf16 v[44:47], v[132:135], v[210:213], v[44:47]
	v_mfma_f32_16x16x32_bf16 v[40:43], v[140:143], v[210:213], v[40:43]
	v_mfma_f32_16x16x32_bf16 v[28:31], v[132:135], v[218:221], v[28:31]
	v_mfma_f32_16x16x32_bf16 v[24:27], v[140:143], v[218:221], v[24:27]
	v_mfma_f32_16x16x32_bf16 v[12:15], v[132:135], v[226:229], v[12:15]
	v_mfma_f32_16x16x32_bf16 v[8:11], v[140:143], v[226:229], v[8:11]
	s_setprio 0
	s_setprio 1
	v_mfma_f32_16x16x32_bf16 v[52:55], v[162:165], v[178:181], v[52:55]
	v_mfma_f32_16x16x32_bf16 v[48:51], v[170:173], v[178:181], v[48:51]
	v_mfma_f32_16x16x32_bf16 v[36:39], v[162:165], v[206:209], v[36:39]
	v_mfma_f32_16x16x32_bf16 v[32:35], v[170:173], v[206:209], v[32:35]
	v_mfma_f32_16x16x32_bf16 v[20:23], v[162:165], v[214:217], v[20:23]
	v_mfma_f32_16x16x32_bf16 v[16:19], v[170:173], v[214:217], v[16:19]
	v_mfma_f32_16x16x32_bf16 v[4:7], v[162:165], v[222:225], v[4:7]
	v_mfma_f32_16x16x32_bf16 v[0:3], v[170:173], v[222:225], v[0:3]
	v_mfma_f32_16x16x32_bf16 v[52:55], v[166:169], v[202:205], v[52:55]
	v_mfma_f32_16x16x32_bf16 v[48:51], v[174:177], v[202:205], v[48:51]
	v_mfma_f32_16x16x32_bf16 v[36:39], v[166:169], v[210:213], v[36:39]
	v_mfma_f32_16x16x32_bf16 v[32:35], v[174:177], v[210:213], v[32:35]
	v_mfma_f32_16x16x32_bf16 v[20:23], v[166:169], v[218:221], v[20:23]
	v_mfma_f32_16x16x32_bf16 v[16:19], v[174:177], v[218:221], v[16:19]
	v_mfma_f32_16x16x32_bf16 v[4:7], v[166:169], v[226:229], v[4:7]
	v_mfma_f32_16x16x32_bf16 v[0:3], v[174:177], v[226:229], v[0:3]
	s_setprio 0
	s_barrier
	ds_read_b128 v[128:131], v193
	ds_read_b128 v[132:135], v194
	ds_read_b128 v[136:139], v195
	ds_read_b128 v[140:143], v196
	ds_read_b128 v[162:165], v197
	ds_read_b128 v[166:169], v198
	ds_read_b128 v[170:173], v199
	ds_read_b128 v[174:177], v200
	s_add_u32 s24, s30, 0xb0000
	s_addc_u32 s25, s31, 0
	s_mov_b32 m0, s36
	ds_read_b128 v[178:181], v153 offset:32768
	ds_read_b128 v[202:205], v153 offset:33792
	ds_read_b128 v[206:209], v153 offset:34816
	ds_read_b128 v[210:213], v153 offset:35840
	ds_read_b128 v[214:217], v153 offset:36864
	ds_read_b128 v[218:221], v153 offset:37888
	ds_read_b128 v[222:225], v153 offset:38912
	ds_read_b128 v[226:229], v153 offset:39936
	global_load_lds_dwordx4 v148, s[24:25]
	s_mov_b32 m0, s37
	s_nop 0
	global_load_lds_dwordx4 v154, s[24:25]
	s_waitcnt vmcnt(8)
	s_waitcnt lgkmcnt(0)
	s_barrier
	s_setprio 1
	s_waitcnt lgkmcnt(0)
	v_mfma_f32_16x16x32_bf16 v[124:127], v[128:131], v[178:181], v[124:127]
	v_mfma_f32_16x16x32_bf16 v[120:123], v[136:139], v[178:181], v[120:123]
	v_mfma_f32_16x16x32_bf16 v[108:111], v[128:131], v[206:209], v[108:111]
	v_mfma_f32_16x16x32_bf16 v[104:107], v[136:139], v[206:209], v[104:107]
	v_mfma_f32_16x16x32_bf16 v[92:95], v[128:131], v[214:217], v[92:95]
	v_mfma_f32_16x16x32_bf16 v[88:91], v[136:139], v[214:217], v[88:91]
	v_mfma_f32_16x16x32_bf16 v[76:79], v[128:131], v[222:225], v[76:79]
	v_mfma_f32_16x16x32_bf16 v[72:75], v[136:139], v[222:225], v[72:75]
	v_mfma_f32_16x16x32_bf16 v[124:127], v[132:135], v[202:205], v[124:127]
	v_mfma_f32_16x16x32_bf16 v[120:123], v[140:143], v[202:205], v[120:123]
	v_mfma_f32_16x16x32_bf16 v[108:111], v[132:135], v[210:213], v[108:111]
	v_mfma_f32_16x16x32_bf16 v[104:107], v[140:143], v[210:213], v[104:107]
	v_mfma_f32_16x16x32_bf16 v[92:95], v[132:135], v[218:221], v[92:95]
	v_mfma_f32_16x16x32_bf16 v[88:91], v[140:143], v[218:221], v[88:91]
	v_mfma_f32_16x16x32_bf16 v[76:79], v[132:135], v[226:229], v[76:79]
	v_mfma_f32_16x16x32_bf16 v[72:75], v[140:143], v[226:229], v[72:75]
	s_setprio 0
	s_setprio 1
	v_mfma_f32_16x16x32_bf16 v[116:119], v[162:165], v[178:181], v[116:119]
	v_mfma_f32_16x16x32_bf16 v[112:115], v[170:173], v[178:181], v[112:115]
	v_mfma_f32_16x16x32_bf16 v[100:103], v[162:165], v[206:209], v[100:103]
	v_mfma_f32_16x16x32_bf16 v[96:99], v[170:173], v[206:209], v[96:99]
	v_mfma_f32_16x16x32_bf16 v[84:87], v[162:165], v[214:217], v[84:87]
	v_mfma_f32_16x16x32_bf16 v[80:83], v[170:173], v[214:217], v[80:83]
	v_mfma_f32_16x16x32_bf16 v[68:71], v[162:165], v[222:225], v[68:71]
	v_mfma_f32_16x16x32_bf16 v[64:67], v[170:173], v[222:225], v[64:67]
	v_mfma_f32_16x16x32_bf16 v[116:119], v[166:169], v[202:205], v[116:119]
	v_mfma_f32_16x16x32_bf16 v[112:115], v[174:177], v[202:205], v[112:115]
	v_mfma_f32_16x16x32_bf16 v[100:103], v[166:169], v[210:213], v[100:103]
	v_mfma_f32_16x16x32_bf16 v[96:99], v[174:177], v[210:213], v[96:99]
	v_mfma_f32_16x16x32_bf16 v[84:87], v[166:169], v[218:221], v[84:87]
	v_mfma_f32_16x16x32_bf16 v[80:83], v[174:177], v[218:221], v[80:83]
	v_mfma_f32_16x16x32_bf16 v[68:71], v[166:169], v[226:229], v[68:71]
	v_mfma_f32_16x16x32_bf16 v[64:67], v[174:177], v[226:229], v[64:67]
	s_setprio 0
	s_barrier
	s_mov_b32 m0, s38
	s_add_u32 s24, s28, 0xb0080
	ds_read_b128 v[178:181], v153 offset:49152
	ds_read_b128 v[202:205], v153 offset:50176
	ds_read_b128 v[206:209], v153 offset:51200
	ds_read_b128 v[210:213], v153 offset:52224
	ds_read_b128 v[214:217], v153 offset:53248
	ds_read_b128 v[218:221], v153 offset:54272
	ds_read_b128 v[222:225], v153 offset:55296
	ds_read_b128 v[226:229], v153 offset:56320
	global_load_lds_dwordx4 v148, s[98:99]
	s_mov_b32 m0, s39
	s_addc_u32 s25, s29, 0
	global_load_lds_dwordx4 v154, s[98:99]
	s_mov_b32 m0, s42
	s_add_u32 s58, s58, 0x100
	global_load_lds_dwordx4 v148, s[24:25]
	s_mov_b32 m0, s43
	s_addc_u32 s59, s59, 0
	global_load_lds_dwordx4 v154, s[24:25]
	s_mov_b32 m0, s40
	s_nop 0
	global_load_lds_dwordx4 v148, s[100:101]
	s_mov_b32 m0, s41
	s_nop 0
	global_load_lds_dwordx4 v154, s[100:101]
	s_waitcnt vmcnt(8)
	s_waitcnt lgkmcnt(0)
	s_barrier
	s_setprio 1
	s_waitcnt lgkmcnt(0)
	v_mfma_f32_16x16x32_bf16 v[60:63], v[128:131], v[178:181], v[60:63]
	v_mfma_f32_16x16x32_bf16 v[56:59], v[136:139], v[178:181], v[56:59]
	v_mfma_f32_16x16x32_bf16 v[44:47], v[128:131], v[206:209], v[44:47]
	v_mfma_f32_16x16x32_bf16 v[40:43], v[136:139], v[206:209], v[40:43]
	v_mfma_f32_16x16x32_bf16 v[28:31], v[128:131], v[214:217], v[28:31]
	v_mfma_f32_16x16x32_bf16 v[24:27], v[136:139], v[214:217], v[24:27]
	v_mfma_f32_16x16x32_bf16 v[12:15], v[128:131], v[222:225], v[12:15]
	v_mfma_f32_16x16x32_bf16 v[8:11], v[136:139], v[222:225], v[8:11]
	v_mfma_f32_16x16x32_bf16 v[60:63], v[132:135], v[202:205], v[60:63]
	v_mfma_f32_16x16x32_bf16 v[56:59], v[140:143], v[202:205], v[56:59]
	v_mfma_f32_16x16x32_bf16 v[44:47], v[132:135], v[210:213], v[44:47]
	v_mfma_f32_16x16x32_bf16 v[40:43], v[140:143], v[210:213], v[40:43]
	v_mfma_f32_16x16x32_bf16 v[28:31], v[132:135], v[218:221], v[28:31]
	v_mfma_f32_16x16x32_bf16 v[24:27], v[140:143], v[218:221], v[24:27]
	v_mfma_f32_16x16x32_bf16 v[12:15], v[132:135], v[226:229], v[12:15]
	v_mfma_f32_16x16x32_bf16 v[8:11], v[140:143], v[226:229], v[8:11]
	s_setprio 0
	s_setprio 1
	v_mfma_f32_16x16x32_bf16 v[52:55], v[162:165], v[178:181], v[52:55]
	v_mfma_f32_16x16x32_bf16 v[48:51], v[170:173], v[178:181], v[48:51]
	v_mfma_f32_16x16x32_bf16 v[36:39], v[162:165], v[206:209], v[36:39]
	v_mfma_f32_16x16x32_bf16 v[32:35], v[170:173], v[206:209], v[32:35]
	v_mfma_f32_16x16x32_bf16 v[20:23], v[162:165], v[214:217], v[20:23]
	v_mfma_f32_16x16x32_bf16 v[16:19], v[170:173], v[214:217], v[16:19]
	v_mfma_f32_16x16x32_bf16 v[4:7], v[162:165], v[222:225], v[4:7]
	v_mfma_f32_16x16x32_bf16 v[0:3], v[170:173], v[222:225], v[0:3]
	v_mfma_f32_16x16x32_bf16 v[52:55], v[166:169], v[202:205], v[52:55]
	v_mfma_f32_16x16x32_bf16 v[48:51], v[174:177], v[202:205], v[48:51]
	v_mfma_f32_16x16x32_bf16 v[36:39], v[166:169], v[210:213], v[36:39]
	v_mfma_f32_16x16x32_bf16 v[32:35], v[174:177], v[210:213], v[32:35]
	v_mfma_f32_16x16x32_bf16 v[20:23], v[166:169], v[218:221], v[20:23]
	v_mfma_f32_16x16x32_bf16 v[16:19], v[174:177], v[218:221], v[16:19]
	v_mfma_f32_16x16x32_bf16 v[4:7], v[166:169], v[226:229], v[4:7]
	v_mfma_f32_16x16x32_bf16 v[0:3], v[174:177], v[226:229], v[0:3]
	s_setprio 0
	s_barrier
	s_add_i32 s60, s60, 2
	s_cmp_gt_u32 s60, 41
	s_mov_b64 s[24:25], s[26:27]
	s_cbranch_scc0 .LBB0_3743
	s_and_b64 vcc, exec, s[18:19]
	s_cbranch_vccz .LBB0_3746
	s_barrier
